# combine: S_mid.q correction with K split over 8-lane groups (full-line loads) + DPP reduce-scatter; GEMM k-tile LDS reads hoisted, LDS writes interleaved into MFMA stream
# speedup vs baseline: 1.0448x; 1.0448x over previous
; template <class AS, class EP>
; DEVI void gemm_tile(const AS& as, const u16* __restrict__ Bt, int K, int m0, int n0, const EP& ep, char* lds) {
;     ...
;   GLOAD(ra0, rb0, 0); GLOAD(ra1, rb1, 1); LWRITE(0, ra0, rb0); __syncthreads();
;   for (int kt = 0; kt < KT; kt += 2) {
;     if (kt + 2 < KT) GLOAD(ra0, rb0, kt + 2);
;     __builtin_amdgcn_sched_barrier(0);
;     COMPUTE(0);
;     __builtin_amdgcn_sched_barrier(0);
;     LWRITE(1, ra1, rb1);
;     __syncthreads();
;     if (kt + 3 < KT) GLOAD(ra1, rb1, kt + 3);
;     __builtin_amdgcn_sched_barrier(0);
;     COMPUTE(1);
;     __builtin_amdgcn_sched_barrier(0);
;     if (kt + 2 < KT) LWRITE(0, ra0, rb0);
;     __syncthreads();
.LBB0_22:
	s_ashr_i32 s16, s44, 31
	s_lshr_b32 s16, s16, 29
	s_add_i32 s16, s44, s16
	v_mov_b32_e32 v32, v131
	s_ashr_i32 s17, s16, 3
	s_lshl_b32 s16, s17, 8
	v_lshlrev_b32_e32 v0, 4, v32
	v_ashrrev_i32_e32 v33, 3, v32
	v_and_b32_e32 v128, 0x70, v0
	s_lshl_b32 s17, s17, 10
	v_add_u32_e32 v124, s16, v33
	v_lshl_add_u64 v[12:13], s[0:1], 0, v[128:129]
	v_subrev_u32_e32 v16, s17, v33
	v_mad_i64_i32 v[0:1], s[38:39], v124, s35, v[12:13]
	v_add_u32_e32 v126, 64, v124
	v_add_u32_e32 v20, s28, v16
	global_load_dwordx4 v[0:3], v[0:1], off
	v_mad_i64_i32 v[4:5], s[38:39], v126, s35, v[12:13]
	v_add_u32_e32 v132, 0x80, v124
	v_ashrrev_i32_e32 v21, 31, v20
	global_load_dwordx4 v[4:7], v[4:5], off
	v_mad_i64_i32 v[8:9], s[38:39], v132, s35, v[12:13]
	v_add_u32_e32 v134, 0xc0, v124
	v_lshlrev_b64 v[24:25], 11, v[20:21]
	v_add_u32_e32 v20, 64, v20
	global_load_dwordx4 v[8:11], v[8:9], off
	v_mad_i64_i32 v[12:13], s[38:39], v134, s35, v[12:13]
	v_lshl_add_u64 v[22:23], s[6:7], 0, v[128:129]
	v_ashrrev_i32_e32 v21, 31, v20
	global_load_dwordx4 v[12:15], v[12:13], off
	v_lshl_add_u64 v[120:121], v[22:23], 0, v[24:25]
	v_lshlrev_b64 v[26:27], 11, v[20:21]
	global_load_dwordx4 v[16:19], v[120:121], off
	v_lshl_add_u64 v[122:123], v[22:23], 0, v[26:27]
	global_load_dwordx4 v[20:23], v[122:123], off
	v_mov_b64_e32 v[28:29], s[0:1]
	v_mad_i64_i32 v[30:31], s[38:39], v124, s35, v[28:29]
	v_lshl_add_u64 v[30:31], v[30:31], 0, v[128:129]
	global_load_dwordx4 v[64:67], v[30:31], off offset:128
	v_mad_i64_i32 v[30:31], s[38:39], v126, s35, v[28:29]
	v_lshl_add_u64 v[30:31], v[30:31], 0, v[128:129]
	global_load_dwordx4 v[68:71], v[30:31], off offset:128
	v_mad_i64_i32 v[30:31], s[38:39], v132, s35, v[28:29]
	v_mad_i64_i32 v[28:29], s[38:39], v134, s35, v[28:29]
	v_lshl_add_u64 v[24:25], s[6:7], 0, v[24:25]
	v_lshl_add_u64 v[28:29], v[28:29], 0, v[128:129]
	v_lshl_add_u64 v[24:25], v[24:25], 0, v[128:129]
	global_load_dwordx4 v[76:79], v[28:29], off offset:128
	global_load_dwordx4 v[80:83], v[24:25], off offset:128
	v_lshl_add_u64 v[24:25], s[6:7], 0, v[26:27]
	v_mul_lo_u32 v112, v33, s96
	v_lshl_add_u64 v[30:31], v[30:31], 0, v[128:129]
	v_lshl_add_u64 v[24:25], v[24:25], 0, v[128:129]
	v_add3_u32 v160, 16, v128, v112
	global_load_dwordx4 v[72:75], v[30:31], off offset:128
	global_load_dwordx4 v[84:87], v[24:25], off offset:128
	v_bfe_u32 v136, v32, 5, 1
	v_and_b32_e32 v137, 0x5f, v32
	v_readlane_b32 s29, v219, 49
	v_ashrrev_i32_e32 v125, 31, v124
	v_ashrrev_i32_e32 v127, 31, v126
	v_ashrrev_i32_e32 v133, 31, v132
	v_ashrrev_i32_e32 v135, 31, v134
	s_waitcnt vmcnt(11)
	ds_write_b128 v160, v[0:3]
	s_waitcnt vmcnt(10)
	ds_write_b128 v160, v[4:7] offset:9216
	s_waitcnt vmcnt(9)
	ds_write_b128 v160, v[8:11] offset:18432
	s_waitcnt vmcnt(8)
	ds_write_b128 v160, v[12:15] offset:27648
	s_waitcnt vmcnt(7)
	ds_write_b128 v160, v[16:19] offset:36864
	s_waitcnt vmcnt(6)
	ds_write_b128 v160, v[20:23] offset:46080
	v_ashrrev_i32_e32 v0, 1, v32
	v_and_b32_e32 v157, 0xffffffc0, v0
	v_and_or_b32 v0, v32, 31, v157
	v_mul_lo_u32 v0, v0, s96
	v_lshlrev_b32_e32 v1, 4, v136
	v_add3_u32 v158, 16, v0, v1
	v_mul_u32_u24_e32 v0, 0x90, v137
	v_add3_u32 v161, 16, v0, v1
	v_add3_u32 v159, s29, v0, v1
	v_mov_b64_e32 v[0:1], s[4:5]
	v_mad_i64_i32 v[2:3], s[38:39], v124, s35, v[0:1]
	v_lshl_add_u64 v[2:3], v[2:3], 0, v[128:129]
	s_waitcnt lgkmcnt(0)
	s_barrier
	global_load_dwordx4 v[88:91], v[2:3], off
	v_mad_i64_i32 v[2:3], s[38:39], v126, s35, v[0:1]
	v_lshl_add_u64 v[2:3], v[2:3], 0, v[128:129]
	global_load_dwordx4 v[92:95], v[2:3], off
	v_mad_i64_i32 v[2:3], s[38:39], v132, s35, v[0:1]
	v_mad_i64_i32 v[0:1], s[38:39], v134, s35, v[0:1]
	v_lshl_add_u64 v[2:3], v[2:3], 0, v[128:129]
	v_lshl_add_u64 v[0:1], v[0:1], 0, v[128:129]
	global_load_dwordx4 v[96:99], v[2:3], off
	global_load_dwordx4 v[100:103], v[0:1], off
	global_load_dwordx4 v[104:107], v[120:121], off offset:256
	global_load_dwordx4 v[108:111], v[122:123], off offset:256
	ds_read_b128 v[170:173], v158
	ds_read_b128 v[174:177], v161 offset:36864
	ds_read_b128 v[178:181], v161 offset:41472
	ds_read_b128 v[182:185], v158 offset:4608
	ds_read_b128 v[186:189], v158 offset:32
	ds_read_b128 v[190:193], v161 offset:36896
	ds_read_b128 v[194:197], v161 offset:41504
	ds_read_b128 v[198:201], v158 offset:4640
	ds_read_b128 v[202:205], v158 offset:64
	ds_read_b128 v[206:209], v161 offset:36928
	ds_read_b128 v[210:213], v161 offset:41536
	ds_read_b128 v[214:217], v158 offset:4672
	s_waitcnt lgkmcnt(10)
	v_mfma_f32_32x32x16_bf16 v[48:63], v[170:173], v[174:177], 0
	s_waitcnt lgkmcnt(9)
	v_mfma_f32_32x32x16_bf16 v[32:47], v[170:173], v[178:181], 0
	s_waitcnt lgkmcnt(8)
	v_mfma_f32_32x32x16_bf16 v[16:31], v[182:185], v[174:177], 0
	v_mfma_f32_32x32x16_bf16 v[0:15], v[182:185], v[178:181], 0
	ds_read_b128 v[222:225], v158 offset:96
	ds_read_b128 v[226:229], v161 offset:36960
	ds_read_b128 v[230:233], v161 offset:41568
	ds_read_b128 v[234:237], v158 offset:4704
	s_waitcnt lgkmcnt(10)
	v_mfma_f32_32x32x16_bf16 v[48:63], v[186:189], v[190:193], v[48:63]
	s_waitcnt lgkmcnt(9)
	v_mfma_f32_32x32x16_bf16 v[32:47], v[186:189], v[194:197], v[32:47]
	s_waitcnt lgkmcnt(8)
	v_mfma_f32_32x32x16_bf16 v[16:31], v[198:201], v[190:193], v[16:31]
	v_mfma_f32_32x32x16_bf16 v[0:15], v[198:201], v[194:197], v[0:15]
	v_readlane_b32 s38, v219, 63
	v_readlane_b32 s39, v218, 0
	v_add_u32_e32 v162, 0xd800, v160
	s_waitcnt vmcnt(11)
	ds_write_b128 v160, v[64:67] offset:55296
	s_waitcnt lgkmcnt(7)
	v_mfma_f32_32x32x16_bf16 v[48:63], v[202:205], v[206:209], v[48:63]
	s_waitcnt vmcnt(10)
	ds_write_b128 v160, v[68:71] offset:64512
	s_waitcnt lgkmcnt(7)
	v_mfma_f32_32x32x16_bf16 v[32:47], v[202:205], v[210:213], v[32:47]
	s_waitcnt vmcnt(7)
	ds_write_b128 v162, v[72:75] offset:18432
	s_waitcnt lgkmcnt(7)
	v_mfma_f32_32x32x16_bf16 v[16:31], v[214:217], v[206:209], v[16:31]
	v_mfma_f32_32x32x16_bf16 v[0:15], v[214:217], v[210:213], v[0:15]
	ds_write_b128 v162, v[76:79] offset:27648
	s_waitcnt lgkmcnt(6)
	v_mfma_f32_32x32x16_bf16 v[48:63], v[222:225], v[226:229], v[48:63]
	v_mov_b64_e32 v[72:73], s[38:39]
	v_mad_i64_i32 v[64:65], s[38:39], v124, s35, v[72:73]
	v_mad_i64_i32 v[66:67], s[38:39], v126, s35, v[72:73]
	v_mad_i64_i32 v[74:75], s[38:39], v132, s35, v[72:73]
	v_add3_u32 v163, s29, v128, v112
	v_lshl_add_u64 v[64:65], v[64:65], 0, v[128:129]
	v_lshl_add_u64 v[68:69], v[66:67], 0, v[128:129]
	v_lshl_add_u64 v[74:75], v[74:75], 0, v[128:129]
	v_mad_i64_i32 v[72:73], s[38:39], v134, s35, v[72:73]
	ds_write_b128 v163, v[80:83]
	s_waitcnt lgkmcnt(6)
	v_mfma_f32_32x32x16_bf16 v[32:47], v[222:225], v[230:233], v[32:47]
	s_waitcnt vmcnt(6)
	ds_write_b128 v163, v[84:87] offset:9216
	s_waitcnt lgkmcnt(6)
	v_mfma_f32_32x32x16_bf16 v[16:31], v[234:237], v[226:229], v[16:31]
	v_mfma_f32_32x32x16_bf16 v[0:15], v[234:237], v[230:233], v[0:15]
	s_waitcnt lgkmcnt(0)
	s_barrier
; template <class AS, class EP>
; DEVI void gemm_tile(const AS& as, const u16* __restrict__ Bt, int K, int m0, int n0, const EP& ep, char* lds) {
;     ...
;   GLOAD(ra0, rb0, 0); GLOAD(ra1, rb1, 1); LWRITE(0, ra0, rb0); __syncthreads();
;   for (int kt = 0; kt < KT; kt += 2) {
;     if (kt + 2 < KT) GLOAD(ra0, rb0, kt + 2);
;     __builtin_amdgcn_sched_barrier(0);
;     COMPUTE(0);
;     __builtin_amdgcn_sched_barrier(0);
;     LWRITE(1, ra1, rb1);
;     __syncthreads();
;     if (kt + 3 < KT) GLOAD(ra1, rb1, kt + 3);
;     __builtin_amdgcn_sched_barrier(0);
;     COMPUTE(1);
;     __builtin_amdgcn_sched_barrier(0);
;     if (kt + 2 < KT) LWRITE(0, ra0, rb0);
;     __syncthreads();
	global_load_dwordx4 v[64:67], v[64:65], off
	s_nop 0
	global_load_dwordx4 v[68:71], v[68:69], off
	v_lshl_add_u64 v[72:73], v[72:73], 0, v[128:129]
	global_load_dwordx4 v[80:83], v[74:75], off
	global_load_dwordx4 v[84:87], v[72:73], off
	global_load_dwordx4 v[112:115], v[120:121], off offset:384
	global_load_dwordx4 v[116:119], v[122:123], off offset:384
	ds_read_b128 v[170:173], v158 offset:55296
	ds_read_b128 v[174:177], v159
	ds_read_b128 v[178:181], v159 offset:4608
	ds_read_b128 v[182:185], v158 offset:59904
	ds_read_b128 v[186:189], v158 offset:55328
	ds_read_b128 v[190:193], v159 offset:32
	ds_read_b128 v[194:197], v159 offset:4640
	ds_read_b128 v[198:201], v158 offset:59936
	ds_read_b128 v[202:205], v158 offset:55360
	ds_read_b128 v[206:209], v159 offset:64
	ds_read_b128 v[210:213], v159 offset:4672
	ds_read_b128 v[214:217], v158 offset:59968
	s_waitcnt lgkmcnt(10)
	v_mfma_f32_32x32x16_bf16 v[48:63], v[170:173], v[174:177], v[48:63]
	s_waitcnt lgkmcnt(9)
	v_mfma_f32_32x32x16_bf16 v[32:47], v[170:173], v[178:181], v[32:47]
	s_waitcnt lgkmcnt(8)
	v_mfma_f32_32x32x16_bf16 v[16:31], v[182:185], v[174:177], v[16:31]
	v_mfma_f32_32x32x16_bf16 v[0:15], v[182:185], v[178:181], v[0:15]
	ds_read_b128 v[222:225], v158 offset:55392
	ds_read_b128 v[226:229], v159 offset:96
	ds_read_b128 v[230:233], v159 offset:4704
	ds_read_b128 v[234:237], v158 offset:60000
	s_waitcnt lgkmcnt(10)
	v_mfma_f32_32x32x16_bf16 v[48:63], v[186:189], v[190:193], v[48:63]
	s_waitcnt lgkmcnt(9)
	v_mfma_f32_32x32x16_bf16 v[32:47], v[186:189], v[194:197], v[32:47]
	s_waitcnt lgkmcnt(8)
	v_mfma_f32_32x32x16_bf16 v[16:31], v[198:201], v[190:193], v[16:31]
	v_mfma_f32_32x32x16_bf16 v[0:15], v[198:201], v[194:197], v[0:15]
	v_readlane_b32 s38, v219, 59
	v_readlane_b32 s39, v219, 60
	s_waitcnt vmcnt(11)
	ds_write_b128 v160, v[88:91]
	s_waitcnt lgkmcnt(7)
	v_mfma_f32_32x32x16_bf16 v[48:63], v[202:205], v[206:209], v[48:63]
	s_waitcnt vmcnt(10)
	ds_write_b128 v160, v[92:95] offset:9216
	s_waitcnt lgkmcnt(7)
	v_mfma_f32_32x32x16_bf16 v[32:47], v[202:205], v[210:213], v[32:47]
	s_waitcnt vmcnt(9)
	ds_write_b128 v160, v[96:99] offset:18432
	s_waitcnt lgkmcnt(7)
	v_mfma_f32_32x32x16_bf16 v[16:31], v[214:217], v[206:209], v[16:31]
	v_mfma_f32_32x32x16_bf16 v[0:15], v[214:217], v[210:213], v[0:15]
	s_waitcnt vmcnt(8)
	ds_write_b128 v160, v[100:103] offset:27648
	s_waitcnt lgkmcnt(6)
	v_mfma_f32_32x32x16_bf16 v[48:63], v[222:225], v[226:229], v[48:63]
	s_waitcnt vmcnt(7)
	ds_write_b128 v160, v[104:107] offset:36864
	s_waitcnt lgkmcnt(6)
	v_mfma_f32_32x32x16_bf16 v[32:47], v[222:225], v[230:233], v[32:47]
	s_waitcnt vmcnt(6)
	ds_write_b128 v160, v[108:111] offset:46080
	s_waitcnt lgkmcnt(6)
	v_mfma_f32_32x32x16_bf16 v[16:31], v[234:237], v[226:229], v[16:31]
	v_mfma_f32_32x32x16_bf16 v[0:15], v[234:237], v[230:233], v[0:15]
	v_mov_b64_e32 v[88:89], s[38:39]
	v_mad_i64_i32 v[72:73], s[38:39], v124, s35, v[88:89]
	v_mad_i64_i32 v[74:75], s[38:39], v126, s35, v[88:89]
	v_mad_i64_i32 v[90:91], s[38:39], v132, s35, v[88:89]
	v_mad_i64_i32 v[88:89], s[38:39], v134, s35, v[88:89]
	v_lshl_add_u64 v[72:73], v[72:73], 0, v[128:129]
	v_lshl_add_u64 v[76:77], v[74:75], 0, v[128:129]
	v_lshl_add_u64 v[90:91], v[90:91], 0, v[128:129]
	v_lshl_add_u64 v[92:93], v[88:89], 0, v[128:129]
	s_waitcnt lgkmcnt(0)
	s_barrier
	global_load_dwordx4 v[72:75], v[72:73], off
	s_nop 0
	global_load_dwordx4 v[76:79], v[76:77], off
	s_nop 0
	global_load_dwordx4 v[88:91], v[90:91], off
	s_nop 0
	global_load_dwordx4 v[92:95], v[92:93], off
	s_nop 0
	global_load_dwordx4 v[96:99], v[120:121], off offset:512
	global_load_dwordx4 v[100:103], v[122:123], off offset:512
	ds_read_b128 v[170:173], v158
	ds_read_b128 v[174:177], v161 offset:36864
	ds_read_b128 v[178:181], v161 offset:41472
	ds_read_b128 v[182:185], v158 offset:4608
	ds_read_b128 v[186:189], v158 offset:32
	ds_read_b128 v[190:193], v161 offset:36896
	ds_read_b128 v[194:197], v161 offset:41504
	ds_read_b128 v[198:201], v158 offset:4640
	ds_read_b128 v[202:205], v158 offset:64
	ds_read_b128 v[206:209], v161 offset:36928
	ds_read_b128 v[210:213], v161 offset:41536
	ds_read_b128 v[214:217], v158 offset:4672
	s_waitcnt lgkmcnt(10)
	v_mfma_f32_32x32x16_bf16 v[48:63], v[170:173], v[174:177], v[48:63]
	s_waitcnt lgkmcnt(9)
	v_mfma_f32_32x32x16_bf16 v[32:47], v[170:173], v[178:181], v[32:47]
	s_waitcnt lgkmcnt(8)
	v_mfma_f32_32x32x16_bf16 v[16:31], v[182:185], v[174:177], v[16:31]
	v_mfma_f32_32x32x16_bf16 v[0:15], v[182:185], v[178:181], v[0:15]
	ds_read_b128 v[222:225], v158 offset:96
	ds_read_b128 v[226:229], v161 offset:36960
	ds_read_b128 v[230:233], v161 offset:41568
	ds_read_b128 v[234:237], v158 offset:4704
	s_waitcnt lgkmcnt(10)
	v_mfma_f32_32x32x16_bf16 v[48:63], v[186:189], v[190:193], v[48:63]
	s_waitcnt lgkmcnt(9)
	v_mfma_f32_32x32x16_bf16 v[32:47], v[186:189], v[194:197], v[32:47]
	s_waitcnt lgkmcnt(8)
	v_mfma_f32_32x32x16_bf16 v[16:31], v[198:201], v[190:193], v[16:31]
	v_mfma_f32_32x32x16_bf16 v[0:15], v[198:201], v[194:197], v[0:15]
	v_readlane_b32 s38, v219, 61
	v_readlane_b32 s39, v219, 62
	s_waitcnt vmcnt(11)
	ds_write_b128 v160, v[64:67] offset:55296
	s_waitcnt lgkmcnt(7)
	v_mfma_f32_32x32x16_bf16 v[48:63], v[202:205], v[206:209], v[48:63]
	s_waitcnt vmcnt(10)
	ds_write_b128 v160, v[68:71] offset:64512
	s_waitcnt lgkmcnt(7)
	v_mfma_f32_32x32x16_bf16 v[32:47], v[202:205], v[210:213], v[32:47]
	s_waitcnt vmcnt(9)
	ds_write_b128 v162, v[80:83] offset:18432
	s_waitcnt lgkmcnt(7)
	v_mfma_f32_32x32x16_bf16 v[16:31], v[214:217], v[206:209], v[16:31]
	v_mfma_f32_32x32x16_bf16 v[0:15], v[214:217], v[210:213], v[0:15]
	s_waitcnt vmcnt(8)
	ds_write_b128 v162, v[84:87] offset:27648
	s_waitcnt lgkmcnt(6)
	v_mfma_f32_32x32x16_bf16 v[48:63], v[222:225], v[226:229], v[48:63]
	s_waitcnt vmcnt(7)
	ds_write_b128 v163, v[112:115]
	s_waitcnt lgkmcnt(6)
	v_mfma_f32_32x32x16_bf16 v[32:47], v[222:225], v[230:233], v[32:47]
	s_waitcnt vmcnt(6)
	ds_write_b128 v163, v[116:119] offset:9216
	s_waitcnt lgkmcnt(6)
	v_mfma_f32_32x32x16_bf16 v[16:31], v[234:237], v[226:229], v[16:31]
	v_mfma_f32_32x32x16_bf16 v[0:15], v[234:237], v[230:233], v[0:15]
	v_mov_b64_e32 v[80:81], s[38:39]
	v_mad_i64_i32 v[64:65], s[38:39], v124, s35, v[80:81]
	v_mad_i64_i32 v[66:67], s[38:39], v126, s35, v[80:81]
	v_mad_i64_i32 v[82:83], s[38:39], v132, s35, v[80:81]
	v_mad_i64_i32 v[80:81], s[38:39], v134, s35, v[80:81]
	v_lshl_add_u64 v[64:65], v[64:65], 0, v[128:129]
	v_lshl_add_u64 v[68:69], v[66:67], 0, v[128:129]
	v_lshl_add_u64 v[82:83], v[82:83], 0, v[128:129]
	v_lshl_add_u64 v[84:85], v[80:81], 0, v[128:129]
	s_waitcnt lgkmcnt(0)
	s_barrier
; template <class AS, class EP>
; DEVI void gemm_tile(const AS& as, const u16* __restrict__ Bt, int K, int m0, int n0, const EP& ep, char* lds) {
;     ...
;   GLOAD(ra0, rb0, 0); GLOAD(ra1, rb1, 1); LWRITE(0, ra0, rb0); __syncthreads();
;   for (int kt = 0; kt < KT; kt += 2) {
;     if (kt + 2 < KT) GLOAD(ra0, rb0, kt + 2);
;     __builtin_amdgcn_sched_barrier(0);
;     COMPUTE(0);
;     __builtin_amdgcn_sched_barrier(0);
;     LWRITE(1, ra1, rb1);
;     __syncthreads();
;     if (kt + 3 < KT) GLOAD(ra1, rb1, kt + 3);
;     __builtin_amdgcn_sched_barrier(0);
;     COMPUTE(1);
;     __builtin_amdgcn_sched_barrier(0);
;     if (kt + 2 < KT) LWRITE(0, ra0, rb0);
;     __syncthreads();
	global_load_dwordx4 v[64:67], v[64:65], off
	s_nop 0
	global_load_dwordx4 v[68:71], v[68:69], off
	s_nop 0
	global_load_dwordx4 v[80:83], v[82:83], off
	s_nop 0
	global_load_dwordx4 v[84:87], v[84:85], off
	s_nop 0
	global_load_dwordx4 v[104:107], v[120:121], off offset:640
	global_load_dwordx4 v[108:111], v[122:123], off offset:640
	ds_read_b128 v[170:173], v158 offset:55296
	ds_read_b128 v[174:177], v159
	ds_read_b128 v[178:181], v159 offset:4608
	ds_read_b128 v[182:185], v158 offset:59904
	ds_read_b128 v[186:189], v158 offset:55328
	ds_read_b128 v[190:193], v159 offset:32
	ds_read_b128 v[194:197], v159 offset:4640
	ds_read_b128 v[198:201], v158 offset:59936
	ds_read_b128 v[202:205], v158 offset:55360
	ds_read_b128 v[206:209], v159 offset:64
	ds_read_b128 v[210:213], v159 offset:4672
	ds_read_b128 v[214:217], v158 offset:59968
	s_waitcnt lgkmcnt(10)
	v_mfma_f32_32x32x16_bf16 v[48:63], v[170:173], v[174:177], v[48:63]
	s_waitcnt lgkmcnt(9)
	v_mfma_f32_32x32x16_bf16 v[32:47], v[170:173], v[178:181], v[32:47]
	s_waitcnt lgkmcnt(8)
	v_mfma_f32_32x32x16_bf16 v[16:31], v[182:185], v[174:177], v[16:31]
	v_mfma_f32_32x32x16_bf16 v[0:15], v[182:185], v[178:181], v[0:15]
	ds_read_b128 v[222:225], v158 offset:55392
	ds_read_b128 v[226:229], v159 offset:96
	ds_read_b128 v[230:233], v159 offset:4704
	ds_read_b128 v[234:237], v158 offset:60000
	s_waitcnt lgkmcnt(10)
	v_mfma_f32_32x32x16_bf16 v[48:63], v[186:189], v[190:193], v[48:63]
	s_waitcnt lgkmcnt(9)
	v_mfma_f32_32x32x16_bf16 v[32:47], v[186:189], v[194:197], v[32:47]
	s_waitcnt lgkmcnt(8)
	v_mfma_f32_32x32x16_bf16 v[16:31], v[198:201], v[190:193], v[16:31]
	v_mfma_f32_32x32x16_bf16 v[0:15], v[198:201], v[194:197], v[0:15]
	v_readlane_b32 s38, v218, 1
	v_readlane_b32 s39, v218, 2
	s_waitcnt vmcnt(11)
	ds_write_b128 v160, v[72:75]
	s_waitcnt lgkmcnt(7)
	v_mfma_f32_32x32x16_bf16 v[48:63], v[202:205], v[206:209], v[48:63]
	s_waitcnt vmcnt(10)
	ds_write_b128 v160, v[76:79] offset:9216
	s_waitcnt lgkmcnt(7)
	v_mfma_f32_32x32x16_bf16 v[32:47], v[202:205], v[210:213], v[32:47]
	s_waitcnt vmcnt(9)
	ds_write_b128 v160, v[88:91] offset:18432
	s_waitcnt lgkmcnt(7)
	v_mfma_f32_32x32x16_bf16 v[16:31], v[214:217], v[206:209], v[16:31]
	v_mfma_f32_32x32x16_bf16 v[0:15], v[214:217], v[210:213], v[0:15]
	s_waitcnt vmcnt(8)
	ds_write_b128 v160, v[92:95] offset:27648
	s_waitcnt lgkmcnt(6)
	v_mfma_f32_32x32x16_bf16 v[48:63], v[222:225], v[226:229], v[48:63]
	s_waitcnt vmcnt(7)
	ds_write_b128 v160, v[96:99] offset:36864
	s_waitcnt lgkmcnt(6)
	v_mfma_f32_32x32x16_bf16 v[32:47], v[222:225], v[230:233], v[32:47]
	s_waitcnt vmcnt(6)
	ds_write_b128 v160, v[100:103] offset:46080
	s_waitcnt lgkmcnt(6)
	v_mfma_f32_32x32x16_bf16 v[16:31], v[234:237], v[226:229], v[16:31]
	v_mfma_f32_32x32x16_bf16 v[0:15], v[234:237], v[230:233], v[0:15]
	v_mov_b64_e32 v[88:89], s[38:39]
	v_mad_i64_i32 v[72:73], s[38:39], v124, s35, v[88:89]
	v_mad_i64_i32 v[74:75], s[38:39], v126, s35, v[88:89]
	v_mad_i64_i32 v[90:91], s[38:39], v132, s35, v[88:89]
	v_mad_i64_i32 v[88:89], s[38:39], v134, s35, v[88:89]
	v_lshl_add_u64 v[72:73], v[72:73], 0, v[128:129]
	v_lshl_add_u64 v[76:77], v[74:75], 0, v[128:129]
	v_lshl_add_u64 v[90:91], v[90:91], 0, v[128:129]
	v_lshl_add_u64 v[92:93], v[88:89], 0, v[128:129]
	s_waitcnt lgkmcnt(0)
	s_barrier
	global_load_dwordx4 v[72:75], v[72:73], off offset:-768
	s_nop 0
	global_load_dwordx4 v[76:79], v[76:77], off offset:-768
	s_nop 0
	global_load_dwordx4 v[88:91], v[90:91], off offset:-768
	s_nop 0
	global_load_dwordx4 v[92:95], v[92:93], off offset:-768
	s_nop 0
	global_load_dwordx4 v[96:99], v[120:121], off offset:768
	global_load_dwordx4 v[100:103], v[122:123], off offset:768
	ds_read_b128 v[170:173], v158
	ds_read_b128 v[174:177], v161 offset:36864
	ds_read_b128 v[178:181], v161 offset:41472
	ds_read_b128 v[182:185], v158 offset:4608
	ds_read_b128 v[186:189], v158 offset:32
	ds_read_b128 v[190:193], v161 offset:36896
	ds_read_b128 v[194:197], v161 offset:41504
	ds_read_b128 v[198:201], v158 offset:4640
	ds_read_b128 v[202:205], v158 offset:64
	ds_read_b128 v[206:209], v161 offset:36928
	ds_read_b128 v[210:213], v161 offset:41536
	ds_read_b128 v[214:217], v158 offset:4672
	s_waitcnt lgkmcnt(10)
	v_mfma_f32_32x32x16_bf16 v[48:63], v[170:173], v[174:177], v[48:63]
	s_waitcnt lgkmcnt(9)
	v_mfma_f32_32x32x16_bf16 v[32:47], v[170:173], v[178:181], v[32:47]
	s_waitcnt lgkmcnt(8)
	v_mfma_f32_32x32x16_bf16 v[16:31], v[182:185], v[174:177], v[16:31]
	v_mfma_f32_32x32x16_bf16 v[0:15], v[182:185], v[178:181], v[0:15]
	ds_read_b128 v[222:225], v158 offset:96
	ds_read_b128 v[226:229], v161 offset:36960
	ds_read_b128 v[230:233], v161 offset:41568
	ds_read_b128 v[234:237], v158 offset:4704
	s_waitcnt lgkmcnt(10)
	v_mfma_f32_32x32x16_bf16 v[48:63], v[186:189], v[190:193], v[48:63]
	s_waitcnt lgkmcnt(9)
	v_mfma_f32_32x32x16_bf16 v[32:47], v[186:189], v[194:197], v[32:47]
	s_waitcnt lgkmcnt(8)
	v_mfma_f32_32x32x16_bf16 v[16:31], v[198:201], v[190:193], v[16:31]
	v_mfma_f32_32x32x16_bf16 v[0:15], v[198:201], v[194:197], v[0:15]
	s_waitcnt vmcnt(11)
	ds_write_b128 v160, v[64:67] offset:55296
	s_waitcnt lgkmcnt(7)
	v_mfma_f32_32x32x16_bf16 v[48:63], v[202:205], v[206:209], v[48:63]
	s_waitcnt vmcnt(10)
	ds_write_b128 v160, v[68:71] offset:64512
	s_waitcnt lgkmcnt(7)
	v_mfma_f32_32x32x16_bf16 v[32:47], v[202:205], v[210:213], v[32:47]
	s_waitcnt vmcnt(9)
	ds_write_b128 v162, v[80:83] offset:18432
	s_waitcnt lgkmcnt(7)
	v_mfma_f32_32x32x16_bf16 v[16:31], v[214:217], v[206:209], v[16:31]
	v_mfma_f32_32x32x16_bf16 v[0:15], v[214:217], v[210:213], v[0:15]
	s_waitcnt vmcnt(8)
	ds_write_b128 v162, v[84:87] offset:27648
	s_waitcnt lgkmcnt(6)
	v_mfma_f32_32x32x16_bf16 v[48:63], v[222:225], v[226:229], v[48:63]
	s_waitcnt vmcnt(7)
	ds_write_b128 v163, v[104:107]
	s_waitcnt lgkmcnt(6)
	v_mfma_f32_32x32x16_bf16 v[32:47], v[222:225], v[230:233], v[32:47]
	s_waitcnt vmcnt(6)
	ds_write_b128 v163, v[108:111] offset:9216
	s_waitcnt lgkmcnt(6)
	v_mfma_f32_32x32x16_bf16 v[16:31], v[234:237], v[226:229], v[16:31]
	v_mfma_f32_32x32x16_bf16 v[0:15], v[234:237], v[230:233], v[0:15]
	v_mov_b64_e32 v[80:81], s[30:31]
	v_mad_i64_i32 v[64:65], s[38:39], v124, s35, v[80:81]
	v_mad_i64_i32 v[66:67], s[38:39], v126, s35, v[80:81]
	v_mad_i64_i32 v[82:83], s[38:39], v132, s35, v[80:81]
	v_mad_i64_i32 v[80:81], s[38:39], v134, s35, v[80:81]
	v_lshl_add_u64 v[64:65], v[64:65], 0, v[128:129]
	v_lshl_add_u64 v[68:69], v[66:67], 0, v[128:129]
	v_lshl_add_u64 v[82:83], v[82:83], 0, v[128:129]
	v_lshl_add_u64 v[84:85], v[80:81], 0, v[128:129]
	s_waitcnt lgkmcnt(0)
	s_barrier
; template <class AS, class EP>
; DEVI void gemm_tile(const AS& as, const u16* __restrict__ Bt, int K, int m0, int n0, const EP& ep, char* lds) {
;     ...
;   GLOAD(ra0, rb0, 0); GLOAD(ra1, rb1, 1); LWRITE(0, ra0, rb0); __syncthreads();
;   for (int kt = 0; kt < KT; kt += 2) {
;     if (kt + 2 < KT) GLOAD(ra0, rb0, kt + 2);
;     __builtin_amdgcn_sched_barrier(0);
;     COMPUTE(0);
;     __builtin_amdgcn_sched_barrier(0);
;     LWRITE(1, ra1, rb1);
;     __syncthreads();
;     if (kt + 3 < KT) GLOAD(ra1, rb1, kt + 3);
;     __builtin_amdgcn_sched_barrier(0);
;     COMPUTE(1);
;     __builtin_amdgcn_sched_barrier(0);
;     if (kt + 2 < KT) LWRITE(0, ra0, rb0);
;     __syncthreads();
	global_load_dwordx4 v[64:67], v[64:65], off offset:-768
	s_nop 0
	global_load_dwordx4 v[68:71], v[68:69], off offset:-768
	s_nop 0
	global_load_dwordx4 v[80:83], v[82:83], off offset:-768
	s_nop 0
	global_load_dwordx4 v[84:87], v[84:85], off offset:-768
	s_nop 0
	global_load_dwordx4 v[104:107], v[120:121], off offset:896
	global_load_dwordx4 v[108:111], v[122:123], off offset:896
	ds_read_b128 v[170:173], v158 offset:55296
	ds_read_b128 v[174:177], v159
	ds_read_b128 v[178:181], v159 offset:4608
	ds_read_b128 v[182:185], v158 offset:59904
	ds_read_b128 v[186:189], v158 offset:55328
	ds_read_b128 v[190:193], v159 offset:32
	ds_read_b128 v[194:197], v159 offset:4640
	ds_read_b128 v[198:201], v158 offset:59936
	ds_read_b128 v[202:205], v158 offset:55360
	ds_read_b128 v[206:209], v159 offset:64
	ds_read_b128 v[210:213], v159 offset:4672
	ds_read_b128 v[214:217], v158 offset:59968
	s_waitcnt lgkmcnt(10)
	v_mfma_f32_32x32x16_bf16 v[48:63], v[170:173], v[174:177], v[48:63]
	s_waitcnt lgkmcnt(9)
	v_mfma_f32_32x32x16_bf16 v[32:47], v[170:173], v[178:181], v[32:47]
	s_waitcnt lgkmcnt(8)
	v_mfma_f32_32x32x16_bf16 v[16:31], v[182:185], v[174:177], v[16:31]
	v_mfma_f32_32x32x16_bf16 v[0:15], v[182:185], v[178:181], v[0:15]
	ds_read_b128 v[222:225], v158 offset:55392
	ds_read_b128 v[226:229], v159 offset:96
	ds_read_b128 v[230:233], v159 offset:4704
	ds_read_b128 v[234:237], v158 offset:60000
	s_waitcnt lgkmcnt(10)
	v_mfma_f32_32x32x16_bf16 v[48:63], v[186:189], v[190:193], v[48:63]
	s_waitcnt lgkmcnt(9)
	v_mfma_f32_32x32x16_bf16 v[32:47], v[186:189], v[194:197], v[32:47]
	s_waitcnt lgkmcnt(8)
	v_mfma_f32_32x32x16_bf16 v[16:31], v[198:201], v[190:193], v[16:31]
	v_mfma_f32_32x32x16_bf16 v[0:15], v[198:201], v[194:197], v[0:15]
	s_waitcnt vmcnt(11)
	ds_write_b128 v160, v[72:75]
	s_waitcnt lgkmcnt(7)
	v_mfma_f32_32x32x16_bf16 v[48:63], v[202:205], v[206:209], v[48:63]
	s_waitcnt vmcnt(10)
	ds_write_b128 v160, v[76:79] offset:9216
	s_waitcnt lgkmcnt(7)
	v_mfma_f32_32x32x16_bf16 v[32:47], v[202:205], v[210:213], v[32:47]
	s_waitcnt vmcnt(9)
	ds_write_b128 v160, v[88:91] offset:18432
	s_waitcnt lgkmcnt(7)
	v_mfma_f32_32x32x16_bf16 v[16:31], v[214:217], v[206:209], v[16:31]
	v_mfma_f32_32x32x16_bf16 v[0:15], v[214:217], v[210:213], v[0:15]
	s_waitcnt vmcnt(8)
	ds_write_b128 v160, v[92:95] offset:27648
	s_waitcnt lgkmcnt(6)
	v_mfma_f32_32x32x16_bf16 v[48:63], v[222:225], v[226:229], v[48:63]
	s_waitcnt vmcnt(7)
	ds_write_b128 v160, v[96:99] offset:36864
	s_waitcnt lgkmcnt(6)
	v_mfma_f32_32x32x16_bf16 v[32:47], v[222:225], v[230:233], v[32:47]
	s_waitcnt vmcnt(6)
	ds_write_b128 v160, v[100:103] offset:46080
	s_waitcnt lgkmcnt(6)
	v_mfma_f32_32x32x16_bf16 v[16:31], v[234:237], v[226:229], v[16:31]
	v_mfma_f32_32x32x16_bf16 v[0:15], v[234:237], v[230:233], v[0:15]
	v_mov_b64_e32 v[88:89], s[40:41]
	v_mad_i64_i32 v[72:73], s[38:39], v124, s35, v[88:89]
	v_mad_i64_i32 v[74:75], s[38:39], v126, s35, v[88:89]
	v_mad_i64_i32 v[90:91], s[38:39], v132, s35, v[88:89]
	v_mad_i64_i32 v[88:89], s[38:39], v134, s35, v[88:89]
	v_lshl_add_u64 v[72:73], v[72:73], 0, v[128:129]
	v_lshl_add_u64 v[76:77], v[74:75], 0, v[128:129]
	v_lshl_add_u64 v[90:91], v[90:91], 0, v[128:129]
	v_lshl_add_u64 v[92:93], v[88:89], 0, v[128:129]
	s_waitcnt lgkmcnt(0)
	s_barrier
	global_load_dwordx4 v[72:75], v[72:73], off offset:-768
	s_nop 0
	global_load_dwordx4 v[76:79], v[76:77], off offset:-768
	s_nop 0
	global_load_dwordx4 v[88:91], v[90:91], off offset:-768
	s_nop 0
	global_load_dwordx4 v[92:95], v[92:93], off offset:-768
	s_nop 0
	global_load_dwordx4 v[96:99], v[120:121], off offset:1024
	global_load_dwordx4 v[100:103], v[122:123], off offset:1024
	ds_read_b128 v[170:173], v158
	ds_read_b128 v[174:177], v161 offset:36864
	ds_read_b128 v[178:181], v161 offset:41472
	ds_read_b128 v[182:185], v158 offset:4608
	ds_read_b128 v[186:189], v158 offset:32
	ds_read_b128 v[190:193], v161 offset:36896
	ds_read_b128 v[194:197], v161 offset:41504
	ds_read_b128 v[198:201], v158 offset:4640
	ds_read_b128 v[202:205], v158 offset:64
	ds_read_b128 v[206:209], v161 offset:36928
	ds_read_b128 v[210:213], v161 offset:41536
	ds_read_b128 v[214:217], v158 offset:4672
	s_waitcnt lgkmcnt(10)
	v_mfma_f32_32x32x16_bf16 v[48:63], v[170:173], v[174:177], v[48:63]
	s_waitcnt lgkmcnt(9)
	v_mfma_f32_32x32x16_bf16 v[32:47], v[170:173], v[178:181], v[32:47]
	s_waitcnt lgkmcnt(8)
	v_mfma_f32_32x32x16_bf16 v[16:31], v[182:185], v[174:177], v[16:31]
	v_mfma_f32_32x32x16_bf16 v[0:15], v[182:185], v[178:181], v[0:15]
	ds_read_b128 v[222:225], v158 offset:96
	ds_read_b128 v[226:229], v161 offset:36960
	ds_read_b128 v[230:233], v161 offset:41568
	ds_read_b128 v[234:237], v158 offset:4704
	s_waitcnt lgkmcnt(10)
	v_mfma_f32_32x32x16_bf16 v[48:63], v[186:189], v[190:193], v[48:63]
	s_waitcnt lgkmcnt(9)
	v_mfma_f32_32x32x16_bf16 v[32:47], v[186:189], v[194:197], v[32:47]
	s_waitcnt lgkmcnt(8)
	v_mfma_f32_32x32x16_bf16 v[16:31], v[198:201], v[190:193], v[16:31]
	v_mfma_f32_32x32x16_bf16 v[0:15], v[198:201], v[194:197], v[0:15]
	s_waitcnt vmcnt(11)
	ds_write_b128 v160, v[64:67] offset:55296
	s_waitcnt lgkmcnt(7)
	v_mfma_f32_32x32x16_bf16 v[48:63], v[202:205], v[206:209], v[48:63]
	s_waitcnt vmcnt(10)
	ds_write_b128 v160, v[68:71] offset:64512
	s_waitcnt lgkmcnt(7)
	v_mfma_f32_32x32x16_bf16 v[32:47], v[202:205], v[210:213], v[32:47]
	s_waitcnt vmcnt(9)
	ds_write_b128 v162, v[80:83] offset:18432
	s_waitcnt lgkmcnt(7)
	v_mfma_f32_32x32x16_bf16 v[16:31], v[214:217], v[206:209], v[16:31]
	v_mfma_f32_32x32x16_bf16 v[0:15], v[214:217], v[210:213], v[0:15]
	s_waitcnt vmcnt(8)
	ds_write_b128 v162, v[84:87] offset:27648
	s_waitcnt lgkmcnt(6)
	v_mfma_f32_32x32x16_bf16 v[48:63], v[222:225], v[226:229], v[48:63]
	s_waitcnt vmcnt(7)
	ds_write_b128 v163, v[104:107]
	s_waitcnt lgkmcnt(6)
	v_mfma_f32_32x32x16_bf16 v[32:47], v[222:225], v[230:233], v[32:47]
	s_waitcnt vmcnt(6)
	ds_write_b128 v163, v[108:111] offset:9216
	s_waitcnt lgkmcnt(6)
	v_mfma_f32_32x32x16_bf16 v[16:31], v[234:237], v[226:229], v[16:31]
	v_mfma_f32_32x32x16_bf16 v[0:15], v[234:237], v[230:233], v[0:15]
	v_mov_b64_e32 v[80:81], s[42:43]
	v_mad_i64_i32 v[64:65], s[38:39], v124, s35, v[80:81]
	v_mad_i64_i32 v[66:67], s[38:39], v126, s35, v[80:81]
	v_mad_i64_i32 v[82:83], s[38:39], v132, s35, v[80:81]
	v_mad_i64_i32 v[80:81], s[38:39], v134, s35, v[80:81]
	v_lshl_add_u64 v[64:65], v[64:65], 0, v[128:129]
	v_lshl_add_u64 v[68:69], v[66:67], 0, v[128:129]
	v_lshl_add_u64 v[82:83], v[82:83], 0, v[128:129]
	v_lshl_add_u64 v[84:85], v[80:81], 0, v[128:129]
	s_waitcnt lgkmcnt(0)
	s_barrier
; template <class AS, class EP>
; DEVI void gemm_tile(const AS& as, const u16* __restrict__ Bt, int K, int m0, int n0, const EP& ep, char* lds) {
;     ...
;   GLOAD(ra0, rb0, 0); GLOAD(ra1, rb1, 1); LWRITE(0, ra0, rb0); __syncthreads();
;   for (int kt = 0; kt < KT; kt += 2) {
;     if (kt + 2 < KT) GLOAD(ra0, rb0, kt + 2);
;     __builtin_amdgcn_sched_barrier(0);
;     COMPUTE(0);
;     __builtin_amdgcn_sched_barrier(0);
;     LWRITE(1, ra1, rb1);
;     __syncthreads();
;     if (kt + 3 < KT) GLOAD(ra1, rb1, kt + 3);
;     __builtin_amdgcn_sched_barrier(0);
;     COMPUTE(1);
;     __builtin_amdgcn_sched_barrier(0);
;     if (kt + 2 < KT) LWRITE(0, ra0, rb0);
;     __syncthreads();
	global_load_dwordx4 v[64:67], v[64:65], off offset:-768
	s_nop 0
	global_load_dwordx4 v[68:71], v[68:69], off offset:-768
	s_nop 0
	global_load_dwordx4 v[80:83], v[82:83], off offset:-768
	s_nop 0
	global_load_dwordx4 v[84:87], v[84:85], off offset:-768
	s_nop 0
	global_load_dwordx4 v[104:107], v[120:121], off offset:1152
	global_load_dwordx4 v[108:111], v[122:123], off offset:1152
	ds_read_b128 v[170:173], v158 offset:55296
	ds_read_b128 v[174:177], v159
	ds_read_b128 v[178:181], v159 offset:4608
	ds_read_b128 v[182:185], v158 offset:59904
	ds_read_b128 v[186:189], v158 offset:55328
	ds_read_b128 v[190:193], v159 offset:32
	ds_read_b128 v[194:197], v159 offset:4640
	ds_read_b128 v[198:201], v158 offset:59936
	ds_read_b128 v[202:205], v158 offset:55360
	ds_read_b128 v[206:209], v159 offset:64
	ds_read_b128 v[210:213], v159 offset:4672
	ds_read_b128 v[214:217], v158 offset:59968
	s_waitcnt lgkmcnt(10)
	v_mfma_f32_32x32x16_bf16 v[48:63], v[170:173], v[174:177], v[48:63]
	s_waitcnt lgkmcnt(9)
	v_mfma_f32_32x32x16_bf16 v[32:47], v[170:173], v[178:181], v[32:47]
	s_waitcnt lgkmcnt(8)
	v_mfma_f32_32x32x16_bf16 v[16:31], v[182:185], v[174:177], v[16:31]
	v_mfma_f32_32x32x16_bf16 v[0:15], v[182:185], v[178:181], v[0:15]
	ds_read_b128 v[222:225], v158 offset:55392
	ds_read_b128 v[226:229], v159 offset:96
	ds_read_b128 v[230:233], v159 offset:4704
	ds_read_b128 v[234:237], v158 offset:60000
	s_waitcnt lgkmcnt(10)
	v_mfma_f32_32x32x16_bf16 v[48:63], v[186:189], v[190:193], v[48:63]
	s_waitcnt lgkmcnt(9)
	v_mfma_f32_32x32x16_bf16 v[32:47], v[186:189], v[194:197], v[32:47]
	s_waitcnt lgkmcnt(8)
	v_mfma_f32_32x32x16_bf16 v[16:31], v[198:201], v[190:193], v[16:31]
	v_mfma_f32_32x32x16_bf16 v[0:15], v[198:201], v[194:197], v[0:15]
	s_waitcnt vmcnt(11)
	ds_write_b128 v160, v[72:75]
	s_waitcnt lgkmcnt(7)
	v_mfma_f32_32x32x16_bf16 v[48:63], v[202:205], v[206:209], v[48:63]
	s_waitcnt vmcnt(10)
	ds_write_b128 v160, v[76:79] offset:9216
	s_waitcnt lgkmcnt(7)
	v_mfma_f32_32x32x16_bf16 v[32:47], v[202:205], v[210:213], v[32:47]
	s_waitcnt vmcnt(9)
	ds_write_b128 v160, v[88:91] offset:18432
	s_waitcnt lgkmcnt(7)
	v_mfma_f32_32x32x16_bf16 v[16:31], v[214:217], v[206:209], v[16:31]
	v_mfma_f32_32x32x16_bf16 v[0:15], v[214:217], v[210:213], v[0:15]
	s_waitcnt vmcnt(8)
	ds_write_b128 v160, v[92:95] offset:27648
	s_waitcnt lgkmcnt(6)
	v_mfma_f32_32x32x16_bf16 v[48:63], v[222:225], v[226:229], v[48:63]
	s_waitcnt vmcnt(7)
	ds_write_b128 v160, v[96:99] offset:36864
	s_waitcnt lgkmcnt(6)
	v_mfma_f32_32x32x16_bf16 v[32:47], v[222:225], v[230:233], v[32:47]
	s_waitcnt vmcnt(6)
	ds_write_b128 v160, v[100:103] offset:46080
	s_waitcnt lgkmcnt(6)
	v_mfma_f32_32x32x16_bf16 v[16:31], v[234:237], v[226:229], v[16:31]
	v_mfma_f32_32x32x16_bf16 v[0:15], v[234:237], v[230:233], v[0:15]
	v_mov_b64_e32 v[88:89], s[82:83]
	v_mad_i64_i32 v[72:73], s[38:39], v124, s35, v[88:89]
	v_mad_i64_i32 v[74:75], s[38:39], v126, s35, v[88:89]
	v_mad_i64_i32 v[90:91], s[38:39], v132, s35, v[88:89]
	v_lshl_add_u64 v[72:73], v[72:73], 0, v[128:129]
	v_lshl_add_u64 v[76:77], v[74:75], 0, v[128:129]
	v_lshl_add_u64 v[90:91], v[90:91], 0, v[128:129]
	v_mad_i64_i32 v[88:89], s[38:39], v134, s35, v[88:89]
	s_waitcnt lgkmcnt(0)
	s_barrier
	global_load_dwordx4 v[72:75], v[72:73], off offset:-768
	s_nop 0
	global_load_dwordx4 v[76:79], v[76:77], off offset:-768
	v_lshl_add_u64 v[88:89], v[88:89], 0, v[128:129]
	global_load_dwordx4 v[96:99], v[90:91], off offset:-768
	global_load_dwordx4 v[100:103], v[88:89], off offset:-768
	global_load_dwordx4 v[112:115], v[120:121], off offset:1280
	global_load_dwordx4 v[116:119], v[122:123], off offset:1280
	ds_read_b128 v[170:173], v158
	ds_read_b128 v[174:177], v161 offset:36864
	ds_read_b128 v[178:181], v161 offset:41472
	ds_read_b128 v[182:185], v158 offset:4608
	ds_read_b128 v[186:189], v158 offset:32
	ds_read_b128 v[190:193], v161 offset:36896
	ds_read_b128 v[194:197], v161 offset:41504
	ds_read_b128 v[198:201], v158 offset:4640
	ds_read_b128 v[202:205], v158 offset:64
	ds_read_b128 v[206:209], v161 offset:36928
	ds_read_b128 v[210:213], v161 offset:41536
	ds_read_b128 v[214:217], v158 offset:4672
	s_waitcnt lgkmcnt(10)
	v_mfma_f32_32x32x16_bf16 v[48:63], v[170:173], v[174:177], v[48:63]
	s_waitcnt lgkmcnt(9)
	v_mfma_f32_32x32x16_bf16 v[32:47], v[170:173], v[178:181], v[32:47]
	s_waitcnt lgkmcnt(8)
	v_mfma_f32_32x32x16_bf16 v[16:31], v[182:185], v[174:177], v[16:31]
	v_mfma_f32_32x32x16_bf16 v[0:15], v[182:185], v[178:181], v[0:15]
	ds_read_b128 v[222:225], v158 offset:96
	ds_read_b128 v[226:229], v161 offset:36960
	ds_read_b128 v[230:233], v161 offset:41568
	ds_read_b128 v[234:237], v158 offset:4704
	s_waitcnt lgkmcnt(10)
	v_mfma_f32_32x32x16_bf16 v[48:63], v[186:189], v[190:193], v[48:63]
	s_waitcnt lgkmcnt(9)
	v_mfma_f32_32x32x16_bf16 v[32:47], v[186:189], v[194:197], v[32:47]
	s_waitcnt lgkmcnt(8)
	v_mfma_f32_32x32x16_bf16 v[16:31], v[198:201], v[190:193], v[16:31]
	v_mfma_f32_32x32x16_bf16 v[0:15], v[198:201], v[194:197], v[0:15]
	s_waitcnt vmcnt(11)
	ds_write_b128 v160, v[64:67] offset:55296
	s_waitcnt lgkmcnt(7)
	v_mfma_f32_32x32x16_bf16 v[48:63], v[202:205], v[206:209], v[48:63]
	s_waitcnt vmcnt(10)
	ds_write_b128 v160, v[68:71] offset:64512
	s_waitcnt lgkmcnt(7)
	v_mfma_f32_32x32x16_bf16 v[32:47], v[202:205], v[210:213], v[32:47]
	s_waitcnt vmcnt(9)
	ds_write_b128 v162, v[80:83] offset:18432
	s_waitcnt lgkmcnt(7)
	v_mfma_f32_32x32x16_bf16 v[16:31], v[214:217], v[206:209], v[16:31]
	v_mfma_f32_32x32x16_bf16 v[0:15], v[214:217], v[210:213], v[0:15]
	s_waitcnt vmcnt(8)
	ds_write_b128 v162, v[84:87] offset:27648
	s_waitcnt lgkmcnt(6)
	v_mfma_f32_32x32x16_bf16 v[48:63], v[222:225], v[226:229], v[48:63]
	s_waitcnt vmcnt(7)
	ds_write_b128 v163, v[104:107]
	s_waitcnt lgkmcnt(6)
	v_mfma_f32_32x32x16_bf16 v[32:47], v[222:225], v[230:233], v[32:47]
	s_waitcnt vmcnt(6)
	ds_write_b128 v163, v[108:111] offset:9216
	s_waitcnt lgkmcnt(6)
	v_mfma_f32_32x32x16_bf16 v[16:31], v[234:237], v[226:229], v[16:31]
	v_mfma_f32_32x32x16_bf16 v[0:15], v[234:237], v[230:233], v[0:15]
	v_mov_b64_e32 v[80:81], s[84:85]
	v_mad_i64_i32 v[64:65], s[38:39], v124, s35, v[80:81]
	v_mad_i64_i32 v[66:67], s[38:39], v126, s35, v[80:81]
	v_mad_i64_i32 v[82:83], s[38:39], v132, s35, v[80:81]
	v_mad_i64_i32 v[80:81], s[38:39], v134, s35, v[80:81]
	v_lshl_add_u64 v[64:65], v[64:65], 0, v[128:129]
	v_lshl_add_u64 v[68:69], v[66:67], 0, v[128:129]
	v_lshl_add_u64 v[82:83], v[82:83], 0, v[128:129]
	v_lshl_add_u64 v[84:85], v[80:81], 0, v[128:129]
	s_waitcnt lgkmcnt(0)
	s_barrier
; template <class AS, class EP>
; DEVI void gemm_tile(const AS& as, const u16* __restrict__ Bt, int K, int m0, int n0, const EP& ep, char* lds) {
;     ...
;   GLOAD(ra0, rb0, 0); GLOAD(ra1, rb1, 1); LWRITE(0, ra0, rb0); __syncthreads();
;   for (int kt = 0; kt < KT; kt += 2) {
;     if (kt + 2 < KT) GLOAD(ra0, rb0, kt + 2);
;     __builtin_amdgcn_sched_barrier(0);
;     COMPUTE(0);
;     __builtin_amdgcn_sched_barrier(0);
;     LWRITE(1, ra1, rb1);
;     __syncthreads();
;     if (kt + 3 < KT) GLOAD(ra1, rb1, kt + 3);
;     __builtin_amdgcn_sched_barrier(0);
;     COMPUTE(1);
;     __builtin_amdgcn_sched_barrier(0);
;     if (kt + 2 < KT) LWRITE(0, ra0, rb0);
;     __syncthreads();
	global_load_dwordx4 v[64:67], v[64:65], off offset:-768
	s_nop 0
	global_load_dwordx4 v[68:71], v[68:69], off offset:-768
	s_nop 0
	global_load_dwordx4 v[80:83], v[82:83], off offset:-768
	s_nop 0
	global_load_dwordx4 v[84:87], v[84:85], off offset:-768
	s_nop 0
	global_load_dwordx4 v[88:91], v[120:121], off offset:1408
	global_load_dwordx4 v[92:95], v[122:123], off offset:1408
	ds_read_b128 v[170:173], v158 offset:55296
	ds_read_b128 v[174:177], v159
	ds_read_b128 v[178:181], v159 offset:4608
	ds_read_b128 v[182:185], v158 offset:59904
	ds_read_b128 v[186:189], v158 offset:55328
	ds_read_b128 v[190:193], v159 offset:32
	ds_read_b128 v[194:197], v159 offset:4640
	ds_read_b128 v[198:201], v158 offset:59936
	ds_read_b128 v[202:205], v158 offset:55360
	ds_read_b128 v[206:209], v159 offset:64
	ds_read_b128 v[210:213], v159 offset:4672
	ds_read_b128 v[214:217], v158 offset:59968
	s_waitcnt lgkmcnt(10)
	v_mfma_f32_32x32x16_bf16 v[48:63], v[170:173], v[174:177], v[48:63]
	s_waitcnt lgkmcnt(9)
	v_mfma_f32_32x32x16_bf16 v[32:47], v[170:173], v[178:181], v[32:47]
	s_waitcnt lgkmcnt(8)
	v_mfma_f32_32x32x16_bf16 v[16:31], v[182:185], v[174:177], v[16:31]
	v_mfma_f32_32x32x16_bf16 v[0:15], v[182:185], v[178:181], v[0:15]
	ds_read_b128 v[222:225], v158 offset:55392
	ds_read_b128 v[226:229], v159 offset:96
	ds_read_b128 v[230:233], v159 offset:4704
	ds_read_b128 v[234:237], v158 offset:60000
	s_waitcnt lgkmcnt(10)
	v_mfma_f32_32x32x16_bf16 v[48:63], v[186:189], v[190:193], v[48:63]
	s_waitcnt lgkmcnt(9)
	v_mfma_f32_32x32x16_bf16 v[32:47], v[186:189], v[194:197], v[32:47]
	s_waitcnt lgkmcnt(8)
	v_mfma_f32_32x32x16_bf16 v[16:31], v[198:201], v[190:193], v[16:31]
	v_mfma_f32_32x32x16_bf16 v[0:15], v[198:201], v[194:197], v[0:15]
	s_waitcnt vmcnt(11)
	ds_write_b128 v160, v[72:75]
	s_waitcnt lgkmcnt(7)
	v_mfma_f32_32x32x16_bf16 v[48:63], v[202:205], v[206:209], v[48:63]
	s_waitcnt vmcnt(10)
	ds_write_b128 v160, v[76:79] offset:9216
	s_waitcnt lgkmcnt(7)
	v_mfma_f32_32x32x16_bf16 v[32:47], v[202:205], v[210:213], v[32:47]
	s_waitcnt vmcnt(9)
	ds_write_b128 v160, v[96:99] offset:18432
	s_waitcnt lgkmcnt(7)
	v_mfma_f32_32x32x16_bf16 v[16:31], v[214:217], v[206:209], v[16:31]
	v_mfma_f32_32x32x16_bf16 v[0:15], v[214:217], v[210:213], v[0:15]
	s_waitcnt vmcnt(8)
	ds_write_b128 v160, v[100:103] offset:27648
	s_waitcnt lgkmcnt(6)
	v_mfma_f32_32x32x16_bf16 v[48:63], v[222:225], v[226:229], v[48:63]
	s_waitcnt vmcnt(7)
	ds_write_b128 v160, v[112:115] offset:36864
	s_waitcnt lgkmcnt(6)
	v_mfma_f32_32x32x16_bf16 v[32:47], v[222:225], v[230:233], v[32:47]
	s_waitcnt vmcnt(6)
	ds_write_b128 v160, v[116:119] offset:46080
	s_waitcnt lgkmcnt(6)
	v_mfma_f32_32x32x16_bf16 v[16:31], v[234:237], v[226:229], v[16:31]
	v_mfma_f32_32x32x16_bf16 v[0:15], v[234:237], v[230:233], v[0:15]
	v_lshlrev_b64 v[112:113], 9, v[124:125]
	v_lshlrev_b64 v[114:115], 9, v[126:127]
	v_lshlrev_b64 v[116:117], 9, v[132:133]
	v_lshlrev_b64 v[118:119], 9, v[134:135]
	v_lshl_add_u64 v[72:73], s[18:19], 0, v[112:113]
	v_lshl_add_u64 v[74:75], s[18:19], 0, v[114:115]
	v_lshl_add_u64 v[96:97], s[18:19], 0, v[116:117]
	v_lshl_add_u64 v[98:99], s[18:19], 0, v[118:119]
	v_lshl_add_u64 v[72:73], v[72:73], 0, v[128:129]
	v_lshl_add_u64 v[76:77], v[74:75], 0, v[128:129]
	v_lshl_add_u64 v[96:97], v[96:97], 0, v[128:129]
	v_lshl_add_u64 v[100:101], v[98:99], 0, v[128:129]
	s_waitcnt lgkmcnt(0)
	s_barrier
	global_load_dwordx4 v[72:75], v[72:73], off offset:-1536
	s_nop 0
	global_load_dwordx4 v[76:79], v[76:77], off offset:-1536
	s_nop 0
	global_load_dwordx4 v[96:99], v[96:97], off offset:-1536
	s_nop 0
	global_load_dwordx4 v[100:103], v[100:101], off offset:-1536
	s_nop 0
	global_load_dwordx4 v[104:107], v[120:121], off offset:1536
	global_load_dwordx4 v[108:111], v[122:123], off offset:1536
	ds_read_b128 v[170:173], v158
	ds_read_b128 v[174:177], v161 offset:36864
	ds_read_b128 v[178:181], v161 offset:41472
	ds_read_b128 v[182:185], v158 offset:4608
	ds_read_b128 v[186:189], v158 offset:32
	ds_read_b128 v[190:193], v161 offset:36896
	ds_read_b128 v[194:197], v161 offset:41504
	ds_read_b128 v[198:201], v158 offset:4640
	ds_read_b128 v[202:205], v158 offset:64
	ds_read_b128 v[206:209], v161 offset:36928
	ds_read_b128 v[210:213], v161 offset:41536
	ds_read_b128 v[214:217], v158 offset:4672
	s_waitcnt lgkmcnt(10)
	v_mfma_f32_32x32x16_bf16 v[48:63], v[170:173], v[174:177], v[48:63]
	s_waitcnt lgkmcnt(9)
	v_mfma_f32_32x32x16_bf16 v[32:47], v[170:173], v[178:181], v[32:47]
	s_waitcnt lgkmcnt(8)
	v_mfma_f32_32x32x16_bf16 v[16:31], v[182:185], v[174:177], v[16:31]
	v_mfma_f32_32x32x16_bf16 v[0:15], v[182:185], v[178:181], v[0:15]
	ds_read_b128 v[222:225], v158 offset:96
	ds_read_b128 v[226:229], v161 offset:36960
	ds_read_b128 v[230:233], v161 offset:41568
	ds_read_b128 v[234:237], v158 offset:4704
	s_waitcnt lgkmcnt(10)
	v_mfma_f32_32x32x16_bf16 v[48:63], v[186:189], v[190:193], v[48:63]
	s_waitcnt lgkmcnt(9)
	v_mfma_f32_32x32x16_bf16 v[32:47], v[186:189], v[194:197], v[32:47]
	s_waitcnt lgkmcnt(8)
	v_mfma_f32_32x32x16_bf16 v[16:31], v[198:201], v[190:193], v[16:31]
	v_mfma_f32_32x32x16_bf16 v[0:15], v[198:201], v[194:197], v[0:15]
	s_waitcnt vmcnt(11)
	ds_write_b128 v160, v[64:67] offset:55296
	s_waitcnt lgkmcnt(7)
	v_mfma_f32_32x32x16_bf16 v[48:63], v[202:205], v[206:209], v[48:63]
	s_waitcnt vmcnt(10)
	ds_write_b128 v160, v[68:71] offset:64512
	s_waitcnt lgkmcnt(7)
	v_mfma_f32_32x32x16_bf16 v[32:47], v[202:205], v[210:213], v[32:47]
	s_waitcnt vmcnt(9)
	ds_write_b128 v162, v[80:83] offset:18432
	s_waitcnt lgkmcnt(7)
	v_mfma_f32_32x32x16_bf16 v[16:31], v[214:217], v[206:209], v[16:31]
	v_mfma_f32_32x32x16_bf16 v[0:15], v[214:217], v[210:213], v[0:15]
	s_waitcnt vmcnt(8)
	ds_write_b128 v162, v[84:87] offset:27648
	s_waitcnt lgkmcnt(6)
	v_mfma_f32_32x32x16_bf16 v[48:63], v[222:225], v[226:229], v[48:63]
	s_waitcnt vmcnt(7)
	ds_write_b128 v163, v[88:91]
	s_waitcnt lgkmcnt(6)
	v_mfma_f32_32x32x16_bf16 v[32:47], v[222:225], v[230:233], v[32:47]
	s_waitcnt vmcnt(6)
	ds_write_b128 v163, v[92:95] offset:9216
	s_waitcnt lgkmcnt(6)
	v_mfma_f32_32x32x16_bf16 v[16:31], v[234:237], v[226:229], v[16:31]
	v_mfma_f32_32x32x16_bf16 v[0:15], v[234:237], v[230:233], v[0:15]
	v_lshl_add_u64 v[64:65], s[8:9], 0, v[112:113]
	v_lshl_add_u64 v[66:67], s[8:9], 0, v[114:115]
	v_lshl_add_u64 v[80:81], s[8:9], 0, v[116:117]
	v_lshl_add_u64 v[82:83], s[8:9], 0, v[118:119]
	v_lshl_add_u64 v[64:65], v[64:65], 0, v[128:129]
	v_lshl_add_u64 v[68:69], v[66:67], 0, v[128:129]
	v_lshl_add_u64 v[80:81], v[80:81], 0, v[128:129]
	v_lshl_add_u64 v[84:85], v[82:83], 0, v[128:129]
	s_waitcnt lgkmcnt(0)
	s_barrier
; template <class AS, class EP>
; DEVI void gemm_tile(const AS& as, const u16* __restrict__ Bt, int K, int m0, int n0, const EP& ep, char* lds) {
;     ...
;   GLOAD(ra0, rb0, 0); GLOAD(ra1, rb1, 1); LWRITE(0, ra0, rb0); __syncthreads();
;   for (int kt = 0; kt < KT; kt += 2) {
;     if (kt + 2 < KT) GLOAD(ra0, rb0, kt + 2);
;     __builtin_amdgcn_sched_barrier(0);
;     COMPUTE(0);
;     __builtin_amdgcn_sched_barrier(0);
;     LWRITE(1, ra1, rb1);
;     __syncthreads();
;     if (kt + 3 < KT) GLOAD(ra1, rb1, kt + 3);
;     __builtin_amdgcn_sched_barrier(0);
;     COMPUTE(1);
;     __builtin_amdgcn_sched_barrier(0);
;     if (kt + 2 < KT) LWRITE(0, ra0, rb0);
;     __syncthreads();
	global_load_dwordx4 v[64:67], v[64:65], off offset:-1536
	s_nop 0
	global_load_dwordx4 v[68:71], v[68:69], off offset:-1536
	s_nop 0
	global_load_dwordx4 v[80:83], v[80:81], off offset:-1536
	s_nop 0
	global_load_dwordx4 v[84:87], v[84:85], off offset:-1536
	s_nop 0
	global_load_dwordx4 v[88:91], v[120:121], off offset:1664
	global_load_dwordx4 v[92:95], v[122:123], off offset:1664
	ds_read_b128 v[170:173], v158 offset:55296
	ds_read_b128 v[174:177], v159
	ds_read_b128 v[178:181], v159 offset:4608
	ds_read_b128 v[182:185], v158 offset:59904
	ds_read_b128 v[186:189], v158 offset:55328
	ds_read_b128 v[190:193], v159 offset:32
	ds_read_b128 v[194:197], v159 offset:4640
	ds_read_b128 v[198:201], v158 offset:59936
	ds_read_b128 v[202:205], v158 offset:55360
	ds_read_b128 v[206:209], v159 offset:64
	ds_read_b128 v[210:213], v159 offset:4672
	ds_read_b128 v[214:217], v158 offset:59968
	s_waitcnt lgkmcnt(10)
	v_mfma_f32_32x32x16_bf16 v[48:63], v[170:173], v[174:177], v[48:63]
	s_waitcnt lgkmcnt(9)
	v_mfma_f32_32x32x16_bf16 v[32:47], v[170:173], v[178:181], v[32:47]
	s_waitcnt lgkmcnt(8)
	v_mfma_f32_32x32x16_bf16 v[16:31], v[182:185], v[174:177], v[16:31]
	v_mfma_f32_32x32x16_bf16 v[0:15], v[182:185], v[178:181], v[0:15]
	ds_read_b128 v[222:225], v158 offset:55392
	ds_read_b128 v[226:229], v159 offset:96
	ds_read_b128 v[230:233], v159 offset:4704
	ds_read_b128 v[234:237], v158 offset:60000
	s_waitcnt lgkmcnt(10)
	v_mfma_f32_32x32x16_bf16 v[48:63], v[186:189], v[190:193], v[48:63]
	s_waitcnt lgkmcnt(9)
	v_mfma_f32_32x32x16_bf16 v[32:47], v[186:189], v[194:197], v[32:47]
	s_waitcnt lgkmcnt(8)
	v_mfma_f32_32x32x16_bf16 v[16:31], v[198:201], v[190:193], v[16:31]
	v_mfma_f32_32x32x16_bf16 v[0:15], v[198:201], v[194:197], v[0:15]
	s_waitcnt vmcnt(11)
	ds_write_b128 v160, v[72:75]
	s_waitcnt lgkmcnt(7)
	v_mfma_f32_32x32x16_bf16 v[48:63], v[202:205], v[206:209], v[48:63]
	s_waitcnt vmcnt(10)
	ds_write_b128 v160, v[76:79] offset:9216
	s_waitcnt lgkmcnt(7)
	v_mfma_f32_32x32x16_bf16 v[32:47], v[202:205], v[210:213], v[32:47]
	s_waitcnt vmcnt(9)
	ds_write_b128 v160, v[96:99] offset:18432
	s_waitcnt lgkmcnt(7)
	v_mfma_f32_32x32x16_bf16 v[16:31], v[214:217], v[206:209], v[16:31]
	v_mfma_f32_32x32x16_bf16 v[0:15], v[214:217], v[210:213], v[0:15]
	s_waitcnt vmcnt(8)
	ds_write_b128 v160, v[100:103] offset:27648
	s_waitcnt lgkmcnt(6)
	v_mfma_f32_32x32x16_bf16 v[48:63], v[222:225], v[226:229], v[48:63]
	s_waitcnt vmcnt(7)
	ds_write_b128 v160, v[104:107] offset:36864
	s_waitcnt lgkmcnt(6)
	v_mfma_f32_32x32x16_bf16 v[32:47], v[222:225], v[230:233], v[32:47]
	s_waitcnt vmcnt(6)
	ds_write_b128 v160, v[108:111] offset:46080
	s_waitcnt lgkmcnt(6)
	v_mfma_f32_32x32x16_bf16 v[16:31], v[234:237], v[226:229], v[16:31]
	v_mfma_f32_32x32x16_bf16 v[0:15], v[234:237], v[230:233], v[0:15]
	v_lshl_add_u64 v[72:73], s[12:13], 0, v[112:113]
	v_lshl_add_u64 v[74:75], s[12:13], 0, v[114:115]
	v_lshl_add_u64 v[96:97], s[12:13], 0, v[116:117]
	v_lshl_add_u64 v[98:99], s[12:13], 0, v[118:119]
	v_lshl_add_u64 v[72:73], v[72:73], 0, v[128:129]
	v_lshl_add_u64 v[76:77], v[74:75], 0, v[128:129]
	v_lshl_add_u64 v[96:97], v[96:97], 0, v[128:129]
	v_lshl_add_u64 v[100:101], v[98:99], 0, v[128:129]
	s_waitcnt lgkmcnt(0)
	s_barrier
	global_load_dwordx4 v[72:75], v[72:73], off offset:-1536
	s_nop 0
	global_load_dwordx4 v[76:79], v[76:77], off offset:-1536
	s_nop 0
	global_load_dwordx4 v[96:99], v[96:97], off offset:-1536
	s_nop 0
	global_load_dwordx4 v[100:103], v[100:101], off offset:-1536
	s_nop 0
	global_load_dwordx4 v[104:107], v[120:121], off offset:1792
	global_load_dwordx4 v[108:111], v[122:123], off offset:1792
	ds_read_b128 v[170:173], v158
	ds_read_b128 v[174:177], v161 offset:36864
	ds_read_b128 v[178:181], v161 offset:41472
	ds_read_b128 v[182:185], v158 offset:4608
	ds_read_b128 v[186:189], v158 offset:32
	ds_read_b128 v[190:193], v161 offset:36896
	ds_read_b128 v[194:197], v161 offset:41504
	ds_read_b128 v[198:201], v158 offset:4640
	ds_read_b128 v[202:205], v158 offset:64
	ds_read_b128 v[206:209], v161 offset:36928
	ds_read_b128 v[210:213], v161 offset:41536
	ds_read_b128 v[214:217], v158 offset:4672
	s_waitcnt lgkmcnt(10)
	v_mfma_f32_32x32x16_bf16 v[48:63], v[170:173], v[174:177], v[48:63]
	s_waitcnt lgkmcnt(9)
	v_mfma_f32_32x32x16_bf16 v[32:47], v[170:173], v[178:181], v[32:47]
	s_waitcnt lgkmcnt(8)
	v_mfma_f32_32x32x16_bf16 v[16:31], v[182:185], v[174:177], v[16:31]
	v_mfma_f32_32x32x16_bf16 v[0:15], v[182:185], v[178:181], v[0:15]
	ds_read_b128 v[222:225], v158 offset:96
	ds_read_b128 v[226:229], v161 offset:36960
	ds_read_b128 v[230:233], v161 offset:41568
	ds_read_b128 v[234:237], v158 offset:4704
	s_waitcnt lgkmcnt(10)
	v_mfma_f32_32x32x16_bf16 v[48:63], v[186:189], v[190:193], v[48:63]
	s_waitcnt lgkmcnt(9)
	v_mfma_f32_32x32x16_bf16 v[32:47], v[186:189], v[194:197], v[32:47]
	s_waitcnt lgkmcnt(8)
	v_mfma_f32_32x32x16_bf16 v[16:31], v[198:201], v[190:193], v[16:31]
	v_mfma_f32_32x32x16_bf16 v[0:15], v[198:201], v[194:197], v[0:15]
	s_waitcnt vmcnt(11)
	ds_write_b128 v160, v[64:67] offset:55296
	s_waitcnt lgkmcnt(7)
	v_mfma_f32_32x32x16_bf16 v[48:63], v[202:205], v[206:209], v[48:63]
	s_waitcnt vmcnt(10)
	ds_write_b128 v160, v[68:71] offset:64512
	s_waitcnt lgkmcnt(7)
	v_mfma_f32_32x32x16_bf16 v[32:47], v[202:205], v[210:213], v[32:47]
	s_waitcnt vmcnt(9)
	ds_write_b128 v162, v[80:83] offset:18432
	s_waitcnt lgkmcnt(7)
	v_mfma_f32_32x32x16_bf16 v[16:31], v[214:217], v[206:209], v[16:31]
	v_mfma_f32_32x32x16_bf16 v[0:15], v[214:217], v[210:213], v[0:15]
	s_waitcnt vmcnt(8)
	ds_write_b128 v162, v[84:87] offset:27648
	s_waitcnt lgkmcnt(6)
	v_mfma_f32_32x32x16_bf16 v[48:63], v[222:225], v[226:229], v[48:63]
	s_waitcnt vmcnt(7)
	ds_write_b128 v163, v[88:91]
	s_waitcnt lgkmcnt(6)
	v_mfma_f32_32x32x16_bf16 v[32:47], v[222:225], v[230:233], v[32:47]
	s_waitcnt vmcnt(6)
	ds_write_b128 v163, v[92:95] offset:9216
	s_waitcnt lgkmcnt(6)
	v_mfma_f32_32x32x16_bf16 v[16:31], v[234:237], v[226:229], v[16:31]
	v_mfma_f32_32x32x16_bf16 v[0:15], v[234:237], v[230:233], v[0:15]
	v_lshl_add_u64 v[64:65], s[14:15], 0, v[112:113]
	v_lshl_add_u64 v[66:67], s[14:15], 0, v[114:115]
	v_lshl_add_u64 v[80:81], s[14:15], 0, v[116:117]
	v_lshl_add_u64 v[82:83], s[14:15], 0, v[118:119]
	v_lshl_add_u64 v[64:65], v[64:65], 0, v[128:129]
	v_lshl_add_u64 v[68:69], v[66:67], 0, v[128:129]
	v_lshl_add_u64 v[80:81], v[80:81], 0, v[128:129]
	v_lshl_add_u64 v[84:85], v[82:83], 0, v[128:129]
	s_waitcnt lgkmcnt(0)
	s_barrier
; template <class AS, class EP>
; DEVI void gemm_tile(const AS& as, const u16* __restrict__ Bt, int K, int m0, int n0, const EP& ep, char* lds) {
;     ...
;   GLOAD(ra0, rb0, 0); GLOAD(ra1, rb1, 1); LWRITE(0, ra0, rb0); __syncthreads();
;   for (int kt = 0; kt < KT; kt += 2) {
;     if (kt + 2 < KT) GLOAD(ra0, rb0, kt + 2);
;     __builtin_amdgcn_sched_barrier(0);
;     COMPUTE(0);
;     __builtin_amdgcn_sched_barrier(0);
;     LWRITE(1, ra1, rb1);
;     __syncthreads();
;     if (kt + 3 < KT) GLOAD(ra1, rb1, kt + 3);
;     __builtin_amdgcn_sched_barrier(0);
;     COMPUTE(1);
;     __builtin_amdgcn_sched_barrier(0);
;     if (kt + 2 < KT) LWRITE(0, ra0, rb0);
;     __syncthreads();
	global_load_dwordx4 v[64:67], v[64:65], off offset:-1536
	s_nop 0
	global_load_dwordx4 v[68:71], v[68:69], off offset:-1536
	s_nop 0
	global_load_dwordx4 v[80:83], v[80:81], off offset:-1536
	s_nop 0
	global_load_dwordx4 v[84:87], v[84:85], off offset:-1536
	s_nop 0
	global_load_dwordx4 v[88:91], v[120:121], off offset:1920
	global_load_dwordx4 v[92:95], v[122:123], off offset:1920
	ds_read_b128 v[170:173], v158 offset:55296
	ds_read_b128 v[174:177], v159
	ds_read_b128 v[178:181], v159 offset:4608
	ds_read_b128 v[182:185], v158 offset:59904
	ds_read_b128 v[186:189], v158 offset:55328
	ds_read_b128 v[190:193], v159 offset:32
	ds_read_b128 v[194:197], v159 offset:4640
	ds_read_b128 v[198:201], v158 offset:59936
	ds_read_b128 v[202:205], v158 offset:55360
	ds_read_b128 v[206:209], v159 offset:64
	ds_read_b128 v[210:213], v159 offset:4672
	ds_read_b128 v[214:217], v158 offset:59968
	s_waitcnt lgkmcnt(10)
	v_mfma_f32_32x32x16_bf16 v[48:63], v[170:173], v[174:177], v[48:63]
	s_waitcnt lgkmcnt(9)
	v_mfma_f32_32x32x16_bf16 v[32:47], v[170:173], v[178:181], v[32:47]
	s_waitcnt lgkmcnt(8)
	v_mfma_f32_32x32x16_bf16 v[16:31], v[182:185], v[174:177], v[16:31]
	v_mfma_f32_32x32x16_bf16 v[0:15], v[182:185], v[178:181], v[0:15]
	ds_read_b128 v[222:225], v158 offset:55392
	ds_read_b128 v[226:229], v159 offset:96
	ds_read_b128 v[230:233], v159 offset:4704
	ds_read_b128 v[234:237], v158 offset:60000
	s_waitcnt lgkmcnt(10)
	v_mfma_f32_32x32x16_bf16 v[48:63], v[186:189], v[190:193], v[48:63]
	s_waitcnt lgkmcnt(9)
	v_mfma_f32_32x32x16_bf16 v[32:47], v[186:189], v[194:197], v[32:47]
	s_waitcnt lgkmcnt(8)
	v_mfma_f32_32x32x16_bf16 v[16:31], v[198:201], v[190:193], v[16:31]
	v_mfma_f32_32x32x16_bf16 v[0:15], v[198:201], v[194:197], v[0:15]
	s_waitcnt vmcnt(11)
	ds_write_b128 v160, v[72:75]
	s_waitcnt lgkmcnt(7)
	v_mfma_f32_32x32x16_bf16 v[48:63], v[202:205], v[206:209], v[48:63]
	s_waitcnt vmcnt(10)
	ds_write_b128 v160, v[76:79] offset:9216
	s_waitcnt lgkmcnt(7)
	v_mfma_f32_32x32x16_bf16 v[32:47], v[202:205], v[210:213], v[32:47]
	s_waitcnt vmcnt(9)
	ds_write_b128 v160, v[96:99] offset:18432
	s_waitcnt lgkmcnt(7)
	v_mfma_f32_32x32x16_bf16 v[16:31], v[214:217], v[206:209], v[16:31]
	v_mfma_f32_32x32x16_bf16 v[0:15], v[214:217], v[210:213], v[0:15]
	s_waitcnt vmcnt(8)
	ds_write_b128 v160, v[100:103] offset:27648
	s_waitcnt lgkmcnt(6)
	v_mfma_f32_32x32x16_bf16 v[48:63], v[222:225], v[226:229], v[48:63]
	s_waitcnt vmcnt(7)
	ds_write_b128 v160, v[104:107] offset:36864
	s_waitcnt lgkmcnt(6)
	v_mfma_f32_32x32x16_bf16 v[32:47], v[222:225], v[230:233], v[32:47]
	s_waitcnt vmcnt(6)
	ds_write_b128 v160, v[108:111] offset:46080
	s_waitcnt lgkmcnt(6)
	v_mfma_f32_32x32x16_bf16 v[16:31], v[234:237], v[226:229], v[16:31]
	v_mfma_f32_32x32x16_bf16 v[0:15], v[234:237], v[230:233], v[0:15]
	s_waitcnt lgkmcnt(0)
	s_barrier
	ds_read_b128 v[170:173], v158
	ds_read_b128 v[174:177], v161 offset:36864
	ds_read_b128 v[178:181], v161 offset:41472
	ds_read_b128 v[182:185], v158 offset:4608
	ds_read_b128 v[186:189], v158 offset:32
	ds_read_b128 v[190:193], v161 offset:36896
	ds_read_b128 v[194:197], v161 offset:41504
	ds_read_b128 v[198:201], v158 offset:4640
	ds_read_b128 v[202:205], v158 offset:64
	ds_read_b128 v[206:209], v161 offset:36928
	ds_read_b128 v[210:213], v161 offset:41536
	ds_read_b128 v[214:217], v158 offset:4672
	s_waitcnt lgkmcnt(10)
	v_mfma_f32_32x32x16_bf16 v[48:63], v[170:173], v[174:177], v[48:63]
	s_waitcnt lgkmcnt(9)
	v_mfma_f32_32x32x16_bf16 v[32:47], v[170:173], v[178:181], v[32:47]
	s_waitcnt lgkmcnt(8)
	v_mfma_f32_32x32x16_bf16 v[16:31], v[182:185], v[174:177], v[16:31]
	v_mfma_f32_32x32x16_bf16 v[0:15], v[182:185], v[178:181], v[0:15]
	ds_read_b128 v[222:225], v158 offset:96
	ds_read_b128 v[226:229], v161 offset:36960
	ds_read_b128 v[230:233], v161 offset:41568
	ds_read_b128 v[234:237], v158 offset:4704
	s_waitcnt lgkmcnt(10)
	v_mfma_f32_32x32x16_bf16 v[48:63], v[186:189], v[190:193], v[48:63]
	s_waitcnt lgkmcnt(9)
	v_mfma_f32_32x32x16_bf16 v[32:47], v[186:189], v[194:197], v[32:47]
	s_waitcnt lgkmcnt(8)
	v_mfma_f32_32x32x16_bf16 v[16:31], v[198:201], v[190:193], v[16:31]
	v_mfma_f32_32x32x16_bf16 v[0:15], v[198:201], v[194:197], v[0:15]
	s_waitcnt vmcnt(5)
	ds_write_b128 v160, v[64:67] offset:55296
	s_waitcnt lgkmcnt(7)
	v_mfma_f32_32x32x16_bf16 v[48:63], v[202:205], v[206:209], v[48:63]
	s_waitcnt vmcnt(4)
	ds_write_b128 v160, v[68:71] offset:64512
	s_waitcnt lgkmcnt(7)
	v_mfma_f32_32x32x16_bf16 v[32:47], v[202:205], v[210:213], v[32:47]
	s_waitcnt vmcnt(3)
	ds_write_b128 v162, v[80:83] offset:18432
	s_waitcnt lgkmcnt(7)
	v_mfma_f32_32x32x16_bf16 v[16:31], v[214:217], v[206:209], v[16:31]
	v_mfma_f32_32x32x16_bf16 v[0:15], v[214:217], v[210:213], v[0:15]
	s_waitcnt vmcnt(2)
	ds_write_b128 v162, v[84:87] offset:27648
	s_waitcnt lgkmcnt(6)
	v_mfma_f32_32x32x16_bf16 v[48:63], v[222:225], v[226:229], v[48:63]
	s_waitcnt vmcnt(1)
	ds_write_b128 v163, v[88:91]
	s_waitcnt lgkmcnt(6)
	v_mfma_f32_32x32x16_bf16 v[32:47], v[222:225], v[230:233], v[32:47]
	s_waitcnt vmcnt(0)
	ds_write_b128 v163, v[92:95] offset:9216
	s_waitcnt lgkmcnt(6)
	v_mfma_f32_32x32x16_bf16 v[16:31], v[234:237], v[226:229], v[16:31]
	v_mfma_f32_32x32x16_bf16 v[0:15], v[234:237], v[230:233], v[0:15]
	s_waitcnt lgkmcnt(0)
	s_barrier
; DEVI int crow(int r, int hi) { return (r & 3) + 8 * (r >> 2) + 4 * hi; }
;   DEVI void operator()(const f32x16 (&acc)[2][2], int m0, int n0, int wm, int wn, int r32, int hi, char* lds) const {
;     const int mb = m0 + wm * 64, nb = n0 + wn * 64;
;     int b = seq_of(mb);
;     const float* gate = (const float*)(p->ws + OFF_MOD) + ((size_t)layer * 18 + b) * 3072 + 2048;
; #pragma unroll
;     for (int i = 0; i < 2; ++i)
; #pragma unroll
;       for (int j = 0; j < 2; ++j) {
;         int col = nb + j * 32 + r32; float g = gate[col];
; #pragma unroll
;         for (int r = 0; r < 16; ++r) {
;           int row = mb + i * 32 + crow(r, hi);
;           float xv = xrow(*p, layer, row)[col];
	ds_read_b128 v[170:173], v158 offset:55296
	ds_read_b128 v[174:177], v159
	ds_read_b128 v[178:181], v159 offset:4608
	ds_read_b128 v[182:185], v158 offset:59904
	ds_read_b128 v[186:189], v158 offset:55328
	ds_read_b128 v[190:193], v159 offset:32
	ds_read_b128 v[194:197], v159 offset:4640
	ds_read_b128 v[198:201], v158 offset:59936
	ds_read_b128 v[202:205], v158 offset:55360
	ds_read_b128 v[206:209], v159 offset:64
	ds_read_b128 v[210:213], v159 offset:4672
	ds_read_b128 v[214:217], v158 offset:59968
	s_waitcnt lgkmcnt(10)
	v_mfma_f32_32x32x16_bf16 v[48:63], v[170:173], v[174:177], v[48:63]
	s_waitcnt lgkmcnt(9)
	v_mfma_f32_32x32x16_bf16 v[32:47], v[170:173], v[178:181], v[32:47]
	s_waitcnt lgkmcnt(8)
	v_mfma_f32_32x32x16_bf16 v[16:31], v[182:185], v[174:177], v[16:31]
	v_mfma_f32_32x32x16_bf16 v[0:15], v[182:185], v[178:181], v[0:15]
	ds_read_b128 v[222:225], v158 offset:55392
	ds_read_b128 v[226:229], v159 offset:96
	ds_read_b128 v[230:233], v159 offset:4704
	ds_read_b128 v[234:237], v158 offset:60000
	s_waitcnt lgkmcnt(10)
	v_mfma_f32_32x32x16_bf16 v[48:63], v[186:189], v[190:193], v[48:63]
	s_waitcnt lgkmcnt(9)
	v_mfma_f32_32x32x16_bf16 v[32:47], v[186:189], v[194:197], v[32:47]
	s_waitcnt lgkmcnt(8)
	v_mfma_f32_32x32x16_bf16 v[16:31], v[198:201], v[190:193], v[16:31]
	v_mfma_f32_32x32x16_bf16 v[0:15], v[198:201], v[194:197], v[0:15]
	s_waitcnt lgkmcnt(6)
	v_mfma_f32_32x32x16_bf16 v[48:63], v[202:205], v[206:209], v[48:63]
	s_waitcnt lgkmcnt(5)
	v_mfma_f32_32x32x16_bf16 v[32:47], v[202:205], v[210:213], v[32:47]
	s_waitcnt lgkmcnt(4)
	v_mfma_f32_32x32x16_bf16 v[16:31], v[214:217], v[206:209], v[16:31]
	v_mfma_f32_32x32x16_bf16 v[0:15], v[214:217], v[210:213], v[0:15]
	s_waitcnt lgkmcnt(2)
	v_mfma_f32_32x32x16_bf16 v[48:63], v[222:225], v[226:229], v[48:63]
	s_waitcnt lgkmcnt(1)
	v_mfma_f32_32x32x16_bf16 v[32:47], v[222:225], v[230:233], v[32:47]
	s_waitcnt lgkmcnt(0)
	v_mfma_f32_32x32x16_bf16 v[16:31], v[234:237], v[226:229], v[16:31]
	v_mfma_f32_32x32x16_bf16 v[0:15], v[234:237], v[230:233], v[0:15]
	v_add_u32_e32 v68, s16, v157
	v_add_u32_e32 v65, 0xffff0000, v68
	s_mov_b32 s16, 0x10000
	v_lshrrev_b32_e32 v65, 14, v65
	v_cmp_gt_i32_e32 vcc, s16, v68
	v_ashrrev_i32_e32 v64, 12, v68
	v_add_u32_e32 v65, 16, v65
	v_cndmask_b32_e32 v64, v65, v64, vcc
	v_ashrrev_i32_e32 v65, 31, v64
	v_lshl_add_u64 v[64:65], s[46:47], 0, v[64:65]
	v_mov_b64_e32 v[66:67], s[90:91]
	v_mad_u64_u32 v[66:67], s[38:39], v64, s3, v[66:67]
	v_mov_b32_e32 v64, v67
	v_mad_u64_u32 v[64:65], s[38:39], v65, s3, v[64:65]
	v_mov_b32_e32 v67, v64
	v_subrev_u32_e32 v64, s17, v137
	s_mov_b64 s[38:39], 0x24da000
	v_add_u32_e32 v64, s28, v64
	v_lshl_add_u64 v[72:73], v[66:67], 0, s[38:39]
	v_ashrrev_i32_e32 v65, 31, v64
	v_lshl_add_u64 v[70:71], v[64:65], 2, v[72:73]
	s_barrier
	global_load_dword v126, v[70:71], off
	v_lshl_or_b32 v66, v136, 2, v68
	s_mov_b64 s[16:17], -1
	s_and_b64 vcc, exec, s[10:11]
	s_cbranch_vccz .LBB0_24
	v_ashrrev_i32_e32 v67, 31, v66
	s_mov_b64 s[16:17], 0

; template <class AS, class EP>
; DEVI void gemm_tile(const AS& as, const u16* __restrict__ Bt, int K, int m0, int n0, const EP& ep, char* lds) {
;     ...
;   GLOAD(ra0, rb0, 0); GLOAD(ra1, rb1, 1); LWRITE(0, ra0, rb0); __syncthreads();
;   for (int kt = 0; kt < KT; kt += 2) {
;     if (kt + 2 < KT) GLOAD(ra0, rb0, kt + 2);
;     __builtin_amdgcn_sched_barrier(0);
;     COMPUTE(0);
;     __builtin_amdgcn_sched_barrier(0);
;     LWRITE(1, ra1, rb1);
;     __syncthreads();
;     if (kt + 3 < KT) GLOAD(ra1, rb1, kt + 3);
;     __builtin_amdgcn_sched_barrier(0);
;     COMPUTE(1);
;     __builtin_amdgcn_sched_barrier(0);
;     if (kt + 2 < KT) LWRITE(0, ra0, rb0);
;     __syncthreads();
.LBB0_363:
	s_ashr_i32 s16, s44, 31
	s_lshr_b32 s16, s16, 29
	s_add_i32 s16, s44, s16
	s_ashr_i32 s17, s16, 3
	v_mov_b32_e32 v32, v131
	s_lshl_b32 s16, s17, 11
	s_or_b32 s16, s16, s45
	v_lshlrev_b32_e32 v0, 4, v32
	v_ashrrev_i32_e32 v33, 3, v32
	v_and_b32_e32 v128, 0x70, v0
	s_lshl_b32 s17, s17, 10
	v_add_u32_e32 v124, s16, v33
	v_lshl_add_u64 v[12:13], s[0:1], 0, v[128:129]
	v_subrev_u32_e32 v16, s17, v33
	v_mad_i64_i32 v[0:1], s[38:39], v124, s35, v[12:13]
	v_add_u32_e32 v126, 64, v124
	v_add_u32_e32 v20, s28, v16
	global_load_dwordx4 v[0:3], v[0:1], off
	v_mad_i64_i32 v[4:5], s[38:39], v126, s35, v[12:13]
	v_add_u32_e32 v132, 0x80, v124
	v_ashrrev_i32_e32 v21, 31, v20
	global_load_dwordx4 v[4:7], v[4:5], off
	v_mad_i64_i32 v[8:9], s[38:39], v132, s35, v[12:13]
	v_add_u32_e32 v134, 0xc0, v124
	v_lshlrev_b64 v[24:25], 11, v[20:21]
	v_add_u32_e32 v20, 64, v20
	global_load_dwordx4 v[8:11], v[8:9], off
	v_mad_i64_i32 v[12:13], s[38:39], v134, s35, v[12:13]
	v_lshl_add_u64 v[22:23], s[6:7], 0, v[128:129]
	v_ashrrev_i32_e32 v21, 31, v20
	global_load_dwordx4 v[12:15], v[12:13], off
	v_lshl_add_u64 v[120:121], v[22:23], 0, v[24:25]
	v_lshlrev_b64 v[26:27], 11, v[20:21]
	global_load_dwordx4 v[16:19], v[120:121], off
	v_lshl_add_u64 v[122:123], v[22:23], 0, v[26:27]
	global_load_dwordx4 v[20:23], v[122:123], off
	v_mov_b64_e32 v[28:29], s[0:1]
	v_mad_i64_i32 v[30:31], s[38:39], v124, s35, v[28:29]
	v_lshl_add_u64 v[30:31], v[30:31], 0, v[128:129]
	global_load_dwordx4 v[64:67], v[30:31], off offset:128
	v_mad_i64_i32 v[30:31], s[38:39], v126, s35, v[28:29]
	v_lshl_add_u64 v[30:31], v[30:31], 0, v[128:129]
	global_load_dwordx4 v[68:71], v[30:31], off offset:128
	v_mad_i64_i32 v[30:31], s[38:39], v132, s35, v[28:29]
	v_mad_i64_i32 v[28:29], s[38:39], v134, s35, v[28:29]
	v_lshl_add_u64 v[24:25], s[6:7], 0, v[24:25]
	v_lshl_add_u64 v[28:29], v[28:29], 0, v[128:129]
	v_lshl_add_u64 v[24:25], v[24:25], 0, v[128:129]
	global_load_dwordx4 v[76:79], v[28:29], off offset:128
	global_load_dwordx4 v[80:83], v[24:25], off offset:128
	v_lshl_add_u64 v[24:25], s[6:7], 0, v[26:27]
	v_mul_lo_u32 v112, v33, s96
	v_lshl_add_u64 v[30:31], v[30:31], 0, v[128:129]
	v_lshl_add_u64 v[24:25], v[24:25], 0, v[128:129]
	v_add3_u32 v160, 16, v128, v112
	global_load_dwordx4 v[72:75], v[30:31], off offset:128
	global_load_dwordx4 v[84:87], v[24:25], off offset:128
	v_bfe_u32 v136, v32, 5, 1
	v_and_b32_e32 v137, 0x5f, v32
	v_readlane_b32 s4, v219, 59
	v_readlane_b32 s46, v219, 49
	v_readlane_b32 s5, v219, 60
	v_ashrrev_i32_e32 v125, 31, v124
	v_ashrrev_i32_e32 v127, 31, v126
	v_ashrrev_i32_e32 v133, 31, v132
	v_ashrrev_i32_e32 v135, 31, v134
	s_waitcnt vmcnt(11)
	ds_write_b128 v160, v[0:3]
	s_waitcnt vmcnt(10)
	ds_write_b128 v160, v[4:7] offset:9216
	s_waitcnt vmcnt(9)
	ds_write_b128 v160, v[8:11] offset:18432
	s_waitcnt vmcnt(8)
	ds_write_b128 v160, v[12:15] offset:27648
	s_waitcnt vmcnt(7)
	ds_write_b128 v160, v[16:19] offset:36864
	s_waitcnt vmcnt(6)
	ds_write_b128 v160, v[20:23] offset:46080
	v_ashrrev_i32_e32 v0, 1, v32
	v_and_b32_e32 v157, 0xffffffc0, v0
	v_and_or_b32 v0, v32, 31, v157
	v_mul_lo_u32 v0, v0, s96
	v_lshlrev_b32_e32 v1, 4, v136
	v_add3_u32 v158, 16, v0, v1
	v_mul_u32_u24_e32 v0, 0x90, v137
	v_add3_u32 v161, 16, v0, v1
	v_add3_u32 v159, s46, v0, v1
	v_mov_b64_e32 v[0:1], s[4:5]
	v_mad_i64_i32 v[2:3], s[38:39], v124, s35, v[0:1]
	v_lshl_add_u64 v[2:3], v[2:3], 0, v[128:129]
	s_waitcnt lgkmcnt(0)
	s_barrier
	global_load_dwordx4 v[88:91], v[2:3], off
	v_mad_i64_i32 v[2:3], s[38:39], v126, s35, v[0:1]
	v_lshl_add_u64 v[2:3], v[2:3], 0, v[128:129]
	global_load_dwordx4 v[92:95], v[2:3], off
	v_mad_i64_i32 v[2:3], s[38:39], v132, s35, v[0:1]
	v_mad_i64_i32 v[0:1], s[38:39], v134, s35, v[0:1]
	v_lshl_add_u64 v[2:3], v[2:3], 0, v[128:129]
	v_lshl_add_u64 v[0:1], v[0:1], 0, v[128:129]
	global_load_dwordx4 v[96:99], v[2:3], off
	global_load_dwordx4 v[100:103], v[0:1], off
	global_load_dwordx4 v[104:107], v[120:121], off offset:256
	global_load_dwordx4 v[108:111], v[122:123], off offset:256
	ds_read_b128 v[170:173], v158
	ds_read_b128 v[174:177], v161 offset:36864
	ds_read_b128 v[178:181], v161 offset:41472
	ds_read_b128 v[182:185], v158 offset:4608
	ds_read_b128 v[186:189], v158 offset:32
	ds_read_b128 v[190:193], v161 offset:36896
	ds_read_b128 v[194:197], v161 offset:41504
	ds_read_b128 v[198:201], v158 offset:4640
	ds_read_b128 v[202:205], v158 offset:64
	ds_read_b128 v[206:209], v161 offset:36928
	ds_read_b128 v[210:213], v161 offset:41536
	ds_read_b128 v[214:217], v158 offset:4672
	s_waitcnt lgkmcnt(10)
	v_mfma_f32_32x32x16_bf16 v[48:63], v[170:173], v[174:177], 0
	s_waitcnt lgkmcnt(9)
	v_mfma_f32_32x32x16_bf16 v[32:47], v[170:173], v[178:181], 0
	s_waitcnt lgkmcnt(8)
	v_mfma_f32_32x32x16_bf16 v[16:31], v[182:185], v[174:177], 0
	v_mfma_f32_32x32x16_bf16 v[0:15], v[182:185], v[178:181], 0
	ds_read_b128 v[222:225], v158 offset:96
	ds_read_b128 v[226:229], v161 offset:36960
	ds_read_b128 v[230:233], v161 offset:41568
	ds_read_b128 v[234:237], v158 offset:4704
	s_waitcnt lgkmcnt(10)
	v_mfma_f32_32x32x16_bf16 v[48:63], v[186:189], v[190:193], v[48:63]
	s_waitcnt lgkmcnt(9)
	v_mfma_f32_32x32x16_bf16 v[32:47], v[186:189], v[194:197], v[32:47]
	s_waitcnt lgkmcnt(8)
	v_mfma_f32_32x32x16_bf16 v[16:31], v[198:201], v[190:193], v[16:31]
	v_mfma_f32_32x32x16_bf16 v[0:15], v[198:201], v[194:197], v[0:15]
	v_readlane_b32 s4, v219, 61
	v_readlane_b32 s5, v219, 62
	v_add_u32_e32 v162, 0xd800, v160
	s_waitcnt vmcnt(11)
	ds_write_b128 v160, v[64:67] offset:55296
	s_waitcnt lgkmcnt(7)
	v_mfma_f32_32x32x16_bf16 v[48:63], v[202:205], v[206:209], v[48:63]
	s_waitcnt vmcnt(10)
	ds_write_b128 v160, v[68:71] offset:64512
	s_waitcnt lgkmcnt(7)
	v_mfma_f32_32x32x16_bf16 v[32:47], v[202:205], v[210:213], v[32:47]
	s_waitcnt vmcnt(7)
	ds_write_b128 v162, v[72:75] offset:18432
	s_waitcnt lgkmcnt(7)
	v_mfma_f32_32x32x16_bf16 v[16:31], v[214:217], v[206:209], v[16:31]
	v_mfma_f32_32x32x16_bf16 v[0:15], v[214:217], v[210:213], v[0:15]
	ds_write_b128 v162, v[76:79] offset:27648
	s_waitcnt lgkmcnt(6)
	v_mfma_f32_32x32x16_bf16 v[48:63], v[222:225], v[226:229], v[48:63]
	v_mov_b64_e32 v[72:73], s[4:5]
	v_mad_i64_i32 v[64:65], s[38:39], v124, s35, v[72:73]
	v_mad_i64_i32 v[66:67], s[38:39], v126, s35, v[72:73]
	v_mad_i64_i32 v[74:75], s[38:39], v132, s35, v[72:73]
	v_add3_u32 v163, s46, v128, v112
	v_lshl_add_u64 v[64:65], v[64:65], 0, v[128:129]
	v_lshl_add_u64 v[68:69], v[66:67], 0, v[128:129]
	v_lshl_add_u64 v[74:75], v[74:75], 0, v[128:129]
	v_mad_i64_i32 v[72:73], s[38:39], v134, s35, v[72:73]
	ds_write_b128 v163, v[80:83]
	s_waitcnt lgkmcnt(6)
	v_mfma_f32_32x32x16_bf16 v[32:47], v[222:225], v[230:233], v[32:47]
	s_waitcnt vmcnt(6)
	ds_write_b128 v163, v[84:87] offset:9216
	s_waitcnt lgkmcnt(6)
	v_mfma_f32_32x32x16_bf16 v[16:31], v[234:237], v[226:229], v[16:31]
	v_mfma_f32_32x32x16_bf16 v[0:15], v[234:237], v[230:233], v[0:15]
	s_waitcnt lgkmcnt(0)
	s_barrier
; template <class AS, class EP>
; DEVI void gemm_tile(const AS& as, const u16* __restrict__ Bt, int K, int m0, int n0, const EP& ep, char* lds) {
;     ...
;   GLOAD(ra0, rb0, 0); GLOAD(ra1, rb1, 1); LWRITE(0, ra0, rb0); __syncthreads();
;   for (int kt = 0; kt < KT; kt += 2) {
;     if (kt + 2 < KT) GLOAD(ra0, rb0, kt + 2);
;     __builtin_amdgcn_sched_barrier(0);
;     COMPUTE(0);
;     __builtin_amdgcn_sched_barrier(0);
;     LWRITE(1, ra1, rb1);
;     __syncthreads();
;     if (kt + 3 < KT) GLOAD(ra1, rb1, kt + 3);
;     __builtin_amdgcn_sched_barrier(0);
;     COMPUTE(1);
;     __builtin_amdgcn_sched_barrier(0);
;     if (kt + 2 < KT) LWRITE(0, ra0, rb0);
;     __syncthreads();
	global_load_dwordx4 v[64:67], v[64:65], off
	s_nop 0
	global_load_dwordx4 v[68:71], v[68:69], off
	v_lshl_add_u64 v[72:73], v[72:73], 0, v[128:129]
	global_load_dwordx4 v[80:83], v[74:75], off
	global_load_dwordx4 v[84:87], v[72:73], off
	global_load_dwordx4 v[112:115], v[120:121], off offset:384
	global_load_dwordx4 v[116:119], v[122:123], off offset:384
	ds_read_b128 v[170:173], v158 offset:55296
	ds_read_b128 v[174:177], v159
	ds_read_b128 v[178:181], v159 offset:4608
	ds_read_b128 v[182:185], v158 offset:59904
	ds_read_b128 v[186:189], v158 offset:55328
	ds_read_b128 v[190:193], v159 offset:32
	ds_read_b128 v[194:197], v159 offset:4640
	ds_read_b128 v[198:201], v158 offset:59936
	ds_read_b128 v[202:205], v158 offset:55360
	ds_read_b128 v[206:209], v159 offset:64
	ds_read_b128 v[210:213], v159 offset:4672
	ds_read_b128 v[214:217], v158 offset:59968
	s_waitcnt lgkmcnt(10)
	v_mfma_f32_32x32x16_bf16 v[48:63], v[170:173], v[174:177], v[48:63]
	s_waitcnt lgkmcnt(9)
	v_mfma_f32_32x32x16_bf16 v[32:47], v[170:173], v[178:181], v[32:47]
	s_waitcnt lgkmcnt(8)
	v_mfma_f32_32x32x16_bf16 v[16:31], v[182:185], v[174:177], v[16:31]
	v_mfma_f32_32x32x16_bf16 v[0:15], v[182:185], v[178:181], v[0:15]
	ds_read_b128 v[222:225], v158 offset:55392
	ds_read_b128 v[226:229], v159 offset:96
	ds_read_b128 v[230:233], v159 offset:4704
	ds_read_b128 v[234:237], v158 offset:60000
	s_waitcnt lgkmcnt(10)
	v_mfma_f32_32x32x16_bf16 v[48:63], v[186:189], v[190:193], v[48:63]
	s_waitcnt lgkmcnt(9)
	v_mfma_f32_32x32x16_bf16 v[32:47], v[186:189], v[194:197], v[32:47]
	s_waitcnt lgkmcnt(8)
	v_mfma_f32_32x32x16_bf16 v[16:31], v[198:201], v[190:193], v[16:31]
	v_mfma_f32_32x32x16_bf16 v[0:15], v[198:201], v[194:197], v[0:15]
	v_readlane_b32 s4, v218, 1
	v_readlane_b32 s5, v218, 2
	s_waitcnt vmcnt(11)
	ds_write_b128 v160, v[88:91]
	s_waitcnt lgkmcnt(7)
	v_mfma_f32_32x32x16_bf16 v[48:63], v[202:205], v[206:209], v[48:63]
	s_waitcnt vmcnt(10)
	ds_write_b128 v160, v[92:95] offset:9216
	s_waitcnt lgkmcnt(7)
	v_mfma_f32_32x32x16_bf16 v[32:47], v[202:205], v[210:213], v[32:47]
	s_waitcnt vmcnt(9)
	ds_write_b128 v160, v[96:99] offset:18432
	s_waitcnt lgkmcnt(7)
	v_mfma_f32_32x32x16_bf16 v[16:31], v[214:217], v[206:209], v[16:31]
	v_mfma_f32_32x32x16_bf16 v[0:15], v[214:217], v[210:213], v[0:15]
	s_waitcnt vmcnt(8)
	ds_write_b128 v160, v[100:103] offset:27648
	s_waitcnt lgkmcnt(6)
	v_mfma_f32_32x32x16_bf16 v[48:63], v[222:225], v[226:229], v[48:63]
	s_waitcnt vmcnt(7)
	ds_write_b128 v160, v[104:107] offset:36864
	s_waitcnt lgkmcnt(6)
	v_mfma_f32_32x32x16_bf16 v[32:47], v[222:225], v[230:233], v[32:47]
	s_waitcnt vmcnt(6)
	ds_write_b128 v160, v[108:111] offset:46080
	s_waitcnt lgkmcnt(6)
	v_mfma_f32_32x32x16_bf16 v[16:31], v[234:237], v[226:229], v[16:31]
	v_mfma_f32_32x32x16_bf16 v[0:15], v[234:237], v[230:233], v[0:15]
	v_mov_b64_e32 v[88:89], s[4:5]
	v_mad_i64_i32 v[72:73], s[38:39], v124, s35, v[88:89]
	v_mad_i64_i32 v[74:75], s[38:39], v126, s35, v[88:89]
	v_mad_i64_i32 v[90:91], s[38:39], v132, s35, v[88:89]
	v_mad_i64_i32 v[88:89], s[38:39], v134, s35, v[88:89]
	v_lshl_add_u64 v[72:73], v[72:73], 0, v[128:129]
	v_lshl_add_u64 v[76:77], v[74:75], 0, v[128:129]
	v_lshl_add_u64 v[90:91], v[90:91], 0, v[128:129]
	v_lshl_add_u64 v[92:93], v[88:89], 0, v[128:129]
	s_waitcnt lgkmcnt(0)
	s_barrier
	global_load_dwordx4 v[72:75], v[72:73], off
	s_nop 0
	global_load_dwordx4 v[76:79], v[76:77], off
	s_nop 0
	global_load_dwordx4 v[88:91], v[90:91], off
	s_nop 0
	global_load_dwordx4 v[92:95], v[92:93], off
	s_nop 0
	global_load_dwordx4 v[96:99], v[120:121], off offset:512
	global_load_dwordx4 v[100:103], v[122:123], off offset:512
	ds_read_b128 v[170:173], v158
	ds_read_b128 v[174:177], v161 offset:36864
	ds_read_b128 v[178:181], v161 offset:41472
	ds_read_b128 v[182:185], v158 offset:4608
	ds_read_b128 v[186:189], v158 offset:32
	ds_read_b128 v[190:193], v161 offset:36896
	ds_read_b128 v[194:197], v161 offset:41504
	ds_read_b128 v[198:201], v158 offset:4640
	ds_read_b128 v[202:205], v158 offset:64
	ds_read_b128 v[206:209], v161 offset:36928
	ds_read_b128 v[210:213], v161 offset:41536
	ds_read_b128 v[214:217], v158 offset:4672
	s_waitcnt lgkmcnt(10)
	v_mfma_f32_32x32x16_bf16 v[48:63], v[170:173], v[174:177], v[48:63]
	s_waitcnt lgkmcnt(9)
	v_mfma_f32_32x32x16_bf16 v[32:47], v[170:173], v[178:181], v[32:47]
	s_waitcnt lgkmcnt(8)
	v_mfma_f32_32x32x16_bf16 v[16:31], v[182:185], v[174:177], v[16:31]
	v_mfma_f32_32x32x16_bf16 v[0:15], v[182:185], v[178:181], v[0:15]
	ds_read_b128 v[222:225], v158 offset:96
	ds_read_b128 v[226:229], v161 offset:36960
	ds_read_b128 v[230:233], v161 offset:41568
	ds_read_b128 v[234:237], v158 offset:4704
	s_waitcnt lgkmcnt(10)
	v_mfma_f32_32x32x16_bf16 v[48:63], v[186:189], v[190:193], v[48:63]
	s_waitcnt lgkmcnt(9)
	v_mfma_f32_32x32x16_bf16 v[32:47], v[186:189], v[194:197], v[32:47]
	s_waitcnt lgkmcnt(8)
	v_mfma_f32_32x32x16_bf16 v[16:31], v[198:201], v[190:193], v[16:31]
	v_mfma_f32_32x32x16_bf16 v[0:15], v[198:201], v[194:197], v[0:15]
	v_readlane_b32 s4, v218, 3
	v_readlane_b32 s5, v218, 4
	s_waitcnt vmcnt(11)
	ds_write_b128 v160, v[64:67] offset:55296
	s_waitcnt lgkmcnt(7)
	v_mfma_f32_32x32x16_bf16 v[48:63], v[202:205], v[206:209], v[48:63]
	s_waitcnt vmcnt(10)
	ds_write_b128 v160, v[68:71] offset:64512
	s_waitcnt lgkmcnt(7)
	v_mfma_f32_32x32x16_bf16 v[32:47], v[202:205], v[210:213], v[32:47]
	s_waitcnt vmcnt(9)
	ds_write_b128 v162, v[80:83] offset:18432
	s_waitcnt lgkmcnt(7)
	v_mfma_f32_32x32x16_bf16 v[16:31], v[214:217], v[206:209], v[16:31]
	v_mfma_f32_32x32x16_bf16 v[0:15], v[214:217], v[210:213], v[0:15]
	s_waitcnt vmcnt(8)
	ds_write_b128 v162, v[84:87] offset:27648
	s_waitcnt lgkmcnt(6)
	v_mfma_f32_32x32x16_bf16 v[48:63], v[222:225], v[226:229], v[48:63]
	s_waitcnt vmcnt(7)
	ds_write_b128 v163, v[112:115]
	s_waitcnt lgkmcnt(6)
	v_mfma_f32_32x32x16_bf16 v[32:47], v[222:225], v[230:233], v[32:47]
	s_waitcnt vmcnt(6)
	ds_write_b128 v163, v[116:119] offset:9216
	s_waitcnt lgkmcnt(6)
	v_mfma_f32_32x32x16_bf16 v[16:31], v[234:237], v[226:229], v[16:31]
	v_mfma_f32_32x32x16_bf16 v[0:15], v[234:237], v[230:233], v[0:15]
	v_mov_b64_e32 v[80:81], s[4:5]
	v_mad_i64_i32 v[64:65], s[38:39], v124, s35, v[80:81]
	v_mad_i64_i32 v[66:67], s[38:39], v126, s35, v[80:81]
	v_mad_i64_i32 v[82:83], s[38:39], v132, s35, v[80:81]
	v_mad_i64_i32 v[80:81], s[38:39], v134, s35, v[80:81]
	v_lshl_add_u64 v[64:65], v[64:65], 0, v[128:129]
	v_lshl_add_u64 v[68:69], v[66:67], 0, v[128:129]
	v_lshl_add_u64 v[82:83], v[82:83], 0, v[128:129]
	v_lshl_add_u64 v[84:85], v[80:81], 0, v[128:129]
	s_waitcnt lgkmcnt(0)
	s_barrier
; template <class AS, class EP>
; DEVI void gemm_tile(const AS& as, const u16* __restrict__ Bt, int K, int m0, int n0, const EP& ep, char* lds) {
;     ...
;   GLOAD(ra0, rb0, 0); GLOAD(ra1, rb1, 1); LWRITE(0, ra0, rb0); __syncthreads();
;   for (int kt = 0; kt < KT; kt += 2) {
;     if (kt + 2 < KT) GLOAD(ra0, rb0, kt + 2);
;     __builtin_amdgcn_sched_barrier(0);
;     COMPUTE(0);
;     __builtin_amdgcn_sched_barrier(0);
;     LWRITE(1, ra1, rb1);
;     __syncthreads();
;     if (kt + 3 < KT) GLOAD(ra1, rb1, kt + 3);
;     __builtin_amdgcn_sched_barrier(0);
;     COMPUTE(1);
;     __builtin_amdgcn_sched_barrier(0);
;     if (kt + 2 < KT) LWRITE(0, ra0, rb0);
;     __syncthreads();
	global_load_dwordx4 v[64:67], v[64:65], off
	s_nop 0
	global_load_dwordx4 v[68:71], v[68:69], off
	s_nop 0
	global_load_dwordx4 v[80:83], v[82:83], off
	s_nop 0
	global_load_dwordx4 v[84:87], v[84:85], off
	s_nop 0
	global_load_dwordx4 v[104:107], v[120:121], off offset:640
	global_load_dwordx4 v[108:111], v[122:123], off offset:640
	ds_read_b128 v[170:173], v158 offset:55296
	ds_read_b128 v[174:177], v159
	ds_read_b128 v[178:181], v159 offset:4608
	ds_read_b128 v[182:185], v158 offset:59904
	ds_read_b128 v[186:189], v158 offset:55328
	ds_read_b128 v[190:193], v159 offset:32
	ds_read_b128 v[194:197], v159 offset:4640
	ds_read_b128 v[198:201], v158 offset:59936
	ds_read_b128 v[202:205], v158 offset:55360
	ds_read_b128 v[206:209], v159 offset:64
	ds_read_b128 v[210:213], v159 offset:4672
	ds_read_b128 v[214:217], v158 offset:59968
	s_waitcnt lgkmcnt(10)
	v_mfma_f32_32x32x16_bf16 v[48:63], v[170:173], v[174:177], v[48:63]
	s_waitcnt lgkmcnt(9)
	v_mfma_f32_32x32x16_bf16 v[32:47], v[170:173], v[178:181], v[32:47]
	s_waitcnt lgkmcnt(8)
	v_mfma_f32_32x32x16_bf16 v[16:31], v[182:185], v[174:177], v[16:31]
	v_mfma_f32_32x32x16_bf16 v[0:15], v[182:185], v[178:181], v[0:15]
	ds_read_b128 v[222:225], v158 offset:55392
	ds_read_b128 v[226:229], v159 offset:96
	ds_read_b128 v[230:233], v159 offset:4704
	ds_read_b128 v[234:237], v158 offset:60000
	s_waitcnt lgkmcnt(10)
	v_mfma_f32_32x32x16_bf16 v[48:63], v[186:189], v[190:193], v[48:63]
	s_waitcnt lgkmcnt(9)
	v_mfma_f32_32x32x16_bf16 v[32:47], v[186:189], v[194:197], v[32:47]
	s_waitcnt lgkmcnt(8)
	v_mfma_f32_32x32x16_bf16 v[16:31], v[198:201], v[190:193], v[16:31]
	v_mfma_f32_32x32x16_bf16 v[0:15], v[198:201], v[194:197], v[0:15]
	v_readlane_b32 s4, v218, 5
	v_readlane_b32 s5, v218, 6
	s_waitcnt vmcnt(11)
	ds_write_b128 v160, v[72:75]
	s_waitcnt lgkmcnt(7)
	v_mfma_f32_32x32x16_bf16 v[48:63], v[202:205], v[206:209], v[48:63]
	s_waitcnt vmcnt(10)
	ds_write_b128 v160, v[76:79] offset:9216
	s_waitcnt lgkmcnt(7)
	v_mfma_f32_32x32x16_bf16 v[32:47], v[202:205], v[210:213], v[32:47]
	s_waitcnt vmcnt(9)
	ds_write_b128 v160, v[88:91] offset:18432
	s_waitcnt lgkmcnt(7)
	v_mfma_f32_32x32x16_bf16 v[16:31], v[214:217], v[206:209], v[16:31]
	v_mfma_f32_32x32x16_bf16 v[0:15], v[214:217], v[210:213], v[0:15]
	s_waitcnt vmcnt(8)
	ds_write_b128 v160, v[92:95] offset:27648
	s_waitcnt lgkmcnt(6)
	v_mfma_f32_32x32x16_bf16 v[48:63], v[222:225], v[226:229], v[48:63]
	s_waitcnt vmcnt(7)
	ds_write_b128 v160, v[96:99] offset:36864
	s_waitcnt lgkmcnt(6)
	v_mfma_f32_32x32x16_bf16 v[32:47], v[222:225], v[230:233], v[32:47]
	s_waitcnt vmcnt(6)
	ds_write_b128 v160, v[100:103] offset:46080
	s_waitcnt lgkmcnt(6)
	v_mfma_f32_32x32x16_bf16 v[16:31], v[234:237], v[226:229], v[16:31]
	v_mfma_f32_32x32x16_bf16 v[0:15], v[234:237], v[230:233], v[0:15]
	v_mov_b64_e32 v[88:89], s[4:5]
	v_mad_i64_i32 v[72:73], s[38:39], v124, s35, v[88:89]
	v_mad_i64_i32 v[74:75], s[38:39], v126, s35, v[88:89]
	v_mad_i64_i32 v[90:91], s[38:39], v132, s35, v[88:89]
	v_mad_i64_i32 v[88:89], s[38:39], v134, s35, v[88:89]
	v_lshl_add_u64 v[72:73], v[72:73], 0, v[128:129]
	v_lshl_add_u64 v[76:77], v[74:75], 0, v[128:129]
	v_lshl_add_u64 v[90:91], v[90:91], 0, v[128:129]
	v_lshl_add_u64 v[92:93], v[88:89], 0, v[128:129]
	s_waitcnt lgkmcnt(0)
	s_barrier
	global_load_dwordx4 v[72:75], v[72:73], off offset:-768
	s_nop 0
	global_load_dwordx4 v[76:79], v[76:77], off offset:-768
	s_nop 0
	global_load_dwordx4 v[88:91], v[90:91], off offset:-768
	s_nop 0
	global_load_dwordx4 v[92:95], v[92:93], off offset:-768
	s_nop 0
	global_load_dwordx4 v[96:99], v[120:121], off offset:768
	global_load_dwordx4 v[100:103], v[122:123], off offset:768
	ds_read_b128 v[170:173], v158
	ds_read_b128 v[174:177], v161 offset:36864
	ds_read_b128 v[178:181], v161 offset:41472
	ds_read_b128 v[182:185], v158 offset:4608
	ds_read_b128 v[186:189], v158 offset:32
	ds_read_b128 v[190:193], v161 offset:36896
	ds_read_b128 v[194:197], v161 offset:41504
	ds_read_b128 v[198:201], v158 offset:4640
	ds_read_b128 v[202:205], v158 offset:64
	ds_read_b128 v[206:209], v161 offset:36928
	ds_read_b128 v[210:213], v161 offset:41536
	ds_read_b128 v[214:217], v158 offset:4672
	s_waitcnt lgkmcnt(10)
	v_mfma_f32_32x32x16_bf16 v[48:63], v[170:173], v[174:177], v[48:63]
	s_waitcnt lgkmcnt(9)
	v_mfma_f32_32x32x16_bf16 v[32:47], v[170:173], v[178:181], v[32:47]
	s_waitcnt lgkmcnt(8)
	v_mfma_f32_32x32x16_bf16 v[16:31], v[182:185], v[174:177], v[16:31]
	v_mfma_f32_32x32x16_bf16 v[0:15], v[182:185], v[178:181], v[0:15]
	ds_read_b128 v[222:225], v158 offset:96
	ds_read_b128 v[226:229], v161 offset:36960
	ds_read_b128 v[230:233], v161 offset:41568
	ds_read_b128 v[234:237], v158 offset:4704
	s_waitcnt lgkmcnt(10)
	v_mfma_f32_32x32x16_bf16 v[48:63], v[186:189], v[190:193], v[48:63]
	s_waitcnt lgkmcnt(9)
	v_mfma_f32_32x32x16_bf16 v[32:47], v[186:189], v[194:197], v[32:47]
	s_waitcnt lgkmcnt(8)
	v_mfma_f32_32x32x16_bf16 v[16:31], v[198:201], v[190:193], v[16:31]
	v_mfma_f32_32x32x16_bf16 v[0:15], v[198:201], v[194:197], v[0:15]
	s_waitcnt vmcnt(11)
	ds_write_b128 v160, v[64:67] offset:55296
	s_waitcnt lgkmcnt(7)
	v_mfma_f32_32x32x16_bf16 v[48:63], v[202:205], v[206:209], v[48:63]
	s_waitcnt vmcnt(10)
	ds_write_b128 v160, v[68:71] offset:64512
	s_waitcnt lgkmcnt(7)
	v_mfma_f32_32x32x16_bf16 v[32:47], v[202:205], v[210:213], v[32:47]
	s_waitcnt vmcnt(9)
	ds_write_b128 v162, v[80:83] offset:18432
	s_waitcnt lgkmcnt(7)
	v_mfma_f32_32x32x16_bf16 v[16:31], v[214:217], v[206:209], v[16:31]
	v_mfma_f32_32x32x16_bf16 v[0:15], v[214:217], v[210:213], v[0:15]
	s_waitcnt vmcnt(8)
	ds_write_b128 v162, v[84:87] offset:27648
	s_waitcnt lgkmcnt(6)
	v_mfma_f32_32x32x16_bf16 v[48:63], v[222:225], v[226:229], v[48:63]
	s_waitcnt vmcnt(7)
	ds_write_b128 v163, v[104:107]
	s_waitcnt lgkmcnt(6)
	v_mfma_f32_32x32x16_bf16 v[32:47], v[222:225], v[230:233], v[32:47]
	s_waitcnt vmcnt(6)
	ds_write_b128 v163, v[108:111] offset:9216
	s_waitcnt lgkmcnt(6)
	v_mfma_f32_32x32x16_bf16 v[16:31], v[234:237], v[226:229], v[16:31]
	v_mfma_f32_32x32x16_bf16 v[0:15], v[234:237], v[230:233], v[0:15]
	v_mov_b64_e32 v[80:81], s[30:31]
	v_mad_i64_i32 v[64:65], s[38:39], v124, s35, v[80:81]
	v_mad_i64_i32 v[66:67], s[38:39], v126, s35, v[80:81]
	v_mad_i64_i32 v[82:83], s[38:39], v132, s35, v[80:81]
	v_mad_i64_i32 v[80:81], s[38:39], v134, s35, v[80:81]
	v_lshl_add_u64 v[64:65], v[64:65], 0, v[128:129]
	v_lshl_add_u64 v[68:69], v[66:67], 0, v[128:129]
	v_lshl_add_u64 v[82:83], v[82:83], 0, v[128:129]
	v_lshl_add_u64 v[84:85], v[80:81], 0, v[128:129]
	s_waitcnt lgkmcnt(0)
	s_barrier
; template <class AS, class EP>
; DEVI void gemm_tile(const AS& as, const u16* __restrict__ Bt, int K, int m0, int n0, const EP& ep, char* lds) {
;     ...
;   GLOAD(ra0, rb0, 0); GLOAD(ra1, rb1, 1); LWRITE(0, ra0, rb0); __syncthreads();
;   for (int kt = 0; kt < KT; kt += 2) {
;     if (kt + 2 < KT) GLOAD(ra0, rb0, kt + 2);
;     __builtin_amdgcn_sched_barrier(0);
;     COMPUTE(0);
;     __builtin_amdgcn_sched_barrier(0);
;     LWRITE(1, ra1, rb1);
;     __syncthreads();
;     if (kt + 3 < KT) GLOAD(ra1, rb1, kt + 3);
;     __builtin_amdgcn_sched_barrier(0);
;     COMPUTE(1);
;     __builtin_amdgcn_sched_barrier(0);
;     if (kt + 2 < KT) LWRITE(0, ra0, rb0);
;     __syncthreads();
	global_load_dwordx4 v[64:67], v[64:65], off offset:-768
	s_nop 0
	global_load_dwordx4 v[68:71], v[68:69], off offset:-768
	s_nop 0
	global_load_dwordx4 v[80:83], v[82:83], off offset:-768
	s_nop 0
	global_load_dwordx4 v[84:87], v[84:85], off offset:-768
	s_nop 0
	global_load_dwordx4 v[104:107], v[120:121], off offset:896
	global_load_dwordx4 v[108:111], v[122:123], off offset:896
	ds_read_b128 v[170:173], v158 offset:55296
	ds_read_b128 v[174:177], v159
	ds_read_b128 v[178:181], v159 offset:4608
	ds_read_b128 v[182:185], v158 offset:59904
	ds_read_b128 v[186:189], v158 offset:55328
	ds_read_b128 v[190:193], v159 offset:32
	ds_read_b128 v[194:197], v159 offset:4640
	ds_read_b128 v[198:201], v158 offset:59936
	ds_read_b128 v[202:205], v158 offset:55360
	ds_read_b128 v[206:209], v159 offset:64
	ds_read_b128 v[210:213], v159 offset:4672
	ds_read_b128 v[214:217], v158 offset:59968
	s_waitcnt lgkmcnt(10)
	v_mfma_f32_32x32x16_bf16 v[48:63], v[170:173], v[174:177], v[48:63]
	s_waitcnt lgkmcnt(9)
	v_mfma_f32_32x32x16_bf16 v[32:47], v[170:173], v[178:181], v[32:47]
	s_waitcnt lgkmcnt(8)
	v_mfma_f32_32x32x16_bf16 v[16:31], v[182:185], v[174:177], v[16:31]
	v_mfma_f32_32x32x16_bf16 v[0:15], v[182:185], v[178:181], v[0:15]
	ds_read_b128 v[222:225], v158 offset:55392
	ds_read_b128 v[226:229], v159 offset:96
	ds_read_b128 v[230:233], v159 offset:4704
	ds_read_b128 v[234:237], v158 offset:60000
	s_waitcnt lgkmcnt(10)
	v_mfma_f32_32x32x16_bf16 v[48:63], v[186:189], v[190:193], v[48:63]
	s_waitcnt lgkmcnt(9)
	v_mfma_f32_32x32x16_bf16 v[32:47], v[186:189], v[194:197], v[32:47]
	s_waitcnt lgkmcnt(8)
	v_mfma_f32_32x32x16_bf16 v[16:31], v[198:201], v[190:193], v[16:31]
	v_mfma_f32_32x32x16_bf16 v[0:15], v[198:201], v[194:197], v[0:15]
	s_waitcnt vmcnt(11)
	ds_write_b128 v160, v[72:75]
	s_waitcnt lgkmcnt(7)
	v_mfma_f32_32x32x16_bf16 v[48:63], v[202:205], v[206:209], v[48:63]
	s_waitcnt vmcnt(10)
	ds_write_b128 v160, v[76:79] offset:9216
	s_waitcnt lgkmcnt(7)
	v_mfma_f32_32x32x16_bf16 v[32:47], v[202:205], v[210:213], v[32:47]
	s_waitcnt vmcnt(9)
	ds_write_b128 v160, v[88:91] offset:18432
	s_waitcnt lgkmcnt(7)
	v_mfma_f32_32x32x16_bf16 v[16:31], v[214:217], v[206:209], v[16:31]
	v_mfma_f32_32x32x16_bf16 v[0:15], v[214:217], v[210:213], v[0:15]
	s_waitcnt vmcnt(8)
	ds_write_b128 v160, v[92:95] offset:27648
	s_waitcnt lgkmcnt(6)
	v_mfma_f32_32x32x16_bf16 v[48:63], v[222:225], v[226:229], v[48:63]
	s_waitcnt vmcnt(7)
	ds_write_b128 v160, v[96:99] offset:36864
	s_waitcnt lgkmcnt(6)
	v_mfma_f32_32x32x16_bf16 v[32:47], v[222:225], v[230:233], v[32:47]
	s_waitcnt vmcnt(6)
	ds_write_b128 v160, v[100:103] offset:46080
	s_waitcnt lgkmcnt(6)
	v_mfma_f32_32x32x16_bf16 v[16:31], v[234:237], v[226:229], v[16:31]
	v_mfma_f32_32x32x16_bf16 v[0:15], v[234:237], v[230:233], v[0:15]
	v_mov_b64_e32 v[88:89], s[40:41]
	v_mad_i64_i32 v[72:73], s[38:39], v124, s35, v[88:89]
	v_mad_i64_i32 v[74:75], s[38:39], v126, s35, v[88:89]
	v_mad_i64_i32 v[90:91], s[38:39], v132, s35, v[88:89]
	v_mad_i64_i32 v[88:89], s[38:39], v134, s35, v[88:89]
	v_lshl_add_u64 v[72:73], v[72:73], 0, v[128:129]
	v_lshl_add_u64 v[76:77], v[74:75], 0, v[128:129]
	v_lshl_add_u64 v[90:91], v[90:91], 0, v[128:129]
	v_lshl_add_u64 v[92:93], v[88:89], 0, v[128:129]
	s_waitcnt lgkmcnt(0)
	s_barrier
	global_load_dwordx4 v[72:75], v[72:73], off offset:-768
	s_nop 0
	global_load_dwordx4 v[76:79], v[76:77], off offset:-768
	s_nop 0
	global_load_dwordx4 v[88:91], v[90:91], off offset:-768
	s_nop 0
	global_load_dwordx4 v[92:95], v[92:93], off offset:-768
	s_nop 0
	global_load_dwordx4 v[96:99], v[120:121], off offset:1024
	global_load_dwordx4 v[100:103], v[122:123], off offset:1024
	ds_read_b128 v[170:173], v158
	ds_read_b128 v[174:177], v161 offset:36864
	ds_read_b128 v[178:181], v161 offset:41472
	ds_read_b128 v[182:185], v158 offset:4608
	ds_read_b128 v[186:189], v158 offset:32
	ds_read_b128 v[190:193], v161 offset:36896
	ds_read_b128 v[194:197], v161 offset:41504
	ds_read_b128 v[198:201], v158 offset:4640
	ds_read_b128 v[202:205], v158 offset:64
	ds_read_b128 v[206:209], v161 offset:36928
	ds_read_b128 v[210:213], v161 offset:41536
	ds_read_b128 v[214:217], v158 offset:4672
	s_waitcnt lgkmcnt(10)
	v_mfma_f32_32x32x16_bf16 v[48:63], v[170:173], v[174:177], v[48:63]
	s_waitcnt lgkmcnt(9)
	v_mfma_f32_32x32x16_bf16 v[32:47], v[170:173], v[178:181], v[32:47]
	s_waitcnt lgkmcnt(8)
	v_mfma_f32_32x32x16_bf16 v[16:31], v[182:185], v[174:177], v[16:31]
	v_mfma_f32_32x32x16_bf16 v[0:15], v[182:185], v[178:181], v[0:15]
	ds_read_b128 v[222:225], v158 offset:96
	ds_read_b128 v[226:229], v161 offset:36960
	ds_read_b128 v[230:233], v161 offset:41568
	ds_read_b128 v[234:237], v158 offset:4704
	s_waitcnt lgkmcnt(10)
	v_mfma_f32_32x32x16_bf16 v[48:63], v[186:189], v[190:193], v[48:63]
	s_waitcnt lgkmcnt(9)
	v_mfma_f32_32x32x16_bf16 v[32:47], v[186:189], v[194:197], v[32:47]
	s_waitcnt lgkmcnt(8)
	v_mfma_f32_32x32x16_bf16 v[16:31], v[198:201], v[190:193], v[16:31]
	v_mfma_f32_32x32x16_bf16 v[0:15], v[198:201], v[194:197], v[0:15]
	s_waitcnt vmcnt(11)
	ds_write_b128 v160, v[64:67] offset:55296
	s_waitcnt lgkmcnt(7)
	v_mfma_f32_32x32x16_bf16 v[48:63], v[202:205], v[206:209], v[48:63]
	s_waitcnt vmcnt(10)
	ds_write_b128 v160, v[68:71] offset:64512
	s_waitcnt lgkmcnt(7)
	v_mfma_f32_32x32x16_bf16 v[32:47], v[202:205], v[210:213], v[32:47]
	s_waitcnt vmcnt(9)
	ds_write_b128 v162, v[80:83] offset:18432
	s_waitcnt lgkmcnt(7)
	v_mfma_f32_32x32x16_bf16 v[16:31], v[214:217], v[206:209], v[16:31]
	v_mfma_f32_32x32x16_bf16 v[0:15], v[214:217], v[210:213], v[0:15]
	s_waitcnt vmcnt(8)
	ds_write_b128 v162, v[84:87] offset:27648
	s_waitcnt lgkmcnt(6)
	v_mfma_f32_32x32x16_bf16 v[48:63], v[222:225], v[226:229], v[48:63]
	s_waitcnt vmcnt(7)
	ds_write_b128 v163, v[104:107]
	s_waitcnt lgkmcnt(6)
	v_mfma_f32_32x32x16_bf16 v[32:47], v[222:225], v[230:233], v[32:47]
	s_waitcnt vmcnt(6)
	ds_write_b128 v163, v[108:111] offset:9216
	s_waitcnt lgkmcnt(6)
	v_mfma_f32_32x32x16_bf16 v[16:31], v[234:237], v[226:229], v[16:31]
	v_mfma_f32_32x32x16_bf16 v[0:15], v[234:237], v[230:233], v[0:15]
	v_mov_b64_e32 v[80:81], s[42:43]
	v_mad_i64_i32 v[64:65], s[38:39], v124, s35, v[80:81]
	v_mad_i64_i32 v[66:67], s[38:39], v126, s35, v[80:81]
	v_mad_i64_i32 v[82:83], s[38:39], v132, s35, v[80:81]
	v_mad_i64_i32 v[80:81], s[38:39], v134, s35, v[80:81]
	v_lshl_add_u64 v[64:65], v[64:65], 0, v[128:129]
	v_lshl_add_u64 v[68:69], v[66:67], 0, v[128:129]
	v_lshl_add_u64 v[82:83], v[82:83], 0, v[128:129]
	v_lshl_add_u64 v[84:85], v[80:81], 0, v[128:129]
	s_waitcnt lgkmcnt(0)
	s_barrier
; template <class AS, class EP>
; DEVI void gemm_tile(const AS& as, const u16* __restrict__ Bt, int K, int m0, int n0, const EP& ep, char* lds) {
;     ...
;   GLOAD(ra0, rb0, 0); GLOAD(ra1, rb1, 1); LWRITE(0, ra0, rb0); __syncthreads();
;   for (int kt = 0; kt < KT; kt += 2) {
;     if (kt + 2 < KT) GLOAD(ra0, rb0, kt + 2);
;     __builtin_amdgcn_sched_barrier(0);
;     COMPUTE(0);
;     __builtin_amdgcn_sched_barrier(0);
;     LWRITE(1, ra1, rb1);
;     __syncthreads();
;     if (kt + 3 < KT) GLOAD(ra1, rb1, kt + 3);
;     __builtin_amdgcn_sched_barrier(0);
;     COMPUTE(1);
;     __builtin_amdgcn_sched_barrier(0);
;     if (kt + 2 < KT) LWRITE(0, ra0, rb0);
;     __syncthreads();
	global_load_dwordx4 v[64:67], v[64:65], off offset:-768
	s_nop 0
	global_load_dwordx4 v[68:71], v[68:69], off offset:-768
	s_nop 0
	global_load_dwordx4 v[80:83], v[82:83], off offset:-768
	s_nop 0
	global_load_dwordx4 v[84:87], v[84:85], off offset:-768
	s_nop 0
	global_load_dwordx4 v[104:107], v[120:121], off offset:1152
	global_load_dwordx4 v[108:111], v[122:123], off offset:1152
	ds_read_b128 v[170:173], v158 offset:55296
	ds_read_b128 v[174:177], v159
	ds_read_b128 v[178:181], v159 offset:4608
	ds_read_b128 v[182:185], v158 offset:59904
	ds_read_b128 v[186:189], v158 offset:55328
	ds_read_b128 v[190:193], v159 offset:32
	ds_read_b128 v[194:197], v159 offset:4640
	ds_read_b128 v[198:201], v158 offset:59936
	ds_read_b128 v[202:205], v158 offset:55360
	ds_read_b128 v[206:209], v159 offset:64
	ds_read_b128 v[210:213], v159 offset:4672
	ds_read_b128 v[214:217], v158 offset:59968
	s_waitcnt lgkmcnt(10)
	v_mfma_f32_32x32x16_bf16 v[48:63], v[170:173], v[174:177], v[48:63]
	s_waitcnt lgkmcnt(9)
	v_mfma_f32_32x32x16_bf16 v[32:47], v[170:173], v[178:181], v[32:47]
	s_waitcnt lgkmcnt(8)
	v_mfma_f32_32x32x16_bf16 v[16:31], v[182:185], v[174:177], v[16:31]
	v_mfma_f32_32x32x16_bf16 v[0:15], v[182:185], v[178:181], v[0:15]
	ds_read_b128 v[222:225], v158 offset:55392
	ds_read_b128 v[226:229], v159 offset:96
	ds_read_b128 v[230:233], v159 offset:4704
	ds_read_b128 v[234:237], v158 offset:60000
	s_waitcnt lgkmcnt(10)
	v_mfma_f32_32x32x16_bf16 v[48:63], v[186:189], v[190:193], v[48:63]
	s_waitcnt lgkmcnt(9)
	v_mfma_f32_32x32x16_bf16 v[32:47], v[186:189], v[194:197], v[32:47]
	s_waitcnt lgkmcnt(8)
	v_mfma_f32_32x32x16_bf16 v[16:31], v[198:201], v[190:193], v[16:31]
	v_mfma_f32_32x32x16_bf16 v[0:15], v[198:201], v[194:197], v[0:15]
	s_waitcnt vmcnt(11)
	ds_write_b128 v160, v[72:75]
	s_waitcnt lgkmcnt(7)
	v_mfma_f32_32x32x16_bf16 v[48:63], v[202:205], v[206:209], v[48:63]
	s_waitcnt vmcnt(10)
	ds_write_b128 v160, v[76:79] offset:9216
	s_waitcnt lgkmcnt(7)
	v_mfma_f32_32x32x16_bf16 v[32:47], v[202:205], v[210:213], v[32:47]
	s_waitcnt vmcnt(9)
	ds_write_b128 v160, v[88:91] offset:18432
	s_waitcnt lgkmcnt(7)
	v_mfma_f32_32x32x16_bf16 v[16:31], v[214:217], v[206:209], v[16:31]
	v_mfma_f32_32x32x16_bf16 v[0:15], v[214:217], v[210:213], v[0:15]
	s_waitcnt vmcnt(8)
	ds_write_b128 v160, v[92:95] offset:27648
	s_waitcnt lgkmcnt(6)
	v_mfma_f32_32x32x16_bf16 v[48:63], v[222:225], v[226:229], v[48:63]
	s_waitcnt vmcnt(7)
	ds_write_b128 v160, v[96:99] offset:36864
	s_waitcnt lgkmcnt(6)
	v_mfma_f32_32x32x16_bf16 v[32:47], v[222:225], v[230:233], v[32:47]
	s_waitcnt vmcnt(6)
	ds_write_b128 v160, v[100:103] offset:46080
	s_waitcnt lgkmcnt(6)
	v_mfma_f32_32x32x16_bf16 v[16:31], v[234:237], v[226:229], v[16:31]
	v_mfma_f32_32x32x16_bf16 v[0:15], v[234:237], v[230:233], v[0:15]
	v_mov_b64_e32 v[88:89], s[82:83]
	v_mad_i64_i32 v[72:73], s[38:39], v124, s35, v[88:89]
	v_mad_i64_i32 v[74:75], s[38:39], v126, s35, v[88:89]
	v_mad_i64_i32 v[90:91], s[38:39], v132, s35, v[88:89]
	v_lshl_add_u64 v[72:73], v[72:73], 0, v[128:129]
	v_lshl_add_u64 v[76:77], v[74:75], 0, v[128:129]
	v_lshl_add_u64 v[90:91], v[90:91], 0, v[128:129]
	v_mad_i64_i32 v[88:89], s[38:39], v134, s35, v[88:89]
	s_waitcnt lgkmcnt(0)
	s_barrier
	global_load_dwordx4 v[72:75], v[72:73], off offset:-768
	s_nop 0
	global_load_dwordx4 v[76:79], v[76:77], off offset:-768
	v_lshl_add_u64 v[88:89], v[88:89], 0, v[128:129]
	global_load_dwordx4 v[96:99], v[90:91], off offset:-768
	global_load_dwordx4 v[100:103], v[88:89], off offset:-768
	global_load_dwordx4 v[112:115], v[120:121], off offset:1280
	global_load_dwordx4 v[116:119], v[122:123], off offset:1280
	ds_read_b128 v[170:173], v158
	ds_read_b128 v[174:177], v161 offset:36864
	ds_read_b128 v[178:181], v161 offset:41472
	ds_read_b128 v[182:185], v158 offset:4608
	ds_read_b128 v[186:189], v158 offset:32
	ds_read_b128 v[190:193], v161 offset:36896
	ds_read_b128 v[194:197], v161 offset:41504
	ds_read_b128 v[198:201], v158 offset:4640
	ds_read_b128 v[202:205], v158 offset:64
	ds_read_b128 v[206:209], v161 offset:36928
	ds_read_b128 v[210:213], v161 offset:41536
	ds_read_b128 v[214:217], v158 offset:4672
	s_waitcnt lgkmcnt(10)
	v_mfma_f32_32x32x16_bf16 v[48:63], v[170:173], v[174:177], v[48:63]
	s_waitcnt lgkmcnt(9)
	v_mfma_f32_32x32x16_bf16 v[32:47], v[170:173], v[178:181], v[32:47]
	s_waitcnt lgkmcnt(8)
	v_mfma_f32_32x32x16_bf16 v[16:31], v[182:185], v[174:177], v[16:31]
	v_mfma_f32_32x32x16_bf16 v[0:15], v[182:185], v[178:181], v[0:15]
	ds_read_b128 v[222:225], v158 offset:96
	ds_read_b128 v[226:229], v161 offset:36960
	ds_read_b128 v[230:233], v161 offset:41568
	ds_read_b128 v[234:237], v158 offset:4704
	s_waitcnt lgkmcnt(10)
	v_mfma_f32_32x32x16_bf16 v[48:63], v[186:189], v[190:193], v[48:63]
	s_waitcnt lgkmcnt(9)
	v_mfma_f32_32x32x16_bf16 v[32:47], v[186:189], v[194:197], v[32:47]
	s_waitcnt lgkmcnt(8)
	v_mfma_f32_32x32x16_bf16 v[16:31], v[198:201], v[190:193], v[16:31]
	v_mfma_f32_32x32x16_bf16 v[0:15], v[198:201], v[194:197], v[0:15]
	s_waitcnt vmcnt(11)
	ds_write_b128 v160, v[64:67] offset:55296
	s_waitcnt lgkmcnt(7)
	v_mfma_f32_32x32x16_bf16 v[48:63], v[202:205], v[206:209], v[48:63]
	s_waitcnt vmcnt(10)
	ds_write_b128 v160, v[68:71] offset:64512
	s_waitcnt lgkmcnt(7)
	v_mfma_f32_32x32x16_bf16 v[32:47], v[202:205], v[210:213], v[32:47]
	s_waitcnt vmcnt(9)
	ds_write_b128 v162, v[80:83] offset:18432
	s_waitcnt lgkmcnt(7)
	v_mfma_f32_32x32x16_bf16 v[16:31], v[214:217], v[206:209], v[16:31]
	v_mfma_f32_32x32x16_bf16 v[0:15], v[214:217], v[210:213], v[0:15]
	s_waitcnt vmcnt(8)
	ds_write_b128 v162, v[84:87] offset:27648
	s_waitcnt lgkmcnt(6)
	v_mfma_f32_32x32x16_bf16 v[48:63], v[222:225], v[226:229], v[48:63]
	s_waitcnt vmcnt(7)
	ds_write_b128 v163, v[104:107]
	s_waitcnt lgkmcnt(6)
	v_mfma_f32_32x32x16_bf16 v[32:47], v[222:225], v[230:233], v[32:47]
	s_waitcnt vmcnt(6)
	ds_write_b128 v163, v[108:111] offset:9216
	s_waitcnt lgkmcnt(6)
	v_mfma_f32_32x32x16_bf16 v[16:31], v[234:237], v[226:229], v[16:31]
	v_mfma_f32_32x32x16_bf16 v[0:15], v[234:237], v[230:233], v[0:15]
	v_mov_b64_e32 v[80:81], s[84:85]
	v_mad_i64_i32 v[64:65], s[38:39], v124, s35, v[80:81]
	v_mad_i64_i32 v[66:67], s[38:39], v126, s35, v[80:81]
	v_mad_i64_i32 v[82:83], s[38:39], v132, s35, v[80:81]
	v_mad_i64_i32 v[80:81], s[38:39], v134, s35, v[80:81]
	v_lshl_add_u64 v[64:65], v[64:65], 0, v[128:129]
	v_lshl_add_u64 v[68:69], v[66:67], 0, v[128:129]
	v_lshl_add_u64 v[82:83], v[82:83], 0, v[128:129]
	v_lshl_add_u64 v[84:85], v[80:81], 0, v[128:129]
	s_waitcnt lgkmcnt(0)
	s_barrier
; template <class AS, class EP>
; DEVI void gemm_tile(const AS& as, const u16* __restrict__ Bt, int K, int m0, int n0, const EP& ep, char* lds) {
;     ...
;   GLOAD(ra0, rb0, 0); GLOAD(ra1, rb1, 1); LWRITE(0, ra0, rb0); __syncthreads();
;   for (int kt = 0; kt < KT; kt += 2) {
;     if (kt + 2 < KT) GLOAD(ra0, rb0, kt + 2);
;     __builtin_amdgcn_sched_barrier(0);
;     COMPUTE(0);
;     __builtin_amdgcn_sched_barrier(0);
;     LWRITE(1, ra1, rb1);
;     __syncthreads();
;     if (kt + 3 < KT) GLOAD(ra1, rb1, kt + 3);
;     __builtin_amdgcn_sched_barrier(0);
;     COMPUTE(1);
;     __builtin_amdgcn_sched_barrier(0);
;     if (kt + 2 < KT) LWRITE(0, ra0, rb0);
;     __syncthreads();
;   }
	global_load_dwordx4 v[64:67], v[64:65], off offset:-768
	s_nop 0
	global_load_dwordx4 v[68:71], v[68:69], off offset:-768
	s_nop 0
	global_load_dwordx4 v[80:83], v[82:83], off offset:-768
	s_nop 0
	global_load_dwordx4 v[84:87], v[84:85], off offset:-768
	s_nop 0
	global_load_dwordx4 v[88:91], v[120:121], off offset:1408
	global_load_dwordx4 v[92:95], v[122:123], off offset:1408
	ds_read_b128 v[170:173], v158 offset:55296
	ds_read_b128 v[174:177], v159
	ds_read_b128 v[178:181], v159 offset:4608
	ds_read_b128 v[182:185], v158 offset:59904
	ds_read_b128 v[186:189], v158 offset:55328
	ds_read_b128 v[190:193], v159 offset:32
	ds_read_b128 v[194:197], v159 offset:4640
	ds_read_b128 v[198:201], v158 offset:59936
	ds_read_b128 v[202:205], v158 offset:55360
	ds_read_b128 v[206:209], v159 offset:64
	ds_read_b128 v[210:213], v159 offset:4672
	ds_read_b128 v[214:217], v158 offset:59968
	s_waitcnt lgkmcnt(10)
	v_mfma_f32_32x32x16_bf16 v[48:63], v[170:173], v[174:177], v[48:63]
	s_waitcnt lgkmcnt(9)
	v_mfma_f32_32x32x16_bf16 v[32:47], v[170:173], v[178:181], v[32:47]
	s_waitcnt lgkmcnt(8)
	v_mfma_f32_32x32x16_bf16 v[16:31], v[182:185], v[174:177], v[16:31]
	v_mfma_f32_32x32x16_bf16 v[0:15], v[182:185], v[178:181], v[0:15]
	ds_read_b128 v[222:225], v158 offset:55392
	ds_read_b128 v[226:229], v159 offset:96
	ds_read_b128 v[230:233], v159 offset:4704
	ds_read_b128 v[234:237], v158 offset:60000
	s_waitcnt lgkmcnt(10)
	v_mfma_f32_32x32x16_bf16 v[48:63], v[186:189], v[190:193], v[48:63]
	s_waitcnt lgkmcnt(9)
	v_mfma_f32_32x32x16_bf16 v[32:47], v[186:189], v[194:197], v[32:47]
	s_waitcnt lgkmcnt(8)
	v_mfma_f32_32x32x16_bf16 v[16:31], v[198:201], v[190:193], v[16:31]
	v_mfma_f32_32x32x16_bf16 v[0:15], v[198:201], v[194:197], v[0:15]
	s_waitcnt vmcnt(11)
	ds_write_b128 v160, v[72:75]
	s_waitcnt lgkmcnt(7)
	v_mfma_f32_32x32x16_bf16 v[48:63], v[202:205], v[206:209], v[48:63]
	s_waitcnt vmcnt(10)
	ds_write_b128 v160, v[76:79] offset:9216
	s_waitcnt lgkmcnt(7)
	v_mfma_f32_32x32x16_bf16 v[32:47], v[202:205], v[210:213], v[32:47]
	s_waitcnt vmcnt(9)
	ds_write_b128 v160, v[96:99] offset:18432
	s_waitcnt lgkmcnt(7)
	v_mfma_f32_32x32x16_bf16 v[16:31], v[214:217], v[206:209], v[16:31]
	v_mfma_f32_32x32x16_bf16 v[0:15], v[214:217], v[210:213], v[0:15]
	s_waitcnt vmcnt(8)
	ds_write_b128 v160, v[100:103] offset:27648
	s_waitcnt lgkmcnt(6)
	v_mfma_f32_32x32x16_bf16 v[48:63], v[222:225], v[226:229], v[48:63]
	s_waitcnt vmcnt(7)
	ds_write_b128 v160, v[112:115] offset:36864
	s_waitcnt lgkmcnt(6)
	v_mfma_f32_32x32x16_bf16 v[32:47], v[222:225], v[230:233], v[32:47]
	s_waitcnt vmcnt(6)
	ds_write_b128 v160, v[116:119] offset:46080
	s_waitcnt lgkmcnt(6)
	v_mfma_f32_32x32x16_bf16 v[16:31], v[234:237], v[226:229], v[16:31]
	v_mfma_f32_32x32x16_bf16 v[0:15], v[234:237], v[230:233], v[0:15]
	v_lshlrev_b64 v[112:113], 9, v[124:125]
	v_lshlrev_b64 v[114:115], 9, v[126:127]
	v_lshlrev_b64 v[116:117], 9, v[132:133]
	v_lshlrev_b64 v[118:119], 9, v[134:135]
	v_lshl_add_u64 v[72:73], s[18:19], 0, v[112:113]
	v_lshl_add_u64 v[74:75], s[18:19], 0, v[114:115]
	v_lshl_add_u64 v[96:97], s[18:19], 0, v[116:117]
	v_lshl_add_u64 v[98:99], s[18:19], 0, v[118:119]
	v_lshl_add_u64 v[72:73], v[72:73], 0, v[128:129]
	v_lshl_add_u64 v[76:77], v[74:75], 0, v[128:129]
	v_lshl_add_u64 v[96:97], v[96:97], 0, v[128:129]
	v_lshl_add_u64 v[100:101], v[98:99], 0, v[128:129]
	s_waitcnt lgkmcnt(0)
	s_barrier
	global_load_dwordx4 v[72:75], v[72:73], off offset:-1536
	s_nop 0
	global_load_dwordx4 v[76:79], v[76:77], off offset:-1536
	s_nop 0
	global_load_dwordx4 v[96:99], v[96:97], off offset:-1536
	s_nop 0
	global_load_dwordx4 v[100:103], v[100:101], off offset:-1536
	s_nop 0
	global_load_dwordx4 v[104:107], v[120:121], off offset:1536
	global_load_dwordx4 v[108:111], v[122:123], off offset:1536
	ds_read_b128 v[170:173], v158
	ds_read_b128 v[174:177], v161 offset:36864
	ds_read_b128 v[178:181], v161 offset:41472
	ds_read_b128 v[182:185], v158 offset:4608
	ds_read_b128 v[186:189], v158 offset:32
	ds_read_b128 v[190:193], v161 offset:36896
	ds_read_b128 v[194:197], v161 offset:41504
	ds_read_b128 v[198:201], v158 offset:4640
	ds_read_b128 v[202:205], v158 offset:64
	ds_read_b128 v[206:209], v161 offset:36928
	ds_read_b128 v[210:213], v161 offset:41536
	ds_read_b128 v[214:217], v158 offset:4672
	s_waitcnt lgkmcnt(10)
	v_mfma_f32_32x32x16_bf16 v[48:63], v[170:173], v[174:177], v[48:63]
	s_waitcnt lgkmcnt(9)
	v_mfma_f32_32x32x16_bf16 v[32:47], v[170:173], v[178:181], v[32:47]
	s_waitcnt lgkmcnt(8)
	v_mfma_f32_32x32x16_bf16 v[16:31], v[182:185], v[174:177], v[16:31]
	v_mfma_f32_32x32x16_bf16 v[0:15], v[182:185], v[178:181], v[0:15]
	ds_read_b128 v[222:225], v158 offset:96
	ds_read_b128 v[226:229], v161 offset:36960
	ds_read_b128 v[230:233], v161 offset:41568
	ds_read_b128 v[234:237], v158 offset:4704
	s_waitcnt lgkmcnt(10)
	v_mfma_f32_32x32x16_bf16 v[48:63], v[186:189], v[190:193], v[48:63]
	s_waitcnt lgkmcnt(9)
	v_mfma_f32_32x32x16_bf16 v[32:47], v[186:189], v[194:197], v[32:47]
	s_waitcnt lgkmcnt(8)
	v_mfma_f32_32x32x16_bf16 v[16:31], v[198:201], v[190:193], v[16:31]
	v_mfma_f32_32x32x16_bf16 v[0:15], v[198:201], v[194:197], v[0:15]
	s_waitcnt vmcnt(11)
	ds_write_b128 v160, v[64:67] offset:55296
	s_waitcnt lgkmcnt(7)
	v_mfma_f32_32x32x16_bf16 v[48:63], v[202:205], v[206:209], v[48:63]
	s_waitcnt vmcnt(10)
	ds_write_b128 v160, v[68:71] offset:64512
	s_waitcnt lgkmcnt(7)
	v_mfma_f32_32x32x16_bf16 v[32:47], v[202:205], v[210:213], v[32:47]
	s_waitcnt vmcnt(9)
	ds_write_b128 v162, v[80:83] offset:18432
	s_waitcnt lgkmcnt(7)
	v_mfma_f32_32x32x16_bf16 v[16:31], v[214:217], v[206:209], v[16:31]
	v_mfma_f32_32x32x16_bf16 v[0:15], v[214:217], v[210:213], v[0:15]
	s_waitcnt vmcnt(8)
	ds_write_b128 v162, v[84:87] offset:27648
	s_waitcnt lgkmcnt(6)
	v_mfma_f32_32x32x16_bf16 v[48:63], v[222:225], v[226:229], v[48:63]
	s_waitcnt vmcnt(7)
	ds_write_b128 v163, v[88:91]
	s_waitcnt lgkmcnt(6)
	v_mfma_f32_32x32x16_bf16 v[32:47], v[222:225], v[230:233], v[32:47]
	s_waitcnt vmcnt(6)
	ds_write_b128 v163, v[92:95] offset:9216
	s_waitcnt lgkmcnt(6)
	v_mfma_f32_32x32x16_bf16 v[16:31], v[234:237], v[226:229], v[16:31]
	v_mfma_f32_32x32x16_bf16 v[0:15], v[234:237], v[230:233], v[0:15]
	v_lshl_add_u64 v[64:65], s[8:9], 0, v[112:113]
	v_lshl_add_u64 v[66:67], s[8:9], 0, v[114:115]
	v_lshl_add_u64 v[80:81], s[8:9], 0, v[116:117]
	v_lshl_add_u64 v[82:83], s[8:9], 0, v[118:119]
	v_lshl_add_u64 v[64:65], v[64:65], 0, v[128:129]
	v_lshl_add_u64 v[68:69], v[66:67], 0, v[128:129]
	v_lshl_add_u64 v[80:81], v[80:81], 0, v[128:129]
	v_lshl_add_u64 v[84:85], v[82:83], 0, v[128:129]
	s_waitcnt lgkmcnt(0)
	s_barrier
; template <class AS, class EP>
; DEVI void gemm_tile(const AS& as, const u16* __restrict__ Bt, int K, int m0, int n0, const EP& ep, char* lds) {
;     ...
;   GLOAD(ra0, rb0, 0); GLOAD(ra1, rb1, 1); LWRITE(0, ra0, rb0); __syncthreads();
;   for (int kt = 0; kt < KT; kt += 2) {
;     if (kt + 2 < KT) GLOAD(ra0, rb0, kt + 2);
;     __builtin_amdgcn_sched_barrier(0);
;     COMPUTE(0);
;     __builtin_amdgcn_sched_barrier(0);
;     LWRITE(1, ra1, rb1);
;     __syncthreads();
;     if (kt + 3 < KT) GLOAD(ra1, rb1, kt + 3);
;     __builtin_amdgcn_sched_barrier(0);
;     COMPUTE(1);
;     __builtin_amdgcn_sched_barrier(0);
;     if (kt + 2 < KT) LWRITE(0, ra0, rb0);
;     __syncthreads();
;   }
	global_load_dwordx4 v[64:67], v[64:65], off offset:-1536
	s_nop 0
	global_load_dwordx4 v[68:71], v[68:69], off offset:-1536
	s_nop 0
	global_load_dwordx4 v[80:83], v[80:81], off offset:-1536
	s_nop 0
	global_load_dwordx4 v[84:87], v[84:85], off offset:-1536
	s_nop 0
	global_load_dwordx4 v[88:91], v[120:121], off offset:1664
	global_load_dwordx4 v[92:95], v[122:123], off offset:1664
	ds_read_b128 v[170:173], v158 offset:55296
	ds_read_b128 v[174:177], v159
	ds_read_b128 v[178:181], v159 offset:4608
	ds_read_b128 v[182:185], v158 offset:59904
	ds_read_b128 v[186:189], v158 offset:55328
	ds_read_b128 v[190:193], v159 offset:32
	ds_read_b128 v[194:197], v159 offset:4640
	ds_read_b128 v[198:201], v158 offset:59936
	ds_read_b128 v[202:205], v158 offset:55360
	ds_read_b128 v[206:209], v159 offset:64
	ds_read_b128 v[210:213], v159 offset:4672
	ds_read_b128 v[214:217], v158 offset:59968
	s_waitcnt lgkmcnt(10)
	v_mfma_f32_32x32x16_bf16 v[48:63], v[170:173], v[174:177], v[48:63]
	s_waitcnt lgkmcnt(9)
	v_mfma_f32_32x32x16_bf16 v[32:47], v[170:173], v[178:181], v[32:47]
	s_waitcnt lgkmcnt(8)
	v_mfma_f32_32x32x16_bf16 v[16:31], v[182:185], v[174:177], v[16:31]
	v_mfma_f32_32x32x16_bf16 v[0:15], v[182:185], v[178:181], v[0:15]
	ds_read_b128 v[222:225], v158 offset:55392
	ds_read_b128 v[226:229], v159 offset:96
	ds_read_b128 v[230:233], v159 offset:4704
	ds_read_b128 v[234:237], v158 offset:60000
	s_waitcnt lgkmcnt(10)
	v_mfma_f32_32x32x16_bf16 v[48:63], v[186:189], v[190:193], v[48:63]
	s_waitcnt lgkmcnt(9)
	v_mfma_f32_32x32x16_bf16 v[32:47], v[186:189], v[194:197], v[32:47]
	s_waitcnt lgkmcnt(8)
	v_mfma_f32_32x32x16_bf16 v[16:31], v[198:201], v[190:193], v[16:31]
	v_mfma_f32_32x32x16_bf16 v[0:15], v[198:201], v[194:197], v[0:15]
	s_waitcnt vmcnt(11)
	ds_write_b128 v160, v[72:75]
	s_waitcnt lgkmcnt(7)
	v_mfma_f32_32x32x16_bf16 v[48:63], v[202:205], v[206:209], v[48:63]
	s_waitcnt vmcnt(10)
	ds_write_b128 v160, v[76:79] offset:9216
	s_waitcnt lgkmcnt(7)
	v_mfma_f32_32x32x16_bf16 v[32:47], v[202:205], v[210:213], v[32:47]
	s_waitcnt vmcnt(9)
	ds_write_b128 v160, v[96:99] offset:18432
	s_waitcnt lgkmcnt(7)
	v_mfma_f32_32x32x16_bf16 v[16:31], v[214:217], v[206:209], v[16:31]
	v_mfma_f32_32x32x16_bf16 v[0:15], v[214:217], v[210:213], v[0:15]
	s_waitcnt vmcnt(8)
	ds_write_b128 v160, v[100:103] offset:27648
	s_waitcnt lgkmcnt(6)
	v_mfma_f32_32x32x16_bf16 v[48:63], v[222:225], v[226:229], v[48:63]
	s_waitcnt vmcnt(7)
	ds_write_b128 v160, v[104:107] offset:36864
	s_waitcnt lgkmcnt(6)
	v_mfma_f32_32x32x16_bf16 v[32:47], v[222:225], v[230:233], v[32:47]
	s_waitcnt vmcnt(6)
	ds_write_b128 v160, v[108:111] offset:46080
	s_waitcnt lgkmcnt(6)
	v_mfma_f32_32x32x16_bf16 v[16:31], v[234:237], v[226:229], v[16:31]
	v_mfma_f32_32x32x16_bf16 v[0:15], v[234:237], v[230:233], v[0:15]
	v_lshl_add_u64 v[72:73], s[12:13], 0, v[112:113]
	v_lshl_add_u64 v[74:75], s[12:13], 0, v[114:115]
	v_lshl_add_u64 v[96:97], s[12:13], 0, v[116:117]
	v_lshl_add_u64 v[98:99], s[12:13], 0, v[118:119]
	v_lshl_add_u64 v[72:73], v[72:73], 0, v[128:129]
	v_lshl_add_u64 v[76:77], v[74:75], 0, v[128:129]
	v_lshl_add_u64 v[96:97], v[96:97], 0, v[128:129]
	v_lshl_add_u64 v[100:101], v[98:99], 0, v[128:129]
	s_waitcnt lgkmcnt(0)
	s_barrier
	global_load_dwordx4 v[72:75], v[72:73], off offset:-1536
	s_nop 0
	global_load_dwordx4 v[76:79], v[76:77], off offset:-1536
	s_nop 0
	global_load_dwordx4 v[96:99], v[96:97], off offset:-1536
	s_nop 0
	global_load_dwordx4 v[100:103], v[100:101], off offset:-1536
	s_nop 0
	global_load_dwordx4 v[104:107], v[120:121], off offset:1792
	global_load_dwordx4 v[108:111], v[122:123], off offset:1792
	ds_read_b128 v[170:173], v158
	ds_read_b128 v[174:177], v161 offset:36864
	ds_read_b128 v[178:181], v161 offset:41472
	ds_read_b128 v[182:185], v158 offset:4608
	ds_read_b128 v[186:189], v158 offset:32
	ds_read_b128 v[190:193], v161 offset:36896
	ds_read_b128 v[194:197], v161 offset:41504
	ds_read_b128 v[198:201], v158 offset:4640
	ds_read_b128 v[202:205], v158 offset:64
	ds_read_b128 v[206:209], v161 offset:36928
	ds_read_b128 v[210:213], v161 offset:41536
	ds_read_b128 v[214:217], v158 offset:4672
	s_waitcnt lgkmcnt(10)
	v_mfma_f32_32x32x16_bf16 v[48:63], v[170:173], v[174:177], v[48:63]
	s_waitcnt lgkmcnt(9)
	v_mfma_f32_32x32x16_bf16 v[32:47], v[170:173], v[178:181], v[32:47]
	s_waitcnt lgkmcnt(8)
	v_mfma_f32_32x32x16_bf16 v[16:31], v[182:185], v[174:177], v[16:31]
	v_mfma_f32_32x32x16_bf16 v[0:15], v[182:185], v[178:181], v[0:15]
	ds_read_b128 v[222:225], v158 offset:96
	ds_read_b128 v[226:229], v161 offset:36960
	ds_read_b128 v[230:233], v161 offset:41568
	ds_read_b128 v[234:237], v158 offset:4704
	s_waitcnt lgkmcnt(10)
	v_mfma_f32_32x32x16_bf16 v[48:63], v[186:189], v[190:193], v[48:63]
	s_waitcnt lgkmcnt(9)
	v_mfma_f32_32x32x16_bf16 v[32:47], v[186:189], v[194:197], v[32:47]
	s_waitcnt lgkmcnt(8)
	v_mfma_f32_32x32x16_bf16 v[16:31], v[198:201], v[190:193], v[16:31]
	v_mfma_f32_32x32x16_bf16 v[0:15], v[198:201], v[194:197], v[0:15]
	s_waitcnt vmcnt(11)
	ds_write_b128 v160, v[64:67] offset:55296
	s_waitcnt lgkmcnt(7)
	v_mfma_f32_32x32x16_bf16 v[48:63], v[202:205], v[206:209], v[48:63]
	s_waitcnt vmcnt(10)
	ds_write_b128 v160, v[68:71] offset:64512
	s_waitcnt lgkmcnt(7)
	v_mfma_f32_32x32x16_bf16 v[32:47], v[202:205], v[210:213], v[32:47]
	s_waitcnt vmcnt(9)
	ds_write_b128 v162, v[80:83] offset:18432
	s_waitcnt lgkmcnt(7)
	v_mfma_f32_32x32x16_bf16 v[16:31], v[214:217], v[206:209], v[16:31]
	v_mfma_f32_32x32x16_bf16 v[0:15], v[214:217], v[210:213], v[0:15]
	s_waitcnt vmcnt(8)
	ds_write_b128 v162, v[84:87] offset:27648
	s_waitcnt lgkmcnt(6)
	v_mfma_f32_32x32x16_bf16 v[48:63], v[222:225], v[226:229], v[48:63]
	s_waitcnt vmcnt(7)
	ds_write_b128 v163, v[88:91]
	s_waitcnt lgkmcnt(6)
	v_mfma_f32_32x32x16_bf16 v[32:47], v[222:225], v[230:233], v[32:47]
	s_waitcnt vmcnt(6)
	ds_write_b128 v163, v[92:95] offset:9216
	s_waitcnt lgkmcnt(6)
	v_mfma_f32_32x32x16_bf16 v[16:31], v[234:237], v[226:229], v[16:31]
	v_mfma_f32_32x32x16_bf16 v[0:15], v[234:237], v[230:233], v[0:15]
	v_lshl_add_u64 v[64:65], s[14:15], 0, v[112:113]
	v_lshl_add_u64 v[66:67], s[14:15], 0, v[114:115]
	v_lshl_add_u64 v[80:81], s[14:15], 0, v[116:117]
	v_lshl_add_u64 v[82:83], s[14:15], 0, v[118:119]
	v_lshl_add_u64 v[64:65], v[64:65], 0, v[128:129]
	v_lshl_add_u64 v[68:69], v[66:67], 0, v[128:129]
	v_lshl_add_u64 v[80:81], v[80:81], 0, v[128:129]
	v_lshl_add_u64 v[84:85], v[82:83], 0, v[128:129]
	s_waitcnt lgkmcnt(0)
	s_barrier
; template <class AS, class EP>
; DEVI void gemm_tile(const AS& as, const u16* __restrict__ Bt, int K, int m0, int n0, const EP& ep, char* lds) {
;     ...
;   GLOAD(ra0, rb0, 0); GLOAD(ra1, rb1, 1); LWRITE(0, ra0, rb0); __syncthreads();
;   for (int kt = 0; kt < KT; kt += 2) {
;     if (kt + 2 < KT) GLOAD(ra0, rb0, kt + 2);
;     __builtin_amdgcn_sched_barrier(0);
;     COMPUTE(0);
;     __builtin_amdgcn_sched_barrier(0);
;     LWRITE(1, ra1, rb1);
;     __syncthreads();
;     if (kt + 3 < KT) GLOAD(ra1, rb1, kt + 3);
;     __builtin_amdgcn_sched_barrier(0);
;     COMPUTE(1);
;     __builtin_amdgcn_sched_barrier(0);
;     if (kt + 2 < KT) LWRITE(0, ra0, rb0);
;     __syncthreads();
;   }
	global_load_dwordx4 v[64:67], v[64:65], off offset:-1536
	s_nop 0
	global_load_dwordx4 v[68:71], v[68:69], off offset:-1536
	s_nop 0
	global_load_dwordx4 v[80:83], v[80:81], off offset:-1536
	s_nop 0
	global_load_dwordx4 v[84:87], v[84:85], off offset:-1536
	s_nop 0
	global_load_dwordx4 v[88:91], v[120:121], off offset:1920
	global_load_dwordx4 v[92:95], v[122:123], off offset:1920
	ds_read_b128 v[170:173], v158 offset:55296
	ds_read_b128 v[174:177], v159
	ds_read_b128 v[178:181], v159 offset:4608
	ds_read_b128 v[182:185], v158 offset:59904
	ds_read_b128 v[186:189], v158 offset:55328
	ds_read_b128 v[190:193], v159 offset:32
	ds_read_b128 v[194:197], v159 offset:4640
	ds_read_b128 v[198:201], v158 offset:59936
	ds_read_b128 v[202:205], v158 offset:55360
	ds_read_b128 v[206:209], v159 offset:64
	ds_read_b128 v[210:213], v159 offset:4672
	ds_read_b128 v[214:217], v158 offset:59968
	s_waitcnt lgkmcnt(10)
	v_mfma_f32_32x32x16_bf16 v[48:63], v[170:173], v[174:177], v[48:63]
	s_waitcnt lgkmcnt(9)
	v_mfma_f32_32x32x16_bf16 v[32:47], v[170:173], v[178:181], v[32:47]
	s_waitcnt lgkmcnt(8)
	v_mfma_f32_32x32x16_bf16 v[16:31], v[182:185], v[174:177], v[16:31]
	v_mfma_f32_32x32x16_bf16 v[0:15], v[182:185], v[178:181], v[0:15]
	ds_read_b128 v[222:225], v158 offset:55392
	ds_read_b128 v[226:229], v159 offset:96
	ds_read_b128 v[230:233], v159 offset:4704
	ds_read_b128 v[234:237], v158 offset:60000
	s_waitcnt lgkmcnt(10)
	v_mfma_f32_32x32x16_bf16 v[48:63], v[186:189], v[190:193], v[48:63]
	s_waitcnt lgkmcnt(9)
	v_mfma_f32_32x32x16_bf16 v[32:47], v[186:189], v[194:197], v[32:47]
	s_waitcnt lgkmcnt(8)
	v_mfma_f32_32x32x16_bf16 v[16:31], v[198:201], v[190:193], v[16:31]
	v_mfma_f32_32x32x16_bf16 v[0:15], v[198:201], v[194:197], v[0:15]
	s_waitcnt vmcnt(11)
	ds_write_b128 v160, v[72:75]
	s_waitcnt lgkmcnt(7)
	v_mfma_f32_32x32x16_bf16 v[48:63], v[202:205], v[206:209], v[48:63]
	s_waitcnt vmcnt(10)
	ds_write_b128 v160, v[76:79] offset:9216
	s_waitcnt lgkmcnt(7)
	v_mfma_f32_32x32x16_bf16 v[32:47], v[202:205], v[210:213], v[32:47]
	s_waitcnt vmcnt(9)
	ds_write_b128 v160, v[96:99] offset:18432
	s_waitcnt lgkmcnt(7)
	v_mfma_f32_32x32x16_bf16 v[16:31], v[214:217], v[206:209], v[16:31]
	v_mfma_f32_32x32x16_bf16 v[0:15], v[214:217], v[210:213], v[0:15]
	s_waitcnt vmcnt(8)
	ds_write_b128 v160, v[100:103] offset:27648
	s_waitcnt lgkmcnt(6)
	v_mfma_f32_32x32x16_bf16 v[48:63], v[222:225], v[226:229], v[48:63]
	s_waitcnt vmcnt(7)
	ds_write_b128 v160, v[104:107] offset:36864
	s_waitcnt lgkmcnt(6)
	v_mfma_f32_32x32x16_bf16 v[32:47], v[222:225], v[230:233], v[32:47]
	s_waitcnt vmcnt(6)
	ds_write_b128 v160, v[108:111] offset:46080
	s_waitcnt lgkmcnt(6)
	v_mfma_f32_32x32x16_bf16 v[16:31], v[234:237], v[226:229], v[16:31]
	v_mfma_f32_32x32x16_bf16 v[0:15], v[234:237], v[230:233], v[0:15]
	s_waitcnt lgkmcnt(0)
	s_barrier
	ds_read_b128 v[170:173], v158
	ds_read_b128 v[174:177], v161 offset:36864
	ds_read_b128 v[178:181], v161 offset:41472
	ds_read_b128 v[182:185], v158 offset:4608
	ds_read_b128 v[186:189], v158 offset:32
	ds_read_b128 v[190:193], v161 offset:36896
	ds_read_b128 v[194:197], v161 offset:41504
	ds_read_b128 v[198:201], v158 offset:4640
	ds_read_b128 v[202:205], v158 offset:64
	ds_read_b128 v[206:209], v161 offset:36928
	ds_read_b128 v[210:213], v161 offset:41536
	ds_read_b128 v[214:217], v158 offset:4672
	s_waitcnt lgkmcnt(10)
	v_mfma_f32_32x32x16_bf16 v[48:63], v[170:173], v[174:177], v[48:63]
	s_waitcnt lgkmcnt(9)
	v_mfma_f32_32x32x16_bf16 v[32:47], v[170:173], v[178:181], v[32:47]
	s_waitcnt lgkmcnt(8)
	v_mfma_f32_32x32x16_bf16 v[16:31], v[182:185], v[174:177], v[16:31]
	v_mfma_f32_32x32x16_bf16 v[0:15], v[182:185], v[178:181], v[0:15]
	ds_read_b128 v[222:225], v158 offset:96
	ds_read_b128 v[226:229], v161 offset:36960
	ds_read_b128 v[230:233], v161 offset:41568
	ds_read_b128 v[234:237], v158 offset:4704
	s_waitcnt lgkmcnt(10)
	v_mfma_f32_32x32x16_bf16 v[48:63], v[186:189], v[190:193], v[48:63]
	s_waitcnt lgkmcnt(9)
	v_mfma_f32_32x32x16_bf16 v[32:47], v[186:189], v[194:197], v[32:47]
	s_waitcnt lgkmcnt(8)
	v_mfma_f32_32x32x16_bf16 v[16:31], v[198:201], v[190:193], v[16:31]
	v_mfma_f32_32x32x16_bf16 v[0:15], v[198:201], v[194:197], v[0:15]
	s_waitcnt vmcnt(5)
	ds_write_b128 v160, v[64:67] offset:55296
	s_waitcnt lgkmcnt(7)
	v_mfma_f32_32x32x16_bf16 v[48:63], v[202:205], v[206:209], v[48:63]
	s_waitcnt vmcnt(4)
	ds_write_b128 v160, v[68:71] offset:64512
	s_waitcnt lgkmcnt(7)
	v_mfma_f32_32x32x16_bf16 v[32:47], v[202:205], v[210:213], v[32:47]
	s_waitcnt vmcnt(3)
	ds_write_b128 v162, v[80:83] offset:18432
	s_waitcnt lgkmcnt(7)
	v_mfma_f32_32x32x16_bf16 v[16:31], v[214:217], v[206:209], v[16:31]
	v_mfma_f32_32x32x16_bf16 v[0:15], v[214:217], v[210:213], v[0:15]
	s_waitcnt vmcnt(2)
	ds_write_b128 v162, v[84:87] offset:27648
	s_waitcnt lgkmcnt(6)
	v_mfma_f32_32x32x16_bf16 v[48:63], v[222:225], v[226:229], v[48:63]
	s_waitcnt vmcnt(1)
	ds_write_b128 v163, v[88:91]
	s_waitcnt lgkmcnt(6)
	v_mfma_f32_32x32x16_bf16 v[32:47], v[222:225], v[230:233], v[32:47]
	s_waitcnt vmcnt(0)
	ds_write_b128 v163, v[92:95] offset:9216
	s_waitcnt lgkmcnt(6)
	v_mfma_f32_32x32x16_bf16 v[16:31], v[234:237], v[226:229], v[16:31]
	v_mfma_f32_32x32x16_bf16 v[0:15], v[234:237], v[230:233], v[0:15]
	s_waitcnt lgkmcnt(0)
	s_barrier
; DEVI int crow(int r, int hi) { return (r & 3) + 8 * (r >> 2) + 4 * hi; }
;   DEVI void operator()(const f32x16 (&acc)[2][2], int m0, int n0, int wm, int wn, int r32, int hi, char* lds) const {
;     const int mb = m0 + wm * 64, nb = n0 + wn * 64;
;     int b = seq_of(mb);
;     const float* gate = (const float*)(p->ws + OFF_MOD) + ((size_t)layer * 18 + b) * 3072 + 2048;
; #pragma unroll
;     for (int i = 0; i < 2; ++i)
; #pragma unroll
;       for (int j = 0; j < 2; ++j) {
;         int col = nb + j * 32 + r32; float g = gate[col];
; #pragma unroll
;         for (int r = 0; r < 16; ++r) {
;           int row = mb + i * 32 + crow(r, hi);
;           float xv = xrow(*p, layer, row)[col];
	ds_read_b128 v[170:173], v158 offset:55296
	ds_read_b128 v[174:177], v159
	ds_read_b128 v[178:181], v159 offset:4608
	ds_read_b128 v[182:185], v158 offset:59904
	ds_read_b128 v[186:189], v158 offset:55328
	ds_read_b128 v[190:193], v159 offset:32
	ds_read_b128 v[194:197], v159 offset:4640
	ds_read_b128 v[198:201], v158 offset:59936
	ds_read_b128 v[202:205], v158 offset:55360
	ds_read_b128 v[206:209], v159 offset:64
	ds_read_b128 v[210:213], v159 offset:4672
	ds_read_b128 v[214:217], v158 offset:59968
	s_waitcnt lgkmcnt(10)
	v_mfma_f32_32x32x16_bf16 v[48:63], v[170:173], v[174:177], v[48:63]
	s_waitcnt lgkmcnt(9)
	v_mfma_f32_32x32x16_bf16 v[32:47], v[170:173], v[178:181], v[32:47]
	s_waitcnt lgkmcnt(8)
	v_mfma_f32_32x32x16_bf16 v[16:31], v[182:185], v[174:177], v[16:31]
	v_mfma_f32_32x32x16_bf16 v[0:15], v[182:185], v[178:181], v[0:15]
	ds_read_b128 v[222:225], v158 offset:55392
	ds_read_b128 v[226:229], v159 offset:96
	ds_read_b128 v[230:233], v159 offset:4704
	ds_read_b128 v[234:237], v158 offset:60000
	s_waitcnt lgkmcnt(10)
	v_mfma_f32_32x32x16_bf16 v[48:63], v[186:189], v[190:193], v[48:63]
	s_waitcnt lgkmcnt(9)
	v_mfma_f32_32x32x16_bf16 v[32:47], v[186:189], v[194:197], v[32:47]
	s_waitcnt lgkmcnt(8)
	v_mfma_f32_32x32x16_bf16 v[16:31], v[198:201], v[190:193], v[16:31]
	v_mfma_f32_32x32x16_bf16 v[0:15], v[198:201], v[194:197], v[0:15]
	s_waitcnt lgkmcnt(6)
	v_mfma_f32_32x32x16_bf16 v[48:63], v[202:205], v[206:209], v[48:63]
	s_waitcnt lgkmcnt(5)
	v_mfma_f32_32x32x16_bf16 v[32:47], v[202:205], v[210:213], v[32:47]
	s_waitcnt lgkmcnt(4)
	v_mfma_f32_32x32x16_bf16 v[16:31], v[214:217], v[206:209], v[16:31]
	v_mfma_f32_32x32x16_bf16 v[0:15], v[214:217], v[210:213], v[0:15]
	s_waitcnt lgkmcnt(2)
	v_mfma_f32_32x32x16_bf16 v[48:63], v[222:225], v[226:229], v[48:63]
	s_waitcnt lgkmcnt(1)
	v_mfma_f32_32x32x16_bf16 v[32:47], v[222:225], v[230:233], v[32:47]
	s_waitcnt lgkmcnt(0)
	v_mfma_f32_32x32x16_bf16 v[16:31], v[234:237], v[226:229], v[16:31]
	v_mfma_f32_32x32x16_bf16 v[0:15], v[234:237], v[230:233], v[0:15]
	v_add_u32_e32 v68, s16, v157
	v_add_u32_e32 v65, 0xffff0000, v68
	s_mov_b32 s16, 0x10000
	v_lshrrev_b32_e32 v65, 14, v65
	v_cmp_gt_i32_e32 vcc, s16, v68
	v_ashrrev_i32_e32 v64, 12, v68
	v_add_u32_e32 v65, 16, v65
	v_cndmask_b32_e32 v64, v65, v64, vcc
	v_readlane_b32 s4, v219, 63
	v_ashrrev_i32_e32 v65, 31, v64
	v_readlane_b32 s5, v218, 0
	v_mov_b64_e32 v[66:67], s[90:91]
	s_nop 0
	v_lshl_add_u64 v[64:65], s[4:5], 0, v[64:65]
	v_mad_u64_u32 v[66:67], s[38:39], v64, s3, v[66:67]
	v_mov_b32_e32 v64, v67
	v_mad_u64_u32 v[64:65], s[38:39], v65, s3, v[64:65]
	v_mov_b32_e32 v67, v64
	v_subrev_u32_e32 v64, s17, v137
	s_mov_b64 s[38:39], 0x24da000
	v_add_u32_e32 v64, s28, v64
	v_lshl_add_u64 v[72:73], v[66:67], 0, s[38:39]
	v_ashrrev_i32_e32 v65, 31, v64
	v_lshl_add_u64 v[70:71], v[64:65], 2, v[72:73]
	s_barrier
	global_load_dword v126, v[70:71], off
	global_load_dword v127, v[70:71], off offset:128
	s_ashr_i32 s16, s44, 3
	s_lshl_b32 s16, s16, 11
	s_or_b32 s16, s16, s45
	v_readlane_b32 s48, v219, 1
	v_readlane_b32 s49, v219, 2
	v_readlane_b32 s50, v219, 3
	v_readlane_b32 s51, v219, 4
	s_lshl_b32 s17, s16, 12
	s_add_u32 s52, s92, s17
	s_addc_u32 s53, s93, 0
	s_and_b64 vcc, exec, s[10:11]
	s_cbranch_vccnz .Lepi_x_out
	s_cmp_lt_i32 s16, 0x10000
	s_cbranch_scc1 .Lepi_x_prompt
	s_add_i32 s16, s16, 0xffff0000
	s_lshl_b32 s17, s16, 12
	s_add_u32 s38, s50, s17
	s_addc_u32 s39, s51, 0
	s_branch .Lepi_x_done

; DEVI int ltid() { int t = __builtin_amdgcn_workitem_id_x(); asm volatile("" : "+v"(t)); return t; }
; template <class AS, class EP>
; DEVI void gemm_tile(const AS& as, const u16* __restrict__ Bt, int K, int m0, int n0, const EP& ep, char* lds) {
;   const int tid = ltid(), wid = tid >> 6, lane = tid & 63, r32 = lane & 31, hi = lane >> 5;
;   const int wm = wid >> 1, wn = wid & 1;
;   constexpr int RS = 144, ABYTES = 256 * RS, STAGE = ABYTES + 128 * RS;
;   f32x16 acc[2][2];
; #pragma unroll
;   for (int i = 0; i < 2; ++i)
; #pragma unroll
;     for (int j = 0; j < 2; ++j)
; #pragma unroll
;       for (int r = 0; r < 16; ++r) acc[i][j][r] = 0.f;
;   const int KT = K >> 6;
;   u32x4 ra0[4], rb0[2], ra1[4], rb1[2];
;   const int srow = tid >> 3, sch = tid & 7;
;     ...
;   GLOAD(ra0, rb0, 0); GLOAD(ra1, rb1, 1); LWRITE(0, ra0, rb0); __syncthreads();
;   for (int kt = 0; kt < KT; kt += 2) {
;     if (kt + 2 < KT) GLOAD(ra0, rb0, kt + 2);
;     __builtin_amdgcn_sched_barrier(0);
;     COMPUTE(0);
;     __builtin_amdgcn_sched_barrier(0);
;     LWRITE(1, ra1, rb1);
;     __syncthreads();
;     if (kt + 3 < KT) GLOAD(ra1, rb1, kt + 3);
;     __builtin_amdgcn_sched_barrier(0);
;     COMPUTE(1);
;     __builtin_amdgcn_sched_barrier(0);
;     if (kt + 2 < KT) LWRITE(0, ra0, rb0);
;     __syncthreads();
;   }
.LBB0_810:
	s_mul_hi_i32 s10, s12, 0x2aaaaaab
	s_lshr_b32 s11, s10, 31
	s_ashr_i32 s10, s10, 1
	s_add_i32 s10, s10, s11
	v_mov_b32_e32 v36, v131
	s_lshl_b32 s14, s10, 8
	s_mulk_i32 s10, 0x600
	v_ashrrev_i32_e32 v37, 3, v36
	v_add_u32_e32 v0, s14, v37
	v_lshlrev_b32_e32 v1, 4, v36
	v_and_b32_e32 v128, 0x70, v1
	v_ashrrev_i32_e32 v1, 31, v0
	v_lshl_add_u64 v[12:13], s[0:1], 0, v[128:129]
	v_lshlrev_b64 v[24:25], 11, v[0:1]
	s_mov_b64 s[16:17], 0x20000
	v_subrev_u32_e32 v16, s10, v37
	v_lshl_add_u64 v[112:113], v[12:13], 0, v[24:25]
	v_lshl_add_u64 v[26:27], v[24:25], 0, s[16:17]
	s_mov_b64 s[16:17], 0x40000
	v_add_u32_e32 v20, s13, v16
	global_load_dwordx4 v[0:3], v[112:113], off
	v_lshl_add_u64 v[114:115], v[12:13], 0, v[26:27]
	v_lshl_add_u64 v[28:29], v[24:25], 0, s[16:17]
	s_mov_b64 s[16:17], 0x60000
	v_ashrrev_i32_e32 v21, 31, v20
	global_load_dwordx4 v[4:7], v[114:115], off
	v_lshl_add_u64 v[116:117], v[12:13], 0, v[28:29]
	v_lshl_add_u64 v[30:31], v[24:25], 0, s[16:17]
	v_lshlrev_b64 v[32:33], 11, v[20:21]
	v_add_u32_e32 v20, 64, v20
	global_load_dwordx4 v[8:11], v[116:117], off
	v_lshl_add_u64 v[118:119], v[12:13], 0, v[30:31]
	v_lshl_add_u64 v[22:23], s[8:9], 0, v[128:129]
	v_ashrrev_i32_e32 v21, 31, v20
	global_load_dwordx4 v[12:15], v[118:119], off
	v_lshl_add_u64 v[120:121], v[22:23], 0, v[32:33]
	v_lshlrev_b64 v[34:35], 11, v[20:21]
	global_load_dwordx4 v[16:19], v[120:121], off
	v_lshl_add_u64 v[122:123], v[22:23], 0, v[34:35]
	global_load_dwordx4 v[20:23], v[122:123], off
	v_lshl_add_u64 v[24:25], s[0:1], 0, v[24:25]
	v_lshl_add_u64 v[24:25], v[24:25], 0, v[128:129]
	global_load_dwordx4 v[64:67], v[24:25], off offset:128
	v_lshl_add_u64 v[24:25], s[0:1], 0, v[26:27]
	v_lshl_add_u64 v[24:25], v[24:25], 0, v[128:129]
	global_load_dwordx4 v[68:71], v[24:25], off offset:128
	v_lshl_add_u64 v[24:25], s[0:1], 0, v[28:29]
	v_lshl_add_u64 v[24:25], v[24:25], 0, v[128:129]
	global_load_dwordx4 v[72:75], v[24:25], off offset:128
	v_lshl_add_u64 v[24:25], s[0:1], 0, v[30:31]
	v_lshl_add_u64 v[24:25], v[24:25], 0, v[128:129]
	global_load_dwordx4 v[76:79], v[24:25], off offset:128
	v_lshl_add_u64 v[24:25], s[8:9], 0, v[32:33]
	v_lshl_add_u64 v[24:25], v[24:25], 0, v[128:129]
	global_load_dwordx4 v[80:83], v[24:25], off offset:128
	v_lshl_add_u64 v[24:25], s[8:9], 0, v[34:35]
	v_lshl_add_u64 v[24:25], v[24:25], 0, v[128:129]
	global_load_dwordx4 v[84:87], v[24:25], off offset:128
	v_mul_lo_u32 v24, v37, s96
	v_add3_u32 v134, 16, v128, v24
	v_and_b32_e32 v125, 31, v36
	v_bfe_u32 v124, v36, 5, 1
	v_bfe_u32 v126, v36, 6, 1
	v_add_u32_e32 v135, 0xd800, v134
	v_add3_u32 v128, s85, v128, v24
	s_waitcnt vmcnt(11)
	ds_write_b128 v134, v[0:3]
	s_waitcnt vmcnt(10)
	ds_write_b128 v134, v[4:7] offset:9216
	s_waitcnt vmcnt(9)
	ds_write_b128 v134, v[8:11] offset:18432
	s_waitcnt vmcnt(8)
	ds_write_b128 v134, v[12:15] offset:27648
	s_waitcnt vmcnt(7)
	ds_write_b128 v134, v[16:19] offset:36864
	s_waitcnt vmcnt(6)
	ds_write_b128 v134, v[20:23] offset:46080
	s_waitcnt lgkmcnt(0)
	s_barrier
	global_load_dwordx4 v[88:91], v[112:113], off offset:256
	global_load_dwordx4 v[92:95], v[114:115], off offset:256
	global_load_dwordx4 v[96:99], v[116:117], off offset:256
	global_load_dwordx4 v[100:103], v[118:119], off offset:256
	global_load_dwordx4 v[104:107], v[120:121], off offset:256
	global_load_dwordx4 v[108:111], v[122:123], off offset:256
	v_ashrrev_i32_e32 v0, 1, v36
	v_and_b32_e32 v127, 0xffffffc0, v0
	v_or_b32_e32 v0, v127, v125
	v_mul_lo_u32 v0, v0, s96
	v_lshlrev_b32_e32 v1, 4, v124
	v_add3_u32 v132, 16, v0, v1
	v_lshl_or_b32 v0, v126, 6, v125
	v_mul_u32_u24_e32 v0, 0x90, v0
	v_add3_u32 v136, 16, v0, v1
	v_add3_u32 v133, s85, v0, v1
	ds_read_b128 v[170:173], v132
	ds_read_b128 v[174:177], v136 offset:36864
	ds_read_b128 v[178:181], v136 offset:41472
	ds_read_b128 v[182:185], v132 offset:4608
	ds_read_b128 v[186:189], v132 offset:32
	ds_read_b128 v[190:193], v136 offset:36896
	ds_read_b128 v[194:197], v136 offset:41504
	ds_read_b128 v[198:201], v132 offset:4640
	ds_read_b128 v[202:205], v132 offset:64
	ds_read_b128 v[206:209], v136 offset:36928
	ds_read_b128 v[210:213], v136 offset:41536
	ds_read_b128 v[214:217], v132 offset:4672
	s_waitcnt lgkmcnt(10)
	v_mfma_f32_32x32x16_bf16 v[48:63], v[170:173], v[174:177], 0
	s_waitcnt lgkmcnt(9)
	v_mfma_f32_32x32x16_bf16 v[32:47], v[170:173], v[178:181], 0
	s_waitcnt lgkmcnt(8)
	v_mfma_f32_32x32x16_bf16 v[16:31], v[182:185], v[174:177], 0
	v_mfma_f32_32x32x16_bf16 v[0:15], v[182:185], v[178:181], 0
	ds_read_b128 v[222:225], v132 offset:96
	ds_read_b128 v[226:229], v136 offset:36960
	ds_read_b128 v[230:233], v136 offset:41568
	ds_read_b128 v[234:237], v132 offset:4704
	s_waitcnt lgkmcnt(10)
	v_mfma_f32_32x32x16_bf16 v[48:63], v[186:189], v[190:193], v[48:63]
	s_waitcnt lgkmcnt(9)
	v_mfma_f32_32x32x16_bf16 v[32:47], v[186:189], v[194:197], v[32:47]
	s_waitcnt lgkmcnt(8)
	v_mfma_f32_32x32x16_bf16 v[16:31], v[198:201], v[190:193], v[16:31]
	v_mfma_f32_32x32x16_bf16 v[0:15], v[198:201], v[194:197], v[0:15]
	s_waitcnt vmcnt(11)
	ds_write_b128 v134, v[64:67] offset:55296
	s_waitcnt lgkmcnt(7)
	v_mfma_f32_32x32x16_bf16 v[48:63], v[202:205], v[206:209], v[48:63]
	s_waitcnt vmcnt(10)
	ds_write_b128 v134, v[68:71] offset:64512
	s_waitcnt lgkmcnt(7)
	v_mfma_f32_32x32x16_bf16 v[32:47], v[202:205], v[210:213], v[32:47]
	s_waitcnt vmcnt(9)
	ds_write_b128 v135, v[72:75] offset:18432
	s_waitcnt lgkmcnt(7)
	v_mfma_f32_32x32x16_bf16 v[16:31], v[214:217], v[206:209], v[16:31]
	v_mfma_f32_32x32x16_bf16 v[0:15], v[214:217], v[210:213], v[0:15]
	s_waitcnt vmcnt(8)
	ds_write_b128 v135, v[76:79] offset:27648
	s_waitcnt lgkmcnt(6)
	v_mfma_f32_32x32x16_bf16 v[48:63], v[222:225], v[226:229], v[48:63]
	s_waitcnt vmcnt(7)
	ds_write_b128 v128, v[80:83]
	s_waitcnt lgkmcnt(6)
	v_mfma_f32_32x32x16_bf16 v[32:47], v[222:225], v[230:233], v[32:47]
	s_waitcnt vmcnt(6)
	ds_write_b128 v128, v[84:87] offset:9216
	s_waitcnt lgkmcnt(6)
	v_mfma_f32_32x32x16_bf16 v[16:31], v[234:237], v[226:229], v[16:31]
	v_mfma_f32_32x32x16_bf16 v[0:15], v[234:237], v[230:233], v[0:15]
	s_waitcnt lgkmcnt(0)
	s_barrier
; template <class AS, class EP>
; DEVI void gemm_tile(const AS& as, const u16* __restrict__ Bt, int K, int m0, int n0, const EP& ep, char* lds) {
;     ...
;   GLOAD(ra0, rb0, 0); GLOAD(ra1, rb1, 1); LWRITE(0, ra0, rb0); __syncthreads();
;   for (int kt = 0; kt < KT; kt += 2) {
;     if (kt + 2 < KT) GLOAD(ra0, rb0, kt + 2);
;     __builtin_amdgcn_sched_barrier(0);
;     COMPUTE(0);
;     __builtin_amdgcn_sched_barrier(0);
;     LWRITE(1, ra1, rb1);
;     __syncthreads();
;     if (kt + 3 < KT) GLOAD(ra1, rb1, kt + 3);
;     __builtin_amdgcn_sched_barrier(0);
;     COMPUTE(1);
;     __builtin_amdgcn_sched_barrier(0);
;     if (kt + 2 < KT) LWRITE(0, ra0, rb0);
;     __syncthreads();
;   }
	global_load_dwordx4 v[64:67], v[112:113], off offset:384
	global_load_dwordx4 v[68:71], v[114:115], off offset:384
	global_load_dwordx4 v[72:75], v[116:117], off offset:384
	global_load_dwordx4 v[76:79], v[118:119], off offset:384
	global_load_dwordx4 v[80:83], v[120:121], off offset:384
	global_load_dwordx4 v[84:87], v[122:123], off offset:384
	ds_read_b128 v[170:173], v132 offset:55296
	ds_read_b128 v[174:177], v133
	ds_read_b128 v[178:181], v133 offset:4608
	ds_read_b128 v[182:185], v132 offset:59904
	ds_read_b128 v[186:189], v132 offset:55328
	ds_read_b128 v[190:193], v133 offset:32
	ds_read_b128 v[194:197], v133 offset:4640
	ds_read_b128 v[198:201], v132 offset:59936
	ds_read_b128 v[202:205], v132 offset:55360
	ds_read_b128 v[206:209], v133 offset:64
	ds_read_b128 v[210:213], v133 offset:4672
	ds_read_b128 v[214:217], v132 offset:59968
	s_waitcnt lgkmcnt(10)
	v_mfma_f32_32x32x16_bf16 v[48:63], v[170:173], v[174:177], v[48:63]
	s_waitcnt lgkmcnt(9)
	v_mfma_f32_32x32x16_bf16 v[32:47], v[170:173], v[178:181], v[32:47]
	s_waitcnt lgkmcnt(8)
	v_mfma_f32_32x32x16_bf16 v[16:31], v[182:185], v[174:177], v[16:31]
	v_mfma_f32_32x32x16_bf16 v[0:15], v[182:185], v[178:181], v[0:15]
	ds_read_b128 v[222:225], v132 offset:55392
	ds_read_b128 v[226:229], v133 offset:96
	ds_read_b128 v[230:233], v133 offset:4704
	ds_read_b128 v[234:237], v132 offset:60000
	s_waitcnt lgkmcnt(10)
	v_mfma_f32_32x32x16_bf16 v[48:63], v[186:189], v[190:193], v[48:63]
	s_waitcnt lgkmcnt(9)
	v_mfma_f32_32x32x16_bf16 v[32:47], v[186:189], v[194:197], v[32:47]
	s_waitcnt lgkmcnt(8)
	v_mfma_f32_32x32x16_bf16 v[16:31], v[198:201], v[190:193], v[16:31]
	v_mfma_f32_32x32x16_bf16 v[0:15], v[198:201], v[194:197], v[0:15]
	s_waitcnt vmcnt(11)
	ds_write_b128 v134, v[88:91]
	s_waitcnt lgkmcnt(7)
	v_mfma_f32_32x32x16_bf16 v[48:63], v[202:205], v[206:209], v[48:63]
	s_waitcnt vmcnt(10)
	ds_write_b128 v134, v[92:95] offset:9216
	s_waitcnt lgkmcnt(7)
	v_mfma_f32_32x32x16_bf16 v[32:47], v[202:205], v[210:213], v[32:47]
	s_waitcnt vmcnt(9)
	ds_write_b128 v134, v[96:99] offset:18432
	s_waitcnt lgkmcnt(7)
	v_mfma_f32_32x32x16_bf16 v[16:31], v[214:217], v[206:209], v[16:31]
	v_mfma_f32_32x32x16_bf16 v[0:15], v[214:217], v[210:213], v[0:15]
	s_waitcnt vmcnt(8)
	ds_write_b128 v134, v[100:103] offset:27648
	s_waitcnt lgkmcnt(6)
	v_mfma_f32_32x32x16_bf16 v[48:63], v[222:225], v[226:229], v[48:63]
	s_waitcnt vmcnt(7)
	ds_write_b128 v134, v[104:107] offset:36864
	s_waitcnt lgkmcnt(6)
	v_mfma_f32_32x32x16_bf16 v[32:47], v[222:225], v[230:233], v[32:47]
	s_waitcnt vmcnt(6)
	ds_write_b128 v134, v[108:111] offset:46080
	s_waitcnt lgkmcnt(6)
	v_mfma_f32_32x32x16_bf16 v[16:31], v[234:237], v[226:229], v[16:31]
	v_mfma_f32_32x32x16_bf16 v[0:15], v[234:237], v[230:233], v[0:15]
	s_waitcnt lgkmcnt(0)
	s_barrier
	global_load_dwordx4 v[88:91], v[112:113], off offset:512
	global_load_dwordx4 v[92:95], v[114:115], off offset:512
	global_load_dwordx4 v[96:99], v[116:117], off offset:512
	global_load_dwordx4 v[100:103], v[118:119], off offset:512
	global_load_dwordx4 v[104:107], v[120:121], off offset:512
	global_load_dwordx4 v[108:111], v[122:123], off offset:512
	ds_read_b128 v[170:173], v132
	ds_read_b128 v[174:177], v136 offset:36864
	ds_read_b128 v[178:181], v136 offset:41472
	ds_read_b128 v[182:185], v132 offset:4608
	ds_read_b128 v[186:189], v132 offset:32
	ds_read_b128 v[190:193], v136 offset:36896
	ds_read_b128 v[194:197], v136 offset:41504
	ds_read_b128 v[198:201], v132 offset:4640
	ds_read_b128 v[202:205], v132 offset:64
	ds_read_b128 v[206:209], v136 offset:36928
	ds_read_b128 v[210:213], v136 offset:41536
	ds_read_b128 v[214:217], v132 offset:4672
	s_waitcnt lgkmcnt(10)
	v_mfma_f32_32x32x16_bf16 v[48:63], v[170:173], v[174:177], v[48:63]
	s_waitcnt lgkmcnt(9)
	v_mfma_f32_32x32x16_bf16 v[32:47], v[170:173], v[178:181], v[32:47]
	s_waitcnt lgkmcnt(8)
	v_mfma_f32_32x32x16_bf16 v[16:31], v[182:185], v[174:177], v[16:31]
	v_mfma_f32_32x32x16_bf16 v[0:15], v[182:185], v[178:181], v[0:15]
	ds_read_b128 v[222:225], v132 offset:96
	ds_read_b128 v[226:229], v136 offset:36960
	ds_read_b128 v[230:233], v136 offset:41568
	ds_read_b128 v[234:237], v132 offset:4704
	s_waitcnt lgkmcnt(10)
	v_mfma_f32_32x32x16_bf16 v[48:63], v[186:189], v[190:193], v[48:63]
	s_waitcnt lgkmcnt(9)
	v_mfma_f32_32x32x16_bf16 v[32:47], v[186:189], v[194:197], v[32:47]
	s_waitcnt lgkmcnt(8)
	v_mfma_f32_32x32x16_bf16 v[16:31], v[198:201], v[190:193], v[16:31]
	v_mfma_f32_32x32x16_bf16 v[0:15], v[198:201], v[194:197], v[0:15]
	s_waitcnt vmcnt(11)
	ds_write_b128 v134, v[64:67] offset:55296
	s_waitcnt lgkmcnt(7)
	v_mfma_f32_32x32x16_bf16 v[48:63], v[202:205], v[206:209], v[48:63]
	s_waitcnt vmcnt(10)
	ds_write_b128 v134, v[68:71] offset:64512
	s_waitcnt lgkmcnt(7)
	v_mfma_f32_32x32x16_bf16 v[32:47], v[202:205], v[210:213], v[32:47]
	s_waitcnt vmcnt(9)
	ds_write_b128 v135, v[72:75] offset:18432
	s_waitcnt lgkmcnt(7)
	v_mfma_f32_32x32x16_bf16 v[16:31], v[214:217], v[206:209], v[16:31]
	v_mfma_f32_32x32x16_bf16 v[0:15], v[214:217], v[210:213], v[0:15]
	s_waitcnt vmcnt(8)
	ds_write_b128 v135, v[76:79] offset:27648
	s_waitcnt lgkmcnt(6)
	v_mfma_f32_32x32x16_bf16 v[48:63], v[222:225], v[226:229], v[48:63]
	s_waitcnt vmcnt(7)
	ds_write_b128 v128, v[80:83]
	s_waitcnt lgkmcnt(6)
	v_mfma_f32_32x32x16_bf16 v[32:47], v[222:225], v[230:233], v[32:47]
	s_waitcnt vmcnt(6)
	ds_write_b128 v128, v[84:87] offset:9216
	s_waitcnt lgkmcnt(6)
	v_mfma_f32_32x32x16_bf16 v[16:31], v[234:237], v[226:229], v[16:31]
	v_mfma_f32_32x32x16_bf16 v[0:15], v[234:237], v[230:233], v[0:15]
	s_waitcnt lgkmcnt(0)
	s_barrier
; template <class AS, class EP>
; DEVI void gemm_tile(const AS& as, const u16* __restrict__ Bt, int K, int m0, int n0, const EP& ep, char* lds) {
;     ...
;   GLOAD(ra0, rb0, 0); GLOAD(ra1, rb1, 1); LWRITE(0, ra0, rb0); __syncthreads();
;   for (int kt = 0; kt < KT; kt += 2) {
;     if (kt + 2 < KT) GLOAD(ra0, rb0, kt + 2);
;     __builtin_amdgcn_sched_barrier(0);
;     COMPUTE(0);
;     __builtin_amdgcn_sched_barrier(0);
;     LWRITE(1, ra1, rb1);
;     __syncthreads();
;     if (kt + 3 < KT) GLOAD(ra1, rb1, kt + 3);
;     __builtin_amdgcn_sched_barrier(0);
;     COMPUTE(1);
;     __builtin_amdgcn_sched_barrier(0);
;     if (kt + 2 < KT) LWRITE(0, ra0, rb0);
;     __syncthreads();
;   }
	global_load_dwordx4 v[64:67], v[112:113], off offset:640
	global_load_dwordx4 v[68:71], v[114:115], off offset:640
	global_load_dwordx4 v[72:75], v[116:117], off offset:640
	global_load_dwordx4 v[76:79], v[118:119], off offset:640
	global_load_dwordx4 v[80:83], v[120:121], off offset:640
	global_load_dwordx4 v[84:87], v[122:123], off offset:640
	ds_read_b128 v[170:173], v132 offset:55296
	ds_read_b128 v[174:177], v133
	ds_read_b128 v[178:181], v133 offset:4608
	ds_read_b128 v[182:185], v132 offset:59904
	ds_read_b128 v[186:189], v132 offset:55328
	ds_read_b128 v[190:193], v133 offset:32
	ds_read_b128 v[194:197], v133 offset:4640
	ds_read_b128 v[198:201], v132 offset:59936
	ds_read_b128 v[202:205], v132 offset:55360
	ds_read_b128 v[206:209], v133 offset:64
	ds_read_b128 v[210:213], v133 offset:4672
	ds_read_b128 v[214:217], v132 offset:59968
	s_waitcnt lgkmcnt(10)
	v_mfma_f32_32x32x16_bf16 v[48:63], v[170:173], v[174:177], v[48:63]
	s_waitcnt lgkmcnt(9)
	v_mfma_f32_32x32x16_bf16 v[32:47], v[170:173], v[178:181], v[32:47]
	s_waitcnt lgkmcnt(8)
	v_mfma_f32_32x32x16_bf16 v[16:31], v[182:185], v[174:177], v[16:31]
	v_mfma_f32_32x32x16_bf16 v[0:15], v[182:185], v[178:181], v[0:15]
	ds_read_b128 v[222:225], v132 offset:55392
	ds_read_b128 v[226:229], v133 offset:96
	ds_read_b128 v[230:233], v133 offset:4704
	ds_read_b128 v[234:237], v132 offset:60000
	s_waitcnt lgkmcnt(10)
	v_mfma_f32_32x32x16_bf16 v[48:63], v[186:189], v[190:193], v[48:63]
	s_waitcnt lgkmcnt(9)
	v_mfma_f32_32x32x16_bf16 v[32:47], v[186:189], v[194:197], v[32:47]
	s_waitcnt lgkmcnt(8)
	v_mfma_f32_32x32x16_bf16 v[16:31], v[198:201], v[190:193], v[16:31]
	v_mfma_f32_32x32x16_bf16 v[0:15], v[198:201], v[194:197], v[0:15]
	s_waitcnt vmcnt(11)
	ds_write_b128 v134, v[88:91]
	s_waitcnt lgkmcnt(7)
	v_mfma_f32_32x32x16_bf16 v[48:63], v[202:205], v[206:209], v[48:63]
	s_waitcnt vmcnt(10)
	ds_write_b128 v134, v[92:95] offset:9216
	s_waitcnt lgkmcnt(7)
	v_mfma_f32_32x32x16_bf16 v[32:47], v[202:205], v[210:213], v[32:47]
	s_waitcnt vmcnt(9)
	ds_write_b128 v134, v[96:99] offset:18432
	s_waitcnt lgkmcnt(7)
	v_mfma_f32_32x32x16_bf16 v[16:31], v[214:217], v[206:209], v[16:31]
	v_mfma_f32_32x32x16_bf16 v[0:15], v[214:217], v[210:213], v[0:15]
	s_waitcnt vmcnt(8)
	ds_write_b128 v134, v[100:103] offset:27648
	s_waitcnt lgkmcnt(6)
	v_mfma_f32_32x32x16_bf16 v[48:63], v[222:225], v[226:229], v[48:63]
	s_waitcnt vmcnt(7)
	ds_write_b128 v134, v[104:107] offset:36864
	s_waitcnt lgkmcnt(6)
	v_mfma_f32_32x32x16_bf16 v[32:47], v[222:225], v[230:233], v[32:47]
	s_waitcnt vmcnt(6)
	ds_write_b128 v134, v[108:111] offset:46080
	s_waitcnt lgkmcnt(6)
	v_mfma_f32_32x32x16_bf16 v[16:31], v[234:237], v[226:229], v[16:31]
	v_mfma_f32_32x32x16_bf16 v[0:15], v[234:237], v[230:233], v[0:15]
	s_waitcnt lgkmcnt(0)
	s_barrier
	global_load_dwordx4 v[88:91], v[112:113], off offset:768
	global_load_dwordx4 v[92:95], v[114:115], off offset:768
	global_load_dwordx4 v[96:99], v[116:117], off offset:768
	global_load_dwordx4 v[100:103], v[118:119], off offset:768
	global_load_dwordx4 v[104:107], v[120:121], off offset:768
	global_load_dwordx4 v[108:111], v[122:123], off offset:768
	ds_read_b128 v[170:173], v132
	ds_read_b128 v[174:177], v136 offset:36864
	ds_read_b128 v[178:181], v136 offset:41472
	ds_read_b128 v[182:185], v132 offset:4608
	ds_read_b128 v[186:189], v132 offset:32
	ds_read_b128 v[190:193], v136 offset:36896
	ds_read_b128 v[194:197], v136 offset:41504
	ds_read_b128 v[198:201], v132 offset:4640
	ds_read_b128 v[202:205], v132 offset:64
	ds_read_b128 v[206:209], v136 offset:36928
	ds_read_b128 v[210:213], v136 offset:41536
	ds_read_b128 v[214:217], v132 offset:4672
	s_waitcnt lgkmcnt(10)
	v_mfma_f32_32x32x16_bf16 v[48:63], v[170:173], v[174:177], v[48:63]
	s_waitcnt lgkmcnt(9)
	v_mfma_f32_32x32x16_bf16 v[32:47], v[170:173], v[178:181], v[32:47]
	s_waitcnt lgkmcnt(8)
	v_mfma_f32_32x32x16_bf16 v[16:31], v[182:185], v[174:177], v[16:31]
	v_mfma_f32_32x32x16_bf16 v[0:15], v[182:185], v[178:181], v[0:15]
	ds_read_b128 v[222:225], v132 offset:96
	ds_read_b128 v[226:229], v136 offset:36960
	ds_read_b128 v[230:233], v136 offset:41568
	ds_read_b128 v[234:237], v132 offset:4704
	s_waitcnt lgkmcnt(10)
	v_mfma_f32_32x32x16_bf16 v[48:63], v[186:189], v[190:193], v[48:63]
	s_waitcnt lgkmcnt(9)
	v_mfma_f32_32x32x16_bf16 v[32:47], v[186:189], v[194:197], v[32:47]
	s_waitcnt lgkmcnt(8)
	v_mfma_f32_32x32x16_bf16 v[16:31], v[198:201], v[190:193], v[16:31]
	v_mfma_f32_32x32x16_bf16 v[0:15], v[198:201], v[194:197], v[0:15]
	s_waitcnt vmcnt(11)
	ds_write_b128 v134, v[64:67] offset:55296
	s_waitcnt lgkmcnt(7)
	v_mfma_f32_32x32x16_bf16 v[48:63], v[202:205], v[206:209], v[48:63]
	s_waitcnt vmcnt(10)
	ds_write_b128 v134, v[68:71] offset:64512
	s_waitcnt lgkmcnt(7)
	v_mfma_f32_32x32x16_bf16 v[32:47], v[202:205], v[210:213], v[32:47]
	s_waitcnt vmcnt(9)
	ds_write_b128 v135, v[72:75] offset:18432
	s_waitcnt lgkmcnt(7)
	v_mfma_f32_32x32x16_bf16 v[16:31], v[214:217], v[206:209], v[16:31]
	v_mfma_f32_32x32x16_bf16 v[0:15], v[214:217], v[210:213], v[0:15]
	s_waitcnt vmcnt(8)
	ds_write_b128 v135, v[76:79] offset:27648
	s_waitcnt lgkmcnt(6)
	v_mfma_f32_32x32x16_bf16 v[48:63], v[222:225], v[226:229], v[48:63]
	s_waitcnt vmcnt(7)
	ds_write_b128 v128, v[80:83]
	s_waitcnt lgkmcnt(6)
	v_mfma_f32_32x32x16_bf16 v[32:47], v[222:225], v[230:233], v[32:47]
	s_waitcnt vmcnt(6)
	ds_write_b128 v128, v[84:87] offset:9216
	s_waitcnt lgkmcnt(6)
	v_mfma_f32_32x32x16_bf16 v[16:31], v[234:237], v[226:229], v[16:31]
	v_mfma_f32_32x32x16_bf16 v[0:15], v[234:237], v[230:233], v[0:15]
	s_waitcnt lgkmcnt(0)
	s_barrier
; template <class AS, class EP>
; DEVI void gemm_tile(const AS& as, const u16* __restrict__ Bt, int K, int m0, int n0, const EP& ep, char* lds) {
;     ...
;   GLOAD(ra0, rb0, 0); GLOAD(ra1, rb1, 1); LWRITE(0, ra0, rb0); __syncthreads();
;   for (int kt = 0; kt < KT; kt += 2) {
;     if (kt + 2 < KT) GLOAD(ra0, rb0, kt + 2);
;     __builtin_amdgcn_sched_barrier(0);
;     COMPUTE(0);
;     __builtin_amdgcn_sched_barrier(0);
;     LWRITE(1, ra1, rb1);
;     __syncthreads();
;     if (kt + 3 < KT) GLOAD(ra1, rb1, kt + 3);
;     __builtin_amdgcn_sched_barrier(0);
;     COMPUTE(1);
;     __builtin_amdgcn_sched_barrier(0);
;     if (kt + 2 < KT) LWRITE(0, ra0, rb0);
;     __syncthreads();
;   }
	global_load_dwordx4 v[64:67], v[112:113], off offset:896
	global_load_dwordx4 v[68:71], v[114:115], off offset:896
	global_load_dwordx4 v[72:75], v[116:117], off offset:896
	global_load_dwordx4 v[76:79], v[118:119], off offset:896
	global_load_dwordx4 v[80:83], v[120:121], off offset:896
	global_load_dwordx4 v[84:87], v[122:123], off offset:896
	ds_read_b128 v[170:173], v132 offset:55296
	ds_read_b128 v[174:177], v133
	ds_read_b128 v[178:181], v133 offset:4608
	ds_read_b128 v[182:185], v132 offset:59904
	ds_read_b128 v[186:189], v132 offset:55328
	ds_read_b128 v[190:193], v133 offset:32
	ds_read_b128 v[194:197], v133 offset:4640
	ds_read_b128 v[198:201], v132 offset:59936
	ds_read_b128 v[202:205], v132 offset:55360
	ds_read_b128 v[206:209], v133 offset:64
	ds_read_b128 v[210:213], v133 offset:4672
	ds_read_b128 v[214:217], v132 offset:59968
	s_waitcnt lgkmcnt(10)
	v_mfma_f32_32x32x16_bf16 v[48:63], v[170:173], v[174:177], v[48:63]
	s_waitcnt lgkmcnt(9)
	v_mfma_f32_32x32x16_bf16 v[32:47], v[170:173], v[178:181], v[32:47]
	s_waitcnt lgkmcnt(8)
	v_mfma_f32_32x32x16_bf16 v[16:31], v[182:185], v[174:177], v[16:31]
	v_mfma_f32_32x32x16_bf16 v[0:15], v[182:185], v[178:181], v[0:15]
	ds_read_b128 v[222:225], v132 offset:55392
	ds_read_b128 v[226:229], v133 offset:96
	ds_read_b128 v[230:233], v133 offset:4704
	ds_read_b128 v[234:237], v132 offset:60000
	s_waitcnt lgkmcnt(10)
	v_mfma_f32_32x32x16_bf16 v[48:63], v[186:189], v[190:193], v[48:63]
	s_waitcnt lgkmcnt(9)
	v_mfma_f32_32x32x16_bf16 v[32:47], v[186:189], v[194:197], v[32:47]
	s_waitcnt lgkmcnt(8)
	v_mfma_f32_32x32x16_bf16 v[16:31], v[198:201], v[190:193], v[16:31]
	v_mfma_f32_32x32x16_bf16 v[0:15], v[198:201], v[194:197], v[0:15]
	s_waitcnt vmcnt(11)
	ds_write_b128 v134, v[88:91]
	s_waitcnt lgkmcnt(7)
	v_mfma_f32_32x32x16_bf16 v[48:63], v[202:205], v[206:209], v[48:63]
	s_waitcnt vmcnt(10)
	ds_write_b128 v134, v[92:95] offset:9216
	s_waitcnt lgkmcnt(7)
	v_mfma_f32_32x32x16_bf16 v[32:47], v[202:205], v[210:213], v[32:47]
	s_waitcnt vmcnt(9)
	ds_write_b128 v134, v[96:99] offset:18432
	s_waitcnt lgkmcnt(7)
	v_mfma_f32_32x32x16_bf16 v[16:31], v[214:217], v[206:209], v[16:31]
	v_mfma_f32_32x32x16_bf16 v[0:15], v[214:217], v[210:213], v[0:15]
	s_waitcnt vmcnt(8)
	ds_write_b128 v134, v[100:103] offset:27648
	s_waitcnt lgkmcnt(6)
	v_mfma_f32_32x32x16_bf16 v[48:63], v[222:225], v[226:229], v[48:63]
	s_waitcnt vmcnt(7)
	ds_write_b128 v134, v[104:107] offset:36864
	s_waitcnt lgkmcnt(6)
	v_mfma_f32_32x32x16_bf16 v[32:47], v[222:225], v[230:233], v[32:47]
	s_waitcnt vmcnt(6)
	ds_write_b128 v134, v[108:111] offset:46080
	s_waitcnt lgkmcnt(6)
	v_mfma_f32_32x32x16_bf16 v[16:31], v[234:237], v[226:229], v[16:31]
	v_mfma_f32_32x32x16_bf16 v[0:15], v[234:237], v[230:233], v[0:15]
	s_waitcnt lgkmcnt(0)
	s_barrier
	global_load_dwordx4 v[88:91], v[112:113], off offset:1024
	global_load_dwordx4 v[92:95], v[114:115], off offset:1024
	global_load_dwordx4 v[96:99], v[116:117], off offset:1024
	global_load_dwordx4 v[100:103], v[118:119], off offset:1024
	global_load_dwordx4 v[104:107], v[120:121], off offset:1024
	global_load_dwordx4 v[108:111], v[122:123], off offset:1024
	ds_read_b128 v[170:173], v132
	ds_read_b128 v[174:177], v136 offset:36864
	ds_read_b128 v[178:181], v136 offset:41472
	ds_read_b128 v[182:185], v132 offset:4608
	ds_read_b128 v[186:189], v132 offset:32
	ds_read_b128 v[190:193], v136 offset:36896
	ds_read_b128 v[194:197], v136 offset:41504
	ds_read_b128 v[198:201], v132 offset:4640
	ds_read_b128 v[202:205], v132 offset:64
	ds_read_b128 v[206:209], v136 offset:36928
	ds_read_b128 v[210:213], v136 offset:41536
	ds_read_b128 v[214:217], v132 offset:4672
	s_waitcnt lgkmcnt(10)
	v_mfma_f32_32x32x16_bf16 v[48:63], v[170:173], v[174:177], v[48:63]
	s_waitcnt lgkmcnt(9)
	v_mfma_f32_32x32x16_bf16 v[32:47], v[170:173], v[178:181], v[32:47]
	s_waitcnt lgkmcnt(8)
	v_mfma_f32_32x32x16_bf16 v[16:31], v[182:185], v[174:177], v[16:31]
	v_mfma_f32_32x32x16_bf16 v[0:15], v[182:185], v[178:181], v[0:15]
	ds_read_b128 v[222:225], v132 offset:96
	ds_read_b128 v[226:229], v136 offset:36960
	ds_read_b128 v[230:233], v136 offset:41568
	ds_read_b128 v[234:237], v132 offset:4704
	s_waitcnt lgkmcnt(10)
	v_mfma_f32_32x32x16_bf16 v[48:63], v[186:189], v[190:193], v[48:63]
	s_waitcnt lgkmcnt(9)
	v_mfma_f32_32x32x16_bf16 v[32:47], v[186:189], v[194:197], v[32:47]
	s_waitcnt lgkmcnt(8)
	v_mfma_f32_32x32x16_bf16 v[16:31], v[198:201], v[190:193], v[16:31]
	v_mfma_f32_32x32x16_bf16 v[0:15], v[198:201], v[194:197], v[0:15]
	s_waitcnt vmcnt(11)
	ds_write_b128 v134, v[64:67] offset:55296
	s_waitcnt lgkmcnt(7)
	v_mfma_f32_32x32x16_bf16 v[48:63], v[202:205], v[206:209], v[48:63]
	s_waitcnt vmcnt(10)
	ds_write_b128 v134, v[68:71] offset:64512
	s_waitcnt lgkmcnt(7)
	v_mfma_f32_32x32x16_bf16 v[32:47], v[202:205], v[210:213], v[32:47]
	s_waitcnt vmcnt(9)
	ds_write_b128 v135, v[72:75] offset:18432
	s_waitcnt lgkmcnt(7)
	v_mfma_f32_32x32x16_bf16 v[16:31], v[214:217], v[206:209], v[16:31]
	v_mfma_f32_32x32x16_bf16 v[0:15], v[214:217], v[210:213], v[0:15]
	s_waitcnt vmcnt(8)
	ds_write_b128 v135, v[76:79] offset:27648
	s_waitcnt lgkmcnt(6)
	v_mfma_f32_32x32x16_bf16 v[48:63], v[222:225], v[226:229], v[48:63]
	s_waitcnt vmcnt(7)
	ds_write_b128 v128, v[80:83]
	s_waitcnt lgkmcnt(6)
	v_mfma_f32_32x32x16_bf16 v[32:47], v[222:225], v[230:233], v[32:47]
	s_waitcnt vmcnt(6)
	ds_write_b128 v128, v[84:87] offset:9216
	s_waitcnt lgkmcnt(6)
	v_mfma_f32_32x32x16_bf16 v[16:31], v[234:237], v[226:229], v[16:31]
	v_mfma_f32_32x32x16_bf16 v[0:15], v[234:237], v[230:233], v[0:15]
	s_waitcnt lgkmcnt(0)
	s_barrier
; template <class AS, class EP>
; DEVI void gemm_tile(const AS& as, const u16* __restrict__ Bt, int K, int m0, int n0, const EP& ep, char* lds) {
;     ...
;   GLOAD(ra0, rb0, 0); GLOAD(ra1, rb1, 1); LWRITE(0, ra0, rb0); __syncthreads();
;   for (int kt = 0; kt < KT; kt += 2) {
;     if (kt + 2 < KT) GLOAD(ra0, rb0, kt + 2);
;     __builtin_amdgcn_sched_barrier(0);
;     COMPUTE(0);
;     __builtin_amdgcn_sched_barrier(0);
;     LWRITE(1, ra1, rb1);
;     __syncthreads();
;     if (kt + 3 < KT) GLOAD(ra1, rb1, kt + 3);
;     __builtin_amdgcn_sched_barrier(0);
;     COMPUTE(1);
;     __builtin_amdgcn_sched_barrier(0);
;     if (kt + 2 < KT) LWRITE(0, ra0, rb0);
;     __syncthreads();
;   }
	global_load_dwordx4 v[64:67], v[112:113], off offset:1152
	global_load_dwordx4 v[68:71], v[114:115], off offset:1152
	global_load_dwordx4 v[72:75], v[116:117], off offset:1152
	global_load_dwordx4 v[76:79], v[118:119], off offset:1152
	global_load_dwordx4 v[80:83], v[120:121], off offset:1152
	global_load_dwordx4 v[84:87], v[122:123], off offset:1152
	ds_read_b128 v[170:173], v132 offset:55296
	ds_read_b128 v[174:177], v133
	ds_read_b128 v[178:181], v133 offset:4608
	ds_read_b128 v[182:185], v132 offset:59904
	ds_read_b128 v[186:189], v132 offset:55328
	ds_read_b128 v[190:193], v133 offset:32
	ds_read_b128 v[194:197], v133 offset:4640
	ds_read_b128 v[198:201], v132 offset:59936
	ds_read_b128 v[202:205], v132 offset:55360
	ds_read_b128 v[206:209], v133 offset:64
	ds_read_b128 v[210:213], v133 offset:4672
	ds_read_b128 v[214:217], v132 offset:59968
	s_waitcnt lgkmcnt(10)
	v_mfma_f32_32x32x16_bf16 v[48:63], v[170:173], v[174:177], v[48:63]
	s_waitcnt lgkmcnt(9)
	v_mfma_f32_32x32x16_bf16 v[32:47], v[170:173], v[178:181], v[32:47]
	s_waitcnt lgkmcnt(8)
	v_mfma_f32_32x32x16_bf16 v[16:31], v[182:185], v[174:177], v[16:31]
	v_mfma_f32_32x32x16_bf16 v[0:15], v[182:185], v[178:181], v[0:15]
	ds_read_b128 v[222:225], v132 offset:55392
	ds_read_b128 v[226:229], v133 offset:96
	ds_read_b128 v[230:233], v133 offset:4704
	ds_read_b128 v[234:237], v132 offset:60000
	s_waitcnt lgkmcnt(10)
	v_mfma_f32_32x32x16_bf16 v[48:63], v[186:189], v[190:193], v[48:63]
	s_waitcnt lgkmcnt(9)
	v_mfma_f32_32x32x16_bf16 v[32:47], v[186:189], v[194:197], v[32:47]
	s_waitcnt lgkmcnt(8)
	v_mfma_f32_32x32x16_bf16 v[16:31], v[198:201], v[190:193], v[16:31]
	v_mfma_f32_32x32x16_bf16 v[0:15], v[198:201], v[194:197], v[0:15]
	s_waitcnt vmcnt(11)
	ds_write_b128 v134, v[88:91]
	s_waitcnt lgkmcnt(7)
	v_mfma_f32_32x32x16_bf16 v[48:63], v[202:205], v[206:209], v[48:63]
	s_waitcnt vmcnt(10)
	ds_write_b128 v134, v[92:95] offset:9216
	s_waitcnt lgkmcnt(7)
	v_mfma_f32_32x32x16_bf16 v[32:47], v[202:205], v[210:213], v[32:47]
	s_waitcnt vmcnt(9)
	ds_write_b128 v134, v[96:99] offset:18432
	s_waitcnt lgkmcnt(7)
	v_mfma_f32_32x32x16_bf16 v[16:31], v[214:217], v[206:209], v[16:31]
	v_mfma_f32_32x32x16_bf16 v[0:15], v[214:217], v[210:213], v[0:15]
	s_waitcnt vmcnt(8)
	ds_write_b128 v134, v[100:103] offset:27648
	s_waitcnt lgkmcnt(6)
	v_mfma_f32_32x32x16_bf16 v[48:63], v[222:225], v[226:229], v[48:63]
	s_waitcnt vmcnt(7)
	ds_write_b128 v134, v[104:107] offset:36864
	s_waitcnt lgkmcnt(6)
	v_mfma_f32_32x32x16_bf16 v[32:47], v[222:225], v[230:233], v[32:47]
	s_waitcnt vmcnt(6)
	ds_write_b128 v134, v[108:111] offset:46080
	s_waitcnt lgkmcnt(6)
	v_mfma_f32_32x32x16_bf16 v[16:31], v[234:237], v[226:229], v[16:31]
	v_mfma_f32_32x32x16_bf16 v[0:15], v[234:237], v[230:233], v[0:15]
	s_waitcnt lgkmcnt(0)
	s_barrier
	global_load_dwordx4 v[88:91], v[112:113], off offset:1280
	global_load_dwordx4 v[92:95], v[114:115], off offset:1280
	global_load_dwordx4 v[96:99], v[116:117], off offset:1280
	global_load_dwordx4 v[100:103], v[118:119], off offset:1280
	global_load_dwordx4 v[104:107], v[120:121], off offset:1280
	global_load_dwordx4 v[108:111], v[122:123], off offset:1280
	ds_read_b128 v[170:173], v132
	ds_read_b128 v[174:177], v136 offset:36864
	ds_read_b128 v[178:181], v136 offset:41472
	ds_read_b128 v[182:185], v132 offset:4608
	ds_read_b128 v[186:189], v132 offset:32
	ds_read_b128 v[190:193], v136 offset:36896
	ds_read_b128 v[194:197], v136 offset:41504
	ds_read_b128 v[198:201], v132 offset:4640
	ds_read_b128 v[202:205], v132 offset:64
	ds_read_b128 v[206:209], v136 offset:36928
	ds_read_b128 v[210:213], v136 offset:41536
	ds_read_b128 v[214:217], v132 offset:4672
	s_waitcnt lgkmcnt(10)
	v_mfma_f32_32x32x16_bf16 v[48:63], v[170:173], v[174:177], v[48:63]
	s_waitcnt lgkmcnt(9)
	v_mfma_f32_32x32x16_bf16 v[32:47], v[170:173], v[178:181], v[32:47]
	s_waitcnt lgkmcnt(8)
	v_mfma_f32_32x32x16_bf16 v[16:31], v[182:185], v[174:177], v[16:31]
	v_mfma_f32_32x32x16_bf16 v[0:15], v[182:185], v[178:181], v[0:15]
	ds_read_b128 v[222:225], v132 offset:96
	ds_read_b128 v[226:229], v136 offset:36960
	ds_read_b128 v[230:233], v136 offset:41568
	ds_read_b128 v[234:237], v132 offset:4704
	s_waitcnt lgkmcnt(10)
	v_mfma_f32_32x32x16_bf16 v[48:63], v[186:189], v[190:193], v[48:63]
	s_waitcnt lgkmcnt(9)
	v_mfma_f32_32x32x16_bf16 v[32:47], v[186:189], v[194:197], v[32:47]
	s_waitcnt lgkmcnt(8)
	v_mfma_f32_32x32x16_bf16 v[16:31], v[198:201], v[190:193], v[16:31]
	v_mfma_f32_32x32x16_bf16 v[0:15], v[198:201], v[194:197], v[0:15]
	s_waitcnt vmcnt(11)
	ds_write_b128 v134, v[64:67] offset:55296
	s_waitcnt lgkmcnt(7)
	v_mfma_f32_32x32x16_bf16 v[48:63], v[202:205], v[206:209], v[48:63]
	s_waitcnt vmcnt(10)
	ds_write_b128 v134, v[68:71] offset:64512
	s_waitcnt lgkmcnt(7)
	v_mfma_f32_32x32x16_bf16 v[32:47], v[202:205], v[210:213], v[32:47]
	s_waitcnt vmcnt(9)
	ds_write_b128 v135, v[72:75] offset:18432
	s_waitcnt lgkmcnt(7)
	v_mfma_f32_32x32x16_bf16 v[16:31], v[214:217], v[206:209], v[16:31]
	v_mfma_f32_32x32x16_bf16 v[0:15], v[214:217], v[210:213], v[0:15]
	s_waitcnt vmcnt(8)
	ds_write_b128 v135, v[76:79] offset:27648
	s_waitcnt lgkmcnt(6)
	v_mfma_f32_32x32x16_bf16 v[48:63], v[222:225], v[226:229], v[48:63]
	s_waitcnt vmcnt(7)
	ds_write_b128 v128, v[80:83]
	s_waitcnt lgkmcnt(6)
	v_mfma_f32_32x32x16_bf16 v[32:47], v[222:225], v[230:233], v[32:47]
	s_waitcnt vmcnt(6)
	ds_write_b128 v128, v[84:87] offset:9216
	s_waitcnt lgkmcnt(6)
	v_mfma_f32_32x32x16_bf16 v[16:31], v[234:237], v[226:229], v[16:31]
	v_mfma_f32_32x32x16_bf16 v[0:15], v[234:237], v[230:233], v[0:15]
	s_waitcnt lgkmcnt(0)
	s_barrier
; template <class AS, class EP>
; DEVI void gemm_tile(const AS& as, const u16* __restrict__ Bt, int K, int m0, int n0, const EP& ep, char* lds) {
;     ...
;   GLOAD(ra0, rb0, 0); GLOAD(ra1, rb1, 1); LWRITE(0, ra0, rb0); __syncthreads();
;   for (int kt = 0; kt < KT; kt += 2) {
;     if (kt + 2 < KT) GLOAD(ra0, rb0, kt + 2);
;     __builtin_amdgcn_sched_barrier(0);
;     COMPUTE(0);
;     __builtin_amdgcn_sched_barrier(0);
;     LWRITE(1, ra1, rb1);
;     __syncthreads();
;     if (kt + 3 < KT) GLOAD(ra1, rb1, kt + 3);
;     __builtin_amdgcn_sched_barrier(0);
;     COMPUTE(1);
;     __builtin_amdgcn_sched_barrier(0);
;     if (kt + 2 < KT) LWRITE(0, ra0, rb0);
;     __syncthreads();
;   }
	global_load_dwordx4 v[64:67], v[112:113], off offset:1408
	global_load_dwordx4 v[68:71], v[114:115], off offset:1408
	global_load_dwordx4 v[72:75], v[116:117], off offset:1408
	global_load_dwordx4 v[76:79], v[118:119], off offset:1408
	global_load_dwordx4 v[80:83], v[120:121], off offset:1408
	global_load_dwordx4 v[84:87], v[122:123], off offset:1408
	ds_read_b128 v[170:173], v132 offset:55296
	ds_read_b128 v[174:177], v133
	ds_read_b128 v[178:181], v133 offset:4608
	ds_read_b128 v[182:185], v132 offset:59904
	ds_read_b128 v[186:189], v132 offset:55328
	ds_read_b128 v[190:193], v133 offset:32
	ds_read_b128 v[194:197], v133 offset:4640
	ds_read_b128 v[198:201], v132 offset:59936
	ds_read_b128 v[202:205], v132 offset:55360
	ds_read_b128 v[206:209], v133 offset:64
	ds_read_b128 v[210:213], v133 offset:4672
	ds_read_b128 v[214:217], v132 offset:59968
	s_waitcnt lgkmcnt(10)
	v_mfma_f32_32x32x16_bf16 v[48:63], v[170:173], v[174:177], v[48:63]
	s_waitcnt lgkmcnt(9)
	v_mfma_f32_32x32x16_bf16 v[32:47], v[170:173], v[178:181], v[32:47]
	s_waitcnt lgkmcnt(8)
	v_mfma_f32_32x32x16_bf16 v[16:31], v[182:185], v[174:177], v[16:31]
	v_mfma_f32_32x32x16_bf16 v[0:15], v[182:185], v[178:181], v[0:15]
	ds_read_b128 v[222:225], v132 offset:55392
	ds_read_b128 v[226:229], v133 offset:96
	ds_read_b128 v[230:233], v133 offset:4704
	ds_read_b128 v[234:237], v132 offset:60000
	s_waitcnt lgkmcnt(10)
	v_mfma_f32_32x32x16_bf16 v[48:63], v[186:189], v[190:193], v[48:63]
	s_waitcnt lgkmcnt(9)
	v_mfma_f32_32x32x16_bf16 v[32:47], v[186:189], v[194:197], v[32:47]
	s_waitcnt lgkmcnt(8)
	v_mfma_f32_32x32x16_bf16 v[16:31], v[198:201], v[190:193], v[16:31]
	v_mfma_f32_32x32x16_bf16 v[0:15], v[198:201], v[194:197], v[0:15]
	s_waitcnt vmcnt(11)
	ds_write_b128 v134, v[88:91]
	s_waitcnt lgkmcnt(7)
	v_mfma_f32_32x32x16_bf16 v[48:63], v[202:205], v[206:209], v[48:63]
	s_waitcnt vmcnt(10)
	ds_write_b128 v134, v[92:95] offset:9216
	s_waitcnt lgkmcnt(7)
	v_mfma_f32_32x32x16_bf16 v[32:47], v[202:205], v[210:213], v[32:47]
	s_waitcnt vmcnt(9)
	ds_write_b128 v134, v[96:99] offset:18432
	s_waitcnt lgkmcnt(7)
	v_mfma_f32_32x32x16_bf16 v[16:31], v[214:217], v[206:209], v[16:31]
	v_mfma_f32_32x32x16_bf16 v[0:15], v[214:217], v[210:213], v[0:15]
	s_waitcnt vmcnt(8)
	ds_write_b128 v134, v[100:103] offset:27648
	s_waitcnt lgkmcnt(6)
	v_mfma_f32_32x32x16_bf16 v[48:63], v[222:225], v[226:229], v[48:63]
	s_waitcnt vmcnt(7)
	ds_write_b128 v134, v[104:107] offset:36864
	s_waitcnt lgkmcnt(6)
	v_mfma_f32_32x32x16_bf16 v[32:47], v[222:225], v[230:233], v[32:47]
	s_waitcnt vmcnt(6)
	ds_write_b128 v134, v[108:111] offset:46080
	s_waitcnt lgkmcnt(6)
	v_mfma_f32_32x32x16_bf16 v[16:31], v[234:237], v[226:229], v[16:31]
	v_mfma_f32_32x32x16_bf16 v[0:15], v[234:237], v[230:233], v[0:15]
	s_waitcnt lgkmcnt(0)
	s_barrier
	global_load_dwordx4 v[88:91], v[112:113], off offset:1536
	global_load_dwordx4 v[92:95], v[114:115], off offset:1536
	global_load_dwordx4 v[96:99], v[116:117], off offset:1536
	global_load_dwordx4 v[100:103], v[118:119], off offset:1536
	global_load_dwordx4 v[104:107], v[120:121], off offset:1536
	global_load_dwordx4 v[108:111], v[122:123], off offset:1536
	ds_read_b128 v[170:173], v132
	ds_read_b128 v[174:177], v136 offset:36864
	ds_read_b128 v[178:181], v136 offset:41472
	ds_read_b128 v[182:185], v132 offset:4608
	ds_read_b128 v[186:189], v132 offset:32
	ds_read_b128 v[190:193], v136 offset:36896
	ds_read_b128 v[194:197], v136 offset:41504
	ds_read_b128 v[198:201], v132 offset:4640
	ds_read_b128 v[202:205], v132 offset:64
	ds_read_b128 v[206:209], v136 offset:36928
	ds_read_b128 v[210:213], v136 offset:41536
	ds_read_b128 v[214:217], v132 offset:4672
	s_waitcnt lgkmcnt(10)
	v_mfma_f32_32x32x16_bf16 v[48:63], v[170:173], v[174:177], v[48:63]
	s_waitcnt lgkmcnt(9)
	v_mfma_f32_32x32x16_bf16 v[32:47], v[170:173], v[178:181], v[32:47]
	s_waitcnt lgkmcnt(8)
	v_mfma_f32_32x32x16_bf16 v[16:31], v[182:185], v[174:177], v[16:31]
	v_mfma_f32_32x32x16_bf16 v[0:15], v[182:185], v[178:181], v[0:15]
	ds_read_b128 v[222:225], v132 offset:96
	ds_read_b128 v[226:229], v136 offset:36960
	ds_read_b128 v[230:233], v136 offset:41568
	ds_read_b128 v[234:237], v132 offset:4704
	s_waitcnt lgkmcnt(10)
	v_mfma_f32_32x32x16_bf16 v[48:63], v[186:189], v[190:193], v[48:63]
	s_waitcnt lgkmcnt(9)
	v_mfma_f32_32x32x16_bf16 v[32:47], v[186:189], v[194:197], v[32:47]
	s_waitcnt lgkmcnt(8)
	v_mfma_f32_32x32x16_bf16 v[16:31], v[198:201], v[190:193], v[16:31]
	v_mfma_f32_32x32x16_bf16 v[0:15], v[198:201], v[194:197], v[0:15]
	s_waitcnt vmcnt(11)
	ds_write_b128 v134, v[64:67] offset:55296
	s_waitcnt lgkmcnt(7)
	v_mfma_f32_32x32x16_bf16 v[48:63], v[202:205], v[206:209], v[48:63]
	s_waitcnt vmcnt(10)
	ds_write_b128 v134, v[68:71] offset:64512
	s_waitcnt lgkmcnt(7)
	v_mfma_f32_32x32x16_bf16 v[32:47], v[202:205], v[210:213], v[32:47]
	s_waitcnt vmcnt(9)
	ds_write_b128 v135, v[72:75] offset:18432
	s_waitcnt lgkmcnt(7)
	v_mfma_f32_32x32x16_bf16 v[16:31], v[214:217], v[206:209], v[16:31]
	v_mfma_f32_32x32x16_bf16 v[0:15], v[214:217], v[210:213], v[0:15]
	s_waitcnt vmcnt(8)
	ds_write_b128 v135, v[76:79] offset:27648
	s_waitcnt lgkmcnt(6)
	v_mfma_f32_32x32x16_bf16 v[48:63], v[222:225], v[226:229], v[48:63]
	s_waitcnt vmcnt(7)
	ds_write_b128 v128, v[80:83]
	s_waitcnt lgkmcnt(6)
	v_mfma_f32_32x32x16_bf16 v[32:47], v[222:225], v[230:233], v[32:47]
	s_waitcnt vmcnt(6)
	ds_write_b128 v128, v[84:87] offset:9216
	s_waitcnt lgkmcnt(6)
	v_mfma_f32_32x32x16_bf16 v[16:31], v[234:237], v[226:229], v[16:31]
	v_mfma_f32_32x32x16_bf16 v[0:15], v[234:237], v[230:233], v[0:15]
	s_waitcnt lgkmcnt(0)
	s_barrier
; template <class AS, class EP>
; DEVI void gemm_tile(const AS& as, const u16* __restrict__ Bt, int K, int m0, int n0, const EP& ep, char* lds) {
;     ...
;   GLOAD(ra0, rb0, 0); GLOAD(ra1, rb1, 1); LWRITE(0, ra0, rb0); __syncthreads();
;   for (int kt = 0; kt < KT; kt += 2) {
;     if (kt + 2 < KT) GLOAD(ra0, rb0, kt + 2);
;     __builtin_amdgcn_sched_barrier(0);
;     COMPUTE(0);
;     __builtin_amdgcn_sched_barrier(0);
;     LWRITE(1, ra1, rb1);
;     __syncthreads();
;     if (kt + 3 < KT) GLOAD(ra1, rb1, kt + 3);
;     __builtin_amdgcn_sched_barrier(0);
;     COMPUTE(1);
;     __builtin_amdgcn_sched_barrier(0);
;     if (kt + 2 < KT) LWRITE(0, ra0, rb0);
;     __syncthreads();
;   }
	global_load_dwordx4 v[64:67], v[112:113], off offset:1664
	global_load_dwordx4 v[68:71], v[114:115], off offset:1664
	global_load_dwordx4 v[72:75], v[116:117], off offset:1664
	global_load_dwordx4 v[76:79], v[118:119], off offset:1664
	global_load_dwordx4 v[80:83], v[120:121], off offset:1664
	global_load_dwordx4 v[84:87], v[122:123], off offset:1664
	ds_read_b128 v[170:173], v132 offset:55296
	ds_read_b128 v[174:177], v133
	ds_read_b128 v[178:181], v133 offset:4608
	ds_read_b128 v[182:185], v132 offset:59904
	ds_read_b128 v[186:189], v132 offset:55328
	ds_read_b128 v[190:193], v133 offset:32
	ds_read_b128 v[194:197], v133 offset:4640
	ds_read_b128 v[198:201], v132 offset:59936
	ds_read_b128 v[202:205], v132 offset:55360
	ds_read_b128 v[206:209], v133 offset:64
	ds_read_b128 v[210:213], v133 offset:4672
	ds_read_b128 v[214:217], v132 offset:59968
	s_waitcnt lgkmcnt(10)
	v_mfma_f32_32x32x16_bf16 v[48:63], v[170:173], v[174:177], v[48:63]
	s_waitcnt lgkmcnt(9)
	v_mfma_f32_32x32x16_bf16 v[32:47], v[170:173], v[178:181], v[32:47]
	s_waitcnt lgkmcnt(8)
	v_mfma_f32_32x32x16_bf16 v[16:31], v[182:185], v[174:177], v[16:31]
	v_mfma_f32_32x32x16_bf16 v[0:15], v[182:185], v[178:181], v[0:15]
	ds_read_b128 v[222:225], v132 offset:55392
	ds_read_b128 v[226:229], v133 offset:96
	ds_read_b128 v[230:233], v133 offset:4704
	ds_read_b128 v[234:237], v132 offset:60000
	s_waitcnt lgkmcnt(10)
	v_mfma_f32_32x32x16_bf16 v[48:63], v[186:189], v[190:193], v[48:63]
	s_waitcnt lgkmcnt(9)
	v_mfma_f32_32x32x16_bf16 v[32:47], v[186:189], v[194:197], v[32:47]
	s_waitcnt lgkmcnt(8)
	v_mfma_f32_32x32x16_bf16 v[16:31], v[198:201], v[190:193], v[16:31]
	v_mfma_f32_32x32x16_bf16 v[0:15], v[198:201], v[194:197], v[0:15]
	s_waitcnt vmcnt(11)
	ds_write_b128 v134, v[88:91]
	s_waitcnt lgkmcnt(7)
	v_mfma_f32_32x32x16_bf16 v[48:63], v[202:205], v[206:209], v[48:63]
	s_waitcnt vmcnt(10)
	ds_write_b128 v134, v[92:95] offset:9216
	s_waitcnt lgkmcnt(7)
	v_mfma_f32_32x32x16_bf16 v[32:47], v[202:205], v[210:213], v[32:47]
	s_waitcnt vmcnt(9)
	ds_write_b128 v134, v[96:99] offset:18432
	s_waitcnt lgkmcnt(7)
	v_mfma_f32_32x32x16_bf16 v[16:31], v[214:217], v[206:209], v[16:31]
	v_mfma_f32_32x32x16_bf16 v[0:15], v[214:217], v[210:213], v[0:15]
	s_waitcnt vmcnt(8)
	ds_write_b128 v134, v[100:103] offset:27648
	s_waitcnt lgkmcnt(6)
	v_mfma_f32_32x32x16_bf16 v[48:63], v[222:225], v[226:229], v[48:63]
	s_waitcnt vmcnt(7)
	ds_write_b128 v134, v[104:107] offset:36864
	s_waitcnt lgkmcnt(6)
	v_mfma_f32_32x32x16_bf16 v[32:47], v[222:225], v[230:233], v[32:47]
	s_waitcnt vmcnt(6)
	ds_write_b128 v134, v[108:111] offset:46080
	s_waitcnt lgkmcnt(6)
	v_mfma_f32_32x32x16_bf16 v[16:31], v[234:237], v[226:229], v[16:31]
	v_mfma_f32_32x32x16_bf16 v[0:15], v[234:237], v[230:233], v[0:15]
	s_waitcnt lgkmcnt(0)
	s_barrier
	global_load_dwordx4 v[88:91], v[112:113], off offset:1792
	global_load_dwordx4 v[92:95], v[114:115], off offset:1792
	global_load_dwordx4 v[96:99], v[116:117], off offset:1792
	global_load_dwordx4 v[100:103], v[118:119], off offset:1792
	global_load_dwordx4 v[104:107], v[120:121], off offset:1792
	global_load_dwordx4 v[108:111], v[122:123], off offset:1792
	ds_read_b128 v[170:173], v132
	ds_read_b128 v[174:177], v136 offset:36864
	ds_read_b128 v[178:181], v136 offset:41472
	ds_read_b128 v[182:185], v132 offset:4608
	ds_read_b128 v[186:189], v132 offset:32
	ds_read_b128 v[190:193], v136 offset:36896
	ds_read_b128 v[194:197], v136 offset:41504
	ds_read_b128 v[198:201], v132 offset:4640
	ds_read_b128 v[202:205], v132 offset:64
	ds_read_b128 v[206:209], v136 offset:36928
	ds_read_b128 v[210:213], v136 offset:41536
	ds_read_b128 v[214:217], v132 offset:4672
	s_waitcnt lgkmcnt(10)
	v_mfma_f32_32x32x16_bf16 v[48:63], v[170:173], v[174:177], v[48:63]
	s_waitcnt lgkmcnt(9)
	v_mfma_f32_32x32x16_bf16 v[32:47], v[170:173], v[178:181], v[32:47]
	s_waitcnt lgkmcnt(8)
	v_mfma_f32_32x32x16_bf16 v[16:31], v[182:185], v[174:177], v[16:31]
	v_mfma_f32_32x32x16_bf16 v[0:15], v[182:185], v[178:181], v[0:15]
	ds_read_b128 v[222:225], v132 offset:96
	ds_read_b128 v[226:229], v136 offset:36960
	ds_read_b128 v[230:233], v136 offset:41568
	ds_read_b128 v[234:237], v132 offset:4704
	s_waitcnt lgkmcnt(10)
	v_mfma_f32_32x32x16_bf16 v[48:63], v[186:189], v[190:193], v[48:63]
	s_waitcnt lgkmcnt(9)
	v_mfma_f32_32x32x16_bf16 v[32:47], v[186:189], v[194:197], v[32:47]
	s_waitcnt lgkmcnt(8)
	v_mfma_f32_32x32x16_bf16 v[16:31], v[198:201], v[190:193], v[16:31]
	v_mfma_f32_32x32x16_bf16 v[0:15], v[198:201], v[194:197], v[0:15]
	s_waitcnt vmcnt(11)
	ds_write_b128 v134, v[64:67] offset:55296
	s_waitcnt lgkmcnt(7)
	v_mfma_f32_32x32x16_bf16 v[48:63], v[202:205], v[206:209], v[48:63]
	s_waitcnt vmcnt(10)
	ds_write_b128 v134, v[68:71] offset:64512
	s_waitcnt lgkmcnt(7)
	v_mfma_f32_32x32x16_bf16 v[32:47], v[202:205], v[210:213], v[32:47]
	s_waitcnt vmcnt(9)
	ds_write_b128 v135, v[72:75] offset:18432
	s_waitcnt lgkmcnt(7)
	v_mfma_f32_32x32x16_bf16 v[16:31], v[214:217], v[206:209], v[16:31]
	v_mfma_f32_32x32x16_bf16 v[0:15], v[214:217], v[210:213], v[0:15]
	s_waitcnt vmcnt(8)
	ds_write_b128 v135, v[76:79] offset:27648
	s_waitcnt lgkmcnt(6)
	v_mfma_f32_32x32x16_bf16 v[48:63], v[222:225], v[226:229], v[48:63]
	s_waitcnt vmcnt(7)
	ds_write_b128 v128, v[80:83]
	s_waitcnt lgkmcnt(6)
	v_mfma_f32_32x32x16_bf16 v[32:47], v[222:225], v[230:233], v[32:47]
	s_waitcnt vmcnt(6)
	ds_write_b128 v128, v[84:87] offset:9216
	s_waitcnt lgkmcnt(6)
	v_mfma_f32_32x32x16_bf16 v[16:31], v[234:237], v[226:229], v[16:31]
	v_mfma_f32_32x32x16_bf16 v[0:15], v[234:237], v[230:233], v[0:15]
	s_waitcnt lgkmcnt(0)
	s_barrier
; template <class AS, class EP>
; DEVI void gemm_tile(const AS& as, const u16* __restrict__ Bt, int K, int m0, int n0, const EP& ep, char* lds) {
;     ...
;   GLOAD(ra0, rb0, 0); GLOAD(ra1, rb1, 1); LWRITE(0, ra0, rb0); __syncthreads();
;   for (int kt = 0; kt < KT; kt += 2) {
;     if (kt + 2 < KT) GLOAD(ra0, rb0, kt + 2);
;     __builtin_amdgcn_sched_barrier(0);
;     COMPUTE(0);
;     __builtin_amdgcn_sched_barrier(0);
;     LWRITE(1, ra1, rb1);
;     __syncthreads();
;     if (kt + 3 < KT) GLOAD(ra1, rb1, kt + 3);
;     __builtin_amdgcn_sched_barrier(0);
;     COMPUTE(1);
;     __builtin_amdgcn_sched_barrier(0);
;     if (kt + 2 < KT) LWRITE(0, ra0, rb0);
;     __syncthreads();
;   }
	global_load_dwordx4 v[64:67], v[112:113], off offset:1920
	global_load_dwordx4 v[68:71], v[114:115], off offset:1920
	global_load_dwordx4 v[72:75], v[116:117], off offset:1920
	global_load_dwordx4 v[76:79], v[118:119], off offset:1920
	global_load_dwordx4 v[80:83], v[120:121], off offset:1920
	global_load_dwordx4 v[84:87], v[122:123], off offset:1920
	ds_read_b128 v[170:173], v132 offset:55296
	ds_read_b128 v[174:177], v133
	ds_read_b128 v[178:181], v133 offset:4608
	ds_read_b128 v[182:185], v132 offset:59904
	ds_read_b128 v[186:189], v132 offset:55328
	ds_read_b128 v[190:193], v133 offset:32
	ds_read_b128 v[194:197], v133 offset:4640
	ds_read_b128 v[198:201], v132 offset:59936
	ds_read_b128 v[202:205], v132 offset:55360
	ds_read_b128 v[206:209], v133 offset:64
	ds_read_b128 v[210:213], v133 offset:4672
	ds_read_b128 v[214:217], v132 offset:59968
	s_waitcnt lgkmcnt(10)
	v_mfma_f32_32x32x16_bf16 v[48:63], v[170:173], v[174:177], v[48:63]
	s_waitcnt lgkmcnt(9)
	v_mfma_f32_32x32x16_bf16 v[32:47], v[170:173], v[178:181], v[32:47]
	s_waitcnt lgkmcnt(8)
	v_mfma_f32_32x32x16_bf16 v[16:31], v[182:185], v[174:177], v[16:31]
	v_mfma_f32_32x32x16_bf16 v[0:15], v[182:185], v[178:181], v[0:15]
	ds_read_b128 v[222:225], v132 offset:55392
	ds_read_b128 v[226:229], v133 offset:96
	ds_read_b128 v[230:233], v133 offset:4704
	ds_read_b128 v[234:237], v132 offset:60000
	s_waitcnt lgkmcnt(10)
	v_mfma_f32_32x32x16_bf16 v[48:63], v[186:189], v[190:193], v[48:63]
	s_waitcnt lgkmcnt(9)
	v_mfma_f32_32x32x16_bf16 v[32:47], v[186:189], v[194:197], v[32:47]
	s_waitcnt lgkmcnt(8)
	v_mfma_f32_32x32x16_bf16 v[16:31], v[198:201], v[190:193], v[16:31]
	v_mfma_f32_32x32x16_bf16 v[0:15], v[198:201], v[194:197], v[0:15]
	s_waitcnt vmcnt(11)
	ds_write_b128 v134, v[88:91]
	s_waitcnt lgkmcnt(7)
	v_mfma_f32_32x32x16_bf16 v[48:63], v[202:205], v[206:209], v[48:63]
	s_waitcnt vmcnt(10)
	ds_write_b128 v134, v[92:95] offset:9216
	s_waitcnt lgkmcnt(7)
	v_mfma_f32_32x32x16_bf16 v[32:47], v[202:205], v[210:213], v[32:47]
	s_waitcnt vmcnt(9)
	ds_write_b128 v134, v[96:99] offset:18432
	s_waitcnt lgkmcnt(7)
	v_mfma_f32_32x32x16_bf16 v[16:31], v[214:217], v[206:209], v[16:31]
	v_mfma_f32_32x32x16_bf16 v[0:15], v[214:217], v[210:213], v[0:15]
	s_waitcnt vmcnt(8)
	ds_write_b128 v134, v[100:103] offset:27648
	s_waitcnt lgkmcnt(6)
	v_mfma_f32_32x32x16_bf16 v[48:63], v[222:225], v[226:229], v[48:63]
	s_waitcnt vmcnt(7)
	ds_write_b128 v134, v[104:107] offset:36864
	s_waitcnt lgkmcnt(6)
	v_mfma_f32_32x32x16_bf16 v[32:47], v[222:225], v[230:233], v[32:47]
	s_waitcnt vmcnt(6)
	ds_write_b128 v134, v[108:111] offset:46080
	s_waitcnt lgkmcnt(6)
	v_mfma_f32_32x32x16_bf16 v[16:31], v[234:237], v[226:229], v[16:31]
	v_mfma_f32_32x32x16_bf16 v[0:15], v[234:237], v[230:233], v[0:15]
	s_waitcnt lgkmcnt(0)
	s_barrier
	ds_read_b128 v[170:173], v132
	ds_read_b128 v[174:177], v136 offset:36864
	ds_read_b128 v[178:181], v136 offset:41472
	ds_read_b128 v[182:185], v132 offset:4608
	ds_read_b128 v[186:189], v132 offset:32
	ds_read_b128 v[190:193], v136 offset:36896
	ds_read_b128 v[194:197], v136 offset:41504
	ds_read_b128 v[198:201], v132 offset:4640
	ds_read_b128 v[202:205], v132 offset:64
	ds_read_b128 v[206:209], v136 offset:36928
	ds_read_b128 v[210:213], v136 offset:41536
	ds_read_b128 v[214:217], v132 offset:4672
	s_waitcnt lgkmcnt(10)
	v_mfma_f32_32x32x16_bf16 v[48:63], v[170:173], v[174:177], v[48:63]
	s_waitcnt lgkmcnt(9)
	v_mfma_f32_32x32x16_bf16 v[32:47], v[170:173], v[178:181], v[32:47]
	s_waitcnt lgkmcnt(8)
	v_mfma_f32_32x32x16_bf16 v[16:31], v[182:185], v[174:177], v[16:31]
	v_mfma_f32_32x32x16_bf16 v[0:15], v[182:185], v[178:181], v[0:15]
	ds_read_b128 v[222:225], v132 offset:96
	ds_read_b128 v[226:229], v136 offset:36960
	ds_read_b128 v[230:233], v136 offset:41568
	ds_read_b128 v[234:237], v132 offset:4704
	s_waitcnt lgkmcnt(10)
	v_mfma_f32_32x32x16_bf16 v[48:63], v[186:189], v[190:193], v[48:63]
	s_waitcnt lgkmcnt(9)
	v_mfma_f32_32x32x16_bf16 v[32:47], v[186:189], v[194:197], v[32:47]
	s_waitcnt lgkmcnt(8)
	v_mfma_f32_32x32x16_bf16 v[16:31], v[198:201], v[190:193], v[16:31]
	v_mfma_f32_32x32x16_bf16 v[0:15], v[198:201], v[194:197], v[0:15]
	s_waitcnt vmcnt(5)
	ds_write_b128 v134, v[64:67] offset:55296
	s_waitcnt lgkmcnt(7)
	v_mfma_f32_32x32x16_bf16 v[48:63], v[202:205], v[206:209], v[48:63]
	s_waitcnt vmcnt(4)
	ds_write_b128 v134, v[68:71] offset:64512
	s_waitcnt lgkmcnt(7)
	v_mfma_f32_32x32x16_bf16 v[32:47], v[202:205], v[210:213], v[32:47]
	s_waitcnt vmcnt(3)
	ds_write_b128 v135, v[72:75] offset:18432
	s_waitcnt lgkmcnt(7)
	v_mfma_f32_32x32x16_bf16 v[16:31], v[214:217], v[206:209], v[16:31]
	v_mfma_f32_32x32x16_bf16 v[0:15], v[214:217], v[210:213], v[0:15]
	s_waitcnt vmcnt(2)
	ds_write_b128 v135, v[76:79] offset:27648
	s_waitcnt lgkmcnt(6)
	v_mfma_f32_32x32x16_bf16 v[48:63], v[222:225], v[226:229], v[48:63]
	s_waitcnt vmcnt(1)
	ds_write_b128 v128, v[80:83]
	s_waitcnt lgkmcnt(6)
	v_mfma_f32_32x32x16_bf16 v[32:47], v[222:225], v[230:233], v[32:47]
	s_waitcnt vmcnt(0)
	ds_write_b128 v128, v[84:87] offset:9216
	s_waitcnt lgkmcnt(6)
	v_mfma_f32_32x32x16_bf16 v[16:31], v[234:237], v[226:229], v[16:31]
	v_mfma_f32_32x32x16_bf16 v[0:15], v[234:237], v[230:233], v[0:15]
	s_waitcnt lgkmcnt(0)
	s_barrier
; DEVI int crow(int r, int hi) { return (r & 3) + 8 * (r >> 2) + 4 * hi; }
;   DEVI void operator()(const f32x16 (&acc)[2][2], int m0, int n0, int wm, int wn, int r32, int hi, char* lds) const {
;     constexpr int RS = 272;
; #pragma unroll
;     for (int i = 0; i < 2; ++i)
; #pragma unroll
;       for (int j = 0; j < 2; ++j)
; #pragma unroll
;         for (int r = 0; r < 16; ++r) {
;           int row = wm * 64 + i * 32 + crow(r, hi), col = wn * 64 + j * 32 + r32;
;           *(h16*)(lds + row * RS + col * 2) = (h16)acc[i][j][r];
;         }
;     __syncthreads();
	ds_read_b128 v[170:173], v132 offset:55296
	ds_read_b128 v[174:177], v133
	ds_read_b128 v[178:181], v133 offset:4608
	ds_read_b128 v[182:185], v132 offset:59904
	ds_read_b128 v[186:189], v132 offset:55328
	ds_read_b128 v[190:193], v133 offset:32
	ds_read_b128 v[194:197], v133 offset:4640
	ds_read_b128 v[198:201], v132 offset:59936
	ds_read_b128 v[202:205], v132 offset:55360
	ds_read_b128 v[206:209], v133 offset:64
	ds_read_b128 v[210:213], v133 offset:4672
	ds_read_b128 v[214:217], v132 offset:59968
	s_waitcnt lgkmcnt(10)
	v_mfma_f32_32x32x16_bf16 v[48:63], v[170:173], v[174:177], v[48:63]
	s_waitcnt lgkmcnt(9)
	v_mfma_f32_32x32x16_bf16 v[32:47], v[170:173], v[178:181], v[32:47]
	s_waitcnt lgkmcnt(8)
	v_mfma_f32_32x32x16_bf16 v[16:31], v[182:185], v[174:177], v[16:31]
	v_mfma_f32_32x32x16_bf16 v[0:15], v[182:185], v[178:181], v[0:15]
	ds_read_b128 v[222:225], v132 offset:55392
	ds_read_b128 v[226:229], v133 offset:96
	ds_read_b128 v[230:233], v133 offset:4704
	ds_read_b128 v[234:237], v132 offset:60000
	s_waitcnt lgkmcnt(10)
	v_mfma_f32_32x32x16_bf16 v[48:63], v[186:189], v[190:193], v[48:63]
	s_waitcnt lgkmcnt(9)
	v_mfma_f32_32x32x16_bf16 v[32:47], v[186:189], v[194:197], v[32:47]
	s_waitcnt lgkmcnt(8)
	v_mfma_f32_32x32x16_bf16 v[16:31], v[198:201], v[190:193], v[16:31]
	v_mfma_f32_32x32x16_bf16 v[0:15], v[198:201], v[194:197], v[0:15]
	s_waitcnt lgkmcnt(6)
	v_mfma_f32_32x32x16_bf16 v[48:63], v[202:205], v[206:209], v[48:63]
	s_waitcnt lgkmcnt(5)
	v_mfma_f32_32x32x16_bf16 v[32:47], v[202:205], v[210:213], v[32:47]
	s_waitcnt lgkmcnt(4)
	v_mfma_f32_32x32x16_bf16 v[16:31], v[214:217], v[206:209], v[16:31]
	v_mfma_f32_32x32x16_bf16 v[0:15], v[214:217], v[210:213], v[0:15]
	s_waitcnt lgkmcnt(2)
	v_mfma_f32_32x32x16_bf16 v[48:63], v[222:225], v[226:229], v[48:63]
	s_waitcnt lgkmcnt(1)
	v_mfma_f32_32x32x16_bf16 v[32:47], v[222:225], v[230:233], v[32:47]
	s_waitcnt lgkmcnt(0)
	v_mfma_f32_32x32x16_bf16 v[16:31], v[234:237], v[226:229], v[16:31]
	v_mfma_f32_32x32x16_bf16 v[0:15], v[234:237], v[230:233], v[0:15]
	s_nop 5
	v_cvt_f16_f32_e32 v48, v48
	v_lshl_or_b32 v64, v124, 2, v127
	v_cvt_f16_f32_e32 v49, v49
	v_lshlrev_b32_e32 v65, 1, v125
	v_lshl_add_u32 v66, v126, 7, 16
	v_mul_lo_u32 v64, v64, s27
	v_cvt_f16_f32_e32 v50, v50
	v_add3_u32 v64, v66, v65, v64
	v_cvt_f16_f32_e32 v51, v51
	s_barrier
	ds_write_b16 v64, v48
	ds_write_b16 v64, v49 offset:272
	ds_write_b16 v64, v50 offset:544
	ds_write_b16 v64, v51 offset:816
	v_cvt_f16_f32_e32 v48, v52
	v_cvt_f16_f32_e32 v49, v53
	v_cvt_f16_f32_e32 v50, v54
	v_cvt_f16_f32_e32 v51, v55
	ds_write_b16 v64, v48 offset:2176
	ds_write_b16 v64, v49 offset:2448
	ds_write_b16 v64, v50 offset:2720
	ds_write_b16 v64, v51 offset:2992
	v_cvt_f16_f32_e32 v48, v56
	v_cvt_f16_f32_e32 v49, v57
	v_cvt_f16_f32_e32 v50, v58
	v_cvt_f16_f32_e32 v51, v59
	ds_write_b16 v64, v48 offset:4352
	ds_write_b16 v64, v49 offset:4624
	ds_write_b16 v64, v50 offset:4896
	ds_write_b16 v64, v51 offset:5168
	v_cvt_f16_f32_e32 v48, v60
	v_cvt_f16_f32_e32 v32, v32
	v_cvt_f16_f32_e32 v49, v61
	v_cvt_f16_f32_e32 v33, v33
	v_cvt_f16_f32_e32 v50, v62
	v_cvt_f16_f32_e32 v34, v34
	v_cvt_f16_f32_e32 v51, v63
	v_cvt_f16_f32_e32 v35, v35
	ds_write_b16 v64, v48 offset:6528
	ds_write_b16 v64, v49 offset:6800
	ds_write_b16 v64, v50 offset:7072
	ds_write_b16 v64, v51 offset:7344
	ds_write_b16 v64, v32 offset:64
	ds_write_b16 v64, v33 offset:336
	ds_write_b16 v64, v34 offset:608
	ds_write_b16 v64, v35 offset:880
	v_cvt_f16_f32_e32 v32, v36
	v_cvt_f16_f32_e32 v33, v37
	v_cvt_f16_f32_e32 v34, v38
	v_cvt_f16_f32_e32 v35, v39
	ds_write_b16 v64, v32 offset:2240
	ds_write_b16 v64, v33 offset:2512
	ds_write_b16 v64, v34 offset:2784
	ds_write_b16 v64, v35 offset:3056
	v_cvt_f16_f32_e32 v32, v40
	v_cvt_f16_f32_e32 v33, v41
	v_cvt_f16_f32_e32 v34, v42
	v_cvt_f16_f32_e32 v35, v43
	ds_write_b16 v64, v32 offset:4416
	ds_write_b16 v64, v33 offset:4688
	ds_write_b16 v64, v34 offset:4960
	ds_write_b16 v64, v35 offset:5232
	v_cvt_f16_f32_e32 v32, v44
	v_cvt_f16_f32_e32 v16, v16
	v_cvt_f16_f32_e32 v33, v45
	v_cvt_f16_f32_e32 v17, v17
	v_cvt_f16_f32_e32 v34, v46
	v_cvt_f16_f32_e32 v18, v18
	v_cvt_f16_f32_e32 v35, v47
	v_cvt_f16_f32_e32 v19, v19
	ds_write_b16 v64, v32 offset:6592
	ds_write_b16 v64, v33 offset:6864
	ds_write_b16 v64, v34 offset:7136
	ds_write_b16 v64, v35 offset:7408
	ds_write_b16 v64, v16 offset:8704
	ds_write_b16 v64, v17 offset:8976
	ds_write_b16 v64, v18 offset:9248
	ds_write_b16 v64, v19 offset:9520
	v_cvt_f16_f32_e32 v16, v20
	v_cvt_f16_f32_e32 v17, v21
	v_cvt_f16_f32_e32 v18, v22
	v_cvt_f16_f32_e32 v19, v23
	ds_write_b16 v64, v16 offset:10880
	ds_write_b16 v64, v17 offset:11152
	ds_write_b16 v64, v18 offset:11424
	ds_write_b16 v64, v19 offset:11696
	v_cvt_f16_f32_e32 v16, v24
	v_cvt_f16_f32_e32 v17, v25
	v_cvt_f16_f32_e32 v18, v26
	v_cvt_f16_f32_e32 v19, v27
	ds_write_b16 v64, v16 offset:13056
	ds_write_b16 v64, v17 offset:13328
	ds_write_b16 v64, v18 offset:13600
	ds_write_b16 v64, v19 offset:13872
	v_cvt_f16_f32_e32 v16, v28
	v_cvt_f16_f32_e32 v0, v0
	v_cvt_f16_f32_e32 v17, v29
	v_cvt_f16_f32_e32 v1, v1
	v_cvt_f16_f32_e32 v18, v30
	v_cvt_f16_f32_e32 v2, v2
	v_cvt_f16_f32_e32 v19, v31
	v_cvt_f16_f32_e32 v3, v3
	ds_write_b16 v64, v16 offset:15232
	ds_write_b16 v64, v17 offset:15504
	ds_write_b16 v64, v18 offset:15776
	ds_write_b16 v64, v19 offset:16048
	ds_write_b16 v64, v0 offset:8768
	ds_write_b16 v64, v1 offset:9040
	ds_write_b16 v64, v2 offset:9312
	ds_write_b16 v64, v3 offset:9584
	v_cvt_f16_f32_e32 v0, v4
	v_cvt_f16_f32_e32 v1, v5
	v_cvt_f16_f32_e32 v2, v6
	v_cvt_f16_f32_e32 v3, v7
	ds_write_b16 v64, v0 offset:10944
	ds_write_b16 v64, v1 offset:11216
	ds_write_b16 v64, v2 offset:11488
	ds_write_b16 v64, v3 offset:11760
	v_cvt_f16_f32_e32 v0, v8
	v_cvt_f16_f32_e32 v1, v9
	v_cvt_f16_f32_e32 v2, v10
	v_cvt_f16_f32_e32 v3, v11
	ds_write_b16 v64, v0 offset:13120
	ds_write_b16 v64, v1 offset:13392
	ds_write_b16 v64, v2 offset:13664
	ds_write_b16 v64, v3 offset:13936
	v_cvt_f16_f32_e32 v0, v12
	v_cvt_f16_f32_e32 v1, v13
	v_cvt_f16_f32_e32 v2, v14
	v_cvt_f16_f32_e32 v3, v15
	ds_write_b16 v64, v0 offset:15296
	ds_write_b16 v64, v1 offset:15568
	ds_write_b16 v64, v2 offset:15840
	ds_write_b16 v64, v3 offset:16112
	v_mov_b32_e32 v2, v131
	s_waitcnt lgkmcnt(0)
	s_barrier
; DEVI int ltid() { int t = __builtin_amdgcn_workitem_id_x(); asm volatile("" : "+v"(t)); return t; }
;   DEVI void operator()(const f32x16 (&acc)[2][2], int m0, int n0, int wm, int wn, int r32, int hi, char* lds) const {
;     ...
;     const int tid = ltid();
; #pragma unroll
;     for (int i = 0; i < 8; ++i) {
;       int c = tid + i * 512; int row = c >> 4, ch = c & 15;
;       int col = n0 + ch * 8;
;       if (col < nvalid) *(u32x4*)(Z + (size_t)(m0 + row) * ldz + col) = *(const u32x4*)(lds + row * RS + ch * 16);
;     }
;     __syncthreads();
	s_nop 0
	v_and_b32_e32 v3, 15, v2
	v_lshlrev_b32_e32 v0, 3, v3
	v_subrev_u32_e32 v0, s10, v0
	v_add_u32_e32 v0, s13, v0
	s_movk_i32 s10, 0x5e0
	v_cmp_gt_i32_e32 vcc, s10, v0
	s_and_saveexec_b64 s[10:11], vcc
	s_cbranch_execz .LBB0_809
	v_lshl_add_u32 v8, v3, 4, 16
	v_ashrrev_i32_e32 v3, 4, v2
	v_mad_u64_u32 v[4:5], s[16:17], v3, s27, v[8:9]
	ds_read_b128 v[4:7], v4
	v_ashrrev_i32_e32 v1, 31, v0
	v_add_u32_e32 v3, s14, v3
	v_mov_b64_e32 v[10:11], s[6:7]
	v_mad_i64_i32 v[12:13], s[16:17], v3, s23, v[10:11]
	v_lshlrev_b64 v[14:15], 1, v[0:1]
	v_lshl_add_u64 v[0:1], v[12:13], 0, v[14:15]
	s_waitcnt lgkmcnt(0)
	global_store_dwordx4 v[0:1], v[4:7], off
	v_add_u32_e32 v0, 0x200, v2
	v_ashrrev_i32_e32 v3, 4, v0
	v_mad_u64_u32 v[0:1], s[16:17], v3, s27, v[8:9]
	ds_read_b128 v[4:7], v0
	v_add_u32_e32 v0, s14, v3
	v_mad_i64_i32 v[0:1], s[16:17], v0, s23, v[10:11]
	v_lshl_add_u64 v[0:1], v[0:1], 0, v[14:15]
	s_waitcnt lgkmcnt(0)
	global_store_dwordx4 v[0:1], v[4:7], off
	v_add_u32_e32 v0, 0x400, v2
	v_ashrrev_i32_e32 v3, 4, v0
	v_mad_u64_u32 v[0:1], s[16:17], v3, s27, v[8:9]
	ds_read_b128 v[4:7], v0
	v_add_u32_e32 v0, s14, v3
	v_mad_i64_i32 v[0:1], s[16:17], v0, s23, v[10:11]
	v_lshl_add_u64 v[0:1], v[0:1], 0, v[14:15]
	s_waitcnt lgkmcnt(0)
	global_store_dwordx4 v[0:1], v[4:7], off
	v_add_u32_e32 v0, 0x600, v2
	v_ashrrev_i32_e32 v3, 4, v0
	v_mad_u64_u32 v[0:1], s[16:17], v3, s27, v[8:9]
	ds_read_b128 v[4:7], v0
	v_add_u32_e32 v0, s14, v3
	v_mad_i64_i32 v[0:1], s[16:17], v0, s23, v[10:11]
	v_lshl_add_u64 v[0:1], v[0:1], 0, v[14:15]
	s_waitcnt lgkmcnt(0)
	global_store_dwordx4 v[0:1], v[4:7], off
	v_add_u32_e32 v0, 0x800, v2
	v_ashrrev_i32_e32 v3, 4, v0
	v_mad_u64_u32 v[0:1], s[16:17], v3, s27, v[8:9]
	ds_read_b128 v[4:7], v0
	v_add_u32_e32 v0, s14, v3
	v_mad_i64_i32 v[0:1], s[16:17], v0, s23, v[10:11]
	v_lshl_add_u64 v[0:1], v[0:1], 0, v[14:15]
	s_waitcnt lgkmcnt(0)
	global_store_dwordx4 v[0:1], v[4:7], off
	v_add_u32_e32 v0, 0xa00, v2
	v_ashrrev_i32_e32 v3, 4, v0
	v_mad_u64_u32 v[0:1], s[16:17], v3, s27, v[8:9]
	ds_read_b128 v[4:7], v0
	v_add_u32_e32 v0, s14, v3
	v_mad_i64_i32 v[0:1], s[16:17], v0, s23, v[10:11]
	v_lshl_add_u64 v[0:1], v[0:1], 0, v[14:15]
	s_waitcnt lgkmcnt(0)
	global_store_dwordx4 v[0:1], v[4:7], off
	v_add_u32_e32 v0, 0xc00, v2
	v_ashrrev_i32_e32 v3, 4, v0
	v_mad_u64_u32 v[0:1], s[16:17], v3, s27, v[8:9]
	ds_read_b128 v[4:7], v0
	v_add_u32_e32 v0, s14, v3
	v_mad_i64_i32 v[0:1], s[16:17], v0, s23, v[10:11]
	v_lshl_add_u64 v[0:1], v[0:1], 0, v[14:15]
	s_waitcnt lgkmcnt(0)
	global_store_dwordx4 v[0:1], v[4:7], off
	v_add_u32_e32 v0, 0xe00, v2
	s_nop 0
	v_ashrrev_i32_e32 v4, 4, v0
	v_mad_u64_u32 v[0:1], s[16:17], v4, s27, v[8:9]
	ds_read_b128 v[0:3], v0
	v_add_u32_e32 v4, s14, v4
	v_mad_i64_i32 v[4:5], s[14:15], v4, s23, v[10:11]
	v_lshl_add_u64 v[4:5], v[4:5], 0, v[14:15]
	s_waitcnt lgkmcnt(0)
	global_store_dwordx4 v[4:5], v[0:3], off
	s_branch .LBB0_809

; DEVI int ltid() { int t = __builtin_amdgcn_workitem_id_x(); asm volatile("" : "+v"(t)); return t; }
; DEVI int lbid() { int t = __builtin_amdgcn_workgroup_id_x(); asm volatile("" : "+s"(t)); return t; }
; template <class AS, class EP>
; DEVI void gemm_tile(const AS& as, const u16* __restrict__ Bt, int K, int m0, int n0, const EP& ep, char* lds) {
;   const int tid = ltid(), wid = tid >> 6, lane = tid & 63, r32 = lane & 31, hi = lane >> 5;
;   const int wm = wid >> 1, wn = wid & 1;
;   constexpr int RS = 144, ABYTES = 256 * RS, STAGE = ABYTES + 128 * RS;
;   f32x16 acc[2][2];
; #pragma unroll
;   for (int i = 0; i < 2; ++i)
; #pragma unroll
;     for (int j = 0; j < 2; ++j)
; #pragma unroll
;       for (int r = 0; r < 16; ++r) acc[i][j][r] = 0.f;
;   const int KT = K >> 6;
;   u32x4 ra0[4], rb0[2], ra1[4], rb1[2];
;   const int srow = tid >> 3, sch = tid & 7;
;     ...
;   GLOAD(ra0, rb0, 0); GLOAD(ra1, rb1, 1); LWRITE(0, ra0, rb0); __syncthreads();
;   for (int kt = 0; kt < KT; kt += 2) {
;     if (kt + 2 < KT) GLOAD(ra0, rb0, kt + 2);
;     __builtin_amdgcn_sched_barrier(0);
;     COMPUTE(0);
;     __builtin_amdgcn_sched_barrier(0);
;     LWRITE(1, ra1, rb1);
;     __syncthreads();
;     if (kt + 3 < KT) GLOAD(ra1, rb1, kt + 3);
;     __builtin_amdgcn_sched_barrier(0);
;     COMPUTE(1);
;     __builtin_amdgcn_sched_barrier(0);
;     if (kt + 2 < KT) LWRITE(0, ra0, rb0);
;     __syncthreads();
;   }
; template <class AS, class EP>
; DEVI void gemm_phase(const AS& as, const u16* Bt, int K, int mtiles, int ntiles, const EP& ep, char* lds) {
;   const int total = mtiles * ntiles;
;   if ((gridDim.x & 7) == 0 && (mtiles & 7) == 0) {
;     const int x = lbid() & 7, j = lbid() >> 3, nb = gridDim.x >> 3, ltot = (mtiles >> 3) * ntiles;
;     for (int lt = j; lt < ltot; lt += nb) {
;       int mt = (lt / ntiles) * 8 + x, nt = lt % ntiles;
;       gemm_tile(as, Bt, K, mt * 256, nt * 128, ep, lds);
.LBB0_817:
	s_mul_hi_i32 s10, s12, 0x2aaaaaab
	s_lshr_b32 s11, s10, 31
	s_ashr_i32 s10, s10, 1
	s_add_i32 s10, s10, s11
	s_lshl_b32 s11, s10, 11
	v_mov_b32_e32 v36, v131
	s_or_b32 s16, s11, s13
	s_mulk_i32 s10, 0x600
	v_ashrrev_i32_e32 v37, 3, v36
	v_add_u32_e32 v0, s16, v37
	v_lshlrev_b32_e32 v1, 4, v36
	v_and_b32_e32 v128, 0x70, v1
	v_ashrrev_i32_e32 v1, 31, v0
	v_lshl_add_u64 v[12:13], s[0:1], 0, v[128:129]
	v_lshlrev_b64 v[24:25], 11, v[0:1]
	s_mov_b64 s[18:19], 0x20000
	v_subrev_u32_e32 v16, s10, v37
	v_lshl_add_u64 v[112:113], v[12:13], 0, v[24:25]
	v_lshl_add_u64 v[26:27], v[24:25], 0, s[18:19]
	s_mov_b64 s[18:19], 0x40000
	v_add_u32_e32 v20, s14, v16
	global_load_dwordx4 v[0:3], v[112:113], off
	v_lshl_add_u64 v[114:115], v[12:13], 0, v[26:27]
	v_lshl_add_u64 v[28:29], v[24:25], 0, s[18:19]
	s_mov_b64 s[18:19], 0x60000
	v_ashrrev_i32_e32 v21, 31, v20
	global_load_dwordx4 v[4:7], v[114:115], off
	v_lshl_add_u64 v[116:117], v[12:13], 0, v[28:29]
	v_lshl_add_u64 v[30:31], v[24:25], 0, s[18:19]
	v_lshlrev_b64 v[32:33], 11, v[20:21]
	v_add_u32_e32 v20, 64, v20
	global_load_dwordx4 v[8:11], v[116:117], off
	v_lshl_add_u64 v[118:119], v[12:13], 0, v[30:31]
	v_lshl_add_u64 v[22:23], s[8:9], 0, v[128:129]
	v_ashrrev_i32_e32 v21, 31, v20
	global_load_dwordx4 v[12:15], v[118:119], off
	v_lshl_add_u64 v[120:121], v[22:23], 0, v[32:33]
	v_lshlrev_b64 v[34:35], 11, v[20:21]
	global_load_dwordx4 v[16:19], v[120:121], off
	v_lshl_add_u64 v[122:123], v[22:23], 0, v[34:35]
	global_load_dwordx4 v[20:23], v[122:123], off
	v_lshl_add_u64 v[24:25], s[0:1], 0, v[24:25]
	v_lshl_add_u64 v[24:25], v[24:25], 0, v[128:129]
	global_load_dwordx4 v[64:67], v[24:25], off offset:128
	v_lshl_add_u64 v[24:25], s[0:1], 0, v[26:27]
	v_lshl_add_u64 v[24:25], v[24:25], 0, v[128:129]
	global_load_dwordx4 v[68:71], v[24:25], off offset:128
	v_lshl_add_u64 v[24:25], s[0:1], 0, v[28:29]
	v_lshl_add_u64 v[24:25], v[24:25], 0, v[128:129]
	global_load_dwordx4 v[72:75], v[24:25], off offset:128
	v_lshl_add_u64 v[24:25], s[0:1], 0, v[30:31]
	v_lshl_add_u64 v[24:25], v[24:25], 0, v[128:129]
	global_load_dwordx4 v[76:79], v[24:25], off offset:128
	v_lshl_add_u64 v[24:25], s[8:9], 0, v[32:33]
	v_lshl_add_u64 v[24:25], v[24:25], 0, v[128:129]
	global_load_dwordx4 v[80:83], v[24:25], off offset:128
	v_lshl_add_u64 v[24:25], s[8:9], 0, v[34:35]
	v_lshl_add_u64 v[24:25], v[24:25], 0, v[128:129]
	global_load_dwordx4 v[84:87], v[24:25], off offset:128
	v_mul_lo_u32 v24, v37, s96
	v_add3_u32 v134, 16, v128, v24
	v_and_b32_e32 v125, 31, v36
	v_bfe_u32 v124, v36, 5, 1
	v_bfe_u32 v126, v36, 6, 1
	v_add_u32_e32 v135, 0xd800, v134
	v_add3_u32 v128, s85, v128, v24
	s_waitcnt vmcnt(11)
	ds_write_b128 v134, v[0:3]
	s_waitcnt vmcnt(10)
	ds_write_b128 v134, v[4:7] offset:9216
	s_waitcnt vmcnt(9)
	ds_write_b128 v134, v[8:11] offset:18432
	s_waitcnt vmcnt(8)
	ds_write_b128 v134, v[12:15] offset:27648
	s_waitcnt vmcnt(7)
	ds_write_b128 v134, v[16:19] offset:36864
	s_waitcnt vmcnt(6)
	ds_write_b128 v134, v[20:23] offset:46080
	s_waitcnt lgkmcnt(0)
	s_barrier
	global_load_dwordx4 v[88:91], v[112:113], off offset:256
	global_load_dwordx4 v[92:95], v[114:115], off offset:256
	global_load_dwordx4 v[96:99], v[116:117], off offset:256
	global_load_dwordx4 v[100:103], v[118:119], off offset:256
	global_load_dwordx4 v[104:107], v[120:121], off offset:256
	global_load_dwordx4 v[108:111], v[122:123], off offset:256
	v_ashrrev_i32_e32 v0, 1, v36
	v_and_b32_e32 v127, 0xffffffc0, v0
	v_or_b32_e32 v0, v127, v125
	v_mul_lo_u32 v0, v0, s96
	v_lshlrev_b32_e32 v1, 4, v124
	v_add3_u32 v132, 16, v0, v1
	v_lshl_or_b32 v0, v126, 6, v125
	v_mul_u32_u24_e32 v0, 0x90, v0
	v_add3_u32 v136, 16, v0, v1
	v_add3_u32 v133, s85, v0, v1
	ds_read_b128 v[170:173], v132
	ds_read_b128 v[174:177], v136 offset:36864
	ds_read_b128 v[178:181], v136 offset:41472
	ds_read_b128 v[182:185], v132 offset:4608
	ds_read_b128 v[186:189], v132 offset:32
	ds_read_b128 v[190:193], v136 offset:36896
	ds_read_b128 v[194:197], v136 offset:41504
	ds_read_b128 v[198:201], v132 offset:4640
	ds_read_b128 v[202:205], v132 offset:64
	ds_read_b128 v[206:209], v136 offset:36928
	ds_read_b128 v[210:213], v136 offset:41536
	ds_read_b128 v[214:217], v132 offset:4672
	s_waitcnt lgkmcnt(10)
	v_mfma_f32_32x32x16_bf16 v[48:63], v[170:173], v[174:177], 0
	s_waitcnt lgkmcnt(9)
	v_mfma_f32_32x32x16_bf16 v[32:47], v[170:173], v[178:181], 0
	s_waitcnt lgkmcnt(8)
	v_mfma_f32_32x32x16_bf16 v[16:31], v[182:185], v[174:177], 0
	v_mfma_f32_32x32x16_bf16 v[0:15], v[182:185], v[178:181], 0
	ds_read_b128 v[222:225], v132 offset:96
	ds_read_b128 v[226:229], v136 offset:36960
	ds_read_b128 v[230:233], v136 offset:41568
	ds_read_b128 v[234:237], v132 offset:4704
	s_waitcnt lgkmcnt(10)
	v_mfma_f32_32x32x16_bf16 v[48:63], v[186:189], v[190:193], v[48:63]
	s_waitcnt lgkmcnt(9)
	v_mfma_f32_32x32x16_bf16 v[32:47], v[186:189], v[194:197], v[32:47]
	s_waitcnt lgkmcnt(8)
	v_mfma_f32_32x32x16_bf16 v[16:31], v[198:201], v[190:193], v[16:31]
	v_mfma_f32_32x32x16_bf16 v[0:15], v[198:201], v[194:197], v[0:15]
	s_waitcnt vmcnt(11)
	ds_write_b128 v134, v[64:67] offset:55296
	s_waitcnt lgkmcnt(7)
	v_mfma_f32_32x32x16_bf16 v[48:63], v[202:205], v[206:209], v[48:63]
	s_waitcnt vmcnt(10)
	ds_write_b128 v134, v[68:71] offset:64512
	s_waitcnt lgkmcnt(7)
	v_mfma_f32_32x32x16_bf16 v[32:47], v[202:205], v[210:213], v[32:47]
	s_waitcnt vmcnt(9)
	ds_write_b128 v135, v[72:75] offset:18432
	s_waitcnt lgkmcnt(7)
	v_mfma_f32_32x32x16_bf16 v[16:31], v[214:217], v[206:209], v[16:31]
	v_mfma_f32_32x32x16_bf16 v[0:15], v[214:217], v[210:213], v[0:15]
	s_waitcnt vmcnt(8)
	ds_write_b128 v135, v[76:79] offset:27648
	s_waitcnt lgkmcnt(6)
	v_mfma_f32_32x32x16_bf16 v[48:63], v[222:225], v[226:229], v[48:63]
	s_waitcnt vmcnt(7)
	ds_write_b128 v128, v[80:83]
	s_waitcnt lgkmcnt(6)
	v_mfma_f32_32x32x16_bf16 v[32:47], v[222:225], v[230:233], v[32:47]
	s_waitcnt vmcnt(6)
	ds_write_b128 v128, v[84:87] offset:9216
	s_waitcnt lgkmcnt(6)
	v_mfma_f32_32x32x16_bf16 v[16:31], v[234:237], v[226:229], v[16:31]
	v_mfma_f32_32x32x16_bf16 v[0:15], v[234:237], v[230:233], v[0:15]
	s_waitcnt lgkmcnt(0)
	s_barrier
; template <class AS, class EP>
; DEVI void gemm_tile(const AS& as, const u16* __restrict__ Bt, int K, int m0, int n0, const EP& ep, char* lds) {
;     ...
;   GLOAD(ra0, rb0, 0); GLOAD(ra1, rb1, 1); LWRITE(0, ra0, rb0); __syncthreads();
;   for (int kt = 0; kt < KT; kt += 2) {
;     if (kt + 2 < KT) GLOAD(ra0, rb0, kt + 2);
;     __builtin_amdgcn_sched_barrier(0);
;     COMPUTE(0);
;     __builtin_amdgcn_sched_barrier(0);
;     LWRITE(1, ra1, rb1);
;     __syncthreads();
;     if (kt + 3 < KT) GLOAD(ra1, rb1, kt + 3);
;     __builtin_amdgcn_sched_barrier(0);
;     COMPUTE(1);
;     __builtin_amdgcn_sched_barrier(0);
;     if (kt + 2 < KT) LWRITE(0, ra0, rb0);
;     __syncthreads();
;   }
	global_load_dwordx4 v[64:67], v[112:113], off offset:384
	global_load_dwordx4 v[68:71], v[114:115], off offset:384
	global_load_dwordx4 v[72:75], v[116:117], off offset:384
	global_load_dwordx4 v[76:79], v[118:119], off offset:384
	global_load_dwordx4 v[80:83], v[120:121], off offset:384
	global_load_dwordx4 v[84:87], v[122:123], off offset:384
	ds_read_b128 v[170:173], v132 offset:55296
	ds_read_b128 v[174:177], v133
	ds_read_b128 v[178:181], v133 offset:4608
	ds_read_b128 v[182:185], v132 offset:59904
	ds_read_b128 v[186:189], v132 offset:55328
	ds_read_b128 v[190:193], v133 offset:32
	ds_read_b128 v[194:197], v133 offset:4640
	ds_read_b128 v[198:201], v132 offset:59936
	ds_read_b128 v[202:205], v132 offset:55360
	ds_read_b128 v[206:209], v133 offset:64
	ds_read_b128 v[210:213], v133 offset:4672
	ds_read_b128 v[214:217], v132 offset:59968
	s_waitcnt lgkmcnt(10)
	v_mfma_f32_32x32x16_bf16 v[48:63], v[170:173], v[174:177], v[48:63]
	s_waitcnt lgkmcnt(9)
	v_mfma_f32_32x32x16_bf16 v[32:47], v[170:173], v[178:181], v[32:47]
	s_waitcnt lgkmcnt(8)
	v_mfma_f32_32x32x16_bf16 v[16:31], v[182:185], v[174:177], v[16:31]
	v_mfma_f32_32x32x16_bf16 v[0:15], v[182:185], v[178:181], v[0:15]
	ds_read_b128 v[222:225], v132 offset:55392
	ds_read_b128 v[226:229], v133 offset:96
	ds_read_b128 v[230:233], v133 offset:4704
	ds_read_b128 v[234:237], v132 offset:60000
	s_waitcnt lgkmcnt(10)
	v_mfma_f32_32x32x16_bf16 v[48:63], v[186:189], v[190:193], v[48:63]
	s_waitcnt lgkmcnt(9)
	v_mfma_f32_32x32x16_bf16 v[32:47], v[186:189], v[194:197], v[32:47]
	s_waitcnt lgkmcnt(8)
	v_mfma_f32_32x32x16_bf16 v[16:31], v[198:201], v[190:193], v[16:31]
	v_mfma_f32_32x32x16_bf16 v[0:15], v[198:201], v[194:197], v[0:15]
	s_waitcnt vmcnt(11)
	ds_write_b128 v134, v[88:91]
	s_waitcnt lgkmcnt(7)
	v_mfma_f32_32x32x16_bf16 v[48:63], v[202:205], v[206:209], v[48:63]
	s_waitcnt vmcnt(10)
	ds_write_b128 v134, v[92:95] offset:9216
	s_waitcnt lgkmcnt(7)
	v_mfma_f32_32x32x16_bf16 v[32:47], v[202:205], v[210:213], v[32:47]
	s_waitcnt vmcnt(9)
	ds_write_b128 v134, v[96:99] offset:18432
	s_waitcnt lgkmcnt(7)
	v_mfma_f32_32x32x16_bf16 v[16:31], v[214:217], v[206:209], v[16:31]
	v_mfma_f32_32x32x16_bf16 v[0:15], v[214:217], v[210:213], v[0:15]
	s_waitcnt vmcnt(8)
	ds_write_b128 v134, v[100:103] offset:27648
	s_waitcnt lgkmcnt(6)
	v_mfma_f32_32x32x16_bf16 v[48:63], v[222:225], v[226:229], v[48:63]
	s_waitcnt vmcnt(7)
	ds_write_b128 v134, v[104:107] offset:36864
	s_waitcnt lgkmcnt(6)
	v_mfma_f32_32x32x16_bf16 v[32:47], v[222:225], v[230:233], v[32:47]
	s_waitcnt vmcnt(6)
	ds_write_b128 v134, v[108:111] offset:46080
	s_waitcnt lgkmcnt(6)
	v_mfma_f32_32x32x16_bf16 v[16:31], v[234:237], v[226:229], v[16:31]
	v_mfma_f32_32x32x16_bf16 v[0:15], v[234:237], v[230:233], v[0:15]
	s_waitcnt lgkmcnt(0)
	s_barrier
	global_load_dwordx4 v[88:91], v[112:113], off offset:512
	global_load_dwordx4 v[92:95], v[114:115], off offset:512
	global_load_dwordx4 v[96:99], v[116:117], off offset:512
	global_load_dwordx4 v[100:103], v[118:119], off offset:512
	global_load_dwordx4 v[104:107], v[120:121], off offset:512
	global_load_dwordx4 v[108:111], v[122:123], off offset:512
	ds_read_b128 v[170:173], v132
	ds_read_b128 v[174:177], v136 offset:36864
	ds_read_b128 v[178:181], v136 offset:41472
	ds_read_b128 v[182:185], v132 offset:4608
	ds_read_b128 v[186:189], v132 offset:32
	ds_read_b128 v[190:193], v136 offset:36896
	ds_read_b128 v[194:197], v136 offset:41504
	ds_read_b128 v[198:201], v132 offset:4640
	ds_read_b128 v[202:205], v132 offset:64
	ds_read_b128 v[206:209], v136 offset:36928
	ds_read_b128 v[210:213], v136 offset:41536
	ds_read_b128 v[214:217], v132 offset:4672
	s_waitcnt lgkmcnt(10)
	v_mfma_f32_32x32x16_bf16 v[48:63], v[170:173], v[174:177], v[48:63]
	s_waitcnt lgkmcnt(9)
	v_mfma_f32_32x32x16_bf16 v[32:47], v[170:173], v[178:181], v[32:47]
	s_waitcnt lgkmcnt(8)
	v_mfma_f32_32x32x16_bf16 v[16:31], v[182:185], v[174:177], v[16:31]
	v_mfma_f32_32x32x16_bf16 v[0:15], v[182:185], v[178:181], v[0:15]
	ds_read_b128 v[222:225], v132 offset:96
	ds_read_b128 v[226:229], v136 offset:36960
	ds_read_b128 v[230:233], v136 offset:41568
	ds_read_b128 v[234:237], v132 offset:4704
	s_waitcnt lgkmcnt(10)
	v_mfma_f32_32x32x16_bf16 v[48:63], v[186:189], v[190:193], v[48:63]
	s_waitcnt lgkmcnt(9)
	v_mfma_f32_32x32x16_bf16 v[32:47], v[186:189], v[194:197], v[32:47]
	s_waitcnt lgkmcnt(8)
	v_mfma_f32_32x32x16_bf16 v[16:31], v[198:201], v[190:193], v[16:31]
	v_mfma_f32_32x32x16_bf16 v[0:15], v[198:201], v[194:197], v[0:15]
	s_waitcnt vmcnt(11)
	ds_write_b128 v134, v[64:67] offset:55296
	s_waitcnt lgkmcnt(7)
	v_mfma_f32_32x32x16_bf16 v[48:63], v[202:205], v[206:209], v[48:63]
	s_waitcnt vmcnt(10)
	ds_write_b128 v134, v[68:71] offset:64512
	s_waitcnt lgkmcnt(7)
	v_mfma_f32_32x32x16_bf16 v[32:47], v[202:205], v[210:213], v[32:47]
	s_waitcnt vmcnt(9)
	ds_write_b128 v135, v[72:75] offset:18432
	s_waitcnt lgkmcnt(7)
	v_mfma_f32_32x32x16_bf16 v[16:31], v[214:217], v[206:209], v[16:31]
	v_mfma_f32_32x32x16_bf16 v[0:15], v[214:217], v[210:213], v[0:15]
	s_waitcnt vmcnt(8)
	ds_write_b128 v135, v[76:79] offset:27648
	s_waitcnt lgkmcnt(6)
	v_mfma_f32_32x32x16_bf16 v[48:63], v[222:225], v[226:229], v[48:63]
	s_waitcnt vmcnt(7)
	ds_write_b128 v128, v[80:83]
	s_waitcnt lgkmcnt(6)
	v_mfma_f32_32x32x16_bf16 v[32:47], v[222:225], v[230:233], v[32:47]
	s_waitcnt vmcnt(6)
	ds_write_b128 v128, v[84:87] offset:9216
	s_waitcnt lgkmcnt(6)
	v_mfma_f32_32x32x16_bf16 v[16:31], v[234:237], v[226:229], v[16:31]
	v_mfma_f32_32x32x16_bf16 v[0:15], v[234:237], v[230:233], v[0:15]
	s_waitcnt lgkmcnt(0)
	s_barrier
; template <class AS, class EP>
; DEVI void gemm_tile(const AS& as, const u16* __restrict__ Bt, int K, int m0, int n0, const EP& ep, char* lds) {
;     ...
;   GLOAD(ra0, rb0, 0); GLOAD(ra1, rb1, 1); LWRITE(0, ra0, rb0); __syncthreads();
;   for (int kt = 0; kt < KT; kt += 2) {
;     if (kt + 2 < KT) GLOAD(ra0, rb0, kt + 2);
;     __builtin_amdgcn_sched_barrier(0);
;     COMPUTE(0);
;     __builtin_amdgcn_sched_barrier(0);
;     LWRITE(1, ra1, rb1);
;     __syncthreads();
;     if (kt + 3 < KT) GLOAD(ra1, rb1, kt + 3);
;     __builtin_amdgcn_sched_barrier(0);
;     COMPUTE(1);
;     __builtin_amdgcn_sched_barrier(0);
;     if (kt + 2 < KT) LWRITE(0, ra0, rb0);
;     __syncthreads();
	global_load_dwordx4 v[64:67], v[112:113], off offset:640
	global_load_dwordx4 v[68:71], v[114:115], off offset:640
	global_load_dwordx4 v[72:75], v[116:117], off offset:640
	global_load_dwordx4 v[76:79], v[118:119], off offset:640
	global_load_dwordx4 v[80:83], v[120:121], off offset:640
	global_load_dwordx4 v[84:87], v[122:123], off offset:640
	ds_read_b128 v[170:173], v132 offset:55296
	ds_read_b128 v[174:177], v133
	ds_read_b128 v[178:181], v133 offset:4608
	ds_read_b128 v[182:185], v132 offset:59904
	ds_read_b128 v[186:189], v132 offset:55328
	ds_read_b128 v[190:193], v133 offset:32
	ds_read_b128 v[194:197], v133 offset:4640
	ds_read_b128 v[198:201], v132 offset:59936
	ds_read_b128 v[202:205], v132 offset:55360
	ds_read_b128 v[206:209], v133 offset:64
	ds_read_b128 v[210:213], v133 offset:4672
	ds_read_b128 v[214:217], v132 offset:59968
	s_waitcnt lgkmcnt(10)
	v_mfma_f32_32x32x16_bf16 v[48:63], v[170:173], v[174:177], v[48:63]
	s_waitcnt lgkmcnt(9)
	v_mfma_f32_32x32x16_bf16 v[32:47], v[170:173], v[178:181], v[32:47]
	s_waitcnt lgkmcnt(8)
	v_mfma_f32_32x32x16_bf16 v[16:31], v[182:185], v[174:177], v[16:31]
	v_mfma_f32_32x32x16_bf16 v[0:15], v[182:185], v[178:181], v[0:15]
	ds_read_b128 v[222:225], v132 offset:55392
	ds_read_b128 v[226:229], v133 offset:96
	ds_read_b128 v[230:233], v133 offset:4704
	ds_read_b128 v[234:237], v132 offset:60000
	s_waitcnt lgkmcnt(10)
	v_mfma_f32_32x32x16_bf16 v[48:63], v[186:189], v[190:193], v[48:63]
	s_waitcnt lgkmcnt(9)
	v_mfma_f32_32x32x16_bf16 v[32:47], v[186:189], v[194:197], v[32:47]
	s_waitcnt lgkmcnt(8)
	v_mfma_f32_32x32x16_bf16 v[16:31], v[198:201], v[190:193], v[16:31]
	v_mfma_f32_32x32x16_bf16 v[0:15], v[198:201], v[194:197], v[0:15]
	s_waitcnt vmcnt(11)
	ds_write_b128 v134, v[88:91]
	s_waitcnt lgkmcnt(7)
	v_mfma_f32_32x32x16_bf16 v[48:63], v[202:205], v[206:209], v[48:63]
	s_waitcnt vmcnt(10)
	ds_write_b128 v134, v[92:95] offset:9216
	s_waitcnt lgkmcnt(7)
	v_mfma_f32_32x32x16_bf16 v[32:47], v[202:205], v[210:213], v[32:47]
	s_waitcnt vmcnt(9)
	ds_write_b128 v134, v[96:99] offset:18432
	s_waitcnt lgkmcnt(7)
	v_mfma_f32_32x32x16_bf16 v[16:31], v[214:217], v[206:209], v[16:31]
	v_mfma_f32_32x32x16_bf16 v[0:15], v[214:217], v[210:213], v[0:15]
	s_waitcnt vmcnt(8)
	ds_write_b128 v134, v[100:103] offset:27648
	s_waitcnt lgkmcnt(6)
	v_mfma_f32_32x32x16_bf16 v[48:63], v[222:225], v[226:229], v[48:63]
	s_waitcnt vmcnt(7)
	ds_write_b128 v134, v[104:107] offset:36864
	s_waitcnt lgkmcnt(6)
	v_mfma_f32_32x32x16_bf16 v[32:47], v[222:225], v[230:233], v[32:47]
	s_waitcnt vmcnt(6)
	ds_write_b128 v134, v[108:111] offset:46080
	s_waitcnt lgkmcnt(6)
	v_mfma_f32_32x32x16_bf16 v[16:31], v[234:237], v[226:229], v[16:31]
	v_mfma_f32_32x32x16_bf16 v[0:15], v[234:237], v[230:233], v[0:15]
	s_waitcnt lgkmcnt(0)
	s_barrier
	global_load_dwordx4 v[88:91], v[112:113], off offset:768
	global_load_dwordx4 v[92:95], v[114:115], off offset:768
	global_load_dwordx4 v[96:99], v[116:117], off offset:768
	global_load_dwordx4 v[100:103], v[118:119], off offset:768
	global_load_dwordx4 v[104:107], v[120:121], off offset:768
	global_load_dwordx4 v[108:111], v[122:123], off offset:768
	ds_read_b128 v[170:173], v132
	ds_read_b128 v[174:177], v136 offset:36864
	ds_read_b128 v[178:181], v136 offset:41472
	ds_read_b128 v[182:185], v132 offset:4608
	ds_read_b128 v[186:189], v132 offset:32
	ds_read_b128 v[190:193], v136 offset:36896
	ds_read_b128 v[194:197], v136 offset:41504
	ds_read_b128 v[198:201], v132 offset:4640
	ds_read_b128 v[202:205], v132 offset:64
	ds_read_b128 v[206:209], v136 offset:36928
	ds_read_b128 v[210:213], v136 offset:41536
	ds_read_b128 v[214:217], v132 offset:4672
	s_waitcnt lgkmcnt(10)
	v_mfma_f32_32x32x16_bf16 v[48:63], v[170:173], v[174:177], v[48:63]
	s_waitcnt lgkmcnt(9)
	v_mfma_f32_32x32x16_bf16 v[32:47], v[170:173], v[178:181], v[32:47]
	s_waitcnt lgkmcnt(8)
	v_mfma_f32_32x32x16_bf16 v[16:31], v[182:185], v[174:177], v[16:31]
	v_mfma_f32_32x32x16_bf16 v[0:15], v[182:185], v[178:181], v[0:15]
	ds_read_b128 v[222:225], v132 offset:96
	ds_read_b128 v[226:229], v136 offset:36960
	ds_read_b128 v[230:233], v136 offset:41568
	ds_read_b128 v[234:237], v132 offset:4704
	s_waitcnt lgkmcnt(10)
	v_mfma_f32_32x32x16_bf16 v[48:63], v[186:189], v[190:193], v[48:63]
	s_waitcnt lgkmcnt(9)
	v_mfma_f32_32x32x16_bf16 v[32:47], v[186:189], v[194:197], v[32:47]
	s_waitcnt lgkmcnt(8)
	v_mfma_f32_32x32x16_bf16 v[16:31], v[198:201], v[190:193], v[16:31]
	v_mfma_f32_32x32x16_bf16 v[0:15], v[198:201], v[194:197], v[0:15]
	s_waitcnt vmcnt(11)
	ds_write_b128 v134, v[64:67] offset:55296
	s_waitcnt lgkmcnt(7)
	v_mfma_f32_32x32x16_bf16 v[48:63], v[202:205], v[206:209], v[48:63]
	s_waitcnt vmcnt(10)
	ds_write_b128 v134, v[68:71] offset:64512
	s_waitcnt lgkmcnt(7)
	v_mfma_f32_32x32x16_bf16 v[32:47], v[202:205], v[210:213], v[32:47]
	s_waitcnt vmcnt(9)
	ds_write_b128 v135, v[72:75] offset:18432
	s_waitcnt lgkmcnt(7)
	v_mfma_f32_32x32x16_bf16 v[16:31], v[214:217], v[206:209], v[16:31]
	v_mfma_f32_32x32x16_bf16 v[0:15], v[214:217], v[210:213], v[0:15]
	s_waitcnt vmcnt(8)
	ds_write_b128 v135, v[76:79] offset:27648
	s_waitcnt lgkmcnt(6)
	v_mfma_f32_32x32x16_bf16 v[48:63], v[222:225], v[226:229], v[48:63]
	s_waitcnt vmcnt(7)
	ds_write_b128 v128, v[80:83]
	s_waitcnt lgkmcnt(6)
	v_mfma_f32_32x32x16_bf16 v[32:47], v[222:225], v[230:233], v[32:47]
	s_waitcnt vmcnt(6)
	ds_write_b128 v128, v[84:87] offset:9216
	s_waitcnt lgkmcnt(6)
	v_mfma_f32_32x32x16_bf16 v[16:31], v[234:237], v[226:229], v[16:31]
	v_mfma_f32_32x32x16_bf16 v[0:15], v[234:237], v[230:233], v[0:15]
	s_waitcnt lgkmcnt(0)
	s_barrier
; template <class AS, class EP>
; DEVI void gemm_tile(const AS& as, const u16* __restrict__ Bt, int K, int m0, int n0, const EP& ep, char* lds) {
;     ...
;   GLOAD(ra0, rb0, 0); GLOAD(ra1, rb1, 1); LWRITE(0, ra0, rb0); __syncthreads();
;   for (int kt = 0; kt < KT; kt += 2) {
;     if (kt + 2 < KT) GLOAD(ra0, rb0, kt + 2);
;     __builtin_amdgcn_sched_barrier(0);
;     COMPUTE(0);
;     __builtin_amdgcn_sched_barrier(0);
;     LWRITE(1, ra1, rb1);
;     __syncthreads();
;     if (kt + 3 < KT) GLOAD(ra1, rb1, kt + 3);
;     __builtin_amdgcn_sched_barrier(0);
;     COMPUTE(1);
;     __builtin_amdgcn_sched_barrier(0);
;     if (kt + 2 < KT) LWRITE(0, ra0, rb0);
;     __syncthreads();
	global_load_dwordx4 v[64:67], v[112:113], off offset:896
	global_load_dwordx4 v[68:71], v[114:115], off offset:896
	global_load_dwordx4 v[72:75], v[116:117], off offset:896
	global_load_dwordx4 v[76:79], v[118:119], off offset:896
	global_load_dwordx4 v[80:83], v[120:121], off offset:896
	global_load_dwordx4 v[84:87], v[122:123], off offset:896
	ds_read_b128 v[170:173], v132 offset:55296
	ds_read_b128 v[174:177], v133
	ds_read_b128 v[178:181], v133 offset:4608
	ds_read_b128 v[182:185], v132 offset:59904
	ds_read_b128 v[186:189], v132 offset:55328
	ds_read_b128 v[190:193], v133 offset:32
	ds_read_b128 v[194:197], v133 offset:4640
	ds_read_b128 v[198:201], v132 offset:59936
	ds_read_b128 v[202:205], v132 offset:55360
	ds_read_b128 v[206:209], v133 offset:64
	ds_read_b128 v[210:213], v133 offset:4672
	ds_read_b128 v[214:217], v132 offset:59968
	s_waitcnt lgkmcnt(10)
	v_mfma_f32_32x32x16_bf16 v[48:63], v[170:173], v[174:177], v[48:63]
	s_waitcnt lgkmcnt(9)
	v_mfma_f32_32x32x16_bf16 v[32:47], v[170:173], v[178:181], v[32:47]
	s_waitcnt lgkmcnt(8)
	v_mfma_f32_32x32x16_bf16 v[16:31], v[182:185], v[174:177], v[16:31]
	v_mfma_f32_32x32x16_bf16 v[0:15], v[182:185], v[178:181], v[0:15]
	ds_read_b128 v[222:225], v132 offset:55392
	ds_read_b128 v[226:229], v133 offset:96
	ds_read_b128 v[230:233], v133 offset:4704
	ds_read_b128 v[234:237], v132 offset:60000
	s_waitcnt lgkmcnt(10)
	v_mfma_f32_32x32x16_bf16 v[48:63], v[186:189], v[190:193], v[48:63]
	s_waitcnt lgkmcnt(9)
	v_mfma_f32_32x32x16_bf16 v[32:47], v[186:189], v[194:197], v[32:47]
	s_waitcnt lgkmcnt(8)
	v_mfma_f32_32x32x16_bf16 v[16:31], v[198:201], v[190:193], v[16:31]
	v_mfma_f32_32x32x16_bf16 v[0:15], v[198:201], v[194:197], v[0:15]
	s_waitcnt vmcnt(11)
	ds_write_b128 v134, v[88:91]
	s_waitcnt lgkmcnt(7)
	v_mfma_f32_32x32x16_bf16 v[48:63], v[202:205], v[206:209], v[48:63]
	s_waitcnt vmcnt(10)
	ds_write_b128 v134, v[92:95] offset:9216
	s_waitcnt lgkmcnt(7)
	v_mfma_f32_32x32x16_bf16 v[32:47], v[202:205], v[210:213], v[32:47]
	s_waitcnt vmcnt(9)
	ds_write_b128 v134, v[96:99] offset:18432
	s_waitcnt lgkmcnt(7)
	v_mfma_f32_32x32x16_bf16 v[16:31], v[214:217], v[206:209], v[16:31]
	v_mfma_f32_32x32x16_bf16 v[0:15], v[214:217], v[210:213], v[0:15]
	s_waitcnt vmcnt(8)
	ds_write_b128 v134, v[100:103] offset:27648
	s_waitcnt lgkmcnt(6)
	v_mfma_f32_32x32x16_bf16 v[48:63], v[222:225], v[226:229], v[48:63]
	s_waitcnt vmcnt(7)
	ds_write_b128 v134, v[104:107] offset:36864
	s_waitcnt lgkmcnt(6)
	v_mfma_f32_32x32x16_bf16 v[32:47], v[222:225], v[230:233], v[32:47]
	s_waitcnt vmcnt(6)
	ds_write_b128 v134, v[108:111] offset:46080
	s_waitcnt lgkmcnt(6)
	v_mfma_f32_32x32x16_bf16 v[16:31], v[234:237], v[226:229], v[16:31]
	v_mfma_f32_32x32x16_bf16 v[0:15], v[234:237], v[230:233], v[0:15]
	s_waitcnt lgkmcnt(0)
	s_barrier
	global_load_dwordx4 v[88:91], v[112:113], off offset:1024
	global_load_dwordx4 v[92:95], v[114:115], off offset:1024
	global_load_dwordx4 v[96:99], v[116:117], off offset:1024
	global_load_dwordx4 v[100:103], v[118:119], off offset:1024
	global_load_dwordx4 v[104:107], v[120:121], off offset:1024
	global_load_dwordx4 v[108:111], v[122:123], off offset:1024
	ds_read_b128 v[170:173], v132
	ds_read_b128 v[174:177], v136 offset:36864
	ds_read_b128 v[178:181], v136 offset:41472
	ds_read_b128 v[182:185], v132 offset:4608
	ds_read_b128 v[186:189], v132 offset:32
	ds_read_b128 v[190:193], v136 offset:36896
	ds_read_b128 v[194:197], v136 offset:41504
	ds_read_b128 v[198:201], v132 offset:4640
	ds_read_b128 v[202:205], v132 offset:64
	ds_read_b128 v[206:209], v136 offset:36928
	ds_read_b128 v[210:213], v136 offset:41536
	ds_read_b128 v[214:217], v132 offset:4672
	s_waitcnt lgkmcnt(10)
	v_mfma_f32_32x32x16_bf16 v[48:63], v[170:173], v[174:177], v[48:63]
	s_waitcnt lgkmcnt(9)
	v_mfma_f32_32x32x16_bf16 v[32:47], v[170:173], v[178:181], v[32:47]
	s_waitcnt lgkmcnt(8)
	v_mfma_f32_32x32x16_bf16 v[16:31], v[182:185], v[174:177], v[16:31]
	v_mfma_f32_32x32x16_bf16 v[0:15], v[182:185], v[178:181], v[0:15]
	ds_read_b128 v[222:225], v132 offset:96
	ds_read_b128 v[226:229], v136 offset:36960
	ds_read_b128 v[230:233], v136 offset:41568
	ds_read_b128 v[234:237], v132 offset:4704
	s_waitcnt lgkmcnt(10)
	v_mfma_f32_32x32x16_bf16 v[48:63], v[186:189], v[190:193], v[48:63]
	s_waitcnt lgkmcnt(9)
	v_mfma_f32_32x32x16_bf16 v[32:47], v[186:189], v[194:197], v[32:47]
	s_waitcnt lgkmcnt(8)
	v_mfma_f32_32x32x16_bf16 v[16:31], v[198:201], v[190:193], v[16:31]
	v_mfma_f32_32x32x16_bf16 v[0:15], v[198:201], v[194:197], v[0:15]
	s_waitcnt vmcnt(11)
	ds_write_b128 v134, v[64:67] offset:55296
	s_waitcnt lgkmcnt(7)
	v_mfma_f32_32x32x16_bf16 v[48:63], v[202:205], v[206:209], v[48:63]
	s_waitcnt vmcnt(10)
	ds_write_b128 v134, v[68:71] offset:64512
	s_waitcnt lgkmcnt(7)
	v_mfma_f32_32x32x16_bf16 v[32:47], v[202:205], v[210:213], v[32:47]
	s_waitcnt vmcnt(9)
	ds_write_b128 v135, v[72:75] offset:18432
	s_waitcnt lgkmcnt(7)
	v_mfma_f32_32x32x16_bf16 v[16:31], v[214:217], v[206:209], v[16:31]
	v_mfma_f32_32x32x16_bf16 v[0:15], v[214:217], v[210:213], v[0:15]
	s_waitcnt vmcnt(8)
	ds_write_b128 v135, v[76:79] offset:27648
	s_waitcnt lgkmcnt(6)
	v_mfma_f32_32x32x16_bf16 v[48:63], v[222:225], v[226:229], v[48:63]
	s_waitcnt vmcnt(7)
	ds_write_b128 v128, v[80:83]
	s_waitcnt lgkmcnt(6)
	v_mfma_f32_32x32x16_bf16 v[32:47], v[222:225], v[230:233], v[32:47]
	s_waitcnt vmcnt(6)
	ds_write_b128 v128, v[84:87] offset:9216
	s_waitcnt lgkmcnt(6)
	v_mfma_f32_32x32x16_bf16 v[16:31], v[234:237], v[226:229], v[16:31]
	v_mfma_f32_32x32x16_bf16 v[0:15], v[234:237], v[230:233], v[0:15]
	s_waitcnt lgkmcnt(0)
	s_barrier
; template <class AS, class EP>
; DEVI void gemm_tile(const AS& as, const u16* __restrict__ Bt, int K, int m0, int n0, const EP& ep, char* lds) {
;     ...
;   GLOAD(ra0, rb0, 0); GLOAD(ra1, rb1, 1); LWRITE(0, ra0, rb0); __syncthreads();
;   for (int kt = 0; kt < KT; kt += 2) {
;     if (kt + 2 < KT) GLOAD(ra0, rb0, kt + 2);
;     __builtin_amdgcn_sched_barrier(0);
;     COMPUTE(0);
;     __builtin_amdgcn_sched_barrier(0);
;     LWRITE(1, ra1, rb1);
;     __syncthreads();
;     if (kt + 3 < KT) GLOAD(ra1, rb1, kt + 3);
;     __builtin_amdgcn_sched_barrier(0);
;     COMPUTE(1);
;     __builtin_amdgcn_sched_barrier(0);
;     if (kt + 2 < KT) LWRITE(0, ra0, rb0);
;     __syncthreads();
	global_load_dwordx4 v[64:67], v[112:113], off offset:1152
	global_load_dwordx4 v[68:71], v[114:115], off offset:1152
	global_load_dwordx4 v[72:75], v[116:117], off offset:1152
	global_load_dwordx4 v[76:79], v[118:119], off offset:1152
	global_load_dwordx4 v[80:83], v[120:121], off offset:1152
	global_load_dwordx4 v[84:87], v[122:123], off offset:1152
	ds_read_b128 v[170:173], v132 offset:55296
	ds_read_b128 v[174:177], v133
	ds_read_b128 v[178:181], v133 offset:4608
	ds_read_b128 v[182:185], v132 offset:59904
	ds_read_b128 v[186:189], v132 offset:55328
	ds_read_b128 v[190:193], v133 offset:32
	ds_read_b128 v[194:197], v133 offset:4640
	ds_read_b128 v[198:201], v132 offset:59936
	ds_read_b128 v[202:205], v132 offset:55360
	ds_read_b128 v[206:209], v133 offset:64
	ds_read_b128 v[210:213], v133 offset:4672
	ds_read_b128 v[214:217], v132 offset:59968
	s_waitcnt lgkmcnt(10)
	v_mfma_f32_32x32x16_bf16 v[48:63], v[170:173], v[174:177], v[48:63]
	s_waitcnt lgkmcnt(9)
	v_mfma_f32_32x32x16_bf16 v[32:47], v[170:173], v[178:181], v[32:47]
	s_waitcnt lgkmcnt(8)
	v_mfma_f32_32x32x16_bf16 v[16:31], v[182:185], v[174:177], v[16:31]
	v_mfma_f32_32x32x16_bf16 v[0:15], v[182:185], v[178:181], v[0:15]
	ds_read_b128 v[222:225], v132 offset:55392
	ds_read_b128 v[226:229], v133 offset:96
	ds_read_b128 v[230:233], v133 offset:4704
	ds_read_b128 v[234:237], v132 offset:60000
	s_waitcnt lgkmcnt(10)
	v_mfma_f32_32x32x16_bf16 v[48:63], v[186:189], v[190:193], v[48:63]
	s_waitcnt lgkmcnt(9)
	v_mfma_f32_32x32x16_bf16 v[32:47], v[186:189], v[194:197], v[32:47]
	s_waitcnt lgkmcnt(8)
	v_mfma_f32_32x32x16_bf16 v[16:31], v[198:201], v[190:193], v[16:31]
	v_mfma_f32_32x32x16_bf16 v[0:15], v[198:201], v[194:197], v[0:15]
	s_waitcnt vmcnt(11)
	ds_write_b128 v134, v[88:91]
	s_waitcnt lgkmcnt(7)
	v_mfma_f32_32x32x16_bf16 v[48:63], v[202:205], v[206:209], v[48:63]
	s_waitcnt vmcnt(10)
	ds_write_b128 v134, v[92:95] offset:9216
	s_waitcnt lgkmcnt(7)
	v_mfma_f32_32x32x16_bf16 v[32:47], v[202:205], v[210:213], v[32:47]
	s_waitcnt vmcnt(9)
	ds_write_b128 v134, v[96:99] offset:18432
	s_waitcnt lgkmcnt(7)
	v_mfma_f32_32x32x16_bf16 v[16:31], v[214:217], v[206:209], v[16:31]
	v_mfma_f32_32x32x16_bf16 v[0:15], v[214:217], v[210:213], v[0:15]
	s_waitcnt vmcnt(8)
	ds_write_b128 v134, v[100:103] offset:27648
	s_waitcnt lgkmcnt(6)
	v_mfma_f32_32x32x16_bf16 v[48:63], v[222:225], v[226:229], v[48:63]
	s_waitcnt vmcnt(7)
	ds_write_b128 v134, v[104:107] offset:36864
	s_waitcnt lgkmcnt(6)
	v_mfma_f32_32x32x16_bf16 v[32:47], v[222:225], v[230:233], v[32:47]
	s_waitcnt vmcnt(6)
	ds_write_b128 v134, v[108:111] offset:46080
	s_waitcnt lgkmcnt(6)
	v_mfma_f32_32x32x16_bf16 v[16:31], v[234:237], v[226:229], v[16:31]
	v_mfma_f32_32x32x16_bf16 v[0:15], v[234:237], v[230:233], v[0:15]
	s_waitcnt lgkmcnt(0)
	s_barrier
	global_load_dwordx4 v[88:91], v[112:113], off offset:1280
	global_load_dwordx4 v[92:95], v[114:115], off offset:1280
	global_load_dwordx4 v[96:99], v[116:117], off offset:1280
	global_load_dwordx4 v[100:103], v[118:119], off offset:1280
	global_load_dwordx4 v[104:107], v[120:121], off offset:1280
	global_load_dwordx4 v[108:111], v[122:123], off offset:1280
	ds_read_b128 v[170:173], v132
	ds_read_b128 v[174:177], v136 offset:36864
	ds_read_b128 v[178:181], v136 offset:41472
	ds_read_b128 v[182:185], v132 offset:4608
	ds_read_b128 v[186:189], v132 offset:32
	ds_read_b128 v[190:193], v136 offset:36896
	ds_read_b128 v[194:197], v136 offset:41504
	ds_read_b128 v[198:201], v132 offset:4640
	ds_read_b128 v[202:205], v132 offset:64
	ds_read_b128 v[206:209], v136 offset:36928
	ds_read_b128 v[210:213], v136 offset:41536
	ds_read_b128 v[214:217], v132 offset:4672
	s_waitcnt lgkmcnt(10)
	v_mfma_f32_32x32x16_bf16 v[48:63], v[170:173], v[174:177], v[48:63]
	s_waitcnt lgkmcnt(9)
	v_mfma_f32_32x32x16_bf16 v[32:47], v[170:173], v[178:181], v[32:47]
	s_waitcnt lgkmcnt(8)
	v_mfma_f32_32x32x16_bf16 v[16:31], v[182:185], v[174:177], v[16:31]
	v_mfma_f32_32x32x16_bf16 v[0:15], v[182:185], v[178:181], v[0:15]
	ds_read_b128 v[222:225], v132 offset:96
	ds_read_b128 v[226:229], v136 offset:36960
	ds_read_b128 v[230:233], v136 offset:41568
	ds_read_b128 v[234:237], v132 offset:4704
	s_waitcnt lgkmcnt(10)
	v_mfma_f32_32x32x16_bf16 v[48:63], v[186:189], v[190:193], v[48:63]
	s_waitcnt lgkmcnt(9)
	v_mfma_f32_32x32x16_bf16 v[32:47], v[186:189], v[194:197], v[32:47]
	s_waitcnt lgkmcnt(8)
	v_mfma_f32_32x32x16_bf16 v[16:31], v[198:201], v[190:193], v[16:31]
	v_mfma_f32_32x32x16_bf16 v[0:15], v[198:201], v[194:197], v[0:15]
	s_waitcnt vmcnt(11)
	ds_write_b128 v134, v[64:67] offset:55296
	s_waitcnt lgkmcnt(7)
	v_mfma_f32_32x32x16_bf16 v[48:63], v[202:205], v[206:209], v[48:63]
	s_waitcnt vmcnt(10)
	ds_write_b128 v134, v[68:71] offset:64512
	s_waitcnt lgkmcnt(7)
	v_mfma_f32_32x32x16_bf16 v[32:47], v[202:205], v[210:213], v[32:47]
	s_waitcnt vmcnt(9)
	ds_write_b128 v135, v[72:75] offset:18432
	s_waitcnt lgkmcnt(7)
	v_mfma_f32_32x32x16_bf16 v[16:31], v[214:217], v[206:209], v[16:31]
	v_mfma_f32_32x32x16_bf16 v[0:15], v[214:217], v[210:213], v[0:15]
	s_waitcnt vmcnt(8)
	ds_write_b128 v135, v[76:79] offset:27648
	s_waitcnt lgkmcnt(6)
	v_mfma_f32_32x32x16_bf16 v[48:63], v[222:225], v[226:229], v[48:63]
	s_waitcnt vmcnt(7)
	ds_write_b128 v128, v[80:83]
	s_waitcnt lgkmcnt(6)
	v_mfma_f32_32x32x16_bf16 v[32:47], v[222:225], v[230:233], v[32:47]
	s_waitcnt vmcnt(6)
	ds_write_b128 v128, v[84:87] offset:9216
	s_waitcnt lgkmcnt(6)
	v_mfma_f32_32x32x16_bf16 v[16:31], v[234:237], v[226:229], v[16:31]
	v_mfma_f32_32x32x16_bf16 v[0:15], v[234:237], v[230:233], v[0:15]
	s_waitcnt lgkmcnt(0)
	s_barrier
; template <class AS, class EP>
; DEVI void gemm_tile(const AS& as, const u16* __restrict__ Bt, int K, int m0, int n0, const EP& ep, char* lds) {
;     ...
;   GLOAD(ra0, rb0, 0); GLOAD(ra1, rb1, 1); LWRITE(0, ra0, rb0); __syncthreads();
;   for (int kt = 0; kt < KT; kt += 2) {
;     if (kt + 2 < KT) GLOAD(ra0, rb0, kt + 2);
;     __builtin_amdgcn_sched_barrier(0);
;     COMPUTE(0);
;     __builtin_amdgcn_sched_barrier(0);
;     LWRITE(1, ra1, rb1);
;     __syncthreads();
;     if (kt + 3 < KT) GLOAD(ra1, rb1, kt + 3);
;     __builtin_amdgcn_sched_barrier(0);
;     COMPUTE(1);
;     __builtin_amdgcn_sched_barrier(0);
;     if (kt + 2 < KT) LWRITE(0, ra0, rb0);
;     __syncthreads();
	global_load_dwordx4 v[64:67], v[112:113], off offset:1408
	global_load_dwordx4 v[68:71], v[114:115], off offset:1408
	global_load_dwordx4 v[72:75], v[116:117], off offset:1408
	global_load_dwordx4 v[76:79], v[118:119], off offset:1408
	global_load_dwordx4 v[80:83], v[120:121], off offset:1408
	global_load_dwordx4 v[84:87], v[122:123], off offset:1408
	ds_read_b128 v[170:173], v132 offset:55296
	ds_read_b128 v[174:177], v133
	ds_read_b128 v[178:181], v133 offset:4608
	ds_read_b128 v[182:185], v132 offset:59904
	ds_read_b128 v[186:189], v132 offset:55328
	ds_read_b128 v[190:193], v133 offset:32
	ds_read_b128 v[194:197], v133 offset:4640
	ds_read_b128 v[198:201], v132 offset:59936
	ds_read_b128 v[202:205], v132 offset:55360
	ds_read_b128 v[206:209], v133 offset:64
	ds_read_b128 v[210:213], v133 offset:4672
	ds_read_b128 v[214:217], v132 offset:59968
	s_waitcnt lgkmcnt(10)
	v_mfma_f32_32x32x16_bf16 v[48:63], v[170:173], v[174:177], v[48:63]
	s_waitcnt lgkmcnt(9)
	v_mfma_f32_32x32x16_bf16 v[32:47], v[170:173], v[178:181], v[32:47]
	s_waitcnt lgkmcnt(8)
	v_mfma_f32_32x32x16_bf16 v[16:31], v[182:185], v[174:177], v[16:31]
	v_mfma_f32_32x32x16_bf16 v[0:15], v[182:185], v[178:181], v[0:15]
	ds_read_b128 v[222:225], v132 offset:55392
	ds_read_b128 v[226:229], v133 offset:96
	ds_read_b128 v[230:233], v133 offset:4704
	ds_read_b128 v[234:237], v132 offset:60000
	s_waitcnt lgkmcnt(10)
	v_mfma_f32_32x32x16_bf16 v[48:63], v[186:189], v[190:193], v[48:63]
	s_waitcnt lgkmcnt(9)
	v_mfma_f32_32x32x16_bf16 v[32:47], v[186:189], v[194:197], v[32:47]
	s_waitcnt lgkmcnt(8)
	v_mfma_f32_32x32x16_bf16 v[16:31], v[198:201], v[190:193], v[16:31]
	v_mfma_f32_32x32x16_bf16 v[0:15], v[198:201], v[194:197], v[0:15]
	s_waitcnt vmcnt(11)
	ds_write_b128 v134, v[88:91]
	s_waitcnt lgkmcnt(7)
	v_mfma_f32_32x32x16_bf16 v[48:63], v[202:205], v[206:209], v[48:63]
	s_waitcnt vmcnt(10)
	ds_write_b128 v134, v[92:95] offset:9216
	s_waitcnt lgkmcnt(7)
	v_mfma_f32_32x32x16_bf16 v[32:47], v[202:205], v[210:213], v[32:47]
	s_waitcnt vmcnt(9)
	ds_write_b128 v134, v[96:99] offset:18432
	s_waitcnt lgkmcnt(7)
	v_mfma_f32_32x32x16_bf16 v[16:31], v[214:217], v[206:209], v[16:31]
	v_mfma_f32_32x32x16_bf16 v[0:15], v[214:217], v[210:213], v[0:15]
	s_waitcnt vmcnt(8)
	ds_write_b128 v134, v[100:103] offset:27648
	s_waitcnt lgkmcnt(6)
	v_mfma_f32_32x32x16_bf16 v[48:63], v[222:225], v[226:229], v[48:63]
	s_waitcnt vmcnt(7)
	ds_write_b128 v134, v[104:107] offset:36864
	s_waitcnt lgkmcnt(6)
	v_mfma_f32_32x32x16_bf16 v[32:47], v[222:225], v[230:233], v[32:47]
	s_waitcnt vmcnt(6)
	ds_write_b128 v134, v[108:111] offset:46080
	s_waitcnt lgkmcnt(6)
	v_mfma_f32_32x32x16_bf16 v[16:31], v[234:237], v[226:229], v[16:31]
	v_mfma_f32_32x32x16_bf16 v[0:15], v[234:237], v[230:233], v[0:15]
	s_waitcnt lgkmcnt(0)
	s_barrier
	global_load_dwordx4 v[88:91], v[112:113], off offset:1536
	global_load_dwordx4 v[92:95], v[114:115], off offset:1536
	global_load_dwordx4 v[96:99], v[116:117], off offset:1536
	global_load_dwordx4 v[100:103], v[118:119], off offset:1536
	global_load_dwordx4 v[104:107], v[120:121], off offset:1536
	global_load_dwordx4 v[108:111], v[122:123], off offset:1536
	ds_read_b128 v[170:173], v132
	ds_read_b128 v[174:177], v136 offset:36864
	ds_read_b128 v[178:181], v136 offset:41472
	ds_read_b128 v[182:185], v132 offset:4608
	ds_read_b128 v[186:189], v132 offset:32
	ds_read_b128 v[190:193], v136 offset:36896
	ds_read_b128 v[194:197], v136 offset:41504
	ds_read_b128 v[198:201], v132 offset:4640
	ds_read_b128 v[202:205], v132 offset:64
	ds_read_b128 v[206:209], v136 offset:36928
	ds_read_b128 v[210:213], v136 offset:41536
	ds_read_b128 v[214:217], v132 offset:4672
	s_waitcnt lgkmcnt(10)
	v_mfma_f32_32x32x16_bf16 v[48:63], v[170:173], v[174:177], v[48:63]
	s_waitcnt lgkmcnt(9)
	v_mfma_f32_32x32x16_bf16 v[32:47], v[170:173], v[178:181], v[32:47]
	s_waitcnt lgkmcnt(8)
	v_mfma_f32_32x32x16_bf16 v[16:31], v[182:185], v[174:177], v[16:31]
	v_mfma_f32_32x32x16_bf16 v[0:15], v[182:185], v[178:181], v[0:15]
	ds_read_b128 v[222:225], v132 offset:96
	ds_read_b128 v[226:229], v136 offset:36960
	ds_read_b128 v[230:233], v136 offset:41568
	ds_read_b128 v[234:237], v132 offset:4704
	s_waitcnt lgkmcnt(10)
	v_mfma_f32_32x32x16_bf16 v[48:63], v[186:189], v[190:193], v[48:63]
	s_waitcnt lgkmcnt(9)
	v_mfma_f32_32x32x16_bf16 v[32:47], v[186:189], v[194:197], v[32:47]
	s_waitcnt lgkmcnt(8)
	v_mfma_f32_32x32x16_bf16 v[16:31], v[198:201], v[190:193], v[16:31]
	v_mfma_f32_32x32x16_bf16 v[0:15], v[198:201], v[194:197], v[0:15]
	s_waitcnt vmcnt(11)
	ds_write_b128 v134, v[64:67] offset:55296
	s_waitcnt lgkmcnt(7)
	v_mfma_f32_32x32x16_bf16 v[48:63], v[202:205], v[206:209], v[48:63]
	s_waitcnt vmcnt(10)
	ds_write_b128 v134, v[68:71] offset:64512
	s_waitcnt lgkmcnt(7)
	v_mfma_f32_32x32x16_bf16 v[32:47], v[202:205], v[210:213], v[32:47]
	s_waitcnt vmcnt(9)
	ds_write_b128 v135, v[72:75] offset:18432
	s_waitcnt lgkmcnt(7)
	v_mfma_f32_32x32x16_bf16 v[16:31], v[214:217], v[206:209], v[16:31]
	v_mfma_f32_32x32x16_bf16 v[0:15], v[214:217], v[210:213], v[0:15]
	s_waitcnt vmcnt(8)
	ds_write_b128 v135, v[76:79] offset:27648
	s_waitcnt lgkmcnt(6)
	v_mfma_f32_32x32x16_bf16 v[48:63], v[222:225], v[226:229], v[48:63]
	s_waitcnt vmcnt(7)
	ds_write_b128 v128, v[80:83]
	s_waitcnt lgkmcnt(6)
	v_mfma_f32_32x32x16_bf16 v[32:47], v[222:225], v[230:233], v[32:47]
	s_waitcnt vmcnt(6)
	ds_write_b128 v128, v[84:87] offset:9216
	s_waitcnt lgkmcnt(6)
	v_mfma_f32_32x32x16_bf16 v[16:31], v[234:237], v[226:229], v[16:31]
	v_mfma_f32_32x32x16_bf16 v[0:15], v[234:237], v[230:233], v[0:15]
	s_waitcnt lgkmcnt(0)
	s_barrier
; template <class AS, class EP>
; DEVI void gemm_tile(const AS& as, const u16* __restrict__ Bt, int K, int m0, int n0, const EP& ep, char* lds) {
;     ...
;   GLOAD(ra0, rb0, 0); GLOAD(ra1, rb1, 1); LWRITE(0, ra0, rb0); __syncthreads();
;   for (int kt = 0; kt < KT; kt += 2) {
;     if (kt + 2 < KT) GLOAD(ra0, rb0, kt + 2);
;     __builtin_amdgcn_sched_barrier(0);
;     COMPUTE(0);
;     __builtin_amdgcn_sched_barrier(0);
;     LWRITE(1, ra1, rb1);
;     __syncthreads();
;     if (kt + 3 < KT) GLOAD(ra1, rb1, kt + 3);
;     __builtin_amdgcn_sched_barrier(0);
;     COMPUTE(1);
;     __builtin_amdgcn_sched_barrier(0);
;     if (kt + 2 < KT) LWRITE(0, ra0, rb0);
;     __syncthreads();
	global_load_dwordx4 v[64:67], v[112:113], off offset:1664
	global_load_dwordx4 v[68:71], v[114:115], off offset:1664
	global_load_dwordx4 v[72:75], v[116:117], off offset:1664
	global_load_dwordx4 v[76:79], v[118:119], off offset:1664
	global_load_dwordx4 v[80:83], v[120:121], off offset:1664
	global_load_dwordx4 v[84:87], v[122:123], off offset:1664
	ds_read_b128 v[170:173], v132 offset:55296
	ds_read_b128 v[174:177], v133
	ds_read_b128 v[178:181], v133 offset:4608
	ds_read_b128 v[182:185], v132 offset:59904
	ds_read_b128 v[186:189], v132 offset:55328
	ds_read_b128 v[190:193], v133 offset:32
	ds_read_b128 v[194:197], v133 offset:4640
	ds_read_b128 v[198:201], v132 offset:59936
	ds_read_b128 v[202:205], v132 offset:55360
	ds_read_b128 v[206:209], v133 offset:64
	ds_read_b128 v[210:213], v133 offset:4672
	ds_read_b128 v[214:217], v132 offset:59968
	s_waitcnt lgkmcnt(10)
	v_mfma_f32_32x32x16_bf16 v[48:63], v[170:173], v[174:177], v[48:63]
	s_waitcnt lgkmcnt(9)
	v_mfma_f32_32x32x16_bf16 v[32:47], v[170:173], v[178:181], v[32:47]
	s_waitcnt lgkmcnt(8)
	v_mfma_f32_32x32x16_bf16 v[16:31], v[182:185], v[174:177], v[16:31]
	v_mfma_f32_32x32x16_bf16 v[0:15], v[182:185], v[178:181], v[0:15]
	ds_read_b128 v[222:225], v132 offset:55392
	ds_read_b128 v[226:229], v133 offset:96
	ds_read_b128 v[230:233], v133 offset:4704
	ds_read_b128 v[234:237], v132 offset:60000
	s_waitcnt lgkmcnt(10)
	v_mfma_f32_32x32x16_bf16 v[48:63], v[186:189], v[190:193], v[48:63]
	s_waitcnt lgkmcnt(9)
	v_mfma_f32_32x32x16_bf16 v[32:47], v[186:189], v[194:197], v[32:47]
	s_waitcnt lgkmcnt(8)
	v_mfma_f32_32x32x16_bf16 v[16:31], v[198:201], v[190:193], v[16:31]
	v_mfma_f32_32x32x16_bf16 v[0:15], v[198:201], v[194:197], v[0:15]
	s_waitcnt vmcnt(11)
	ds_write_b128 v134, v[88:91]
	s_waitcnt lgkmcnt(7)
	v_mfma_f32_32x32x16_bf16 v[48:63], v[202:205], v[206:209], v[48:63]
	s_waitcnt vmcnt(10)
	ds_write_b128 v134, v[92:95] offset:9216
	s_waitcnt lgkmcnt(7)
	v_mfma_f32_32x32x16_bf16 v[32:47], v[202:205], v[210:213], v[32:47]
	s_waitcnt vmcnt(9)
	ds_write_b128 v134, v[96:99] offset:18432
	s_waitcnt lgkmcnt(7)
	v_mfma_f32_32x32x16_bf16 v[16:31], v[214:217], v[206:209], v[16:31]
	v_mfma_f32_32x32x16_bf16 v[0:15], v[214:217], v[210:213], v[0:15]
	s_waitcnt vmcnt(8)
	ds_write_b128 v134, v[100:103] offset:27648
	s_waitcnt lgkmcnt(6)
	v_mfma_f32_32x32x16_bf16 v[48:63], v[222:225], v[226:229], v[48:63]
	s_waitcnt vmcnt(7)
	ds_write_b128 v134, v[104:107] offset:36864
	s_waitcnt lgkmcnt(6)
	v_mfma_f32_32x32x16_bf16 v[32:47], v[222:225], v[230:233], v[32:47]
	s_waitcnt vmcnt(6)
	ds_write_b128 v134, v[108:111] offset:46080
	s_waitcnt lgkmcnt(6)
	v_mfma_f32_32x32x16_bf16 v[16:31], v[234:237], v[226:229], v[16:31]
	v_mfma_f32_32x32x16_bf16 v[0:15], v[234:237], v[230:233], v[0:15]
	s_waitcnt lgkmcnt(0)
	s_barrier
	global_load_dwordx4 v[88:91], v[112:113], off offset:1792
	global_load_dwordx4 v[92:95], v[114:115], off offset:1792
	global_load_dwordx4 v[96:99], v[116:117], off offset:1792
	global_load_dwordx4 v[100:103], v[118:119], off offset:1792
	global_load_dwordx4 v[104:107], v[120:121], off offset:1792
	global_load_dwordx4 v[108:111], v[122:123], off offset:1792
	ds_read_b128 v[170:173], v132
	ds_read_b128 v[174:177], v136 offset:36864
	ds_read_b128 v[178:181], v136 offset:41472
	ds_read_b128 v[182:185], v132 offset:4608
	ds_read_b128 v[186:189], v132 offset:32
	ds_read_b128 v[190:193], v136 offset:36896
	ds_read_b128 v[194:197], v136 offset:41504
	ds_read_b128 v[198:201], v132 offset:4640
	ds_read_b128 v[202:205], v132 offset:64
	ds_read_b128 v[206:209], v136 offset:36928
	ds_read_b128 v[210:213], v136 offset:41536
	ds_read_b128 v[214:217], v132 offset:4672
	s_waitcnt lgkmcnt(10)
	v_mfma_f32_32x32x16_bf16 v[48:63], v[170:173], v[174:177], v[48:63]
	s_waitcnt lgkmcnt(9)
	v_mfma_f32_32x32x16_bf16 v[32:47], v[170:173], v[178:181], v[32:47]
	s_waitcnt lgkmcnt(8)
	v_mfma_f32_32x32x16_bf16 v[16:31], v[182:185], v[174:177], v[16:31]
	v_mfma_f32_32x32x16_bf16 v[0:15], v[182:185], v[178:181], v[0:15]
	ds_read_b128 v[222:225], v132 offset:96
	ds_read_b128 v[226:229], v136 offset:36960
	ds_read_b128 v[230:233], v136 offset:41568
	ds_read_b128 v[234:237], v132 offset:4704
	s_waitcnt lgkmcnt(10)
	v_mfma_f32_32x32x16_bf16 v[48:63], v[186:189], v[190:193], v[48:63]
	s_waitcnt lgkmcnt(9)
	v_mfma_f32_32x32x16_bf16 v[32:47], v[186:189], v[194:197], v[32:47]
	s_waitcnt lgkmcnt(8)
	v_mfma_f32_32x32x16_bf16 v[16:31], v[198:201], v[190:193], v[16:31]
	v_mfma_f32_32x32x16_bf16 v[0:15], v[198:201], v[194:197], v[0:15]
	s_waitcnt vmcnt(11)
	ds_write_b128 v134, v[64:67] offset:55296
	s_waitcnt lgkmcnt(7)
	v_mfma_f32_32x32x16_bf16 v[48:63], v[202:205], v[206:209], v[48:63]
	s_waitcnt vmcnt(10)
	ds_write_b128 v134, v[68:71] offset:64512
	s_waitcnt lgkmcnt(7)
	v_mfma_f32_32x32x16_bf16 v[32:47], v[202:205], v[210:213], v[32:47]
	s_waitcnt vmcnt(9)
	ds_write_b128 v135, v[72:75] offset:18432
	s_waitcnt lgkmcnt(7)
	v_mfma_f32_32x32x16_bf16 v[16:31], v[214:217], v[206:209], v[16:31]
	v_mfma_f32_32x32x16_bf16 v[0:15], v[214:217], v[210:213], v[0:15]
	s_waitcnt vmcnt(8)
	ds_write_b128 v135, v[76:79] offset:27648
	s_waitcnt lgkmcnt(6)
	v_mfma_f32_32x32x16_bf16 v[48:63], v[222:225], v[226:229], v[48:63]
	s_waitcnt vmcnt(7)
	ds_write_b128 v128, v[80:83]
	s_waitcnt lgkmcnt(6)
	v_mfma_f32_32x32x16_bf16 v[32:47], v[222:225], v[230:233], v[32:47]
	s_waitcnt vmcnt(6)
	ds_write_b128 v128, v[84:87] offset:9216
	s_waitcnt lgkmcnt(6)
	v_mfma_f32_32x32x16_bf16 v[16:31], v[234:237], v[226:229], v[16:31]
	v_mfma_f32_32x32x16_bf16 v[0:15], v[234:237], v[230:233], v[0:15]
	s_waitcnt lgkmcnt(0)
	s_barrier
; template <class AS, class EP>
; DEVI void gemm_tile(const AS& as, const u16* __restrict__ Bt, int K, int m0, int n0, const EP& ep, char* lds) {
;     ...
;   GLOAD(ra0, rb0, 0); GLOAD(ra1, rb1, 1); LWRITE(0, ra0, rb0); __syncthreads();
;   for (int kt = 0; kt < KT; kt += 2) {
;     if (kt + 2 < KT) GLOAD(ra0, rb0, kt + 2);
;     __builtin_amdgcn_sched_barrier(0);
;     COMPUTE(0);
;     __builtin_amdgcn_sched_barrier(0);
;     LWRITE(1, ra1, rb1);
;     __syncthreads();
;     if (kt + 3 < KT) GLOAD(ra1, rb1, kt + 3);
;     __builtin_amdgcn_sched_barrier(0);
;     COMPUTE(1);
;     __builtin_amdgcn_sched_barrier(0);
;     if (kt + 2 < KT) LWRITE(0, ra0, rb0);
;     __syncthreads();
	global_load_dwordx4 v[64:67], v[112:113], off offset:1920
	global_load_dwordx4 v[68:71], v[114:115], off offset:1920
	global_load_dwordx4 v[72:75], v[116:117], off offset:1920
	global_load_dwordx4 v[76:79], v[118:119], off offset:1920
	global_load_dwordx4 v[80:83], v[120:121], off offset:1920
	global_load_dwordx4 v[84:87], v[122:123], off offset:1920
	ds_read_b128 v[170:173], v132 offset:55296
	ds_read_b128 v[174:177], v133
	ds_read_b128 v[178:181], v133 offset:4608
	ds_read_b128 v[182:185], v132 offset:59904
	ds_read_b128 v[186:189], v132 offset:55328
	ds_read_b128 v[190:193], v133 offset:32
	ds_read_b128 v[194:197], v133 offset:4640
	ds_read_b128 v[198:201], v132 offset:59936
	ds_read_b128 v[202:205], v132 offset:55360
	ds_read_b128 v[206:209], v133 offset:64
	ds_read_b128 v[210:213], v133 offset:4672
	ds_read_b128 v[214:217], v132 offset:59968
	s_waitcnt lgkmcnt(10)
	v_mfma_f32_32x32x16_bf16 v[48:63], v[170:173], v[174:177], v[48:63]
	s_waitcnt lgkmcnt(9)
	v_mfma_f32_32x32x16_bf16 v[32:47], v[170:173], v[178:181], v[32:47]
	s_waitcnt lgkmcnt(8)
	v_mfma_f32_32x32x16_bf16 v[16:31], v[182:185], v[174:177], v[16:31]
	v_mfma_f32_32x32x16_bf16 v[0:15], v[182:185], v[178:181], v[0:15]
	ds_read_b128 v[222:225], v132 offset:55392
	ds_read_b128 v[226:229], v133 offset:96
	ds_read_b128 v[230:233], v133 offset:4704
	ds_read_b128 v[234:237], v132 offset:60000
	s_waitcnt lgkmcnt(10)
	v_mfma_f32_32x32x16_bf16 v[48:63], v[186:189], v[190:193], v[48:63]
	s_waitcnt lgkmcnt(9)
	v_mfma_f32_32x32x16_bf16 v[32:47], v[186:189], v[194:197], v[32:47]
	s_waitcnt lgkmcnt(8)
	v_mfma_f32_32x32x16_bf16 v[16:31], v[198:201], v[190:193], v[16:31]
	v_mfma_f32_32x32x16_bf16 v[0:15], v[198:201], v[194:197], v[0:15]
	s_waitcnt vmcnt(11)
	ds_write_b128 v134, v[88:91]
	s_waitcnt lgkmcnt(7)
	v_mfma_f32_32x32x16_bf16 v[48:63], v[202:205], v[206:209], v[48:63]
	s_waitcnt vmcnt(10)
	ds_write_b128 v134, v[92:95] offset:9216
	s_waitcnt lgkmcnt(7)
	v_mfma_f32_32x32x16_bf16 v[32:47], v[202:205], v[210:213], v[32:47]
	s_waitcnt vmcnt(9)
	ds_write_b128 v134, v[96:99] offset:18432
	s_waitcnt lgkmcnt(7)
	v_mfma_f32_32x32x16_bf16 v[16:31], v[214:217], v[206:209], v[16:31]
	v_mfma_f32_32x32x16_bf16 v[0:15], v[214:217], v[210:213], v[0:15]
	s_waitcnt vmcnt(8)
	ds_write_b128 v134, v[100:103] offset:27648
	s_waitcnt lgkmcnt(6)
	v_mfma_f32_32x32x16_bf16 v[48:63], v[222:225], v[226:229], v[48:63]
	s_waitcnt vmcnt(7)
	ds_write_b128 v134, v[104:107] offset:36864
	s_waitcnt lgkmcnt(6)
	v_mfma_f32_32x32x16_bf16 v[32:47], v[222:225], v[230:233], v[32:47]
	s_waitcnt vmcnt(6)
	ds_write_b128 v134, v[108:111] offset:46080
	s_waitcnt lgkmcnt(6)
	v_mfma_f32_32x32x16_bf16 v[16:31], v[234:237], v[226:229], v[16:31]
	v_mfma_f32_32x32x16_bf16 v[0:15], v[234:237], v[230:233], v[0:15]
	s_waitcnt lgkmcnt(0)
	s_barrier
	ds_read_b128 v[170:173], v132
	ds_read_b128 v[174:177], v136 offset:36864
	ds_read_b128 v[178:181], v136 offset:41472
	ds_read_b128 v[182:185], v132 offset:4608
	ds_read_b128 v[186:189], v132 offset:32
	ds_read_b128 v[190:193], v136 offset:36896
	ds_read_b128 v[194:197], v136 offset:41504
	ds_read_b128 v[198:201], v132 offset:4640
	ds_read_b128 v[202:205], v132 offset:64
	ds_read_b128 v[206:209], v136 offset:36928
	ds_read_b128 v[210:213], v136 offset:41536
	ds_read_b128 v[214:217], v132 offset:4672
	s_waitcnt lgkmcnt(10)
	v_mfma_f32_32x32x16_bf16 v[48:63], v[170:173], v[174:177], v[48:63]
	s_waitcnt lgkmcnt(9)
	v_mfma_f32_32x32x16_bf16 v[32:47], v[170:173], v[178:181], v[32:47]
	s_waitcnt lgkmcnt(8)
	v_mfma_f32_32x32x16_bf16 v[16:31], v[182:185], v[174:177], v[16:31]
	v_mfma_f32_32x32x16_bf16 v[0:15], v[182:185], v[178:181], v[0:15]
	ds_read_b128 v[222:225], v132 offset:96
	ds_read_b128 v[226:229], v136 offset:36960
	ds_read_b128 v[230:233], v136 offset:41568
	ds_read_b128 v[234:237], v132 offset:4704
	s_waitcnt lgkmcnt(10)
	v_mfma_f32_32x32x16_bf16 v[48:63], v[186:189], v[190:193], v[48:63]
	s_waitcnt lgkmcnt(9)
	v_mfma_f32_32x32x16_bf16 v[32:47], v[186:189], v[194:197], v[32:47]
	s_waitcnt lgkmcnt(8)
	v_mfma_f32_32x32x16_bf16 v[16:31], v[198:201], v[190:193], v[16:31]
	v_mfma_f32_32x32x16_bf16 v[0:15], v[198:201], v[194:197], v[0:15]
	s_waitcnt vmcnt(5)
	ds_write_b128 v134, v[64:67] offset:55296
	s_waitcnt lgkmcnt(7)
	v_mfma_f32_32x32x16_bf16 v[48:63], v[202:205], v[206:209], v[48:63]
	s_waitcnt vmcnt(4)
	ds_write_b128 v134, v[68:71] offset:64512
	s_waitcnt lgkmcnt(7)
	v_mfma_f32_32x32x16_bf16 v[32:47], v[202:205], v[210:213], v[32:47]
	s_waitcnt vmcnt(3)
	ds_write_b128 v135, v[72:75] offset:18432
	s_waitcnt lgkmcnt(7)
	v_mfma_f32_32x32x16_bf16 v[16:31], v[214:217], v[206:209], v[16:31]
	v_mfma_f32_32x32x16_bf16 v[0:15], v[214:217], v[210:213], v[0:15]
	s_waitcnt vmcnt(2)
	ds_write_b128 v135, v[76:79] offset:27648
	s_waitcnt lgkmcnt(6)
	v_mfma_f32_32x32x16_bf16 v[48:63], v[222:225], v[226:229], v[48:63]
	s_waitcnt vmcnt(1)
	ds_write_b128 v128, v[80:83]
	s_waitcnt lgkmcnt(6)
	v_mfma_f32_32x32x16_bf16 v[32:47], v[222:225], v[230:233], v[32:47]
	s_waitcnt vmcnt(0)
	ds_write_b128 v128, v[84:87] offset:9216
	s_waitcnt lgkmcnt(6)
	v_mfma_f32_32x32x16_bf16 v[16:31], v[234:237], v[226:229], v[16:31]
	v_mfma_f32_32x32x16_bf16 v[0:15], v[234:237], v[230:233], v[0:15]
	s_waitcnt lgkmcnt(0)
	s_barrier
; DEVI int crow(int r, int hi) { return (r & 3) + 8 * (r >> 2) + 4 * hi; }
;   DEVI void operator()(const f32x16 (&acc)[2][2], int m0, int n0, int wm, int wn, int r32, int hi, char* lds) const {
;     constexpr int RS = 272;
; #pragma unroll
;     for (int i = 0; i < 2; ++i)
; #pragma unroll
;       for (int j = 0; j < 2; ++j)
; #pragma unroll
;         for (int r = 0; r < 16; ++r) {
;           int row = wm * 64 + i * 32 + crow(r, hi), col = wn * 64 + j * 32 + r32;
;           *(h16*)(lds + row * RS + col * 2) = (h16)acc[i][j][r];
;         }
;     __syncthreads();
	ds_read_b128 v[170:173], v132 offset:55296
	ds_read_b128 v[174:177], v133
	ds_read_b128 v[178:181], v133 offset:4608
	ds_read_b128 v[182:185], v132 offset:59904
	ds_read_b128 v[186:189], v132 offset:55328
	ds_read_b128 v[190:193], v133 offset:32
	ds_read_b128 v[194:197], v133 offset:4640
	ds_read_b128 v[198:201], v132 offset:59936
	ds_read_b128 v[202:205], v132 offset:55360
	ds_read_b128 v[206:209], v133 offset:64
	ds_read_b128 v[210:213], v133 offset:4672
	ds_read_b128 v[214:217], v132 offset:59968
	s_waitcnt lgkmcnt(10)
	v_mfma_f32_32x32x16_bf16 v[48:63], v[170:173], v[174:177], v[48:63]
	s_waitcnt lgkmcnt(9)
	v_mfma_f32_32x32x16_bf16 v[32:47], v[170:173], v[178:181], v[32:47]
	s_waitcnt lgkmcnt(8)
	v_mfma_f32_32x32x16_bf16 v[16:31], v[182:185], v[174:177], v[16:31]
	v_mfma_f32_32x32x16_bf16 v[0:15], v[182:185], v[178:181], v[0:15]
	ds_read_b128 v[222:225], v132 offset:55392
	ds_read_b128 v[226:229], v133 offset:96
	ds_read_b128 v[230:233], v133 offset:4704
	ds_read_b128 v[234:237], v132 offset:60000
	s_waitcnt lgkmcnt(10)
	v_mfma_f32_32x32x16_bf16 v[48:63], v[186:189], v[190:193], v[48:63]
	s_waitcnt lgkmcnt(9)
	v_mfma_f32_32x32x16_bf16 v[32:47], v[186:189], v[194:197], v[32:47]
	s_waitcnt lgkmcnt(8)
	v_mfma_f32_32x32x16_bf16 v[16:31], v[198:201], v[190:193], v[16:31]
	v_mfma_f32_32x32x16_bf16 v[0:15], v[198:201], v[194:197], v[0:15]
	s_waitcnt lgkmcnt(6)
	v_mfma_f32_32x32x16_bf16 v[48:63], v[202:205], v[206:209], v[48:63]
	s_waitcnt lgkmcnt(5)
	v_mfma_f32_32x32x16_bf16 v[32:47], v[202:205], v[210:213], v[32:47]
	s_waitcnt lgkmcnt(4)
	v_mfma_f32_32x32x16_bf16 v[16:31], v[214:217], v[206:209], v[16:31]
	v_mfma_f32_32x32x16_bf16 v[0:15], v[214:217], v[210:213], v[0:15]
	s_waitcnt lgkmcnt(2)
	v_mfma_f32_32x32x16_bf16 v[48:63], v[222:225], v[226:229], v[48:63]
	s_waitcnt lgkmcnt(1)
	v_mfma_f32_32x32x16_bf16 v[32:47], v[222:225], v[230:233], v[32:47]
	s_waitcnt lgkmcnt(0)
	v_mfma_f32_32x32x16_bf16 v[16:31], v[234:237], v[226:229], v[16:31]
	v_mfma_f32_32x32x16_bf16 v[0:15], v[234:237], v[230:233], v[0:15]
	s_nop 5
	v_cvt_f16_f32_e32 v48, v48
	v_lshl_or_b32 v64, v124, 2, v127
	v_cvt_f16_f32_e32 v49, v49
	v_lshlrev_b32_e32 v65, 1, v125
	v_lshl_add_u32 v66, v126, 7, 16
	v_mul_lo_u32 v64, v64, s27
	v_cvt_f16_f32_e32 v50, v50
	v_add3_u32 v64, v66, v65, v64
	v_cvt_f16_f32_e32 v51, v51
	s_barrier
	ds_write_b16 v64, v48
	ds_write_b16 v64, v49 offset:272
	ds_write_b16 v64, v50 offset:544
	ds_write_b16 v64, v51 offset:816
	v_cvt_f16_f32_e32 v48, v52
	v_cvt_f16_f32_e32 v49, v53
	v_cvt_f16_f32_e32 v50, v54
	v_cvt_f16_f32_e32 v51, v55
	ds_write_b16 v64, v48 offset:2176
	ds_write_b16 v64, v49 offset:2448
	ds_write_b16 v64, v50 offset:2720
	ds_write_b16 v64, v51 offset:2992
	v_cvt_f16_f32_e32 v48, v56
	v_cvt_f16_f32_e32 v49, v57
	v_cvt_f16_f32_e32 v50, v58
	v_cvt_f16_f32_e32 v51, v59
	ds_write_b16 v64, v48 offset:4352
	ds_write_b16 v64, v49 offset:4624
	ds_write_b16 v64, v50 offset:4896
	ds_write_b16 v64, v51 offset:5168
	v_cvt_f16_f32_e32 v48, v60
	v_cvt_f16_f32_e32 v32, v32
	v_cvt_f16_f32_e32 v49, v61
	v_cvt_f16_f32_e32 v33, v33
	v_cvt_f16_f32_e32 v50, v62
	v_cvt_f16_f32_e32 v34, v34
	v_cvt_f16_f32_e32 v51, v63
	v_cvt_f16_f32_e32 v35, v35
	ds_write_b16 v64, v48 offset:6528
	ds_write_b16 v64, v49 offset:6800
	ds_write_b16 v64, v50 offset:7072
	ds_write_b16 v64, v51 offset:7344
	ds_write_b16 v64, v32 offset:64
	ds_write_b16 v64, v33 offset:336
	ds_write_b16 v64, v34 offset:608
	ds_write_b16 v64, v35 offset:880
	v_cvt_f16_f32_e32 v32, v36
	v_cvt_f16_f32_e32 v33, v37
	v_cvt_f16_f32_e32 v34, v38
	v_cvt_f16_f32_e32 v35, v39
	ds_write_b16 v64, v32 offset:2240
	ds_write_b16 v64, v33 offset:2512
	ds_write_b16 v64, v34 offset:2784
	ds_write_b16 v64, v35 offset:3056
	v_cvt_f16_f32_e32 v32, v40
	v_cvt_f16_f32_e32 v33, v41
	v_cvt_f16_f32_e32 v34, v42
	v_cvt_f16_f32_e32 v35, v43
	ds_write_b16 v64, v32 offset:4416
	ds_write_b16 v64, v33 offset:4688
	ds_write_b16 v64, v34 offset:4960
	ds_write_b16 v64, v35 offset:5232
	v_cvt_f16_f32_e32 v32, v44
	v_cvt_f16_f32_e32 v16, v16
	v_cvt_f16_f32_e32 v33, v45
	v_cvt_f16_f32_e32 v17, v17
	v_cvt_f16_f32_e32 v34, v46
	v_cvt_f16_f32_e32 v18, v18
	v_cvt_f16_f32_e32 v35, v47
	v_cvt_f16_f32_e32 v19, v19
	ds_write_b16 v64, v32 offset:6592
	ds_write_b16 v64, v33 offset:6864
	ds_write_b16 v64, v34 offset:7136
	ds_write_b16 v64, v35 offset:7408
	ds_write_b16 v64, v16 offset:8704
	ds_write_b16 v64, v17 offset:8976
	ds_write_b16 v64, v18 offset:9248
	ds_write_b16 v64, v19 offset:9520
	v_cvt_f16_f32_e32 v16, v20
	v_cvt_f16_f32_e32 v17, v21
	v_cvt_f16_f32_e32 v18, v22
	v_cvt_f16_f32_e32 v19, v23
	ds_write_b16 v64, v16 offset:10880
	ds_write_b16 v64, v17 offset:11152
	ds_write_b16 v64, v18 offset:11424
	ds_write_b16 v64, v19 offset:11696
	v_cvt_f16_f32_e32 v16, v24
	v_cvt_f16_f32_e32 v17, v25
	v_cvt_f16_f32_e32 v18, v26
	v_cvt_f16_f32_e32 v19, v27
	ds_write_b16 v64, v16 offset:13056
	ds_write_b16 v64, v17 offset:13328
	ds_write_b16 v64, v18 offset:13600
	ds_write_b16 v64, v19 offset:13872
	v_cvt_f16_f32_e32 v16, v28
	v_cvt_f16_f32_e32 v0, v0
	v_cvt_f16_f32_e32 v17, v29
	v_cvt_f16_f32_e32 v1, v1
	v_cvt_f16_f32_e32 v18, v30
	v_cvt_f16_f32_e32 v2, v2
	v_cvt_f16_f32_e32 v19, v31
	v_cvt_f16_f32_e32 v3, v3
	ds_write_b16 v64, v16 offset:15232
	ds_write_b16 v64, v17 offset:15504
	ds_write_b16 v64, v18 offset:15776
	ds_write_b16 v64, v19 offset:16048
	ds_write_b16 v64, v0 offset:8768
	ds_write_b16 v64, v1 offset:9040
	ds_write_b16 v64, v2 offset:9312
	ds_write_b16 v64, v3 offset:9584
	v_cvt_f16_f32_e32 v0, v4
	v_cvt_f16_f32_e32 v1, v5
	v_cvt_f16_f32_e32 v2, v6
	v_cvt_f16_f32_e32 v3, v7
	ds_write_b16 v64, v0 offset:10944
	ds_write_b16 v64, v1 offset:11216
	ds_write_b16 v64, v2 offset:11488
	ds_write_b16 v64, v3 offset:11760
	v_cvt_f16_f32_e32 v0, v8
	v_cvt_f16_f32_e32 v1, v9
	v_cvt_f16_f32_e32 v2, v10
	v_cvt_f16_f32_e32 v3, v11
	ds_write_b16 v64, v0 offset:13120
	ds_write_b16 v64, v1 offset:13392
	ds_write_b16 v64, v2 offset:13664
	ds_write_b16 v64, v3 offset:13936
	v_cvt_f16_f32_e32 v0, v12
	v_cvt_f16_f32_e32 v1, v13
	v_cvt_f16_f32_e32 v2, v14
	v_cvt_f16_f32_e32 v3, v15
	ds_write_b16 v64, v0 offset:15296
	ds_write_b16 v64, v1 offset:15568
	ds_write_b16 v64, v2 offset:15840
	ds_write_b16 v64, v3 offset:16112
	v_mov_b32_e32 v2, v131
	s_waitcnt lgkmcnt(0)
	s_barrier
; DEVI int ltid() { int t = __builtin_amdgcn_workitem_id_x(); asm volatile("" : "+v"(t)); return t; }
;   DEVI void operator()(const f32x16 (&acc)[2][2], int m0, int n0, int wm, int wn, int r32, int hi, char* lds) const {
;     ...
;     const int tid = ltid();
; #pragma unroll
;     for (int i = 0; i < 8; ++i) {
;       int c = tid + i * 512; int row = c >> 4, ch = c & 15;
;       int col = n0 + ch * 8;
;       if (col < nvalid) *(u32x4*)(Z + (size_t)(m0 + row) * ldz + col) = *(const u32x4*)(lds + row * RS + ch * 16);
;     }
;     __syncthreads();
	s_nop 0
	v_and_b32_e32 v3, 15, v2
	v_lshlrev_b32_e32 v0, 3, v3
	v_subrev_u32_e32 v0, s10, v0
	v_add_u32_e32 v0, s14, v0
	s_movk_i32 s10, 0x5e0
	v_cmp_gt_i32_e32 vcc, s10, v0
	s_and_saveexec_b64 s[10:11], vcc
	s_cbranch_execz .LBB0_816
	v_lshl_add_u32 v8, v3, 4, 16
	v_ashrrev_i32_e32 v3, 4, v2
	v_mad_u64_u32 v[4:5], s[18:19], v3, s27, v[8:9]
	ds_read_b128 v[4:7], v4
	v_ashrrev_i32_e32 v1, 31, v0
	v_add_u32_e32 v3, s16, v3
	v_mov_b64_e32 v[10:11], s[6:7]
	v_mad_i64_i32 v[12:13], s[18:19], v3, s23, v[10:11]
	v_lshlrev_b64 v[14:15], 1, v[0:1]
	v_lshl_add_u64 v[0:1], v[12:13], 0, v[14:15]
	s_waitcnt lgkmcnt(0)
	global_store_dwordx4 v[0:1], v[4:7], off
	v_add_u32_e32 v0, 0x200, v2
	v_ashrrev_i32_e32 v3, 4, v0
	v_mad_u64_u32 v[0:1], s[18:19], v3, s27, v[8:9]
	ds_read_b128 v[4:7], v0
	v_add_u32_e32 v0, s16, v3
	v_mad_i64_i32 v[0:1], s[18:19], v0, s23, v[10:11]
	v_lshl_add_u64 v[0:1], v[0:1], 0, v[14:15]
	s_waitcnt lgkmcnt(0)
	global_store_dwordx4 v[0:1], v[4:7], off
	v_add_u32_e32 v0, 0x400, v2
	v_ashrrev_i32_e32 v3, 4, v0
	v_mad_u64_u32 v[0:1], s[18:19], v3, s27, v[8:9]
	ds_read_b128 v[4:7], v0
	v_add_u32_e32 v0, s16, v3
	v_mad_i64_i32 v[0:1], s[18:19], v0, s23, v[10:11]
	v_lshl_add_u64 v[0:1], v[0:1], 0, v[14:15]
	s_waitcnt lgkmcnt(0)
	global_store_dwordx4 v[0:1], v[4:7], off
	v_add_u32_e32 v0, 0x600, v2
	v_ashrrev_i32_e32 v3, 4, v0
	v_mad_u64_u32 v[0:1], s[18:19], v3, s27, v[8:9]
	ds_read_b128 v[4:7], v0
	v_add_u32_e32 v0, s16, v3
	v_mad_i64_i32 v[0:1], s[18:19], v0, s23, v[10:11]
	v_lshl_add_u64 v[0:1], v[0:1], 0, v[14:15]
	s_waitcnt lgkmcnt(0)
	global_store_dwordx4 v[0:1], v[4:7], off
	v_add_u32_e32 v0, 0x800, v2
	v_ashrrev_i32_e32 v3, 4, v0
	v_mad_u64_u32 v[0:1], s[18:19], v3, s27, v[8:9]
	ds_read_b128 v[4:7], v0
	v_add_u32_e32 v0, s16, v3
	v_mad_i64_i32 v[0:1], s[18:19], v0, s23, v[10:11]
	v_lshl_add_u64 v[0:1], v[0:1], 0, v[14:15]
	s_waitcnt lgkmcnt(0)
	global_store_dwordx4 v[0:1], v[4:7], off
	v_add_u32_e32 v0, 0xa00, v2
	v_ashrrev_i32_e32 v3, 4, v0
	v_mad_u64_u32 v[0:1], s[18:19], v3, s27, v[8:9]
	ds_read_b128 v[4:7], v0
	v_add_u32_e32 v0, s16, v3
	v_mad_i64_i32 v[0:1], s[18:19], v0, s23, v[10:11]
	v_lshl_add_u64 v[0:1], v[0:1], 0, v[14:15]
	s_waitcnt lgkmcnt(0)
	global_store_dwordx4 v[0:1], v[4:7], off
	v_add_u32_e32 v0, 0xc00, v2
	v_ashrrev_i32_e32 v3, 4, v0
	v_mad_u64_u32 v[0:1], s[18:19], v3, s27, v[8:9]
	ds_read_b128 v[4:7], v0
	v_add_u32_e32 v0, s16, v3
	v_mad_i64_i32 v[0:1], s[18:19], v0, s23, v[10:11]
	v_lshl_add_u64 v[0:1], v[0:1], 0, v[14:15]
	s_waitcnt lgkmcnt(0)
	global_store_dwordx4 v[0:1], v[4:7], off
	v_add_u32_e32 v0, 0xe00, v2
	s_nop 0
	v_ashrrev_i32_e32 v4, 4, v0
	v_mad_u64_u32 v[0:1], s[18:19], v4, s27, v[8:9]
	ds_read_b128 v[0:3], v0
	v_add_u32_e32 v4, s16, v4
	v_mad_i64_i32 v[4:5], s[16:17], v4, s23, v[10:11]
	v_lshl_add_u64 v[4:5], v[4:5], 0, v[14:15]
	s_waitcnt lgkmcnt(0)
	global_store_dwordx4 v[4:5], v[0:3], off
	s_branch .LBB0_816

; DEVI void phase_combine(const Params& p, int l) {
;     ...
;     int t = it / 48, ch = it % 48; int c0 = ch * 8; size_t idx = (size_t)t * 384 + c0;
;     h16x8 a = *(const h16x8*)(Of + idx), bq = *(const h16x8*)(Ob + idx), r = *(const h16x8*)(Xr + idx), k = *(const h16x8*)(Xk + idx),
;           v = *(const h16x8*)(Xv + idx), sg = *(const h16x8*)(Sga + idx);
;     float of[8]; float s1 = 0.f, rks = 0.f;
; #pragma unroll
;     for (int j = 0; j < 8; ++j) { of[j] = (float)a[j] + (float)bq[j]; s1 += of[j]; rks += (float)r[j] * (float)k[j] * rk[c0 + j]; }
;     if (t >= 65536) {
;       const int bs = (t - 65536) >> 14, pos = (t - 65536) & 16383;
;       const int dsel = pos >= 8192 ? 0 : 1, ls = dsel == 0 ? pos - 8192 : 8191 - pos, hh = c0 >> 6;
;       const h16* qv = (const h16*)(p.ws + OFF_QP) + ((size_t)(dsel * 2 + bs) * 8192 + ls) * 384 + hh * 64;
;       const float* Sm = (const float*)(p.ws + OFF_SMID) + ((size_t)((bs * 6 + hh) * 2 + dsel) * 64 + (c0 & 63)) * 64;
;       float corr[8];
; #pragma unroll
;       for (int j = 0; j < 8; ++j) corr[j] = 0.f;
; #pragma unroll 2
;       for (int i8 = 0; i8 < 8; ++i8) {
;         h16x8 q8 = *(const h16x8*)(qv + i8 * 8);
; #pragma unroll
;         for (int j = 0; j < 8; ++j) {
;           f32x4 m0 = *(const f32x4*)(Sm + j * 64 + i8 * 8), m1 = *(const f32x4*)(Sm + j * 64 + i8 * 8 + 4);
;           corr[j] += m0[0] * (float)q8[0] + m0[1] * (float)q8[1] + m0[2] * (float)q8[2] + m0[3] * (float)q8[3]
;                    + m1[0] * (float)q8[4] + m1[1] * (float)q8[5] + m1[2] * (float)q8[6] + m1[3] * (float)q8[7];
.LBB0_823:
	s_mov_b32 s42, 0x2aaaaaab
	v_mul_hi_i32 v0, v59, s42
	v_lshrrev_b32_e32 v1, 31, v0
	v_ashrrev_i32_e32 v0, 3, v0
	v_add_u32_e32 v25, v0, v1
	v_mul_lo_u32 v0, v25, 48
	v_sub_u32_e32 v24, v59, v0
	v_lshlrev_b32_e32 v34, 3, v24
	v_ashrrev_i32_e32 v35, 31, v34
	v_mad_i64_i32 v[0:1], s[42:43], v25, s24, v[34:35]
	v_lshlrev_b64 v[0:1], 1, v[0:1]
	v_lshl_add_u64 v[32:33], s[6:7], 0, v[0:1]
	v_lshl_add_u64 v[2:3], s[8:9], 0, v[0:1]
	global_load_dwordx4 v[26:29], v[32:33], off
	global_load_dwordx4 v[40:43], v[2:3], off
	v_lshl_add_u64 v[2:3], s[10:11], 0, v[0:1]
	global_load_dwordx4 v[8:11], v[2:3], off
	v_lshl_add_u64 v[2:3], s[12:13], 0, v[0:1]
	global_load_dwordx4 v[12:15], v[2:3], off
	v_lshl_add_u64 v[2:3], s[14:15], 0, v[0:1]
	v_lshl_add_u64 v[0:1], s[16:17], 0, v[0:1]
	v_lshl_add_u64 v[20:21], v[34:35], 2, s[30:31]
	global_load_dwordx4 v[4:7], v[2:3], off
	s_mov_b32 s42, 0x2fffff
	global_load_dwordx4 v[0:3], v[0:1], off
	s_nop 0
	global_load_dwordx4 v[16:19], v[20:21], off offset:16
	s_nop 0
	global_load_dwordx4 v[20:23], v[20:21], off
	v_cmp_lt_i32_e32 vcc, s42, v59
	s_waitcnt vmcnt(7)
	v_cvt_f32_f16_e32 v30, v26
	v_cvt_f32_f16_sdwa v31, v26 dst_sel:DWORD dst_unused:UNUSED_PAD src0_sel:WORD_1
	s_waitcnt vmcnt(6)
	v_cvt_f32_f16_e32 v36, v40
	v_cvt_f32_f16_sdwa v37, v40 dst_sel:DWORD dst_unused:UNUSED_PAD src0_sel:WORD_1
	v_pk_add_f32 v[36:37], v[30:31], v[36:37]
	s_nop 0
	v_add_f32_e32 v26, 0, v36
	v_add_f32_e32 v40, v37, v26
	v_cvt_f32_f16_e32 v26, v27
	v_cvt_f32_f16_sdwa v27, v27 dst_sel:DWORD dst_unused:UNUSED_PAD src0_sel:WORD_1
	v_cvt_f32_f16_e32 v30, v41
	v_cvt_f32_f16_sdwa v31, v41 dst_sel:DWORD dst_unused:UNUSED_PAD src0_sel:WORD_1
	v_pk_add_f32 v[38:39], v[26:27], v[30:31]
	s_nop 0
	v_add_f32_e32 v26, v38, v40
	v_add_f32_e32 v44, v39, v26
	v_cvt_f32_f16_e32 v26, v28
	v_cvt_f32_f16_sdwa v27, v28 dst_sel:DWORD dst_unused:UNUSED_PAD src0_sel:WORD_1
	v_cvt_f32_f16_e32 v30, v42
	v_cvt_f32_f16_sdwa v31, v42 dst_sel:DWORD dst_unused:UNUSED_PAD src0_sel:WORD_1
	v_cvt_f32_f16_e32 v28, v43
	v_pk_add_f32 v[40:41], v[26:27], v[30:31]
	s_nop 0
	v_add_f32_e32 v26, v40, v44
	v_add_f32_e32 v30, v41, v26
	v_cvt_f32_f16_e32 v26, v29
	v_cvt_f32_f16_sdwa v27, v29 dst_sel:DWORD dst_unused:UNUSED_PAD src0_sel:WORD_1
	v_cvt_f32_f16_sdwa v29, v43 dst_sel:DWORD dst_unused:UNUSED_PAD src0_sel:WORD_1
	v_pk_add_f32 v[42:43], v[26:27], v[28:29]
	s_nop 0
	v_add_f32_e32 v26, v42, v30
	v_add_f32_e32 v26, v43, v26
	s_and_saveexec_b64 s[42:43], vcc
	s_cbranch_execz .LBB0_822
	v_add_u32_e32 v26, 0xffff0000, v25
	v_and_b32_e32 v25, 0x3fff, v25
	v_subrev_co_u32_e32 v27, vcc, 0x2000, v25
	v_lshrrev_b32_e32 v26, 14, v26
	v_sub_u32_e32 v25, 0x1fff, v25
	v_cndmask_b32_e64 v28, 0, 2, vcc
	v_cndmask_b32_e32 v25, v27, v25, vcc
	v_lshrrev_b32_e32 v27, 6, v34
	v_add_u32_e32 v28, v28, v26
	v_mul_u32_u24_e32 v26, 6, v26
	v_add_lshl_u32 v29, v26, v27, 1
	v_mad_i64_i32 v[26:27], s[80:81], v25, s35, 0
	s_mov_b32 s44, 0x600000
	v_lshlrev_b32_e32 v25, 1, v34
	v_mad_u64_u32 v[26:27], s[80:81], v28, s44, v[26:27]
	v_and_b32_e32 v128, 0x380, v25
	v_lshl_add_u64 v[26:27], v[26:27], 0, v[128:129]
	v_addc_co_u32_e32 v128, vcc, 0, v29, vcc
	v_lshl_add_u64 v[44:45], s[90:91], 0, v[26:27]
	v_lshlrev_b64 v[26:27], 14, v[128:129]
	v_and_b32_e32 v24, 7, v24
	v_lshl_or_b32 v26, v24, 4, v26
	v_lshl_add_u64 v[46:47], s[38:39], 0, v[26:27]
	v_mov_b32_e32 v58, v24
	v_lshlrev_b32_e32 v56, 3, v24
	v_mov_b32_e32 v57, 0
	v_lshl_add_u64 v[56:57], v[44:45], 0, v[56:57]
	v_add_co_u32_e32 v56, vcc, 0x3d2b0000, v56
	s_mov_b64 s[80:81], 0x1000
	s_nop 0
	v_addc_co_u32_e32 v57, vcc, 0, v57, vcc
	global_load_dwordx2 v[132:133], v[56:57], off
	global_load_dwordx2 v[134:135], v[56:57], off offset:64
	global_load_dwordx4 v[158:161], v[46:47], off offset:-1024
	global_load_dwordx4 v[162:165], v[46:47], off offset:-896
	global_load_dwordx4 v[166:169], v[46:47], off offset:-768
	global_load_dwordx4 v[170:173], v[46:47], off offset:-640
	global_load_dwordx4 v[174:177], v[46:47], off offset:-512
	global_load_dwordx4 v[178:181], v[46:47], off offset:-384
	global_load_dwordx4 v[182:185], v[46:47], off offset:-256
	global_load_dwordx4 v[186:189], v[46:47], off offset:-128
	s_waitcnt vmcnt(8)
	v_cvt_f32_f16_e32 v24, v132
	v_cvt_f32_f16_sdwa v25, v132 dst_sel:DWORD dst_unused:UNUSED_PAD src0_sel:WORD_1
	v_cvt_f32_f16_e32 v26, v133
	v_cvt_f32_f16_sdwa v27, v133 dst_sel:DWORD dst_unused:UNUSED_PAD src0_sel:WORD_1
	v_cvt_f32_f16_e32 v28, v134
	v_cvt_f32_f16_sdwa v29, v134 dst_sel:DWORD dst_unused:UNUSED_PAD src0_sel:WORD_1
	v_cvt_f32_f16_e32 v30, v135
	v_cvt_f32_f16_sdwa v31, v135 dst_sel:DWORD dst_unused:UNUSED_PAD src0_sel:WORD_1
	global_load_dwordx4 v[190:193], v[46:47], off
	global_load_dwordx4 v[194:197], v[46:47], off offset:128
	global_load_dwordx4 v[198:201], v[46:47], off offset:256
	global_load_dwordx4 v[202:205], v[46:47], off offset:384
	global_load_dwordx4 v[206:209], v[46:47], off offset:512
	global_load_dwordx4 v[210:213], v[46:47], off offset:640
	global_load_dwordx4 v[214:217], v[46:47], off offset:768
	global_load_dwordx4 v[222:225], v[46:47], off offset:896
	s_waitcnt vmcnt(8)
; DEVI void phase_combine(const Params& p, int l) {
;     ...
; #pragma unroll 2
;       for (int i8 = 0; i8 < 8; ++i8) {
;         h16x8 q8 = *(const h16x8*)(qv + i8 * 8);
; #pragma unroll
;         for (int j = 0; j < 8; ++j) {
;           f32x4 m0 = *(const f32x4*)(Sm + j * 64 + i8 * 8), m1 = *(const f32x4*)(Sm + j * 64 + i8 * 8 + 4);
;           corr[j] += m0[0] * (float)q8[0] + m0[1] * (float)q8[1] + m0[2] * (float)q8[2] + m0[3] * (float)q8[3]
;                    + m1[0] * (float)q8[4] + m1[1] * (float)q8[5] + m1[2] * (float)q8[6] + m1[3] * (float)q8[7];
;         }
	v_mul_f32_e32 v60, v158, v24
	v_mul_f32_e32 v61, v166, v24
	v_mul_f32_e32 v62, v174, v24
	v_mul_f32_e32 v63, v182, v24
	v_fmac_f32_e32 v60, v159, v25
	v_fmac_f32_e32 v61, v167, v25
	v_fmac_f32_e32 v62, v175, v25
	v_fmac_f32_e32 v63, v183, v25
	v_fmac_f32_e32 v60, v160, v26
	v_fmac_f32_e32 v61, v168, v26
	v_fmac_f32_e32 v62, v176, v26
	v_fmac_f32_e32 v63, v184, v26
	v_fmac_f32_e32 v60, v161, v27
	v_fmac_f32_e32 v61, v169, v27
	v_fmac_f32_e32 v62, v177, v27
	v_fmac_f32_e32 v63, v185, v27
	v_fmac_f32_e32 v60, v162, v28
	v_fmac_f32_e32 v61, v170, v28
	v_fmac_f32_e32 v62, v178, v28
	v_fmac_f32_e32 v63, v186, v28
	v_fmac_f32_e32 v60, v163, v29
	v_fmac_f32_e32 v61, v171, v29
	v_fmac_f32_e32 v62, v179, v29
	v_fmac_f32_e32 v63, v187, v29
	v_fmac_f32_e32 v60, v164, v30
	v_fmac_f32_e32 v61, v172, v30
	v_fmac_f32_e32 v62, v180, v30
	v_fmac_f32_e32 v63, v188, v30
	v_fmac_f32_e32 v60, v165, v31
	v_fmac_f32_e32 v61, v173, v31
	v_fmac_f32_e32 v62, v181, v31
	v_fmac_f32_e32 v63, v189, v31
	global_load_dwordx4 v[158:161], v[46:47], off offset:1024
	global_load_dwordx4 v[162:165], v[46:47], off offset:1152
	global_load_dwordx4 v[166:169], v[46:47], off offset:1280
	global_load_dwordx4 v[170:173], v[46:47], off offset:1408
	global_load_dwordx4 v[174:177], v[46:47], off offset:1536
	global_load_dwordx4 v[178:181], v[46:47], off offset:1664
	global_load_dwordx4 v[182:185], v[46:47], off offset:1792
	global_load_dwordx4 v[186:189], v[46:47], off offset:1920
	s_waitcnt vmcnt(8)
	v_mul_f32_e32 v64, v190, v24
	v_mul_f32_e32 v65, v198, v24
	v_mul_f32_e32 v66, v206, v24
	v_mul_f32_e32 v67, v214, v24
	v_fmac_f32_e32 v64, v191, v25
	v_fmac_f32_e32 v65, v199, v25
	v_fmac_f32_e32 v66, v207, v25
	v_fmac_f32_e32 v67, v215, v25
	v_fmac_f32_e32 v64, v192, v26
	v_fmac_f32_e32 v65, v200, v26
	v_fmac_f32_e32 v66, v208, v26
	v_fmac_f32_e32 v67, v216, v26
	v_fmac_f32_e32 v64, v193, v27
	v_fmac_f32_e32 v65, v201, v27
	v_fmac_f32_e32 v66, v209, v27
	v_fmac_f32_e32 v67, v217, v27
	v_fmac_f32_e32 v64, v194, v28
	v_fmac_f32_e32 v65, v202, v28
	v_fmac_f32_e32 v66, v210, v28
	v_fmac_f32_e32 v67, v222, v28
	v_fmac_f32_e32 v64, v195, v29
	v_fmac_f32_e32 v65, v203, v29
	v_fmac_f32_e32 v66, v211, v29
	v_fmac_f32_e32 v67, v223, v29
	v_fmac_f32_e32 v64, v196, v30
	v_fmac_f32_e32 v65, v204, v30
	v_fmac_f32_e32 v66, v212, v30
	v_fmac_f32_e32 v67, v224, v30
	v_fmac_f32_e32 v64, v197, v31
	v_fmac_f32_e32 v65, v205, v31
	v_fmac_f32_e32 v66, v213, v31
	v_fmac_f32_e32 v67, v225, v31
	global_load_dwordx4 v[190:193], v[46:47], off offset:2048
	global_load_dwordx4 v[194:197], v[46:47], off offset:2176
	global_load_dwordx4 v[198:201], v[46:47], off offset:2304
	global_load_dwordx4 v[202:205], v[46:47], off offset:2432
	global_load_dwordx4 v[206:209], v[46:47], off offset:2560
	global_load_dwordx4 v[210:213], v[46:47], off offset:2688
	global_load_dwordx4 v[214:217], v[46:47], off offset:2816
	global_load_dwordx4 v[222:225], v[46:47], off offset:2944
	s_waitcnt vmcnt(8)
	v_mul_f32_e32 v68, v158, v24
	v_mul_f32_e32 v69, v166, v24
	v_mul_f32_e32 v70, v174, v24
	v_mul_f32_e32 v71, v182, v24
	v_fmac_f32_e32 v68, v159, v25
	v_fmac_f32_e32 v69, v167, v25
	v_fmac_f32_e32 v70, v175, v25
	v_fmac_f32_e32 v71, v183, v25
	v_fmac_f32_e32 v68, v160, v26
	v_fmac_f32_e32 v69, v168, v26
	v_fmac_f32_e32 v70, v176, v26
	v_fmac_f32_e32 v71, v184, v26
	v_fmac_f32_e32 v68, v161, v27
	v_fmac_f32_e32 v69, v169, v27
	v_fmac_f32_e32 v70, v177, v27
	v_fmac_f32_e32 v71, v185, v27
	v_fmac_f32_e32 v68, v162, v28
	v_fmac_f32_e32 v69, v170, v28
	v_fmac_f32_e32 v70, v178, v28
	v_fmac_f32_e32 v71, v186, v28
	v_fmac_f32_e32 v68, v163, v29
	v_fmac_f32_e32 v69, v171, v29
	v_fmac_f32_e32 v70, v179, v29
	v_fmac_f32_e32 v71, v187, v29
	v_fmac_f32_e32 v68, v164, v30
	v_fmac_f32_e32 v69, v172, v30
	v_fmac_f32_e32 v70, v180, v30
	v_fmac_f32_e32 v71, v188, v30
	v_fmac_f32_e32 v68, v165, v31
	v_fmac_f32_e32 v69, v173, v31
	v_fmac_f32_e32 v70, v181, v31
	v_fmac_f32_e32 v71, v189, v31
	v_lshl_add_u64 v[46:47], v[46:47], 0, s[80:81]
	global_load_dwordx4 v[158:161], v[46:47], off offset:-1024
	global_load_dwordx4 v[162:165], v[46:47], off offset:-896
	global_load_dwordx4 v[166:169], v[46:47], off offset:-768
	global_load_dwordx4 v[170:173], v[46:47], off offset:-640
	global_load_dwordx4 v[174:177], v[46:47], off offset:-512
	global_load_dwordx4 v[178:181], v[46:47], off offset:-384
	global_load_dwordx4 v[182:185], v[46:47], off offset:-256
	global_load_dwordx4 v[186:189], v[46:47], off offset:-128
	s_waitcnt vmcnt(8)
	v_mul_f32_e32 v72, v190, v24
	v_mul_f32_e32 v73, v198, v24
	v_mul_f32_e32 v74, v206, v24
	v_mul_f32_e32 v75, v214, v24
	v_fmac_f32_e32 v72, v191, v25
	v_fmac_f32_e32 v73, v199, v25
	v_fmac_f32_e32 v74, v207, v25
	v_fmac_f32_e32 v75, v215, v25
	v_fmac_f32_e32 v72, v192, v26
	v_fmac_f32_e32 v73, v200, v26
	v_fmac_f32_e32 v74, v208, v26
	v_fmac_f32_e32 v75, v216, v26
	v_fmac_f32_e32 v72, v193, v27
	v_fmac_f32_e32 v73, v201, v27
	v_fmac_f32_e32 v74, v209, v27
	v_fmac_f32_e32 v75, v217, v27
	v_fmac_f32_e32 v72, v194, v28
	v_fmac_f32_e32 v73, v202, v28
	v_fmac_f32_e32 v74, v210, v28
	v_fmac_f32_e32 v75, v222, v28
	v_fmac_f32_e32 v72, v195, v29
	v_fmac_f32_e32 v73, v203, v29
	v_fmac_f32_e32 v74, v211, v29
	v_fmac_f32_e32 v75, v223, v29
	v_fmac_f32_e32 v72, v196, v30
	v_fmac_f32_e32 v73, v204, v30
	v_fmac_f32_e32 v74, v212, v30
	v_fmac_f32_e32 v75, v224, v30
	v_fmac_f32_e32 v72, v197, v31
	v_fmac_f32_e32 v73, v205, v31
	v_fmac_f32_e32 v74, v213, v31
	v_fmac_f32_e32 v75, v225, v31
	global_load_dwordx4 v[190:193], v[46:47], off
	global_load_dwordx4 v[194:197], v[46:47], off offset:128
	global_load_dwordx4 v[198:201], v[46:47], off offset:256
	global_load_dwordx4 v[202:205], v[46:47], off offset:384
	global_load_dwordx4 v[206:209], v[46:47], off offset:512
	global_load_dwordx4 v[210:213], v[46:47], off offset:640
	global_load_dwordx4 v[214:217], v[46:47], off offset:768
	global_load_dwordx4 v[222:225], v[46:47], off offset:896
	s_waitcnt vmcnt(8)
; DEVI void phase_combine(const Params& p, int l) {
;     ...
; #pragma unroll 2
;       for (int i8 = 0; i8 < 8; ++i8) {
;         h16x8 q8 = *(const h16x8*)(qv + i8 * 8);
; #pragma unroll
;         for (int j = 0; j < 8; ++j) {
;           f32x4 m0 = *(const f32x4*)(Sm + j * 64 + i8 * 8), m1 = *(const f32x4*)(Sm + j * 64 + i8 * 8 + 4);
;           corr[j] += m0[0] * (float)q8[0] + m0[1] * (float)q8[1] + m0[2] * (float)q8[2] + m0[3] * (float)q8[3]
;                    + m1[0] * (float)q8[4] + m1[1] * (float)q8[5] + m1[2] * (float)q8[6] + m1[3] * (float)q8[7];
;         }
	v_mul_f32_e32 v76, v158, v24
	v_mul_f32_e32 v77, v166, v24
	v_mul_f32_e32 v78, v174, v24
	v_mul_f32_e32 v79, v182, v24
	v_fmac_f32_e32 v76, v159, v25
	v_fmac_f32_e32 v77, v167, v25
	v_fmac_f32_e32 v78, v175, v25
	v_fmac_f32_e32 v79, v183, v25
	v_fmac_f32_e32 v76, v160, v26
	v_fmac_f32_e32 v77, v168, v26
	v_fmac_f32_e32 v78, v176, v26
	v_fmac_f32_e32 v79, v184, v26
	v_fmac_f32_e32 v76, v161, v27
	v_fmac_f32_e32 v77, v169, v27
	v_fmac_f32_e32 v78, v177, v27
	v_fmac_f32_e32 v79, v185, v27
	v_fmac_f32_e32 v76, v162, v28
	v_fmac_f32_e32 v77, v170, v28
	v_fmac_f32_e32 v78, v178, v28
	v_fmac_f32_e32 v79, v186, v28
	v_fmac_f32_e32 v76, v163, v29
	v_fmac_f32_e32 v77, v171, v29
	v_fmac_f32_e32 v78, v179, v29
	v_fmac_f32_e32 v79, v187, v29
	v_fmac_f32_e32 v76, v164, v30
	v_fmac_f32_e32 v77, v172, v30
	v_fmac_f32_e32 v78, v180, v30
	v_fmac_f32_e32 v79, v188, v30
	v_fmac_f32_e32 v76, v165, v31
	v_fmac_f32_e32 v77, v173, v31
	v_fmac_f32_e32 v78, v181, v31
	v_fmac_f32_e32 v79, v189, v31
	global_load_dwordx4 v[158:161], v[46:47], off offset:1024
	global_load_dwordx4 v[162:165], v[46:47], off offset:1152
	global_load_dwordx4 v[166:169], v[46:47], off offset:1280
	global_load_dwordx4 v[170:173], v[46:47], off offset:1408
	global_load_dwordx4 v[174:177], v[46:47], off offset:1536
	global_load_dwordx4 v[178:181], v[46:47], off offset:1664
	global_load_dwordx4 v[182:185], v[46:47], off offset:1792
	global_load_dwordx4 v[186:189], v[46:47], off offset:1920
	s_waitcnt vmcnt(8)
	v_mul_f32_e32 v80, v190, v24
	v_mul_f32_e32 v81, v198, v24
	v_mul_f32_e32 v82, v206, v24
	v_mul_f32_e32 v83, v214, v24
	v_fmac_f32_e32 v80, v191, v25
	v_fmac_f32_e32 v81, v199, v25
	v_fmac_f32_e32 v82, v207, v25
	v_fmac_f32_e32 v83, v215, v25
	v_fmac_f32_e32 v80, v192, v26
	v_fmac_f32_e32 v81, v200, v26
	v_fmac_f32_e32 v82, v208, v26
	v_fmac_f32_e32 v83, v216, v26
	v_fmac_f32_e32 v80, v193, v27
	v_fmac_f32_e32 v81, v201, v27
	v_fmac_f32_e32 v82, v209, v27
	v_fmac_f32_e32 v83, v217, v27
	v_fmac_f32_e32 v80, v194, v28
	v_fmac_f32_e32 v81, v202, v28
	v_fmac_f32_e32 v82, v210, v28
	v_fmac_f32_e32 v83, v222, v28
	v_fmac_f32_e32 v80, v195, v29
	v_fmac_f32_e32 v81, v203, v29
	v_fmac_f32_e32 v82, v211, v29
	v_fmac_f32_e32 v83, v223, v29
	v_fmac_f32_e32 v80, v196, v30
	v_fmac_f32_e32 v81, v204, v30
	v_fmac_f32_e32 v82, v212, v30
	v_fmac_f32_e32 v83, v224, v30
	v_fmac_f32_e32 v80, v197, v31
	v_fmac_f32_e32 v81, v205, v31
	v_fmac_f32_e32 v82, v213, v31
	v_fmac_f32_e32 v83, v225, v31
	global_load_dwordx4 v[190:193], v[46:47], off offset:2048
	global_load_dwordx4 v[194:197], v[46:47], off offset:2176
	global_load_dwordx4 v[198:201], v[46:47], off offset:2304
	global_load_dwordx4 v[202:205], v[46:47], off offset:2432
	global_load_dwordx4 v[206:209], v[46:47], off offset:2560
	global_load_dwordx4 v[210:213], v[46:47], off offset:2688
	global_load_dwordx4 v[214:217], v[46:47], off offset:2816
	global_load_dwordx4 v[222:225], v[46:47], off offset:2944
	s_waitcnt vmcnt(8)
	v_mul_f32_e32 v84, v158, v24
	v_mul_f32_e32 v85, v166, v24
	v_mul_f32_e32 v86, v174, v24
	v_mul_f32_e32 v87, v182, v24
	v_fmac_f32_e32 v84, v159, v25
	v_fmac_f32_e32 v85, v167, v25
	v_fmac_f32_e32 v86, v175, v25
	v_fmac_f32_e32 v87, v183, v25
	v_fmac_f32_e32 v84, v160, v26
	v_fmac_f32_e32 v85, v168, v26
	v_fmac_f32_e32 v86, v176, v26
	v_fmac_f32_e32 v87, v184, v26
	v_fmac_f32_e32 v84, v161, v27
	v_fmac_f32_e32 v85, v169, v27
	v_fmac_f32_e32 v86, v177, v27
	v_fmac_f32_e32 v87, v185, v27
	v_fmac_f32_e32 v84, v162, v28
	v_fmac_f32_e32 v85, v170, v28
	v_fmac_f32_e32 v86, v178, v28
	v_fmac_f32_e32 v87, v186, v28
	v_fmac_f32_e32 v84, v163, v29
	v_fmac_f32_e32 v85, v171, v29
	v_fmac_f32_e32 v86, v179, v29
	v_fmac_f32_e32 v87, v187, v29
	v_fmac_f32_e32 v84, v164, v30
	v_fmac_f32_e32 v85, v172, v30
	v_fmac_f32_e32 v86, v180, v30
	v_fmac_f32_e32 v87, v188, v30
	v_fmac_f32_e32 v84, v165, v31
	v_fmac_f32_e32 v85, v173, v31
	v_fmac_f32_e32 v86, v181, v31
	v_fmac_f32_e32 v87, v189, v31
	v_lshl_add_u64 v[46:47], v[46:47], 0, s[80:81]
	global_load_dwordx4 v[158:161], v[46:47], off offset:-1024
	global_load_dwordx4 v[162:165], v[46:47], off offset:-896
	global_load_dwordx4 v[166:169], v[46:47], off offset:-768
	global_load_dwordx4 v[170:173], v[46:47], off offset:-640
	global_load_dwordx4 v[174:177], v[46:47], off offset:-512
	global_load_dwordx4 v[178:181], v[46:47], off offset:-384
	global_load_dwordx4 v[182:185], v[46:47], off offset:-256
	global_load_dwordx4 v[186:189], v[46:47], off offset:-128
	s_waitcnt vmcnt(8)
	v_mul_f32_e32 v88, v190, v24
	v_mul_f32_e32 v89, v198, v24
	v_mul_f32_e32 v90, v206, v24
	v_mul_f32_e32 v91, v214, v24
	v_fmac_f32_e32 v88, v191, v25
	v_fmac_f32_e32 v89, v199, v25
	v_fmac_f32_e32 v90, v207, v25
	v_fmac_f32_e32 v91, v215, v25
	v_fmac_f32_e32 v88, v192, v26
	v_fmac_f32_e32 v89, v200, v26
	v_fmac_f32_e32 v90, v208, v26
	v_fmac_f32_e32 v91, v216, v26
	v_fmac_f32_e32 v88, v193, v27
	v_fmac_f32_e32 v89, v201, v27
	v_fmac_f32_e32 v90, v209, v27
	v_fmac_f32_e32 v91, v217, v27
	v_fmac_f32_e32 v88, v194, v28
	v_fmac_f32_e32 v89, v202, v28
	v_fmac_f32_e32 v90, v210, v28
	v_fmac_f32_e32 v91, v222, v28
	v_fmac_f32_e32 v88, v195, v29
	v_fmac_f32_e32 v89, v203, v29
	v_fmac_f32_e32 v90, v211, v29
	v_fmac_f32_e32 v91, v223, v29
	v_fmac_f32_e32 v88, v196, v30
	v_fmac_f32_e32 v89, v204, v30
	v_fmac_f32_e32 v90, v212, v30
	v_fmac_f32_e32 v91, v224, v30
	v_fmac_f32_e32 v88, v197, v31
	v_fmac_f32_e32 v89, v205, v31
	v_fmac_f32_e32 v90, v213, v31
	v_fmac_f32_e32 v91, v225, v31
	global_load_dwordx4 v[190:193], v[46:47], off
	global_load_dwordx4 v[194:197], v[46:47], off offset:128
	global_load_dwordx4 v[198:201], v[46:47], off offset:256
	global_load_dwordx4 v[202:205], v[46:47], off offset:384
	global_load_dwordx4 v[206:209], v[46:47], off offset:512
	global_load_dwordx4 v[210:213], v[46:47], off offset:640
	global_load_dwordx4 v[214:217], v[46:47], off offset:768
	global_load_dwordx4 v[222:225], v[46:47], off offset:896
	s_waitcnt vmcnt(8)
; DEVI void phase_combine(const Params& p, int l) {
;     ...
; #pragma unroll 2
;       for (int i8 = 0; i8 < 8; ++i8) {
;         h16x8 q8 = *(const h16x8*)(qv + i8 * 8);
; #pragma unroll
;         for (int j = 0; j < 8; ++j) {
;           f32x4 m0 = *(const f32x4*)(Sm + j * 64 + i8 * 8), m1 = *(const f32x4*)(Sm + j * 64 + i8 * 8 + 4);
;           corr[j] += m0[0] * (float)q8[0] + m0[1] * (float)q8[1] + m0[2] * (float)q8[2] + m0[3] * (float)q8[3]
;                    + m1[0] * (float)q8[4] + m1[1] * (float)q8[5] + m1[2] * (float)q8[6] + m1[3] * (float)q8[7];
;         }
	v_mul_f32_e32 v92, v158, v24
	v_mul_f32_e32 v93, v166, v24
	v_mul_f32_e32 v94, v174, v24
	v_mul_f32_e32 v95, v182, v24
	v_fmac_f32_e32 v92, v159, v25
	v_fmac_f32_e32 v93, v167, v25
	v_fmac_f32_e32 v94, v175, v25
	v_fmac_f32_e32 v95, v183, v25
	v_fmac_f32_e32 v92, v160, v26
	v_fmac_f32_e32 v93, v168, v26
	v_fmac_f32_e32 v94, v176, v26
	v_fmac_f32_e32 v95, v184, v26
	v_fmac_f32_e32 v92, v161, v27
	v_fmac_f32_e32 v93, v169, v27
	v_fmac_f32_e32 v94, v177, v27
	v_fmac_f32_e32 v95, v185, v27
	v_fmac_f32_e32 v92, v162, v28
	v_fmac_f32_e32 v93, v170, v28
	v_fmac_f32_e32 v94, v178, v28
	v_fmac_f32_e32 v95, v186, v28
	v_fmac_f32_e32 v92, v163, v29
	v_fmac_f32_e32 v93, v171, v29
	v_fmac_f32_e32 v94, v179, v29
	v_fmac_f32_e32 v95, v187, v29
	v_fmac_f32_e32 v92, v164, v30
	v_fmac_f32_e32 v93, v172, v30
	v_fmac_f32_e32 v94, v180, v30
	v_fmac_f32_e32 v95, v188, v30
	v_fmac_f32_e32 v92, v165, v31
	v_fmac_f32_e32 v93, v173, v31
	v_fmac_f32_e32 v94, v181, v31
	v_fmac_f32_e32 v95, v189, v31
	global_load_dwordx4 v[158:161], v[46:47], off offset:1024
	global_load_dwordx4 v[162:165], v[46:47], off offset:1152
	global_load_dwordx4 v[166:169], v[46:47], off offset:1280
	global_load_dwordx4 v[170:173], v[46:47], off offset:1408
	global_load_dwordx4 v[174:177], v[46:47], off offset:1536
	global_load_dwordx4 v[178:181], v[46:47], off offset:1664
	global_load_dwordx4 v[182:185], v[46:47], off offset:1792
	global_load_dwordx4 v[186:189], v[46:47], off offset:1920
	s_waitcnt vmcnt(8)
	v_mul_f32_e32 v96, v190, v24
	v_mul_f32_e32 v97, v198, v24
	v_mul_f32_e32 v98, v206, v24
	v_mul_f32_e32 v99, v214, v24
	v_fmac_f32_e32 v96, v191, v25
	v_fmac_f32_e32 v97, v199, v25
	v_fmac_f32_e32 v98, v207, v25
	v_fmac_f32_e32 v99, v215, v25
	v_fmac_f32_e32 v96, v192, v26
	v_fmac_f32_e32 v97, v200, v26
	v_fmac_f32_e32 v98, v208, v26
	v_fmac_f32_e32 v99, v216, v26
	v_fmac_f32_e32 v96, v193, v27
	v_fmac_f32_e32 v97, v201, v27
	v_fmac_f32_e32 v98, v209, v27
	v_fmac_f32_e32 v99, v217, v27
	v_fmac_f32_e32 v96, v194, v28
	v_fmac_f32_e32 v97, v202, v28
	v_fmac_f32_e32 v98, v210, v28
	v_fmac_f32_e32 v99, v222, v28
	v_fmac_f32_e32 v96, v195, v29
	v_fmac_f32_e32 v97, v203, v29
	v_fmac_f32_e32 v98, v211, v29
	v_fmac_f32_e32 v99, v223, v29
	v_fmac_f32_e32 v96, v196, v30
	v_fmac_f32_e32 v97, v204, v30
	v_fmac_f32_e32 v98, v212, v30
	v_fmac_f32_e32 v99, v224, v30
	v_fmac_f32_e32 v96, v197, v31
	v_fmac_f32_e32 v97, v205, v31
	v_fmac_f32_e32 v98, v213, v31
	v_fmac_f32_e32 v99, v225, v31
	global_load_dwordx4 v[190:193], v[46:47], off offset:2048
	global_load_dwordx4 v[194:197], v[46:47], off offset:2176
	global_load_dwordx4 v[198:201], v[46:47], off offset:2304
	global_load_dwordx4 v[202:205], v[46:47], off offset:2432
	global_load_dwordx4 v[206:209], v[46:47], off offset:2560
	global_load_dwordx4 v[210:213], v[46:47], off offset:2688
	global_load_dwordx4 v[214:217], v[46:47], off offset:2816
	global_load_dwordx4 v[222:225], v[46:47], off offset:2944
	s_waitcnt vmcnt(8)
	v_mul_f32_e32 v100, v158, v24
	v_mul_f32_e32 v101, v166, v24
	v_mul_f32_e32 v102, v174, v24
	v_mul_f32_e32 v103, v182, v24
	v_fmac_f32_e32 v100, v159, v25
	v_fmac_f32_e32 v101, v167, v25
	v_fmac_f32_e32 v102, v175, v25
	v_fmac_f32_e32 v103, v183, v25
	v_fmac_f32_e32 v100, v160, v26
	v_fmac_f32_e32 v101, v168, v26
	v_fmac_f32_e32 v102, v176, v26
	v_fmac_f32_e32 v103, v184, v26
	v_fmac_f32_e32 v100, v161, v27
	v_fmac_f32_e32 v101, v169, v27
	v_fmac_f32_e32 v102, v177, v27
	v_fmac_f32_e32 v103, v185, v27
	v_fmac_f32_e32 v100, v162, v28
	v_fmac_f32_e32 v101, v170, v28
	v_fmac_f32_e32 v102, v178, v28
	v_fmac_f32_e32 v103, v186, v28
	v_fmac_f32_e32 v100, v163, v29
	v_fmac_f32_e32 v101, v171, v29
	v_fmac_f32_e32 v102, v179, v29
	v_fmac_f32_e32 v103, v187, v29
	v_fmac_f32_e32 v100, v164, v30
	v_fmac_f32_e32 v101, v172, v30
	v_fmac_f32_e32 v102, v180, v30
	v_fmac_f32_e32 v103, v188, v30
	v_fmac_f32_e32 v100, v165, v31
	v_fmac_f32_e32 v101, v173, v31
	v_fmac_f32_e32 v102, v181, v31
	v_fmac_f32_e32 v103, v189, v31
	v_lshl_add_u64 v[46:47], v[46:47], 0, s[80:81]
	global_load_dwordx4 v[158:161], v[46:47], off offset:-1024
	global_load_dwordx4 v[162:165], v[46:47], off offset:-896
	global_load_dwordx4 v[166:169], v[46:47], off offset:-768
	global_load_dwordx4 v[170:173], v[46:47], off offset:-640
	global_load_dwordx4 v[174:177], v[46:47], off offset:-512
	global_load_dwordx4 v[178:181], v[46:47], off offset:-384
	global_load_dwordx4 v[182:185], v[46:47], off offset:-256
	global_load_dwordx4 v[186:189], v[46:47], off offset:-128
	s_waitcnt vmcnt(8)
	v_mul_f32_e32 v104, v190, v24
	v_mul_f32_e32 v105, v198, v24
	v_mul_f32_e32 v106, v206, v24
	v_mul_f32_e32 v107, v214, v24
	v_fmac_f32_e32 v104, v191, v25
	v_fmac_f32_e32 v105, v199, v25
	v_fmac_f32_e32 v106, v207, v25
	v_fmac_f32_e32 v107, v215, v25
	v_fmac_f32_e32 v104, v192, v26
	v_fmac_f32_e32 v105, v200, v26
	v_fmac_f32_e32 v106, v208, v26
	v_fmac_f32_e32 v107, v216, v26
	v_fmac_f32_e32 v104, v193, v27
	v_fmac_f32_e32 v105, v201, v27
	v_fmac_f32_e32 v106, v209, v27
	v_fmac_f32_e32 v107, v217, v27
	v_fmac_f32_e32 v104, v194, v28
	v_fmac_f32_e32 v105, v202, v28
	v_fmac_f32_e32 v106, v210, v28
	v_fmac_f32_e32 v107, v222, v28
	v_fmac_f32_e32 v104, v195, v29
	v_fmac_f32_e32 v105, v203, v29
	v_fmac_f32_e32 v106, v211, v29
	v_fmac_f32_e32 v107, v223, v29
	v_fmac_f32_e32 v104, v196, v30
	v_fmac_f32_e32 v105, v204, v30
	v_fmac_f32_e32 v106, v212, v30
	v_fmac_f32_e32 v107, v224, v30
	v_fmac_f32_e32 v104, v197, v31
	v_fmac_f32_e32 v105, v205, v31
	v_fmac_f32_e32 v106, v213, v31
	v_fmac_f32_e32 v107, v225, v31
	global_load_dwordx4 v[190:193], v[46:47], off
	global_load_dwordx4 v[194:197], v[46:47], off offset:128
	global_load_dwordx4 v[198:201], v[46:47], off offset:256
	global_load_dwordx4 v[202:205], v[46:47], off offset:384
	global_load_dwordx4 v[206:209], v[46:47], off offset:512
	global_load_dwordx4 v[210:213], v[46:47], off offset:640
	global_load_dwordx4 v[214:217], v[46:47], off offset:768
	global_load_dwordx4 v[222:225], v[46:47], off offset:896
	s_waitcnt vmcnt(8)
; DEVI void phase_combine(const Params& p, int l) {
;     ...
; #pragma unroll 2
;       for (int i8 = 0; i8 < 8; ++i8) {
;         h16x8 q8 = *(const h16x8*)(qv + i8 * 8);
; #pragma unroll
;         for (int j = 0; j < 8; ++j) {
;           f32x4 m0 = *(const f32x4*)(Sm + j * 64 + i8 * 8), m1 = *(const f32x4*)(Sm + j * 64 + i8 * 8 + 4);
;           corr[j] += m0[0] * (float)q8[0] + m0[1] * (float)q8[1] + m0[2] * (float)q8[2] + m0[3] * (float)q8[3]
;                    + m1[0] * (float)q8[4] + m1[1] * (float)q8[5] + m1[2] * (float)q8[6] + m1[3] * (float)q8[7];
;         }
;       }
;       s1 = 0.f;
; #pragma unroll
;       for (int j = 0; j < 8; ++j) { of[j] += corr[j]; s1 += of[j]; }
	v_mul_f32_e32 v108, v158, v24
	v_mul_f32_e32 v109, v166, v24
	v_mul_f32_e32 v110, v174, v24
	v_mul_f32_e32 v111, v182, v24
	v_fmac_f32_e32 v108, v159, v25
	v_fmac_f32_e32 v109, v167, v25
	v_fmac_f32_e32 v110, v175, v25
	v_fmac_f32_e32 v111, v183, v25
	v_fmac_f32_e32 v108, v160, v26
	v_fmac_f32_e32 v109, v168, v26
	v_fmac_f32_e32 v110, v176, v26
	v_fmac_f32_e32 v111, v184, v26
	v_fmac_f32_e32 v108, v161, v27
	v_fmac_f32_e32 v109, v169, v27
	v_fmac_f32_e32 v110, v177, v27
	v_fmac_f32_e32 v111, v185, v27
	v_fmac_f32_e32 v108, v162, v28
	v_fmac_f32_e32 v109, v170, v28
	v_fmac_f32_e32 v110, v178, v28
	v_fmac_f32_e32 v111, v186, v28
	v_fmac_f32_e32 v108, v163, v29
	v_fmac_f32_e32 v109, v171, v29
	v_fmac_f32_e32 v110, v179, v29
	v_fmac_f32_e32 v111, v187, v29
	v_fmac_f32_e32 v108, v164, v30
	v_fmac_f32_e32 v109, v172, v30
	v_fmac_f32_e32 v110, v180, v30
	v_fmac_f32_e32 v111, v188, v30
	v_fmac_f32_e32 v108, v165, v31
	v_fmac_f32_e32 v109, v173, v31
	v_fmac_f32_e32 v110, v181, v31
	v_fmac_f32_e32 v111, v189, v31
	global_load_dwordx4 v[158:161], v[46:47], off offset:1024
	global_load_dwordx4 v[162:165], v[46:47], off offset:1152
	global_load_dwordx4 v[166:169], v[46:47], off offset:1280
	global_load_dwordx4 v[170:173], v[46:47], off offset:1408
	global_load_dwordx4 v[174:177], v[46:47], off offset:1536
	global_load_dwordx4 v[178:181], v[46:47], off offset:1664
	global_load_dwordx4 v[182:185], v[46:47], off offset:1792
	global_load_dwordx4 v[186:189], v[46:47], off offset:1920
	s_waitcnt vmcnt(8)
	v_mul_f32_e32 v112, v190, v24
	v_mul_f32_e32 v113, v198, v24
	v_mul_f32_e32 v114, v206, v24
	v_mul_f32_e32 v115, v214, v24
	v_fmac_f32_e32 v112, v191, v25
	v_fmac_f32_e32 v113, v199, v25
	v_fmac_f32_e32 v114, v207, v25
	v_fmac_f32_e32 v115, v215, v25
	v_fmac_f32_e32 v112, v192, v26
	v_fmac_f32_e32 v113, v200, v26
	v_fmac_f32_e32 v114, v208, v26
	v_fmac_f32_e32 v115, v216, v26
	v_fmac_f32_e32 v112, v193, v27
	v_fmac_f32_e32 v113, v201, v27
	v_fmac_f32_e32 v114, v209, v27
	v_fmac_f32_e32 v115, v217, v27
	v_fmac_f32_e32 v112, v194, v28
	v_fmac_f32_e32 v113, v202, v28
	v_fmac_f32_e32 v114, v210, v28
	v_fmac_f32_e32 v115, v222, v28
	v_fmac_f32_e32 v112, v195, v29
	v_fmac_f32_e32 v113, v203, v29
	v_fmac_f32_e32 v114, v211, v29
	v_fmac_f32_e32 v115, v223, v29
	v_fmac_f32_e32 v112, v196, v30
	v_fmac_f32_e32 v113, v204, v30
	v_fmac_f32_e32 v114, v212, v30
	v_fmac_f32_e32 v115, v224, v30
	v_fmac_f32_e32 v112, v197, v31
	v_fmac_f32_e32 v113, v205, v31
	v_fmac_f32_e32 v114, v213, v31
	v_fmac_f32_e32 v115, v225, v31
	global_load_dwordx4 v[190:193], v[46:47], off offset:2048
	global_load_dwordx4 v[194:197], v[46:47], off offset:2176
	global_load_dwordx4 v[198:201], v[46:47], off offset:2304
	global_load_dwordx4 v[202:205], v[46:47], off offset:2432
	global_load_dwordx4 v[206:209], v[46:47], off offset:2560
	global_load_dwordx4 v[210:213], v[46:47], off offset:2688
	global_load_dwordx4 v[214:217], v[46:47], off offset:2816
	global_load_dwordx4 v[222:225], v[46:47], off offset:2944
	s_waitcnt vmcnt(8)
	v_mul_f32_e32 v116, v158, v24
	v_mul_f32_e32 v117, v166, v24
	v_mul_f32_e32 v118, v174, v24
	v_mul_f32_e32 v119, v182, v24
	v_fmac_f32_e32 v116, v159, v25
	v_fmac_f32_e32 v117, v167, v25
	v_fmac_f32_e32 v118, v175, v25
	v_fmac_f32_e32 v119, v183, v25
	v_fmac_f32_e32 v116, v160, v26
	v_fmac_f32_e32 v117, v168, v26
	v_fmac_f32_e32 v118, v176, v26
	v_fmac_f32_e32 v119, v184, v26
	v_fmac_f32_e32 v116, v161, v27
	v_fmac_f32_e32 v117, v169, v27
	v_fmac_f32_e32 v118, v177, v27
	v_fmac_f32_e32 v119, v185, v27
	v_fmac_f32_e32 v116, v162, v28
	v_fmac_f32_e32 v117, v170, v28
	v_fmac_f32_e32 v118, v178, v28
	v_fmac_f32_e32 v119, v186, v28
	v_fmac_f32_e32 v116, v163, v29
	v_fmac_f32_e32 v117, v171, v29
	v_fmac_f32_e32 v118, v179, v29
	v_fmac_f32_e32 v119, v187, v29
	v_fmac_f32_e32 v116, v164, v30
	v_fmac_f32_e32 v117, v172, v30
	v_fmac_f32_e32 v118, v180, v30
	v_fmac_f32_e32 v119, v188, v30
	v_fmac_f32_e32 v116, v165, v31
	v_fmac_f32_e32 v117, v173, v31
	v_fmac_f32_e32 v118, v181, v31
	v_fmac_f32_e32 v119, v189, v31
	s_waitcnt vmcnt(0)
	v_mul_f32_e32 v120, v190, v24
	v_mul_f32_e32 v121, v198, v24
	v_mul_f32_e32 v122, v206, v24
	v_mul_f32_e32 v123, v214, v24
	v_fmac_f32_e32 v120, v191, v25
	v_fmac_f32_e32 v121, v199, v25
	v_fmac_f32_e32 v122, v207, v25
	v_fmac_f32_e32 v123, v215, v25
	v_fmac_f32_e32 v120, v192, v26
	v_fmac_f32_e32 v121, v200, v26
	v_fmac_f32_e32 v122, v208, v26
	v_fmac_f32_e32 v123, v216, v26
	v_fmac_f32_e32 v120, v193, v27
	v_fmac_f32_e32 v121, v201, v27
	v_fmac_f32_e32 v122, v209, v27
	v_fmac_f32_e32 v123, v217, v27
	v_fmac_f32_e32 v120, v194, v28
	v_fmac_f32_e32 v121, v202, v28
	v_fmac_f32_e32 v122, v210, v28
	v_fmac_f32_e32 v123, v222, v28
	v_fmac_f32_e32 v120, v195, v29
	v_fmac_f32_e32 v121, v203, v29
	v_fmac_f32_e32 v122, v211, v29
	v_fmac_f32_e32 v123, v223, v29
	v_fmac_f32_e32 v120, v196, v30
	v_fmac_f32_e32 v121, v204, v30
	v_fmac_f32_e32 v122, v212, v30
	v_fmac_f32_e32 v123, v224, v30
	v_fmac_f32_e32 v120, v197, v31
	v_fmac_f32_e32 v121, v205, v31
	v_fmac_f32_e32 v122, v213, v31
	v_fmac_f32_e32 v123, v225, v31
	v_and_b32_e32 v56, 4, v58
	v_cmp_ne_u32_e32 vcc, 0, v56
	s_nop 1
	v_cndmask_b32_e32 v132, v92, v60, vcc
	v_cndmask_b32_e32 v133, v93, v61, vcc
	v_cndmask_b32_e32 v134, v94, v62, vcc
	v_cndmask_b32_e32 v135, v95, v63, vcc
	v_cndmask_b32_e32 v124, v60, v92, vcc
	v_cndmask_b32_e32 v125, v61, v93, vcc
	v_cndmask_b32_e32 v126, v62, v94, vcc
	v_cndmask_b32_e32 v127, v63, v95, vcc
	v_add_f32_dpp v60, v132, v124 row_half_mirror row_mask:0xf bank_mask:0xf bound_ctrl:1
	v_add_f32_dpp v61, v133, v125 row_half_mirror row_mask:0xf bank_mask:0xf bound_ctrl:1
; DEVI void phase_combine(const Params& p, int l) {
;     ...
; #pragma unroll 2
;       for (int i8 = 0; i8 < 8; ++i8) {
;         h16x8 q8 = *(const h16x8*)(qv + i8 * 8);
; #pragma unroll
;         for (int j = 0; j < 8; ++j) {
;           f32x4 m0 = *(const f32x4*)(Sm + j * 64 + i8 * 8), m1 = *(const f32x4*)(Sm + j * 64 + i8 * 8 + 4);
;           corr[j] += m0[0] * (float)q8[0] + m0[1] * (float)q8[1] + m0[2] * (float)q8[2] + m0[3] * (float)q8[3]
;                    + m1[0] * (float)q8[4] + m1[1] * (float)q8[5] + m1[2] * (float)q8[6] + m1[3] * (float)q8[7];
;         }
;       }
;       s1 = 0.f;
; #pragma unroll
;       for (int j = 0; j < 8; ++j) { of[j] += corr[j]; s1 += of[j]; }
	v_add_f32_dpp v62, v134, v126 row_half_mirror row_mask:0xf bank_mask:0xf bound_ctrl:1
	v_add_f32_dpp v63, v135, v127 row_half_mirror row_mask:0xf bank_mask:0xf bound_ctrl:1
	v_cndmask_b32_e32 v132, v96, v64, vcc
	v_cndmask_b32_e32 v133, v97, v65, vcc
	v_cndmask_b32_e32 v134, v98, v66, vcc
	v_cndmask_b32_e32 v135, v99, v67, vcc
	v_cndmask_b32_e32 v124, v64, v96, vcc
	v_cndmask_b32_e32 v125, v65, v97, vcc
	v_cndmask_b32_e32 v126, v66, v98, vcc
	v_cndmask_b32_e32 v127, v67, v99, vcc
	v_add_f32_dpp v64, v132, v124 row_half_mirror row_mask:0xf bank_mask:0xf bound_ctrl:1
	v_add_f32_dpp v65, v133, v125 row_half_mirror row_mask:0xf bank_mask:0xf bound_ctrl:1
	v_add_f32_dpp v66, v134, v126 row_half_mirror row_mask:0xf bank_mask:0xf bound_ctrl:1
	v_add_f32_dpp v67, v135, v127 row_half_mirror row_mask:0xf bank_mask:0xf bound_ctrl:1
	v_cndmask_b32_e32 v132, v100, v68, vcc
	v_cndmask_b32_e32 v133, v101, v69, vcc
	v_cndmask_b32_e32 v134, v102, v70, vcc
	v_cndmask_b32_e32 v135, v103, v71, vcc
	v_cndmask_b32_e32 v124, v68, v100, vcc
	v_cndmask_b32_e32 v125, v69, v101, vcc
	v_cndmask_b32_e32 v126, v70, v102, vcc
	v_cndmask_b32_e32 v127, v71, v103, vcc
	v_add_f32_dpp v68, v132, v124 row_half_mirror row_mask:0xf bank_mask:0xf bound_ctrl:1
	v_add_f32_dpp v69, v133, v125 row_half_mirror row_mask:0xf bank_mask:0xf bound_ctrl:1
	v_add_f32_dpp v70, v134, v126 row_half_mirror row_mask:0xf bank_mask:0xf bound_ctrl:1
	v_add_f32_dpp v71, v135, v127 row_half_mirror row_mask:0xf bank_mask:0xf bound_ctrl:1
	v_cndmask_b32_e32 v132, v104, v72, vcc
	v_cndmask_b32_e32 v133, v105, v73, vcc
	v_cndmask_b32_e32 v134, v106, v74, vcc
	v_cndmask_b32_e32 v135, v107, v75, vcc
	v_cndmask_b32_e32 v124, v72, v104, vcc
	v_cndmask_b32_e32 v125, v73, v105, vcc
	v_cndmask_b32_e32 v126, v74, v106, vcc
	v_cndmask_b32_e32 v127, v75, v107, vcc
	v_add_f32_dpp v72, v132, v124 row_half_mirror row_mask:0xf bank_mask:0xf bound_ctrl:1
	v_add_f32_dpp v73, v133, v125 row_half_mirror row_mask:0xf bank_mask:0xf bound_ctrl:1
	v_add_f32_dpp v74, v134, v126 row_half_mirror row_mask:0xf bank_mask:0xf bound_ctrl:1
	v_add_f32_dpp v75, v135, v127 row_half_mirror row_mask:0xf bank_mask:0xf bound_ctrl:1
	v_cndmask_b32_e32 v132, v108, v76, vcc
	v_cndmask_b32_e32 v133, v109, v77, vcc
	v_cndmask_b32_e32 v134, v110, v78, vcc
	v_cndmask_b32_e32 v135, v111, v79, vcc
	v_cndmask_b32_e32 v124, v76, v108, vcc
	v_cndmask_b32_e32 v125, v77, v109, vcc
	v_cndmask_b32_e32 v126, v78, v110, vcc
	v_cndmask_b32_e32 v127, v79, v111, vcc
	v_add_f32_dpp v76, v132, v124 row_half_mirror row_mask:0xf bank_mask:0xf bound_ctrl:1
	v_add_f32_dpp v77, v133, v125 row_half_mirror row_mask:0xf bank_mask:0xf bound_ctrl:1
	v_add_f32_dpp v78, v134, v126 row_half_mirror row_mask:0xf bank_mask:0xf bound_ctrl:1
	v_add_f32_dpp v79, v135, v127 row_half_mirror row_mask:0xf bank_mask:0xf bound_ctrl:1
	v_cndmask_b32_e32 v132, v112, v80, vcc
	v_cndmask_b32_e32 v133, v113, v81, vcc
	v_cndmask_b32_e32 v134, v114, v82, vcc
	v_cndmask_b32_e32 v135, v115, v83, vcc
	v_cndmask_b32_e32 v124, v80, v112, vcc
	v_cndmask_b32_e32 v125, v81, v113, vcc
	v_cndmask_b32_e32 v126, v82, v114, vcc
	v_cndmask_b32_e32 v127, v83, v115, vcc
	v_add_f32_dpp v80, v132, v124 row_half_mirror row_mask:0xf bank_mask:0xf bound_ctrl:1
	v_add_f32_dpp v81, v133, v125 row_half_mirror row_mask:0xf bank_mask:0xf bound_ctrl:1
	v_add_f32_dpp v82, v134, v126 row_half_mirror row_mask:0xf bank_mask:0xf bound_ctrl:1
	v_add_f32_dpp v83, v135, v127 row_half_mirror row_mask:0xf bank_mask:0xf bound_ctrl:1
	v_cndmask_b32_e32 v132, v116, v84, vcc
	v_cndmask_b32_e32 v133, v117, v85, vcc
	v_cndmask_b32_e32 v134, v118, v86, vcc
	v_cndmask_b32_e32 v135, v119, v87, vcc
	v_cndmask_b32_e32 v124, v84, v116, vcc
	v_cndmask_b32_e32 v125, v85, v117, vcc
	v_cndmask_b32_e32 v126, v86, v118, vcc
	v_cndmask_b32_e32 v127, v87, v119, vcc
	v_add_f32_dpp v84, v132, v124 row_half_mirror row_mask:0xf bank_mask:0xf bound_ctrl:1
	v_add_f32_dpp v85, v133, v125 row_half_mirror row_mask:0xf bank_mask:0xf bound_ctrl:1
	v_add_f32_dpp v86, v134, v126 row_half_mirror row_mask:0xf bank_mask:0xf bound_ctrl:1
	v_add_f32_dpp v87, v135, v127 row_half_mirror row_mask:0xf bank_mask:0xf bound_ctrl:1
	v_cndmask_b32_e32 v132, v120, v88, vcc
	v_cndmask_b32_e32 v133, v121, v89, vcc
	v_cndmask_b32_e32 v134, v122, v90, vcc
	v_cndmask_b32_e32 v135, v123, v91, vcc
	v_cndmask_b32_e32 v124, v88, v120, vcc
	v_cndmask_b32_e32 v125, v89, v121, vcc
	v_cndmask_b32_e32 v126, v90, v122, vcc
	v_cndmask_b32_e32 v127, v91, v123, vcc
	v_add_f32_dpp v88, v132, v124 row_half_mirror row_mask:0xf bank_mask:0xf bound_ctrl:1
	v_add_f32_dpp v89, v133, v125 row_half_mirror row_mask:0xf bank_mask:0xf bound_ctrl:1
	v_add_f32_dpp v90, v134, v126 row_half_mirror row_mask:0xf bank_mask:0xf bound_ctrl:1
; DEVI void phase_combine(const Params& p, int l) {
;     ...
; #pragma unroll 2
;       for (int i8 = 0; i8 < 8; ++i8) {
;         h16x8 q8 = *(const h16x8*)(qv + i8 * 8);
; #pragma unroll
;         for (int j = 0; j < 8; ++j) {
;           f32x4 m0 = *(const f32x4*)(Sm + j * 64 + i8 * 8), m1 = *(const f32x4*)(Sm + j * 64 + i8 * 8 + 4);
;           corr[j] += m0[0] * (float)q8[0] + m0[1] * (float)q8[1] + m0[2] * (float)q8[2] + m0[3] * (float)q8[3]
;                    + m1[0] * (float)q8[4] + m1[1] * (float)q8[5] + m1[2] * (float)q8[6] + m1[3] * (float)q8[7];
;         }
;       }
;       s1 = 0.f;
; #pragma unroll
;       for (int j = 0; j < 8; ++j) { of[j] += corr[j]; s1 += of[j]; }
;     }
;     s1 = rowreduce<8>(s1);
;     rks = rowreduce<8>(rks);
	v_add_f32_dpp v91, v135, v127 row_half_mirror row_mask:0xf bank_mask:0xf bound_ctrl:1
	v_and_b32_e32 v56, 2, v58
	v_cmp_ne_u32_e32 vcc, 0, v56
	s_nop 1
	v_cndmask_b32_e32 v132, v76, v60, vcc
	v_cndmask_b32_e32 v133, v77, v61, vcc
	v_cndmask_b32_e32 v134, v78, v62, vcc
	v_cndmask_b32_e32 v135, v79, v63, vcc
	v_cndmask_b32_e32 v124, v60, v76, vcc
	v_cndmask_b32_e32 v125, v61, v77, vcc
	v_cndmask_b32_e32 v126, v62, v78, vcc
	v_cndmask_b32_e32 v127, v63, v79, vcc
	v_add_f32_dpp v60, v132, v124 quad_perm:[2,3,0,1] row_mask:0xf bank_mask:0xf bound_ctrl:1
	v_add_f32_dpp v61, v133, v125 quad_perm:[2,3,0,1] row_mask:0xf bank_mask:0xf bound_ctrl:1
	v_add_f32_dpp v62, v134, v126 quad_perm:[2,3,0,1] row_mask:0xf bank_mask:0xf bound_ctrl:1
	v_add_f32_dpp v63, v135, v127 quad_perm:[2,3,0,1] row_mask:0xf bank_mask:0xf bound_ctrl:1
	v_cndmask_b32_e32 v132, v80, v64, vcc
	v_cndmask_b32_e32 v133, v81, v65, vcc
	v_cndmask_b32_e32 v134, v82, v66, vcc
	v_cndmask_b32_e32 v135, v83, v67, vcc
	v_cndmask_b32_e32 v124, v64, v80, vcc
	v_cndmask_b32_e32 v125, v65, v81, vcc
	v_cndmask_b32_e32 v126, v66, v82, vcc
	v_cndmask_b32_e32 v127, v67, v83, vcc
	v_add_f32_dpp v64, v132, v124 quad_perm:[2,3,0,1] row_mask:0xf bank_mask:0xf bound_ctrl:1
	v_add_f32_dpp v65, v133, v125 quad_perm:[2,3,0,1] row_mask:0xf bank_mask:0xf bound_ctrl:1
	v_add_f32_dpp v66, v134, v126 quad_perm:[2,3,0,1] row_mask:0xf bank_mask:0xf bound_ctrl:1
	v_add_f32_dpp v67, v135, v127 quad_perm:[2,3,0,1] row_mask:0xf bank_mask:0xf bound_ctrl:1
	v_cndmask_b32_e32 v132, v84, v68, vcc
	v_cndmask_b32_e32 v133, v85, v69, vcc
	v_cndmask_b32_e32 v134, v86, v70, vcc
	v_cndmask_b32_e32 v135, v87, v71, vcc
	v_cndmask_b32_e32 v124, v68, v84, vcc
	v_cndmask_b32_e32 v125, v69, v85, vcc
	v_cndmask_b32_e32 v126, v70, v86, vcc
	v_cndmask_b32_e32 v127, v71, v87, vcc
	v_add_f32_dpp v68, v132, v124 quad_perm:[2,3,0,1] row_mask:0xf bank_mask:0xf bound_ctrl:1
	v_add_f32_dpp v69, v133, v125 quad_perm:[2,3,0,1] row_mask:0xf bank_mask:0xf bound_ctrl:1
	v_add_f32_dpp v70, v134, v126 quad_perm:[2,3,0,1] row_mask:0xf bank_mask:0xf bound_ctrl:1
	v_add_f32_dpp v71, v135, v127 quad_perm:[2,3,0,1] row_mask:0xf bank_mask:0xf bound_ctrl:1
	v_cndmask_b32_e32 v132, v88, v72, vcc
	v_cndmask_b32_e32 v133, v89, v73, vcc
	v_cndmask_b32_e32 v134, v90, v74, vcc
	v_cndmask_b32_e32 v135, v91, v75, vcc
	v_cndmask_b32_e32 v124, v72, v88, vcc
	v_cndmask_b32_e32 v125, v73, v89, vcc
	v_cndmask_b32_e32 v126, v74, v90, vcc
	v_cndmask_b32_e32 v127, v75, v91, vcc
	v_add_f32_dpp v72, v132, v124 quad_perm:[2,3,0,1] row_mask:0xf bank_mask:0xf bound_ctrl:1
	v_add_f32_dpp v73, v133, v125 quad_perm:[2,3,0,1] row_mask:0xf bank_mask:0xf bound_ctrl:1
	v_add_f32_dpp v74, v134, v126 quad_perm:[2,3,0,1] row_mask:0xf bank_mask:0xf bound_ctrl:1
	v_add_f32_dpp v75, v135, v127 quad_perm:[2,3,0,1] row_mask:0xf bank_mask:0xf bound_ctrl:1
	v_and_b32_e32 v56, 1, v58
	v_cmp_ne_u32_e32 vcc, 0, v56
	s_nop 1
	v_cndmask_b32_e32 v132, v68, v60, vcc
	v_cndmask_b32_e32 v133, v69, v61, vcc
	v_cndmask_b32_e32 v134, v70, v62, vcc
	v_cndmask_b32_e32 v135, v71, v63, vcc
	v_cndmask_b32_e32 v124, v60, v68, vcc
	v_cndmask_b32_e32 v125, v61, v69, vcc
	v_cndmask_b32_e32 v126, v62, v70, vcc
	v_cndmask_b32_e32 v127, v63, v71, vcc
	v_add_f32_dpp v54, v132, v124 quad_perm:[1,0,3,2] row_mask:0xf bank_mask:0xf bound_ctrl:1
	v_add_f32_dpp v55, v133, v125 quad_perm:[1,0,3,2] row_mask:0xf bank_mask:0xf bound_ctrl:1
	v_add_f32_dpp v52, v134, v126 quad_perm:[1,0,3,2] row_mask:0xf bank_mask:0xf bound_ctrl:1
	v_add_f32_dpp v53, v135, v127 quad_perm:[1,0,3,2] row_mask:0xf bank_mask:0xf bound_ctrl:1
	v_cndmask_b32_e32 v132, v72, v64, vcc
	v_cndmask_b32_e32 v133, v73, v65, vcc
	v_cndmask_b32_e32 v134, v74, v66, vcc
	v_cndmask_b32_e32 v135, v75, v67, vcc
	v_cndmask_b32_e32 v124, v64, v72, vcc
	v_cndmask_b32_e32 v125, v65, v73, vcc
	v_cndmask_b32_e32 v126, v66, v74, vcc
	v_cndmask_b32_e32 v127, v67, v75, vcc
	v_add_f32_dpp v50, v132, v124 quad_perm:[1,0,3,2] row_mask:0xf bank_mask:0xf bound_ctrl:1
	v_add_f32_dpp v51, v133, v125 quad_perm:[1,0,3,2] row_mask:0xf bank_mask:0xf bound_ctrl:1
	v_add_f32_dpp v48, v134, v126 quad_perm:[1,0,3,2] row_mask:0xf bank_mask:0xf bound_ctrl:1
	v_add_f32_dpp v49, v135, v127 quad_perm:[1,0,3,2] row_mask:0xf bank_mask:0xf bound_ctrl:1
	v_pk_add_f32 v[36:37], v[36:37], v[54:55]
	v_pk_add_f32 v[38:39], v[38:39], v[52:53]
	v_add_f32_e32 v24, 0, v36
	v_add_f32_e32 v24, v24, v37
	v_add_f32_e32 v24, v24, v38
	v_add_f32_e32 v24, v24, v39
	v_pk_add_f32 v[40:41], v[40:41], v[50:51]
	v_pk_add_f32 v[42:43], v[42:43], v[48:49]
	v_add_f32_e32 v24, v24, v40
	v_add_f32_e32 v24, v24, v41
	v_add_f32_e32 v24, v24, v42
	v_add_f32_e32 v26, v24, v43
	s_branch .LBB0_822

; DEVI int ltid() { int t = __builtin_amdgcn_workitem_id_x(); asm volatile("" : "+v"(t)); return t; }
; DEVI int lbid() { int t = __builtin_amdgcn_workgroup_id_x(); asm volatile("" : "+s"(t)); return t; }
; template <class AS, class EP>
; DEVI void gemm_tile(const AS& as, const u16* __restrict__ Bt, int K, int m0, int n0, const EP& ep, char* lds) {
;   const int tid = ltid(), wid = tid >> 6, lane = tid & 63, r32 = lane & 31, hi = lane >> 5;
;   const int wm = wid >> 1, wn = wid & 1;
;   constexpr int RS = 144, ABYTES = 256 * RS, STAGE = ABYTES + 128 * RS;
;   f32x16 acc[2][2];
; #pragma unroll
;   for (int i = 0; i < 2; ++i)
; #pragma unroll
;     for (int j = 0; j < 2; ++j)
; #pragma unroll
;       for (int r = 0; r < 16; ++r) acc[i][j][r] = 0.f;
;   const int KT = K >> 6;
;   u32x4 ra0[4], rb0[2], ra1[4], rb1[2];
;   const int srow = tid >> 3, sch = tid & 7;
;     ...
;   GLOAD(ra0, rb0, 0); GLOAD(ra1, rb1, 1); LWRITE(0, ra0, rb0); __syncthreads();
;   for (int kt = 0; kt < KT; kt += 2) {
;     if (kt + 2 < KT) GLOAD(ra0, rb0, kt + 2);
;     __builtin_amdgcn_sched_barrier(0);
;     COMPUTE(0);
;     __builtin_amdgcn_sched_barrier(0);
;     LWRITE(1, ra1, rb1);
;     __syncthreads();
;     if (kt + 3 < KT) GLOAD(ra1, rb1, kt + 3);
;     __builtin_amdgcn_sched_barrier(0);
;     COMPUTE(1);
;     __builtin_amdgcn_sched_barrier(0);
;     if (kt + 2 < KT) LWRITE(0, ra0, rb0);
;     __syncthreads();
; template <class AS, class EP>
; DEVI void gemm_phase(const AS& as, const u16* Bt, int K, int mtiles, int ntiles, const EP& ep, char* lds) {
;     ...
;   if ((gridDim.x & 7) == 0 && (mtiles & 7) == 0) {
;     const int x = lbid() & 7, j = lbid() >> 3, nb = gridDim.x >> 3, ltot = (mtiles >> 3) * ntiles;
;     for (int lt = j; lt < ltot; lt += nb) {
;       int mt = (lt / ntiles) * 8 + x, nt = lt % ntiles;
;       gemm_tile(as, Bt, K, mt * 256, nt * 128, ep, lds);
.LBB0_953:
	s_mul_hi_i32 s6, s14, 0x92492493
	s_add_i32 s6, s6, s14
	s_lshr_b32 s7, s6, 31
	s_ashr_i32 s6, s6, 3
	s_add_i32 s12, s6, s7
	v_mov_b32_e32 v36, v131
	s_lshl_b32 s16, s12, 8
	s_mulk_i32 s12, 0x700
	v_ashrrev_i32_e32 v37, 3, v36
	v_add_u32_e32 v0, s16, v37
	v_lshlrev_b32_e32 v1, 4, v36
	v_subrev_u32_e32 v16, s12, v37
	v_and_b32_e32 v128, 0x70, v1
	v_ashrrev_i32_e32 v1, 31, v0
	v_add_u32_e32 v16, s15, v16
	v_lshlrev_b64 v[24:25], 11, v[0:1]
	s_mov_b64 s[6:7], 0x20000
	v_ashrrev_i32_e32 v17, 31, v16
	v_lshl_add_u64 v[26:27], v[24:25], 0, s[6:7]
	s_mov_b64 s[6:7], 0x40000
	v_lshlrev_b64 v[32:33], 11, v[16:17]
	v_add_u32_e32 v16, 64, v16
	v_lshl_add_u64 v[8:9], s[0:1], 0, v[128:129]
	v_lshl_add_u64 v[28:29], v[24:25], 0, s[6:7]
	s_mov_b64 s[6:7], 0x60000
	v_lshl_add_u64 v[18:19], s[10:11], 0, v[128:129]
	v_ashrrev_i32_e32 v17, 31, v16
	v_lshl_add_u64 v[112:113], v[8:9], 0, v[24:25]
	v_lshl_add_u64 v[116:117], v[8:9], 0, v[28:29]
	v_lshl_add_u64 v[30:31], v[24:25], 0, s[6:7]
	v_lshl_add_u64 v[120:121], v[18:19], 0, v[32:33]
	v_lshlrev_b64 v[34:35], 11, v[16:17]
	v_lshl_add_u64 v[114:115], v[8:9], 0, v[26:27]
	global_load_dwordx4 v[0:3], v[112:113], off
	global_load_dwordx4 v[4:7], v[114:115], off
	v_lshl_add_u64 v[118:119], v[8:9], 0, v[30:31]
	global_load_dwordx4 v[8:11], v[116:117], off
	global_load_dwordx4 v[12:15], v[118:119], off
	v_lshl_add_u64 v[122:123], v[18:19], 0, v[34:35]
	global_load_dwordx4 v[16:19], v[120:121], off
	global_load_dwordx4 v[20:23], v[122:123], off
	v_mul_lo_u32 v37, v37, s96
	v_lshl_add_u64 v[24:25], s[0:1], 0, v[24:25]
	v_lshl_add_u64 v[32:33], s[10:11], 0, v[32:33]
	v_add3_u32 v134, 16, v128, v37
	v_lshl_add_u64 v[24:25], v[24:25], 0, v[128:129]
	v_lshl_add_u64 v[26:27], s[0:1], 0, v[26:27]
	v_lshl_add_u64 v[28:29], s[0:1], 0, v[28:29]
	v_lshl_add_u64 v[30:31], s[0:1], 0, v[30:31]
	v_lshl_add_u64 v[32:33], v[32:33], 0, v[128:129]
	v_lshl_add_u64 v[34:35], s[10:11], 0, v[34:35]
	v_lshl_add_u64 v[26:27], v[26:27], 0, v[128:129]
	v_lshl_add_u64 v[28:29], v[28:29], 0, v[128:129]
	v_lshl_add_u64 v[30:31], v[30:31], 0, v[128:129]
	global_load_dwordx4 v[88:91], v[24:25], off offset:128
	global_load_dwordx4 v[92:95], v[26:27], off offset:128
	global_load_dwordx4 v[96:99], v[28:29], off offset:128
	global_load_dwordx4 v[100:103], v[30:31], off offset:128
	v_lshl_add_u64 v[24:25], v[34:35], 0, v[128:129]
	global_load_dwordx4 v[104:107], v[32:33], off offset:128
	global_load_dwordx4 v[108:111], v[24:25], off offset:128
	v_and_b32_e32 v125, 31, v36
	v_bfe_u32 v124, v36, 5, 1
	v_bfe_u32 v126, v36, 6, 1
	v_add_u32_e32 v135, 0xd800, v134
	v_add3_u32 v128, s85, v128, v37
	s_waitcnt vmcnt(11)
	ds_write_b128 v134, v[0:3]
	s_waitcnt vmcnt(10)
	ds_write_b128 v134, v[4:7] offset:9216
	s_waitcnt vmcnt(9)
	ds_write_b128 v134, v[8:11] offset:18432
	s_waitcnt vmcnt(8)
	ds_write_b128 v134, v[12:15] offset:27648
	s_waitcnt vmcnt(7)
	ds_write_b128 v134, v[16:19] offset:36864
	s_waitcnt vmcnt(6)
	ds_write_b128 v134, v[20:23] offset:46080
	s_waitcnt lgkmcnt(0)
	s_barrier
	global_load_dwordx4 v[64:67], v[112:113], off offset:256
	global_load_dwordx4 v[68:71], v[114:115], off offset:256
	global_load_dwordx4 v[72:75], v[116:117], off offset:256
	global_load_dwordx4 v[76:79], v[118:119], off offset:256
	global_load_dwordx4 v[80:83], v[120:121], off offset:256
	global_load_dwordx4 v[84:87], v[122:123], off offset:256
	v_ashrrev_i32_e32 v0, 1, v36
	v_and_b32_e32 v127, 0xffffffc0, v0
	v_or_b32_e32 v0, v127, v125
	v_mul_lo_u32 v0, v0, s96
	v_lshlrev_b32_e32 v1, 4, v124
	v_add3_u32 v132, 16, v0, v1
	v_lshl_or_b32 v0, v126, 6, v125
	v_mul_u32_u24_e32 v0, 0x90, v0
	v_add3_u32 v136, 16, v0, v1
	v_add3_u32 v133, s85, v0, v1
	ds_read_b128 v[170:173], v132
	ds_read_b128 v[174:177], v136 offset:36864
	ds_read_b128 v[178:181], v136 offset:41472
	ds_read_b128 v[182:185], v132 offset:4608
	ds_read_b128 v[186:189], v132 offset:32
	ds_read_b128 v[190:193], v136 offset:36896
	ds_read_b128 v[194:197], v136 offset:41504
	ds_read_b128 v[198:201], v132 offset:4640
	ds_read_b128 v[202:205], v132 offset:64
	ds_read_b128 v[206:209], v136 offset:36928
	ds_read_b128 v[210:213], v136 offset:41536
	ds_read_b128 v[214:217], v132 offset:4672
	s_waitcnt lgkmcnt(10)
	v_mfma_f32_32x32x16_bf16 v[48:63], v[170:173], v[174:177], 0
	s_waitcnt lgkmcnt(9)
	v_mfma_f32_32x32x16_bf16 v[32:47], v[170:173], v[178:181], 0
	s_waitcnt lgkmcnt(8)
	v_mfma_f32_32x32x16_bf16 v[16:31], v[182:185], v[174:177], 0
	v_mfma_f32_32x32x16_bf16 v[0:15], v[182:185], v[178:181], 0
	ds_read_b128 v[222:225], v132 offset:96
	ds_read_b128 v[226:229], v136 offset:36960
	ds_read_b128 v[230:233], v136 offset:41568
	ds_read_b128 v[234:237], v132 offset:4704
	s_waitcnt lgkmcnt(10)
	v_mfma_f32_32x32x16_bf16 v[48:63], v[186:189], v[190:193], v[48:63]
	s_waitcnt lgkmcnt(9)
	v_mfma_f32_32x32x16_bf16 v[32:47], v[186:189], v[194:197], v[32:47]
	s_waitcnt lgkmcnt(8)
	v_mfma_f32_32x32x16_bf16 v[16:31], v[198:201], v[190:193], v[16:31]
	v_mfma_f32_32x32x16_bf16 v[0:15], v[198:201], v[194:197], v[0:15]
	s_waitcnt vmcnt(11)
	ds_write_b128 v134, v[88:91] offset:55296
	s_waitcnt lgkmcnt(7)
	v_mfma_f32_32x32x16_bf16 v[48:63], v[202:205], v[206:209], v[48:63]
	s_waitcnt vmcnt(10)
	ds_write_b128 v134, v[92:95] offset:64512
	s_waitcnt lgkmcnt(7)
	v_mfma_f32_32x32x16_bf16 v[32:47], v[202:205], v[210:213], v[32:47]
	s_waitcnt vmcnt(9)
	ds_write_b128 v135, v[96:99] offset:18432
	s_waitcnt lgkmcnt(7)
	v_mfma_f32_32x32x16_bf16 v[16:31], v[214:217], v[206:209], v[16:31]
	v_mfma_f32_32x32x16_bf16 v[0:15], v[214:217], v[210:213], v[0:15]
	s_waitcnt vmcnt(8)
	ds_write_b128 v135, v[100:103] offset:27648
	s_waitcnt lgkmcnt(6)
	v_mfma_f32_32x32x16_bf16 v[48:63], v[222:225], v[226:229], v[48:63]
	s_waitcnt vmcnt(7)
	ds_write_b128 v128, v[104:107]
	s_waitcnt lgkmcnt(6)
	v_mfma_f32_32x32x16_bf16 v[32:47], v[222:225], v[230:233], v[32:47]
	s_waitcnt vmcnt(6)
	ds_write_b128 v128, v[108:111] offset:9216
	s_waitcnt lgkmcnt(6)
	v_mfma_f32_32x32x16_bf16 v[16:31], v[234:237], v[226:229], v[16:31]
	v_mfma_f32_32x32x16_bf16 v[0:15], v[234:237], v[230:233], v[0:15]
	s_waitcnt lgkmcnt(0)
	s_barrier
; template <class AS, class EP>
; DEVI void gemm_tile(const AS& as, const u16* __restrict__ Bt, int K, int m0, int n0, const EP& ep, char* lds) {
;     ...
;   for (int kt = 0; kt < KT; kt += 2) {
;     if (kt + 2 < KT) GLOAD(ra0, rb0, kt + 2);
;     __builtin_amdgcn_sched_barrier(0);
;     COMPUTE(0);
;     __builtin_amdgcn_sched_barrier(0);
;     LWRITE(1, ra1, rb1);
;     __syncthreads();
;     if (kt + 3 < KT) GLOAD(ra1, rb1, kt + 3);
;     __builtin_amdgcn_sched_barrier(0);
;     COMPUTE(1);
;     __builtin_amdgcn_sched_barrier(0);
;     if (kt + 2 < KT) LWRITE(0, ra0, rb0);
;     __syncthreads();
	global_load_dwordx4 v[88:91], v[112:113], off offset:384
	global_load_dwordx4 v[92:95], v[114:115], off offset:384
	global_load_dwordx4 v[96:99], v[116:117], off offset:384
	global_load_dwordx4 v[100:103], v[118:119], off offset:384
	global_load_dwordx4 v[104:107], v[120:121], off offset:384
	global_load_dwordx4 v[108:111], v[122:123], off offset:384
	ds_read_b128 v[170:173], v132 offset:55296
	ds_read_b128 v[174:177], v133
	ds_read_b128 v[178:181], v133 offset:4608
	ds_read_b128 v[182:185], v132 offset:59904
	ds_read_b128 v[186:189], v132 offset:55328
	ds_read_b128 v[190:193], v133 offset:32
	ds_read_b128 v[194:197], v133 offset:4640
	ds_read_b128 v[198:201], v132 offset:59936
	ds_read_b128 v[202:205], v132 offset:55360
	ds_read_b128 v[206:209], v133 offset:64
	ds_read_b128 v[210:213], v133 offset:4672
	ds_read_b128 v[214:217], v132 offset:59968
	s_waitcnt lgkmcnt(10)
	v_mfma_f32_32x32x16_bf16 v[48:63], v[170:173], v[174:177], v[48:63]
	s_waitcnt lgkmcnt(9)
	v_mfma_f32_32x32x16_bf16 v[32:47], v[170:173], v[178:181], v[32:47]
	s_waitcnt lgkmcnt(8)
	v_mfma_f32_32x32x16_bf16 v[16:31], v[182:185], v[174:177], v[16:31]
	v_mfma_f32_32x32x16_bf16 v[0:15], v[182:185], v[178:181], v[0:15]
	ds_read_b128 v[222:225], v132 offset:55392
	ds_read_b128 v[226:229], v133 offset:96
	ds_read_b128 v[230:233], v133 offset:4704
	ds_read_b128 v[234:237], v132 offset:60000
	s_waitcnt lgkmcnt(10)
	v_mfma_f32_32x32x16_bf16 v[48:63], v[186:189], v[190:193], v[48:63]
	s_waitcnt lgkmcnt(9)
	v_mfma_f32_32x32x16_bf16 v[32:47], v[186:189], v[194:197], v[32:47]
	s_waitcnt lgkmcnt(8)
	v_mfma_f32_32x32x16_bf16 v[16:31], v[198:201], v[190:193], v[16:31]
	v_mfma_f32_32x32x16_bf16 v[0:15], v[198:201], v[194:197], v[0:15]
	s_waitcnt vmcnt(11)
	ds_write_b128 v134, v[64:67]
	s_waitcnt lgkmcnt(7)
	v_mfma_f32_32x32x16_bf16 v[48:63], v[202:205], v[206:209], v[48:63]
	s_waitcnt vmcnt(10)
	ds_write_b128 v134, v[68:71] offset:9216
	s_waitcnt lgkmcnt(7)
	v_mfma_f32_32x32x16_bf16 v[32:47], v[202:205], v[210:213], v[32:47]
	s_waitcnt vmcnt(9)
	ds_write_b128 v134, v[72:75] offset:18432
	s_waitcnt lgkmcnt(7)
	v_mfma_f32_32x32x16_bf16 v[16:31], v[214:217], v[206:209], v[16:31]
	v_mfma_f32_32x32x16_bf16 v[0:15], v[214:217], v[210:213], v[0:15]
	s_waitcnt vmcnt(8)
	ds_write_b128 v134, v[76:79] offset:27648
	s_waitcnt lgkmcnt(6)
	v_mfma_f32_32x32x16_bf16 v[48:63], v[222:225], v[226:229], v[48:63]
	s_waitcnt vmcnt(7)
	ds_write_b128 v134, v[80:83] offset:36864
	s_waitcnt lgkmcnt(6)
	v_mfma_f32_32x32x16_bf16 v[32:47], v[222:225], v[230:233], v[32:47]
	s_waitcnt vmcnt(6)
	ds_write_b128 v134, v[84:87] offset:46080
	s_waitcnt lgkmcnt(6)
	v_mfma_f32_32x32x16_bf16 v[16:31], v[234:237], v[226:229], v[16:31]
	v_mfma_f32_32x32x16_bf16 v[0:15], v[234:237], v[230:233], v[0:15]
	s_waitcnt lgkmcnt(0)
	s_barrier
	global_load_dwordx4 v[64:67], v[112:113], off offset:512
	global_load_dwordx4 v[68:71], v[114:115], off offset:512
	global_load_dwordx4 v[72:75], v[116:117], off offset:512
	global_load_dwordx4 v[76:79], v[118:119], off offset:512
	global_load_dwordx4 v[80:83], v[120:121], off offset:512
	global_load_dwordx4 v[84:87], v[122:123], off offset:512
	ds_read_b128 v[170:173], v132
	ds_read_b128 v[174:177], v136 offset:36864
	ds_read_b128 v[178:181], v136 offset:41472
	ds_read_b128 v[182:185], v132 offset:4608
	ds_read_b128 v[186:189], v132 offset:32
	ds_read_b128 v[190:193], v136 offset:36896
	ds_read_b128 v[194:197], v136 offset:41504
	ds_read_b128 v[198:201], v132 offset:4640
	ds_read_b128 v[202:205], v132 offset:64
	ds_read_b128 v[206:209], v136 offset:36928
	ds_read_b128 v[210:213], v136 offset:41536
	ds_read_b128 v[214:217], v132 offset:4672
	s_waitcnt lgkmcnt(10)
	v_mfma_f32_32x32x16_bf16 v[48:63], v[170:173], v[174:177], v[48:63]
	s_waitcnt lgkmcnt(9)
	v_mfma_f32_32x32x16_bf16 v[32:47], v[170:173], v[178:181], v[32:47]
	s_waitcnt lgkmcnt(8)
	v_mfma_f32_32x32x16_bf16 v[16:31], v[182:185], v[174:177], v[16:31]
	v_mfma_f32_32x32x16_bf16 v[0:15], v[182:185], v[178:181], v[0:15]
	ds_read_b128 v[222:225], v132 offset:96
	ds_read_b128 v[226:229], v136 offset:36960
	ds_read_b128 v[230:233], v136 offset:41568
	ds_read_b128 v[234:237], v132 offset:4704
	s_waitcnt lgkmcnt(10)
	v_mfma_f32_32x32x16_bf16 v[48:63], v[186:189], v[190:193], v[48:63]
	s_waitcnt lgkmcnt(9)
	v_mfma_f32_32x32x16_bf16 v[32:47], v[186:189], v[194:197], v[32:47]
	s_waitcnt lgkmcnt(8)
	v_mfma_f32_32x32x16_bf16 v[16:31], v[198:201], v[190:193], v[16:31]
	v_mfma_f32_32x32x16_bf16 v[0:15], v[198:201], v[194:197], v[0:15]
	s_waitcnt vmcnt(11)
	ds_write_b128 v134, v[88:91] offset:55296
	s_waitcnt lgkmcnt(7)
	v_mfma_f32_32x32x16_bf16 v[48:63], v[202:205], v[206:209], v[48:63]
	s_waitcnt vmcnt(10)
	ds_write_b128 v134, v[92:95] offset:64512
	s_waitcnt lgkmcnt(7)
	v_mfma_f32_32x32x16_bf16 v[32:47], v[202:205], v[210:213], v[32:47]
	s_waitcnt vmcnt(9)
	ds_write_b128 v135, v[96:99] offset:18432
	s_waitcnt lgkmcnt(7)
	v_mfma_f32_32x32x16_bf16 v[16:31], v[214:217], v[206:209], v[16:31]
	v_mfma_f32_32x32x16_bf16 v[0:15], v[214:217], v[210:213], v[0:15]
	s_waitcnt vmcnt(8)
	ds_write_b128 v135, v[100:103] offset:27648
	s_waitcnt lgkmcnt(6)
	v_mfma_f32_32x32x16_bf16 v[48:63], v[222:225], v[226:229], v[48:63]
	s_waitcnt vmcnt(7)
	ds_write_b128 v128, v[104:107]
	s_waitcnt lgkmcnt(6)
	v_mfma_f32_32x32x16_bf16 v[32:47], v[222:225], v[230:233], v[32:47]
	s_waitcnt vmcnt(6)
	ds_write_b128 v128, v[108:111] offset:9216
	s_waitcnt lgkmcnt(6)
	v_mfma_f32_32x32x16_bf16 v[16:31], v[234:237], v[226:229], v[16:31]
	v_mfma_f32_32x32x16_bf16 v[0:15], v[234:237], v[230:233], v[0:15]
	s_waitcnt lgkmcnt(0)
	s_barrier
; template <class AS, class EP>
; DEVI void gemm_tile(const AS& as, const u16* __restrict__ Bt, int K, int m0, int n0, const EP& ep, char* lds) {
;     ...
;   GLOAD(ra0, rb0, 0); GLOAD(ra1, rb1, 1); LWRITE(0, ra0, rb0); __syncthreads();
;   for (int kt = 0; kt < KT; kt += 2) {
;     if (kt + 2 < KT) GLOAD(ra0, rb0, kt + 2);
;     __builtin_amdgcn_sched_barrier(0);
;     COMPUTE(0);
;     __builtin_amdgcn_sched_barrier(0);
;     LWRITE(1, ra1, rb1);
;     __syncthreads();
;     if (kt + 3 < KT) GLOAD(ra1, rb1, kt + 3);
;     __builtin_amdgcn_sched_barrier(0);
;     COMPUTE(1);
;     __builtin_amdgcn_sched_barrier(0);
;     if (kt + 2 < KT) LWRITE(0, ra0, rb0);
;     __syncthreads();
	global_load_dwordx4 v[88:91], v[112:113], off offset:640
	global_load_dwordx4 v[92:95], v[114:115], off offset:640
	global_load_dwordx4 v[96:99], v[116:117], off offset:640
	global_load_dwordx4 v[100:103], v[118:119], off offset:640
	global_load_dwordx4 v[104:107], v[120:121], off offset:640
	global_load_dwordx4 v[108:111], v[122:123], off offset:640
	ds_read_b128 v[170:173], v132 offset:55296
	ds_read_b128 v[174:177], v133
	ds_read_b128 v[178:181], v133 offset:4608
	ds_read_b128 v[182:185], v132 offset:59904
	ds_read_b128 v[186:189], v132 offset:55328
	ds_read_b128 v[190:193], v133 offset:32
	ds_read_b128 v[194:197], v133 offset:4640
	ds_read_b128 v[198:201], v132 offset:59936
	ds_read_b128 v[202:205], v132 offset:55360
	ds_read_b128 v[206:209], v133 offset:64
	ds_read_b128 v[210:213], v133 offset:4672
	ds_read_b128 v[214:217], v132 offset:59968
	s_waitcnt lgkmcnt(10)
	v_mfma_f32_32x32x16_bf16 v[48:63], v[170:173], v[174:177], v[48:63]
	s_waitcnt lgkmcnt(9)
	v_mfma_f32_32x32x16_bf16 v[32:47], v[170:173], v[178:181], v[32:47]
	s_waitcnt lgkmcnt(8)
	v_mfma_f32_32x32x16_bf16 v[16:31], v[182:185], v[174:177], v[16:31]
	v_mfma_f32_32x32x16_bf16 v[0:15], v[182:185], v[178:181], v[0:15]
	ds_read_b128 v[222:225], v132 offset:55392
	ds_read_b128 v[226:229], v133 offset:96
	ds_read_b128 v[230:233], v133 offset:4704
	ds_read_b128 v[234:237], v132 offset:60000
	s_waitcnt lgkmcnt(10)
	v_mfma_f32_32x32x16_bf16 v[48:63], v[186:189], v[190:193], v[48:63]
	s_waitcnt lgkmcnt(9)
	v_mfma_f32_32x32x16_bf16 v[32:47], v[186:189], v[194:197], v[32:47]
	s_waitcnt lgkmcnt(8)
	v_mfma_f32_32x32x16_bf16 v[16:31], v[198:201], v[190:193], v[16:31]
	v_mfma_f32_32x32x16_bf16 v[0:15], v[198:201], v[194:197], v[0:15]
	s_waitcnt vmcnt(11)
	ds_write_b128 v134, v[64:67]
	s_waitcnt lgkmcnt(7)
	v_mfma_f32_32x32x16_bf16 v[48:63], v[202:205], v[206:209], v[48:63]
	s_waitcnt vmcnt(10)
	ds_write_b128 v134, v[68:71] offset:9216
	s_waitcnt lgkmcnt(7)
	v_mfma_f32_32x32x16_bf16 v[32:47], v[202:205], v[210:213], v[32:47]
	s_waitcnt vmcnt(9)
	ds_write_b128 v134, v[72:75] offset:18432
	s_waitcnt lgkmcnt(7)
	v_mfma_f32_32x32x16_bf16 v[16:31], v[214:217], v[206:209], v[16:31]
	v_mfma_f32_32x32x16_bf16 v[0:15], v[214:217], v[210:213], v[0:15]
	s_waitcnt vmcnt(8)
	ds_write_b128 v134, v[76:79] offset:27648
	s_waitcnt lgkmcnt(6)
	v_mfma_f32_32x32x16_bf16 v[48:63], v[222:225], v[226:229], v[48:63]
	s_waitcnt vmcnt(7)
	ds_write_b128 v134, v[80:83] offset:36864
	s_waitcnt lgkmcnt(6)
	v_mfma_f32_32x32x16_bf16 v[32:47], v[222:225], v[230:233], v[32:47]
	s_waitcnt vmcnt(6)
	ds_write_b128 v134, v[84:87] offset:46080
	s_waitcnt lgkmcnt(6)
	v_mfma_f32_32x32x16_bf16 v[16:31], v[234:237], v[226:229], v[16:31]
	v_mfma_f32_32x32x16_bf16 v[0:15], v[234:237], v[230:233], v[0:15]
	s_waitcnt lgkmcnt(0)
	s_barrier
	global_load_dwordx4 v[64:67], v[112:113], off offset:768
	global_load_dwordx4 v[68:71], v[114:115], off offset:768
	global_load_dwordx4 v[72:75], v[116:117], off offset:768
	global_load_dwordx4 v[76:79], v[118:119], off offset:768
	global_load_dwordx4 v[80:83], v[120:121], off offset:768
	global_load_dwordx4 v[84:87], v[122:123], off offset:768
	ds_read_b128 v[170:173], v132
	ds_read_b128 v[174:177], v136 offset:36864
	ds_read_b128 v[178:181], v136 offset:41472
	ds_read_b128 v[182:185], v132 offset:4608
	ds_read_b128 v[186:189], v132 offset:32
	ds_read_b128 v[190:193], v136 offset:36896
	ds_read_b128 v[194:197], v136 offset:41504
	ds_read_b128 v[198:201], v132 offset:4640
	ds_read_b128 v[202:205], v132 offset:64
	ds_read_b128 v[206:209], v136 offset:36928
	ds_read_b128 v[210:213], v136 offset:41536
	ds_read_b128 v[214:217], v132 offset:4672
	s_waitcnt lgkmcnt(10)
	v_mfma_f32_32x32x16_bf16 v[48:63], v[170:173], v[174:177], v[48:63]
	s_waitcnt lgkmcnt(9)
	v_mfma_f32_32x32x16_bf16 v[32:47], v[170:173], v[178:181], v[32:47]
	s_waitcnt lgkmcnt(8)
	v_mfma_f32_32x32x16_bf16 v[16:31], v[182:185], v[174:177], v[16:31]
	v_mfma_f32_32x32x16_bf16 v[0:15], v[182:185], v[178:181], v[0:15]
	ds_read_b128 v[222:225], v132 offset:96
	ds_read_b128 v[226:229], v136 offset:36960
	ds_read_b128 v[230:233], v136 offset:41568
	ds_read_b128 v[234:237], v132 offset:4704
	s_waitcnt lgkmcnt(10)
	v_mfma_f32_32x32x16_bf16 v[48:63], v[186:189], v[190:193], v[48:63]
	s_waitcnt lgkmcnt(9)
	v_mfma_f32_32x32x16_bf16 v[32:47], v[186:189], v[194:197], v[32:47]
	s_waitcnt lgkmcnt(8)
	v_mfma_f32_32x32x16_bf16 v[16:31], v[198:201], v[190:193], v[16:31]
	v_mfma_f32_32x32x16_bf16 v[0:15], v[198:201], v[194:197], v[0:15]
	s_waitcnt vmcnt(11)
	ds_write_b128 v134, v[88:91] offset:55296
	s_waitcnt lgkmcnt(7)
	v_mfma_f32_32x32x16_bf16 v[48:63], v[202:205], v[206:209], v[48:63]
	s_waitcnt vmcnt(10)
	ds_write_b128 v134, v[92:95] offset:64512
	s_waitcnt lgkmcnt(7)
	v_mfma_f32_32x32x16_bf16 v[32:47], v[202:205], v[210:213], v[32:47]
	s_waitcnt vmcnt(9)
	ds_write_b128 v135, v[96:99] offset:18432
	s_waitcnt lgkmcnt(7)
	v_mfma_f32_32x32x16_bf16 v[16:31], v[214:217], v[206:209], v[16:31]
	v_mfma_f32_32x32x16_bf16 v[0:15], v[214:217], v[210:213], v[0:15]
	s_waitcnt vmcnt(8)
	ds_write_b128 v135, v[100:103] offset:27648
	s_waitcnt lgkmcnt(6)
	v_mfma_f32_32x32x16_bf16 v[48:63], v[222:225], v[226:229], v[48:63]
	s_waitcnt vmcnt(7)
	ds_write_b128 v128, v[104:107]
	s_waitcnt lgkmcnt(6)
	v_mfma_f32_32x32x16_bf16 v[32:47], v[222:225], v[230:233], v[32:47]
	s_waitcnt vmcnt(6)
	ds_write_b128 v128, v[108:111] offset:9216
	s_waitcnt lgkmcnt(6)
	v_mfma_f32_32x32x16_bf16 v[16:31], v[234:237], v[226:229], v[16:31]
	v_mfma_f32_32x32x16_bf16 v[0:15], v[234:237], v[230:233], v[0:15]
	s_waitcnt lgkmcnt(0)
	s_barrier
; template <class AS, class EP>
; DEVI void gemm_tile(const AS& as, const u16* __restrict__ Bt, int K, int m0, int n0, const EP& ep, char* lds) {
;     ...
;   GLOAD(ra0, rb0, 0); GLOAD(ra1, rb1, 1); LWRITE(0, ra0, rb0); __syncthreads();
;   for (int kt = 0; kt < KT; kt += 2) {
;     if (kt + 2 < KT) GLOAD(ra0, rb0, kt + 2);
;     __builtin_amdgcn_sched_barrier(0);
;     COMPUTE(0);
;     __builtin_amdgcn_sched_barrier(0);
;     LWRITE(1, ra1, rb1);
;     __syncthreads();
;     if (kt + 3 < KT) GLOAD(ra1, rb1, kt + 3);
;     __builtin_amdgcn_sched_barrier(0);
;     COMPUTE(1);
;     __builtin_amdgcn_sched_barrier(0);
;     if (kt + 2 < KT) LWRITE(0, ra0, rb0);
;     __syncthreads();
	global_load_dwordx4 v[88:91], v[112:113], off offset:896
	global_load_dwordx4 v[92:95], v[114:115], off offset:896
	global_load_dwordx4 v[96:99], v[116:117], off offset:896
	global_load_dwordx4 v[100:103], v[118:119], off offset:896
	global_load_dwordx4 v[104:107], v[120:121], off offset:896
	global_load_dwordx4 v[108:111], v[122:123], off offset:896
	ds_read_b128 v[170:173], v132 offset:55296
	ds_read_b128 v[174:177], v133
	ds_read_b128 v[178:181], v133 offset:4608
	ds_read_b128 v[182:185], v132 offset:59904
	ds_read_b128 v[186:189], v132 offset:55328
	ds_read_b128 v[190:193], v133 offset:32
	ds_read_b128 v[194:197], v133 offset:4640
	ds_read_b128 v[198:201], v132 offset:59936
	ds_read_b128 v[202:205], v132 offset:55360
	ds_read_b128 v[206:209], v133 offset:64
	ds_read_b128 v[210:213], v133 offset:4672
	ds_read_b128 v[214:217], v132 offset:59968
	s_waitcnt lgkmcnt(10)
	v_mfma_f32_32x32x16_bf16 v[48:63], v[170:173], v[174:177], v[48:63]
	s_waitcnt lgkmcnt(9)
	v_mfma_f32_32x32x16_bf16 v[32:47], v[170:173], v[178:181], v[32:47]
	s_waitcnt lgkmcnt(8)
	v_mfma_f32_32x32x16_bf16 v[16:31], v[182:185], v[174:177], v[16:31]
	v_mfma_f32_32x32x16_bf16 v[0:15], v[182:185], v[178:181], v[0:15]
	ds_read_b128 v[222:225], v132 offset:55392
	ds_read_b128 v[226:229], v133 offset:96
	ds_read_b128 v[230:233], v133 offset:4704
	ds_read_b128 v[234:237], v132 offset:60000
	s_waitcnt lgkmcnt(10)
	v_mfma_f32_32x32x16_bf16 v[48:63], v[186:189], v[190:193], v[48:63]
	s_waitcnt lgkmcnt(9)
	v_mfma_f32_32x32x16_bf16 v[32:47], v[186:189], v[194:197], v[32:47]
	s_waitcnt lgkmcnt(8)
	v_mfma_f32_32x32x16_bf16 v[16:31], v[198:201], v[190:193], v[16:31]
	v_mfma_f32_32x32x16_bf16 v[0:15], v[198:201], v[194:197], v[0:15]
	s_waitcnt vmcnt(11)
	ds_write_b128 v134, v[64:67]
	s_waitcnt lgkmcnt(7)
	v_mfma_f32_32x32x16_bf16 v[48:63], v[202:205], v[206:209], v[48:63]
	s_waitcnt vmcnt(10)
	ds_write_b128 v134, v[68:71] offset:9216
	s_waitcnt lgkmcnt(7)
	v_mfma_f32_32x32x16_bf16 v[32:47], v[202:205], v[210:213], v[32:47]
	s_waitcnt vmcnt(9)
	ds_write_b128 v134, v[72:75] offset:18432
	s_waitcnt lgkmcnt(7)
	v_mfma_f32_32x32x16_bf16 v[16:31], v[214:217], v[206:209], v[16:31]
	v_mfma_f32_32x32x16_bf16 v[0:15], v[214:217], v[210:213], v[0:15]
	s_waitcnt vmcnt(8)
	ds_write_b128 v134, v[76:79] offset:27648
	s_waitcnt lgkmcnt(6)
	v_mfma_f32_32x32x16_bf16 v[48:63], v[222:225], v[226:229], v[48:63]
	s_waitcnt vmcnt(7)
	ds_write_b128 v134, v[80:83] offset:36864
	s_waitcnt lgkmcnt(6)
	v_mfma_f32_32x32x16_bf16 v[32:47], v[222:225], v[230:233], v[32:47]
	s_waitcnt vmcnt(6)
	ds_write_b128 v134, v[84:87] offset:46080
	s_waitcnt lgkmcnt(6)
	v_mfma_f32_32x32x16_bf16 v[16:31], v[234:237], v[226:229], v[16:31]
	v_mfma_f32_32x32x16_bf16 v[0:15], v[234:237], v[230:233], v[0:15]
	s_waitcnt lgkmcnt(0)
	s_barrier
	global_load_dwordx4 v[64:67], v[112:113], off offset:1024
	global_load_dwordx4 v[68:71], v[114:115], off offset:1024
	global_load_dwordx4 v[72:75], v[116:117], off offset:1024
	global_load_dwordx4 v[76:79], v[118:119], off offset:1024
	global_load_dwordx4 v[80:83], v[120:121], off offset:1024
	global_load_dwordx4 v[84:87], v[122:123], off offset:1024
	ds_read_b128 v[170:173], v132
	ds_read_b128 v[174:177], v136 offset:36864
	ds_read_b128 v[178:181], v136 offset:41472
	ds_read_b128 v[182:185], v132 offset:4608
	ds_read_b128 v[186:189], v132 offset:32
	ds_read_b128 v[190:193], v136 offset:36896
	ds_read_b128 v[194:197], v136 offset:41504
	ds_read_b128 v[198:201], v132 offset:4640
	ds_read_b128 v[202:205], v132 offset:64
	ds_read_b128 v[206:209], v136 offset:36928
	ds_read_b128 v[210:213], v136 offset:41536
	ds_read_b128 v[214:217], v132 offset:4672
	s_waitcnt lgkmcnt(10)
	v_mfma_f32_32x32x16_bf16 v[48:63], v[170:173], v[174:177], v[48:63]
	s_waitcnt lgkmcnt(9)
	v_mfma_f32_32x32x16_bf16 v[32:47], v[170:173], v[178:181], v[32:47]
	s_waitcnt lgkmcnt(8)
	v_mfma_f32_32x32x16_bf16 v[16:31], v[182:185], v[174:177], v[16:31]
	v_mfma_f32_32x32x16_bf16 v[0:15], v[182:185], v[178:181], v[0:15]
	ds_read_b128 v[222:225], v132 offset:96
	ds_read_b128 v[226:229], v136 offset:36960
	ds_read_b128 v[230:233], v136 offset:41568
	ds_read_b128 v[234:237], v132 offset:4704
	s_waitcnt lgkmcnt(10)
	v_mfma_f32_32x32x16_bf16 v[48:63], v[186:189], v[190:193], v[48:63]
	s_waitcnt lgkmcnt(9)
	v_mfma_f32_32x32x16_bf16 v[32:47], v[186:189], v[194:197], v[32:47]
	s_waitcnt lgkmcnt(8)
	v_mfma_f32_32x32x16_bf16 v[16:31], v[198:201], v[190:193], v[16:31]
	v_mfma_f32_32x32x16_bf16 v[0:15], v[198:201], v[194:197], v[0:15]
	s_waitcnt vmcnt(11)
	ds_write_b128 v134, v[88:91] offset:55296
	s_waitcnt lgkmcnt(7)
	v_mfma_f32_32x32x16_bf16 v[48:63], v[202:205], v[206:209], v[48:63]
	s_waitcnt vmcnt(10)
	ds_write_b128 v134, v[92:95] offset:64512
	s_waitcnt lgkmcnt(7)
	v_mfma_f32_32x32x16_bf16 v[32:47], v[202:205], v[210:213], v[32:47]
	s_waitcnt vmcnt(9)
	ds_write_b128 v135, v[96:99] offset:18432
	s_waitcnt lgkmcnt(7)
	v_mfma_f32_32x32x16_bf16 v[16:31], v[214:217], v[206:209], v[16:31]
	v_mfma_f32_32x32x16_bf16 v[0:15], v[214:217], v[210:213], v[0:15]
	s_waitcnt vmcnt(8)
	ds_write_b128 v135, v[100:103] offset:27648
	s_waitcnt lgkmcnt(6)
	v_mfma_f32_32x32x16_bf16 v[48:63], v[222:225], v[226:229], v[48:63]
	s_waitcnt vmcnt(7)
	ds_write_b128 v128, v[104:107]
	s_waitcnt lgkmcnt(6)
	v_mfma_f32_32x32x16_bf16 v[32:47], v[222:225], v[230:233], v[32:47]
	s_waitcnt vmcnt(6)
	ds_write_b128 v128, v[108:111] offset:9216
	s_waitcnt lgkmcnt(6)
	v_mfma_f32_32x32x16_bf16 v[16:31], v[234:237], v[226:229], v[16:31]
	v_mfma_f32_32x32x16_bf16 v[0:15], v[234:237], v[230:233], v[0:15]
	s_waitcnt lgkmcnt(0)
	s_barrier
; template <class AS, class EP>
; DEVI void gemm_tile(const AS& as, const u16* __restrict__ Bt, int K, int m0, int n0, const EP& ep, char* lds) {
;     ...
;   GLOAD(ra0, rb0, 0); GLOAD(ra1, rb1, 1); LWRITE(0, ra0, rb0); __syncthreads();
;   for (int kt = 0; kt < KT; kt += 2) {
;     if (kt + 2 < KT) GLOAD(ra0, rb0, kt + 2);
;     __builtin_amdgcn_sched_barrier(0);
;     COMPUTE(0);
;     __builtin_amdgcn_sched_barrier(0);
;     LWRITE(1, ra1, rb1);
;     __syncthreads();
;     if (kt + 3 < KT) GLOAD(ra1, rb1, kt + 3);
;     __builtin_amdgcn_sched_barrier(0);
;     COMPUTE(1);
;     __builtin_amdgcn_sched_barrier(0);
;     if (kt + 2 < KT) LWRITE(0, ra0, rb0);
;     __syncthreads();
	global_load_dwordx4 v[88:91], v[112:113], off offset:1152
	global_load_dwordx4 v[92:95], v[114:115], off offset:1152
	global_load_dwordx4 v[96:99], v[116:117], off offset:1152
	global_load_dwordx4 v[100:103], v[118:119], off offset:1152
	global_load_dwordx4 v[104:107], v[120:121], off offset:1152
	global_load_dwordx4 v[108:111], v[122:123], off offset:1152
	ds_read_b128 v[170:173], v132 offset:55296
	ds_read_b128 v[174:177], v133
	ds_read_b128 v[178:181], v133 offset:4608
	ds_read_b128 v[182:185], v132 offset:59904
	ds_read_b128 v[186:189], v132 offset:55328
	ds_read_b128 v[190:193], v133 offset:32
	ds_read_b128 v[194:197], v133 offset:4640
	ds_read_b128 v[198:201], v132 offset:59936
	ds_read_b128 v[202:205], v132 offset:55360
	ds_read_b128 v[206:209], v133 offset:64
	ds_read_b128 v[210:213], v133 offset:4672
	ds_read_b128 v[214:217], v132 offset:59968
	s_waitcnt lgkmcnt(10)
	v_mfma_f32_32x32x16_bf16 v[48:63], v[170:173], v[174:177], v[48:63]
	s_waitcnt lgkmcnt(9)
	v_mfma_f32_32x32x16_bf16 v[32:47], v[170:173], v[178:181], v[32:47]
	s_waitcnt lgkmcnt(8)
	v_mfma_f32_32x32x16_bf16 v[16:31], v[182:185], v[174:177], v[16:31]
	v_mfma_f32_32x32x16_bf16 v[0:15], v[182:185], v[178:181], v[0:15]
	ds_read_b128 v[222:225], v132 offset:55392
	ds_read_b128 v[226:229], v133 offset:96
	ds_read_b128 v[230:233], v133 offset:4704
	ds_read_b128 v[234:237], v132 offset:60000
	s_waitcnt lgkmcnt(10)
	v_mfma_f32_32x32x16_bf16 v[48:63], v[186:189], v[190:193], v[48:63]
	s_waitcnt lgkmcnt(9)
	v_mfma_f32_32x32x16_bf16 v[32:47], v[186:189], v[194:197], v[32:47]
	s_waitcnt lgkmcnt(8)
	v_mfma_f32_32x32x16_bf16 v[16:31], v[198:201], v[190:193], v[16:31]
	v_mfma_f32_32x32x16_bf16 v[0:15], v[198:201], v[194:197], v[0:15]
	s_waitcnt vmcnt(11)
	ds_write_b128 v134, v[64:67]
	s_waitcnt lgkmcnt(7)
	v_mfma_f32_32x32x16_bf16 v[48:63], v[202:205], v[206:209], v[48:63]
	s_waitcnt vmcnt(10)
	ds_write_b128 v134, v[68:71] offset:9216
	s_waitcnt lgkmcnt(7)
	v_mfma_f32_32x32x16_bf16 v[32:47], v[202:205], v[210:213], v[32:47]
	s_waitcnt vmcnt(9)
	ds_write_b128 v134, v[72:75] offset:18432
	s_waitcnt lgkmcnt(7)
	v_mfma_f32_32x32x16_bf16 v[16:31], v[214:217], v[206:209], v[16:31]
	v_mfma_f32_32x32x16_bf16 v[0:15], v[214:217], v[210:213], v[0:15]
	s_waitcnt vmcnt(8)
	ds_write_b128 v134, v[76:79] offset:27648
	s_waitcnt lgkmcnt(6)
	v_mfma_f32_32x32x16_bf16 v[48:63], v[222:225], v[226:229], v[48:63]
	s_waitcnt vmcnt(7)
	ds_write_b128 v134, v[80:83] offset:36864
	s_waitcnt lgkmcnt(6)
	v_mfma_f32_32x32x16_bf16 v[32:47], v[222:225], v[230:233], v[32:47]
	s_waitcnt vmcnt(6)
	ds_write_b128 v134, v[84:87] offset:46080
	s_waitcnt lgkmcnt(6)
	v_mfma_f32_32x32x16_bf16 v[16:31], v[234:237], v[226:229], v[16:31]
	v_mfma_f32_32x32x16_bf16 v[0:15], v[234:237], v[230:233], v[0:15]
	s_waitcnt lgkmcnt(0)
	s_barrier
	global_load_dwordx4 v[64:67], v[112:113], off offset:1280
	global_load_dwordx4 v[68:71], v[114:115], off offset:1280
	global_load_dwordx4 v[72:75], v[116:117], off offset:1280
	global_load_dwordx4 v[76:79], v[118:119], off offset:1280
	global_load_dwordx4 v[80:83], v[120:121], off offset:1280
	global_load_dwordx4 v[84:87], v[122:123], off offset:1280
	ds_read_b128 v[170:173], v132
	ds_read_b128 v[174:177], v136 offset:36864
	ds_read_b128 v[178:181], v136 offset:41472
	ds_read_b128 v[182:185], v132 offset:4608
	ds_read_b128 v[186:189], v132 offset:32
	ds_read_b128 v[190:193], v136 offset:36896
	ds_read_b128 v[194:197], v136 offset:41504
	ds_read_b128 v[198:201], v132 offset:4640
	ds_read_b128 v[202:205], v132 offset:64
	ds_read_b128 v[206:209], v136 offset:36928
	ds_read_b128 v[210:213], v136 offset:41536
	ds_read_b128 v[214:217], v132 offset:4672
	s_waitcnt lgkmcnt(10)
	v_mfma_f32_32x32x16_bf16 v[48:63], v[170:173], v[174:177], v[48:63]
	s_waitcnt lgkmcnt(9)
	v_mfma_f32_32x32x16_bf16 v[32:47], v[170:173], v[178:181], v[32:47]
	s_waitcnt lgkmcnt(8)
	v_mfma_f32_32x32x16_bf16 v[16:31], v[182:185], v[174:177], v[16:31]
	v_mfma_f32_32x32x16_bf16 v[0:15], v[182:185], v[178:181], v[0:15]
	ds_read_b128 v[222:225], v132 offset:96
	ds_read_b128 v[226:229], v136 offset:36960
	ds_read_b128 v[230:233], v136 offset:41568
	ds_read_b128 v[234:237], v132 offset:4704
	s_waitcnt lgkmcnt(10)
	v_mfma_f32_32x32x16_bf16 v[48:63], v[186:189], v[190:193], v[48:63]
	s_waitcnt lgkmcnt(9)
	v_mfma_f32_32x32x16_bf16 v[32:47], v[186:189], v[194:197], v[32:47]
	s_waitcnt lgkmcnt(8)
	v_mfma_f32_32x32x16_bf16 v[16:31], v[198:201], v[190:193], v[16:31]
	v_mfma_f32_32x32x16_bf16 v[0:15], v[198:201], v[194:197], v[0:15]
	s_waitcnt vmcnt(11)
	ds_write_b128 v134, v[88:91] offset:55296
	s_waitcnt lgkmcnt(7)
	v_mfma_f32_32x32x16_bf16 v[48:63], v[202:205], v[206:209], v[48:63]
	s_waitcnt vmcnt(10)
	ds_write_b128 v134, v[92:95] offset:64512
	s_waitcnt lgkmcnt(7)
	v_mfma_f32_32x32x16_bf16 v[32:47], v[202:205], v[210:213], v[32:47]
	s_waitcnt vmcnt(9)
	ds_write_b128 v135, v[96:99] offset:18432
	s_waitcnt lgkmcnt(7)
	v_mfma_f32_32x32x16_bf16 v[16:31], v[214:217], v[206:209], v[16:31]
	v_mfma_f32_32x32x16_bf16 v[0:15], v[214:217], v[210:213], v[0:15]
	s_waitcnt vmcnt(8)
	ds_write_b128 v135, v[100:103] offset:27648
	s_waitcnt lgkmcnt(6)
	v_mfma_f32_32x32x16_bf16 v[48:63], v[222:225], v[226:229], v[48:63]
	s_waitcnt vmcnt(7)
	ds_write_b128 v128, v[104:107]
	s_waitcnt lgkmcnt(6)
	v_mfma_f32_32x32x16_bf16 v[32:47], v[222:225], v[230:233], v[32:47]
	s_waitcnt vmcnt(6)
	ds_write_b128 v128, v[108:111] offset:9216
	s_waitcnt lgkmcnt(6)
	v_mfma_f32_32x32x16_bf16 v[16:31], v[234:237], v[226:229], v[16:31]
	v_mfma_f32_32x32x16_bf16 v[0:15], v[234:237], v[230:233], v[0:15]
	s_waitcnt lgkmcnt(0)
	s_barrier
; template <class AS, class EP>
; DEVI void gemm_tile(const AS& as, const u16* __restrict__ Bt, int K, int m0, int n0, const EP& ep, char* lds) {
;     ...
;   GLOAD(ra0, rb0, 0); GLOAD(ra1, rb1, 1); LWRITE(0, ra0, rb0); __syncthreads();
;   for (int kt = 0; kt < KT; kt += 2) {
;     if (kt + 2 < KT) GLOAD(ra0, rb0, kt + 2);
;     __builtin_amdgcn_sched_barrier(0);
;     COMPUTE(0);
;     __builtin_amdgcn_sched_barrier(0);
;     LWRITE(1, ra1, rb1);
;     __syncthreads();
;     if (kt + 3 < KT) GLOAD(ra1, rb1, kt + 3);
;     __builtin_amdgcn_sched_barrier(0);
;     COMPUTE(1);
;     __builtin_amdgcn_sched_barrier(0);
;     if (kt + 2 < KT) LWRITE(0, ra0, rb0);
;     __syncthreads();
	global_load_dwordx4 v[88:91], v[112:113], off offset:1408
	global_load_dwordx4 v[92:95], v[114:115], off offset:1408
	global_load_dwordx4 v[96:99], v[116:117], off offset:1408
	global_load_dwordx4 v[100:103], v[118:119], off offset:1408
	global_load_dwordx4 v[104:107], v[120:121], off offset:1408
	global_load_dwordx4 v[108:111], v[122:123], off offset:1408
	ds_read_b128 v[170:173], v132 offset:55296
	ds_read_b128 v[174:177], v133
	ds_read_b128 v[178:181], v133 offset:4608
	ds_read_b128 v[182:185], v132 offset:59904
	ds_read_b128 v[186:189], v132 offset:55328
	ds_read_b128 v[190:193], v133 offset:32
	ds_read_b128 v[194:197], v133 offset:4640
	ds_read_b128 v[198:201], v132 offset:59936
	ds_read_b128 v[202:205], v132 offset:55360
	ds_read_b128 v[206:209], v133 offset:64
	ds_read_b128 v[210:213], v133 offset:4672
	ds_read_b128 v[214:217], v132 offset:59968
	s_waitcnt lgkmcnt(10)
	v_mfma_f32_32x32x16_bf16 v[48:63], v[170:173], v[174:177], v[48:63]
	s_waitcnt lgkmcnt(9)
	v_mfma_f32_32x32x16_bf16 v[32:47], v[170:173], v[178:181], v[32:47]
	s_waitcnt lgkmcnt(8)
	v_mfma_f32_32x32x16_bf16 v[16:31], v[182:185], v[174:177], v[16:31]
	v_mfma_f32_32x32x16_bf16 v[0:15], v[182:185], v[178:181], v[0:15]
	ds_read_b128 v[222:225], v132 offset:55392
	ds_read_b128 v[226:229], v133 offset:96
	ds_read_b128 v[230:233], v133 offset:4704
	ds_read_b128 v[234:237], v132 offset:60000
	s_waitcnt lgkmcnt(10)
	v_mfma_f32_32x32x16_bf16 v[48:63], v[186:189], v[190:193], v[48:63]
	s_waitcnt lgkmcnt(9)
	v_mfma_f32_32x32x16_bf16 v[32:47], v[186:189], v[194:197], v[32:47]
	s_waitcnt lgkmcnt(8)
	v_mfma_f32_32x32x16_bf16 v[16:31], v[198:201], v[190:193], v[16:31]
	v_mfma_f32_32x32x16_bf16 v[0:15], v[198:201], v[194:197], v[0:15]
	s_waitcnt vmcnt(11)
	ds_write_b128 v134, v[64:67]
	s_waitcnt lgkmcnt(7)
	v_mfma_f32_32x32x16_bf16 v[48:63], v[202:205], v[206:209], v[48:63]
	s_waitcnt vmcnt(10)
	ds_write_b128 v134, v[68:71] offset:9216
	s_waitcnt lgkmcnt(7)
	v_mfma_f32_32x32x16_bf16 v[32:47], v[202:205], v[210:213], v[32:47]
	s_waitcnt vmcnt(9)
	ds_write_b128 v134, v[72:75] offset:18432
	s_waitcnt lgkmcnt(7)
	v_mfma_f32_32x32x16_bf16 v[16:31], v[214:217], v[206:209], v[16:31]
	v_mfma_f32_32x32x16_bf16 v[0:15], v[214:217], v[210:213], v[0:15]
	s_waitcnt vmcnt(8)
	ds_write_b128 v134, v[76:79] offset:27648
	s_waitcnt lgkmcnt(6)
	v_mfma_f32_32x32x16_bf16 v[48:63], v[222:225], v[226:229], v[48:63]
	s_waitcnt vmcnt(7)
	ds_write_b128 v134, v[80:83] offset:36864
	s_waitcnt lgkmcnt(6)
	v_mfma_f32_32x32x16_bf16 v[32:47], v[222:225], v[230:233], v[32:47]
	s_waitcnt vmcnt(6)
	ds_write_b128 v134, v[84:87] offset:46080
	s_waitcnt lgkmcnt(6)
	v_mfma_f32_32x32x16_bf16 v[16:31], v[234:237], v[226:229], v[16:31]
	v_mfma_f32_32x32x16_bf16 v[0:15], v[234:237], v[230:233], v[0:15]
	s_waitcnt lgkmcnt(0)
	s_barrier
	global_load_dwordx4 v[64:67], v[112:113], off offset:1536
	global_load_dwordx4 v[68:71], v[114:115], off offset:1536
	global_load_dwordx4 v[72:75], v[116:117], off offset:1536
	global_load_dwordx4 v[76:79], v[118:119], off offset:1536
	global_load_dwordx4 v[80:83], v[120:121], off offset:1536
	global_load_dwordx4 v[84:87], v[122:123], off offset:1536
	ds_read_b128 v[170:173], v132
	ds_read_b128 v[174:177], v136 offset:36864
	ds_read_b128 v[178:181], v136 offset:41472
	ds_read_b128 v[182:185], v132 offset:4608
	ds_read_b128 v[186:189], v132 offset:32
	ds_read_b128 v[190:193], v136 offset:36896
	ds_read_b128 v[194:197], v136 offset:41504
	ds_read_b128 v[198:201], v132 offset:4640
	ds_read_b128 v[202:205], v132 offset:64
	ds_read_b128 v[206:209], v136 offset:36928
	ds_read_b128 v[210:213], v136 offset:41536
	ds_read_b128 v[214:217], v132 offset:4672
	s_waitcnt lgkmcnt(10)
	v_mfma_f32_32x32x16_bf16 v[48:63], v[170:173], v[174:177], v[48:63]
	s_waitcnt lgkmcnt(9)
	v_mfma_f32_32x32x16_bf16 v[32:47], v[170:173], v[178:181], v[32:47]
	s_waitcnt lgkmcnt(8)
	v_mfma_f32_32x32x16_bf16 v[16:31], v[182:185], v[174:177], v[16:31]
	v_mfma_f32_32x32x16_bf16 v[0:15], v[182:185], v[178:181], v[0:15]
	ds_read_b128 v[222:225], v132 offset:96
	ds_read_b128 v[226:229], v136 offset:36960
	ds_read_b128 v[230:233], v136 offset:41568
	ds_read_b128 v[234:237], v132 offset:4704
	s_waitcnt lgkmcnt(10)
	v_mfma_f32_32x32x16_bf16 v[48:63], v[186:189], v[190:193], v[48:63]
	s_waitcnt lgkmcnt(9)
	v_mfma_f32_32x32x16_bf16 v[32:47], v[186:189], v[194:197], v[32:47]
	s_waitcnt lgkmcnt(8)
	v_mfma_f32_32x32x16_bf16 v[16:31], v[198:201], v[190:193], v[16:31]
	v_mfma_f32_32x32x16_bf16 v[0:15], v[198:201], v[194:197], v[0:15]
	s_waitcnt vmcnt(11)
	ds_write_b128 v134, v[88:91] offset:55296
	s_waitcnt lgkmcnt(7)
	v_mfma_f32_32x32x16_bf16 v[48:63], v[202:205], v[206:209], v[48:63]
	s_waitcnt vmcnt(10)
	ds_write_b128 v134, v[92:95] offset:64512
	s_waitcnt lgkmcnt(7)
	v_mfma_f32_32x32x16_bf16 v[32:47], v[202:205], v[210:213], v[32:47]
	s_waitcnt vmcnt(9)
	ds_write_b128 v135, v[96:99] offset:18432
	s_waitcnt lgkmcnt(7)
	v_mfma_f32_32x32x16_bf16 v[16:31], v[214:217], v[206:209], v[16:31]
	v_mfma_f32_32x32x16_bf16 v[0:15], v[214:217], v[210:213], v[0:15]
	s_waitcnt vmcnt(8)
	ds_write_b128 v135, v[100:103] offset:27648
	s_waitcnt lgkmcnt(6)
	v_mfma_f32_32x32x16_bf16 v[48:63], v[222:225], v[226:229], v[48:63]
	s_waitcnt vmcnt(7)
	ds_write_b128 v128, v[104:107]
	s_waitcnt lgkmcnt(6)
	v_mfma_f32_32x32x16_bf16 v[32:47], v[222:225], v[230:233], v[32:47]
	s_waitcnt vmcnt(6)
	ds_write_b128 v128, v[108:111] offset:9216
	s_waitcnt lgkmcnt(6)
	v_mfma_f32_32x32x16_bf16 v[16:31], v[234:237], v[226:229], v[16:31]
	v_mfma_f32_32x32x16_bf16 v[0:15], v[234:237], v[230:233], v[0:15]
	s_waitcnt lgkmcnt(0)
	s_barrier
; template <class AS, class EP>
; DEVI void gemm_tile(const AS& as, const u16* __restrict__ Bt, int K, int m0, int n0, const EP& ep, char* lds) {
;     ...
;   GLOAD(ra0, rb0, 0); GLOAD(ra1, rb1, 1); LWRITE(0, ra0, rb0); __syncthreads();
;   for (int kt = 0; kt < KT; kt += 2) {
;     if (kt + 2 < KT) GLOAD(ra0, rb0, kt + 2);
;     __builtin_amdgcn_sched_barrier(0);
;     COMPUTE(0);
;     __builtin_amdgcn_sched_barrier(0);
;     LWRITE(1, ra1, rb1);
;     __syncthreads();
;     if (kt + 3 < KT) GLOAD(ra1, rb1, kt + 3);
;     __builtin_amdgcn_sched_barrier(0);
;     COMPUTE(1);
;     __builtin_amdgcn_sched_barrier(0);
;     if (kt + 2 < KT) LWRITE(0, ra0, rb0);
;     __syncthreads();
	global_load_dwordx4 v[88:91], v[112:113], off offset:1664
	global_load_dwordx4 v[92:95], v[114:115], off offset:1664
	global_load_dwordx4 v[96:99], v[116:117], off offset:1664
	global_load_dwordx4 v[100:103], v[118:119], off offset:1664
	global_load_dwordx4 v[104:107], v[120:121], off offset:1664
	global_load_dwordx4 v[108:111], v[122:123], off offset:1664
	ds_read_b128 v[170:173], v132 offset:55296
	ds_read_b128 v[174:177], v133
	ds_read_b128 v[178:181], v133 offset:4608
	ds_read_b128 v[182:185], v132 offset:59904
	ds_read_b128 v[186:189], v132 offset:55328
	ds_read_b128 v[190:193], v133 offset:32
	ds_read_b128 v[194:197], v133 offset:4640
	ds_read_b128 v[198:201], v132 offset:59936
	ds_read_b128 v[202:205], v132 offset:55360
	ds_read_b128 v[206:209], v133 offset:64
	ds_read_b128 v[210:213], v133 offset:4672
	ds_read_b128 v[214:217], v132 offset:59968
	s_waitcnt lgkmcnt(10)
	v_mfma_f32_32x32x16_bf16 v[48:63], v[170:173], v[174:177], v[48:63]
	s_waitcnt lgkmcnt(9)
	v_mfma_f32_32x32x16_bf16 v[32:47], v[170:173], v[178:181], v[32:47]
	s_waitcnt lgkmcnt(8)
	v_mfma_f32_32x32x16_bf16 v[16:31], v[182:185], v[174:177], v[16:31]
	v_mfma_f32_32x32x16_bf16 v[0:15], v[182:185], v[178:181], v[0:15]
	ds_read_b128 v[222:225], v132 offset:55392
	ds_read_b128 v[226:229], v133 offset:96
	ds_read_b128 v[230:233], v133 offset:4704
	ds_read_b128 v[234:237], v132 offset:60000
	s_waitcnt lgkmcnt(10)
	v_mfma_f32_32x32x16_bf16 v[48:63], v[186:189], v[190:193], v[48:63]
	s_waitcnt lgkmcnt(9)
	v_mfma_f32_32x32x16_bf16 v[32:47], v[186:189], v[194:197], v[32:47]
	s_waitcnt lgkmcnt(8)
	v_mfma_f32_32x32x16_bf16 v[16:31], v[198:201], v[190:193], v[16:31]
	v_mfma_f32_32x32x16_bf16 v[0:15], v[198:201], v[194:197], v[0:15]
	s_waitcnt vmcnt(11)
	ds_write_b128 v134, v[64:67]
	s_waitcnt lgkmcnt(7)
	v_mfma_f32_32x32x16_bf16 v[48:63], v[202:205], v[206:209], v[48:63]
	s_waitcnt vmcnt(10)
	ds_write_b128 v134, v[68:71] offset:9216
	s_waitcnt lgkmcnt(7)
	v_mfma_f32_32x32x16_bf16 v[32:47], v[202:205], v[210:213], v[32:47]
	s_waitcnt vmcnt(9)
	ds_write_b128 v134, v[72:75] offset:18432
	s_waitcnt lgkmcnt(7)
	v_mfma_f32_32x32x16_bf16 v[16:31], v[214:217], v[206:209], v[16:31]
	v_mfma_f32_32x32x16_bf16 v[0:15], v[214:217], v[210:213], v[0:15]
	s_waitcnt vmcnt(8)
	ds_write_b128 v134, v[76:79] offset:27648
	s_waitcnt lgkmcnt(6)
	v_mfma_f32_32x32x16_bf16 v[48:63], v[222:225], v[226:229], v[48:63]
	s_waitcnt vmcnt(7)
	ds_write_b128 v134, v[80:83] offset:36864
	s_waitcnt lgkmcnt(6)
	v_mfma_f32_32x32x16_bf16 v[32:47], v[222:225], v[230:233], v[32:47]
	s_waitcnt vmcnt(6)
	ds_write_b128 v134, v[84:87] offset:46080
	s_waitcnt lgkmcnt(6)
	v_mfma_f32_32x32x16_bf16 v[16:31], v[234:237], v[226:229], v[16:31]
	v_mfma_f32_32x32x16_bf16 v[0:15], v[234:237], v[230:233], v[0:15]
	s_waitcnt lgkmcnt(0)
	s_barrier
	global_load_dwordx4 v[64:67], v[112:113], off offset:1792
	global_load_dwordx4 v[68:71], v[114:115], off offset:1792
	global_load_dwordx4 v[72:75], v[116:117], off offset:1792
	global_load_dwordx4 v[76:79], v[118:119], off offset:1792
	global_load_dwordx4 v[80:83], v[120:121], off offset:1792
	global_load_dwordx4 v[84:87], v[122:123], off offset:1792
	ds_read_b128 v[170:173], v132
	ds_read_b128 v[174:177], v136 offset:36864
	ds_read_b128 v[178:181], v136 offset:41472
	ds_read_b128 v[182:185], v132 offset:4608
	ds_read_b128 v[186:189], v132 offset:32
	ds_read_b128 v[190:193], v136 offset:36896
	ds_read_b128 v[194:197], v136 offset:41504
	ds_read_b128 v[198:201], v132 offset:4640
	ds_read_b128 v[202:205], v132 offset:64
	ds_read_b128 v[206:209], v136 offset:36928
	ds_read_b128 v[210:213], v136 offset:41536
	ds_read_b128 v[214:217], v132 offset:4672
	s_waitcnt lgkmcnt(10)
	v_mfma_f32_32x32x16_bf16 v[48:63], v[170:173], v[174:177], v[48:63]
	s_waitcnt lgkmcnt(9)
	v_mfma_f32_32x32x16_bf16 v[32:47], v[170:173], v[178:181], v[32:47]
	s_waitcnt lgkmcnt(8)
	v_mfma_f32_32x32x16_bf16 v[16:31], v[182:185], v[174:177], v[16:31]
	v_mfma_f32_32x32x16_bf16 v[0:15], v[182:185], v[178:181], v[0:15]
	ds_read_b128 v[222:225], v132 offset:96
	ds_read_b128 v[226:229], v136 offset:36960
	ds_read_b128 v[230:233], v136 offset:41568
	ds_read_b128 v[234:237], v132 offset:4704
	s_waitcnt lgkmcnt(10)
	v_mfma_f32_32x32x16_bf16 v[48:63], v[186:189], v[190:193], v[48:63]
	s_waitcnt lgkmcnt(9)
	v_mfma_f32_32x32x16_bf16 v[32:47], v[186:189], v[194:197], v[32:47]
	s_waitcnt lgkmcnt(8)
	v_mfma_f32_32x32x16_bf16 v[16:31], v[198:201], v[190:193], v[16:31]
	v_mfma_f32_32x32x16_bf16 v[0:15], v[198:201], v[194:197], v[0:15]
	s_waitcnt vmcnt(11)
	ds_write_b128 v134, v[88:91] offset:55296
	s_waitcnt lgkmcnt(7)
	v_mfma_f32_32x32x16_bf16 v[48:63], v[202:205], v[206:209], v[48:63]
	s_waitcnt vmcnt(10)
	ds_write_b128 v134, v[92:95] offset:64512
	s_waitcnt lgkmcnt(7)
	v_mfma_f32_32x32x16_bf16 v[32:47], v[202:205], v[210:213], v[32:47]
	s_waitcnt vmcnt(9)
	ds_write_b128 v135, v[96:99] offset:18432
	s_waitcnt lgkmcnt(7)
	v_mfma_f32_32x32x16_bf16 v[16:31], v[214:217], v[206:209], v[16:31]
	v_mfma_f32_32x32x16_bf16 v[0:15], v[214:217], v[210:213], v[0:15]
	s_waitcnt vmcnt(8)
	ds_write_b128 v135, v[100:103] offset:27648
	s_waitcnt lgkmcnt(6)
	v_mfma_f32_32x32x16_bf16 v[48:63], v[222:225], v[226:229], v[48:63]
	s_waitcnt vmcnt(7)
	ds_write_b128 v128, v[104:107]
	s_waitcnt lgkmcnt(6)
	v_mfma_f32_32x32x16_bf16 v[32:47], v[222:225], v[230:233], v[32:47]
	s_waitcnt vmcnt(6)
	ds_write_b128 v128, v[108:111] offset:9216
	s_waitcnt lgkmcnt(6)
	v_mfma_f32_32x32x16_bf16 v[16:31], v[234:237], v[226:229], v[16:31]
	v_mfma_f32_32x32x16_bf16 v[0:15], v[234:237], v[230:233], v[0:15]
	s_waitcnt lgkmcnt(0)
	s_barrier
; template <class AS, class EP>
; DEVI void gemm_tile(const AS& as, const u16* __restrict__ Bt, int K, int m0, int n0, const EP& ep, char* lds) {
;     ...
;   GLOAD(ra0, rb0, 0); GLOAD(ra1, rb1, 1); LWRITE(0, ra0, rb0); __syncthreads();
;   for (int kt = 0; kt < KT; kt += 2) {
;     if (kt + 2 < KT) GLOAD(ra0, rb0, kt + 2);
;     __builtin_amdgcn_sched_barrier(0);
;     COMPUTE(0);
;     __builtin_amdgcn_sched_barrier(0);
;     LWRITE(1, ra1, rb1);
;     __syncthreads();
;     if (kt + 3 < KT) GLOAD(ra1, rb1, kt + 3);
;     __builtin_amdgcn_sched_barrier(0);
;     COMPUTE(1);
;     __builtin_amdgcn_sched_barrier(0);
;     if (kt + 2 < KT) LWRITE(0, ra0, rb0);
;     __syncthreads();
	global_load_dwordx4 v[88:91], v[112:113], off offset:1920
	global_load_dwordx4 v[92:95], v[114:115], off offset:1920
	global_load_dwordx4 v[96:99], v[116:117], off offset:1920
	global_load_dwordx4 v[100:103], v[118:119], off offset:1920
	global_load_dwordx4 v[104:107], v[120:121], off offset:1920
	global_load_dwordx4 v[108:111], v[122:123], off offset:1920
	ds_read_b128 v[170:173], v132 offset:55296
	ds_read_b128 v[174:177], v133
	ds_read_b128 v[178:181], v133 offset:4608
	ds_read_b128 v[182:185], v132 offset:59904
	ds_read_b128 v[186:189], v132 offset:55328
	ds_read_b128 v[190:193], v133 offset:32
	ds_read_b128 v[194:197], v133 offset:4640
	ds_read_b128 v[198:201], v132 offset:59936
	ds_read_b128 v[202:205], v132 offset:55360
	ds_read_b128 v[206:209], v133 offset:64
	ds_read_b128 v[210:213], v133 offset:4672
	ds_read_b128 v[214:217], v132 offset:59968
	s_waitcnt lgkmcnt(10)
	v_mfma_f32_32x32x16_bf16 v[48:63], v[170:173], v[174:177], v[48:63]
	s_waitcnt lgkmcnt(9)
	v_mfma_f32_32x32x16_bf16 v[32:47], v[170:173], v[178:181], v[32:47]
	s_waitcnt lgkmcnt(8)
	v_mfma_f32_32x32x16_bf16 v[16:31], v[182:185], v[174:177], v[16:31]
	v_mfma_f32_32x32x16_bf16 v[0:15], v[182:185], v[178:181], v[0:15]
	ds_read_b128 v[222:225], v132 offset:55392
	ds_read_b128 v[226:229], v133 offset:96
	ds_read_b128 v[230:233], v133 offset:4704
	ds_read_b128 v[234:237], v132 offset:60000
	s_waitcnt lgkmcnt(10)
	v_mfma_f32_32x32x16_bf16 v[48:63], v[186:189], v[190:193], v[48:63]
	s_waitcnt lgkmcnt(9)
	v_mfma_f32_32x32x16_bf16 v[32:47], v[186:189], v[194:197], v[32:47]
	s_waitcnt lgkmcnt(8)
	v_mfma_f32_32x32x16_bf16 v[16:31], v[198:201], v[190:193], v[16:31]
	v_mfma_f32_32x32x16_bf16 v[0:15], v[198:201], v[194:197], v[0:15]
	s_waitcnt vmcnt(11)
	ds_write_b128 v134, v[64:67]
	s_waitcnt lgkmcnt(7)
	v_mfma_f32_32x32x16_bf16 v[48:63], v[202:205], v[206:209], v[48:63]
	s_waitcnt vmcnt(10)
	ds_write_b128 v134, v[68:71] offset:9216
	s_waitcnt lgkmcnt(7)
	v_mfma_f32_32x32x16_bf16 v[32:47], v[202:205], v[210:213], v[32:47]
	s_waitcnt vmcnt(9)
	ds_write_b128 v134, v[72:75] offset:18432
	s_waitcnt lgkmcnt(7)
	v_mfma_f32_32x32x16_bf16 v[16:31], v[214:217], v[206:209], v[16:31]
	v_mfma_f32_32x32x16_bf16 v[0:15], v[214:217], v[210:213], v[0:15]
	s_waitcnt vmcnt(8)
	ds_write_b128 v134, v[76:79] offset:27648
	s_waitcnt lgkmcnt(6)
	v_mfma_f32_32x32x16_bf16 v[48:63], v[222:225], v[226:229], v[48:63]
	s_waitcnt vmcnt(7)
	ds_write_b128 v134, v[80:83] offset:36864
	s_waitcnt lgkmcnt(6)
	v_mfma_f32_32x32x16_bf16 v[32:47], v[222:225], v[230:233], v[32:47]
	s_waitcnt vmcnt(6)
	ds_write_b128 v134, v[84:87] offset:46080
	s_waitcnt lgkmcnt(6)
	v_mfma_f32_32x32x16_bf16 v[16:31], v[234:237], v[226:229], v[16:31]
	v_mfma_f32_32x32x16_bf16 v[0:15], v[234:237], v[230:233], v[0:15]
	s_waitcnt lgkmcnt(0)
	s_barrier
	ds_read_b128 v[170:173], v132
	ds_read_b128 v[174:177], v136 offset:36864
	ds_read_b128 v[178:181], v136 offset:41472
	ds_read_b128 v[182:185], v132 offset:4608
	ds_read_b128 v[186:189], v132 offset:32
	ds_read_b128 v[190:193], v136 offset:36896
	ds_read_b128 v[194:197], v136 offset:41504
	ds_read_b128 v[198:201], v132 offset:4640
	ds_read_b128 v[202:205], v132 offset:64
	ds_read_b128 v[206:209], v136 offset:36928
	ds_read_b128 v[210:213], v136 offset:41536
	ds_read_b128 v[214:217], v132 offset:4672
	s_waitcnt lgkmcnt(10)
	v_mfma_f32_32x32x16_bf16 v[48:63], v[170:173], v[174:177], v[48:63]
	s_waitcnt lgkmcnt(9)
	v_mfma_f32_32x32x16_bf16 v[32:47], v[170:173], v[178:181], v[32:47]
	s_waitcnt lgkmcnt(8)
	v_mfma_f32_32x32x16_bf16 v[16:31], v[182:185], v[174:177], v[16:31]
	v_mfma_f32_32x32x16_bf16 v[0:15], v[182:185], v[178:181], v[0:15]
	ds_read_b128 v[222:225], v132 offset:96
	ds_read_b128 v[226:229], v136 offset:36960
	ds_read_b128 v[230:233], v136 offset:41568
	ds_read_b128 v[234:237], v132 offset:4704
	s_waitcnt lgkmcnt(10)
	v_mfma_f32_32x32x16_bf16 v[48:63], v[186:189], v[190:193], v[48:63]
	s_waitcnt lgkmcnt(9)
	v_mfma_f32_32x32x16_bf16 v[32:47], v[186:189], v[194:197], v[32:47]
	s_waitcnt lgkmcnt(8)
	v_mfma_f32_32x32x16_bf16 v[16:31], v[198:201], v[190:193], v[16:31]
	v_mfma_f32_32x32x16_bf16 v[0:15], v[198:201], v[194:197], v[0:15]
	s_waitcnt vmcnt(5)
	ds_write_b128 v134, v[88:91] offset:55296
	s_waitcnt lgkmcnt(7)
	v_mfma_f32_32x32x16_bf16 v[48:63], v[202:205], v[206:209], v[48:63]
	s_waitcnt vmcnt(4)
	ds_write_b128 v134, v[92:95] offset:64512
	s_waitcnt lgkmcnt(7)
	v_mfma_f32_32x32x16_bf16 v[32:47], v[202:205], v[210:213], v[32:47]
	s_waitcnt vmcnt(3)
	ds_write_b128 v135, v[96:99] offset:18432
	s_waitcnt lgkmcnt(7)
	v_mfma_f32_32x32x16_bf16 v[16:31], v[214:217], v[206:209], v[16:31]
	v_mfma_f32_32x32x16_bf16 v[0:15], v[214:217], v[210:213], v[0:15]
	s_waitcnt vmcnt(2)
	ds_write_b128 v135, v[100:103] offset:27648
	s_waitcnt lgkmcnt(6)
	v_mfma_f32_32x32x16_bf16 v[48:63], v[222:225], v[226:229], v[48:63]
	s_waitcnt vmcnt(1)
	ds_write_b128 v128, v[104:107]
	s_waitcnt lgkmcnt(6)
	v_mfma_f32_32x32x16_bf16 v[32:47], v[222:225], v[230:233], v[32:47]
	s_waitcnt vmcnt(0)
	ds_write_b128 v128, v[108:111] offset:9216
	s_waitcnt lgkmcnt(6)
	v_mfma_f32_32x32x16_bf16 v[16:31], v[234:237], v[226:229], v[16:31]
	v_mfma_f32_32x32x16_bf16 v[0:15], v[234:237], v[230:233], v[0:15]
	s_waitcnt lgkmcnt(0)
	s_barrier
; DEVI int crow(int r, int hi) { return (r & 3) + 8 * (r >> 2) + 4 * hi; }
;   DEVI void operator()(const f32x16 (&acc)[2][2], int m0, int n0, int wm, int wn, int r32, int hi, char* lds) const {
;     constexpr int RS = 272;
; #pragma unroll
;     for (int i = 0; i < 2; ++i)
; #pragma unroll
;       for (int j = 0; j < 2; ++j)
; #pragma unroll
;         for (int r = 0; r < 16; ++r) {
;           int row = wm * 64 + i * 32 + crow(r, hi), col = wn * 64 + j * 32 + r32;
;           *(h16*)(lds + row * RS + col * 2) = (h16)acc[i][j][r];
;         }
;     __syncthreads();
	ds_read_b128 v[170:173], v132 offset:55296
	ds_read_b128 v[174:177], v133
	ds_read_b128 v[178:181], v133 offset:4608
	ds_read_b128 v[182:185], v132 offset:59904
	ds_read_b128 v[186:189], v132 offset:55328
	ds_read_b128 v[190:193], v133 offset:32
	ds_read_b128 v[194:197], v133 offset:4640
	ds_read_b128 v[198:201], v132 offset:59936
	ds_read_b128 v[202:205], v132 offset:55360
	ds_read_b128 v[206:209], v133 offset:64
	ds_read_b128 v[210:213], v133 offset:4672
	ds_read_b128 v[214:217], v132 offset:59968
	s_waitcnt lgkmcnt(10)
	v_mfma_f32_32x32x16_bf16 v[48:63], v[170:173], v[174:177], v[48:63]
	s_waitcnt lgkmcnt(9)
	v_mfma_f32_32x32x16_bf16 v[32:47], v[170:173], v[178:181], v[32:47]
	s_waitcnt lgkmcnt(8)
	v_mfma_f32_32x32x16_bf16 v[16:31], v[182:185], v[174:177], v[16:31]
	v_mfma_f32_32x32x16_bf16 v[0:15], v[182:185], v[178:181], v[0:15]
	ds_read_b128 v[222:225], v132 offset:55392
	ds_read_b128 v[226:229], v133 offset:96
	ds_read_b128 v[230:233], v133 offset:4704
	ds_read_b128 v[234:237], v132 offset:60000
	s_waitcnt lgkmcnt(10)
	v_mfma_f32_32x32x16_bf16 v[48:63], v[186:189], v[190:193], v[48:63]
	s_waitcnt lgkmcnt(9)
	v_mfma_f32_32x32x16_bf16 v[32:47], v[186:189], v[194:197], v[32:47]
	s_waitcnt lgkmcnt(8)
	v_mfma_f32_32x32x16_bf16 v[16:31], v[198:201], v[190:193], v[16:31]
	v_mfma_f32_32x32x16_bf16 v[0:15], v[198:201], v[194:197], v[0:15]
	s_waitcnt lgkmcnt(6)
	v_mfma_f32_32x32x16_bf16 v[48:63], v[202:205], v[206:209], v[48:63]
	s_waitcnt lgkmcnt(5)
	v_mfma_f32_32x32x16_bf16 v[32:47], v[202:205], v[210:213], v[32:47]
	s_waitcnt lgkmcnt(4)
	v_mfma_f32_32x32x16_bf16 v[16:31], v[214:217], v[206:209], v[16:31]
	v_mfma_f32_32x32x16_bf16 v[0:15], v[214:217], v[210:213], v[0:15]
	s_waitcnt lgkmcnt(2)
	v_mfma_f32_32x32x16_bf16 v[48:63], v[222:225], v[226:229], v[48:63]
	s_waitcnt lgkmcnt(1)
	v_mfma_f32_32x32x16_bf16 v[32:47], v[222:225], v[230:233], v[32:47]
	s_waitcnt lgkmcnt(0)
	v_mfma_f32_32x32x16_bf16 v[16:31], v[234:237], v[226:229], v[16:31]
	v_mfma_f32_32x32x16_bf16 v[0:15], v[234:237], v[230:233], v[0:15]
	s_nop 9
	v_cvt_f16_f32_e32 v48, v48
	v_lshl_or_b32 v64, v124, 2, v127
	v_cvt_f16_f32_e32 v49, v49
	v_lshlrev_b32_e32 v65, 1, v125
	v_lshl_add_u32 v66, v126, 7, 16
	v_mul_lo_u32 v64, v64, s27
	v_cvt_f16_f32_e32 v50, v50
	v_add3_u32 v64, v66, v65, v64
	v_cvt_f16_f32_e32 v51, v51
	s_barrier
	ds_write_b16 v64, v48
	ds_write_b16 v64, v49 offset:272
	ds_write_b16 v64, v50 offset:544
	ds_write_b16 v64, v51 offset:816
	v_cvt_f16_f32_e32 v48, v52
	v_cvt_f16_f32_e32 v49, v53
	v_cvt_f16_f32_e32 v50, v54
	v_cvt_f16_f32_e32 v51, v55
	ds_write_b16 v64, v48 offset:2176
	ds_write_b16 v64, v49 offset:2448
	ds_write_b16 v64, v50 offset:2720
	ds_write_b16 v64, v51 offset:2992
	v_cvt_f16_f32_e32 v48, v56
	v_cvt_f16_f32_e32 v49, v57
	v_cvt_f16_f32_e32 v50, v58
	v_cvt_f16_f32_e32 v51, v59
	ds_write_b16 v64, v48 offset:4352
	ds_write_b16 v64, v49 offset:4624
	ds_write_b16 v64, v50 offset:4896
	ds_write_b16 v64, v51 offset:5168
	v_cvt_f16_f32_e32 v48, v60
	v_cvt_f16_f32_e32 v32, v32
	v_cvt_f16_f32_e32 v49, v61
	v_cvt_f16_f32_e32 v33, v33
	v_cvt_f16_f32_e32 v50, v62
	v_cvt_f16_f32_e32 v34, v34
	v_cvt_f16_f32_e32 v51, v63
	v_cvt_f16_f32_e32 v35, v35
	ds_write_b16 v64, v48 offset:6528
	ds_write_b16 v64, v49 offset:6800
	ds_write_b16 v64, v50 offset:7072
	ds_write_b16 v64, v51 offset:7344
	ds_write_b16 v64, v32 offset:64
	ds_write_b16 v64, v33 offset:336
	ds_write_b16 v64, v34 offset:608
	ds_write_b16 v64, v35 offset:880
	v_cvt_f16_f32_e32 v32, v36
	v_cvt_f16_f32_e32 v33, v37
	v_cvt_f16_f32_e32 v34, v38
	v_cvt_f16_f32_e32 v35, v39
	ds_write_b16 v64, v32 offset:2240
	ds_write_b16 v64, v33 offset:2512
	ds_write_b16 v64, v34 offset:2784
	ds_write_b16 v64, v35 offset:3056
	v_cvt_f16_f32_e32 v32, v40
	v_cvt_f16_f32_e32 v33, v41
	v_cvt_f16_f32_e32 v34, v42
	v_cvt_f16_f32_e32 v35, v43
	ds_write_b16 v64, v32 offset:4416
	ds_write_b16 v64, v33 offset:4688
	ds_write_b16 v64, v34 offset:4960
	ds_write_b16 v64, v35 offset:5232
	v_cvt_f16_f32_e32 v32, v44
	v_cvt_f16_f32_e32 v16, v16
	v_cvt_f16_f32_e32 v33, v45
	v_cvt_f16_f32_e32 v17, v17
	v_cvt_f16_f32_e32 v34, v46
	v_cvt_f16_f32_e32 v18, v18
	v_cvt_f16_f32_e32 v35, v47
	v_cvt_f16_f32_e32 v19, v19
	ds_write_b16 v64, v32 offset:6592
	ds_write_b16 v64, v33 offset:6864
	ds_write_b16 v64, v34 offset:7136
	ds_write_b16 v64, v35 offset:7408
	ds_write_b16 v64, v16 offset:8704
	ds_write_b16 v64, v17 offset:8976
	ds_write_b16 v64, v18 offset:9248
	ds_write_b16 v64, v19 offset:9520
	v_cvt_f16_f32_e32 v16, v20
	v_cvt_f16_f32_e32 v17, v21
	v_cvt_f16_f32_e32 v18, v22
	v_cvt_f16_f32_e32 v19, v23
	ds_write_b16 v64, v16 offset:10880
	ds_write_b16 v64, v17 offset:11152
	ds_write_b16 v64, v18 offset:11424
	ds_write_b16 v64, v19 offset:11696
	v_cvt_f16_f32_e32 v16, v24
	v_cvt_f16_f32_e32 v17, v25
	v_cvt_f16_f32_e32 v18, v26
	v_cvt_f16_f32_e32 v19, v27
	ds_write_b16 v64, v16 offset:13056
	ds_write_b16 v64, v17 offset:13328
	ds_write_b16 v64, v18 offset:13600
	ds_write_b16 v64, v19 offset:13872
	v_cvt_f16_f32_e32 v16, v28
	v_cvt_f16_f32_e32 v0, v0
	v_cvt_f16_f32_e32 v17, v29
	v_cvt_f16_f32_e32 v1, v1
	v_cvt_f16_f32_e32 v18, v30
	v_cvt_f16_f32_e32 v2, v2
	v_cvt_f16_f32_e32 v19, v31
	v_cvt_f16_f32_e32 v3, v3
	ds_write_b16 v64, v16 offset:15232
	ds_write_b16 v64, v17 offset:15504
	ds_write_b16 v64, v18 offset:15776
	ds_write_b16 v64, v19 offset:16048
	ds_write_b16 v64, v0 offset:8768
	ds_write_b16 v64, v1 offset:9040
	ds_write_b16 v64, v2 offset:9312
	ds_write_b16 v64, v3 offset:9584
	v_cvt_f16_f32_e32 v0, v4
	v_cvt_f16_f32_e32 v1, v5
	v_cvt_f16_f32_e32 v2, v6
	v_cvt_f16_f32_e32 v3, v7
	ds_write_b16 v64, v0 offset:10944
	ds_write_b16 v64, v1 offset:11216
	ds_write_b16 v64, v2 offset:11488
	ds_write_b16 v64, v3 offset:11760
	v_cvt_f16_f32_e32 v0, v8
	v_cvt_f16_f32_e32 v1, v9
	v_cvt_f16_f32_e32 v2, v10
	v_cvt_f16_f32_e32 v3, v11
	ds_write_b16 v64, v0 offset:13120
	ds_write_b16 v64, v1 offset:13392
	ds_write_b16 v64, v2 offset:13664
	ds_write_b16 v64, v3 offset:13936
	v_cvt_f16_f32_e32 v0, v12
	v_cvt_f16_f32_e32 v1, v13
	v_cvt_f16_f32_e32 v2, v14
	v_cvt_f16_f32_e32 v3, v15
	ds_write_b16 v64, v0 offset:15296
	ds_write_b16 v64, v1 offset:15568
	ds_write_b16 v64, v2 offset:15840
	ds_write_b16 v64, v3 offset:16112
	v_mov_b32_e32 v2, v131
	s_waitcnt lgkmcnt(0)
	s_barrier
; DEVI int ltid() { int t = __builtin_amdgcn_workitem_id_x(); asm volatile("" : "+v"(t)); return t; }
;   DEVI void operator()(const f32x16 (&acc)[2][2], int m0, int n0, int wm, int wn, int r32, int hi, char* lds) const {
;     ...
;     const int tid = ltid();
; #pragma unroll
;     for (int i = 0; i < 8; ++i) {
;       int c = tid + i * 512; int row = c >> 4, ch = c & 15;
;       int col = n0 + ch * 8;
;       if (col < nvalid) *(u32x4*)(Z + (size_t)(m0 + row) * ldz + col) = *(const u32x4*)(lds + row * RS + ch * 16);
;     }
;     __syncthreads();
	s_movk_i32 s6, 0x700
	v_and_b32_e32 v3, 15, v2
	v_lshlrev_b32_e32 v0, 3, v3
	v_subrev_u32_e32 v0, s12, v0
	v_add_u32_e32 v0, s15, v0
	v_cmp_gt_i32_e32 vcc, s6, v0
	s_and_saveexec_b64 s[12:13], vcc
	s_cbranch_execz .LBB0_952
	v_lshl_add_u32 v12, v3, 4, 16
	v_ashrrev_i32_e32 v3, 4, v2
	v_mad_u64_u32 v[4:5], s[6:7], v3, s27, v[12:13]
	v_add_u32_e32 v3, s16, v3
	v_mov_b64_e32 v[14:15], s[8:9]
	v_ashrrev_i32_e32 v1, 31, v0
	ds_read_b128 v[4:7], v4
	v_mad_i64_i32 v[8:9], s[6:7], v3, s25, v[14:15]
	v_add_u32_e32 v3, 0x200, v2
	v_lshlrev_b64 v[16:17], 1, v[0:1]
	v_ashrrev_i32_e32 v3, 4, v3
	v_lshl_add_u64 v[0:1], v[8:9], 0, v[16:17]
	v_mad_u64_u32 v[8:9], s[6:7], v3, s27, v[12:13]
	ds_read_b128 v[8:11], v8
	s_waitcnt lgkmcnt(1)
	global_store_dwordx4 v[0:1], v[4:7], off
	v_add_u32_e32 v0, s16, v3
	v_mad_i64_i32 v[0:1], s[6:7], v0, s25, v[14:15]
	v_lshl_add_u64 v[0:1], v[0:1], 0, v[16:17]
	s_waitcnt lgkmcnt(0)
	global_store_dwordx4 v[0:1], v[8:11], off
	v_add_u32_e32 v0, 0x400, v2
	v_ashrrev_i32_e32 v3, 4, v0
	v_mad_u64_u32 v[0:1], s[6:7], v3, s27, v[12:13]
	ds_read_b128 v[4:7], v0
	v_add_u32_e32 v0, s16, v3
	v_add_u32_e32 v3, 0x600, v2
	v_ashrrev_i32_e32 v3, 4, v3
	v_mad_u64_u32 v[8:9], s[6:7], v3, s27, v[12:13]
	v_mad_i64_i32 v[0:1], s[6:7], v0, s25, v[14:15]
	ds_read_b128 v[8:11], v8
	v_lshl_add_u64 v[0:1], v[0:1], 0, v[16:17]
	s_waitcnt lgkmcnt(1)
	global_store_dwordx4 v[0:1], v[4:7], off
	v_add_u32_e32 v0, s16, v3
	v_mad_i64_i32 v[0:1], s[6:7], v0, s25, v[14:15]
	v_lshl_add_u64 v[0:1], v[0:1], 0, v[16:17]
	s_waitcnt lgkmcnt(0)
	global_store_dwordx4 v[0:1], v[8:11], off
	v_add_u32_e32 v0, 0x800, v2
	v_ashrrev_i32_e32 v3, 4, v0
	v_mad_u64_u32 v[0:1], s[6:7], v3, s27, v[12:13]
	ds_read_b128 v[4:7], v0
	v_add_u32_e32 v0, s16, v3
	v_add_u32_e32 v3, 0xa00, v2
	v_ashrrev_i32_e32 v3, 4, v3
	v_mad_u64_u32 v[8:9], s[6:7], v3, s27, v[12:13]
	v_mad_i64_i32 v[0:1], s[6:7], v0, s25, v[14:15]
	ds_read_b128 v[8:11], v8
	v_lshl_add_u64 v[0:1], v[0:1], 0, v[16:17]
	s_waitcnt lgkmcnt(1)
	global_store_dwordx4 v[0:1], v[4:7], off
	v_add_u32_e32 v0, s16, v3
	v_mad_i64_i32 v[0:1], s[6:7], v0, s25, v[14:15]
	v_lshl_add_u64 v[0:1], v[0:1], 0, v[16:17]
	s_waitcnt lgkmcnt(0)
	global_store_dwordx4 v[0:1], v[8:11], off
	v_add_u32_e32 v0, 0xc00, v2
	v_ashrrev_i32_e32 v3, 4, v0
	v_mad_u64_u32 v[0:1], s[6:7], v3, s27, v[12:13]
	ds_read_b128 v[4:7], v0
	v_add_u32_e32 v0, s16, v3
	v_mad_i64_i32 v[0:1], s[6:7], v0, s25, v[14:15]
	v_lshl_add_u64 v[8:9], v[0:1], 0, v[16:17]
	v_add_u32_e32 v0, 0xe00, v2
	v_ashrrev_i32_e32 v10, 4, v0
	v_mad_u64_u32 v[0:1], s[6:7], v10, s27, v[12:13]
	ds_read_b128 v[0:3], v0
	s_waitcnt lgkmcnt(1)
	global_store_dwordx4 v[8:9], v[4:7], off
	s_nop 1
	v_add_u32_e32 v4, s16, v10
	v_mad_i64_i32 v[4:5], s[6:7], v4, s25, v[14:15]
	v_lshl_add_u64 v[4:5], v[4:5], 0, v[16:17]
	s_waitcnt lgkmcnt(0)
	global_store_dwordx4 v[4:5], v[0:3], off
	s_branch .LBB0_952

; DEVI int ltid() { int t = __builtin_amdgcn_workitem_id_x(); asm volatile("" : "+v"(t)); return t; }
; DEVI int lbid() { int t = __builtin_amdgcn_workgroup_id_x(); asm volatile("" : "+s"(t)); return t; }
; template <class AS, class EP>
; DEVI void gemm_tile(const AS& as, const u16* __restrict__ Bt, int K, int m0, int n0, const EP& ep, char* lds) {
;   const int tid = ltid(), wid = tid >> 6, lane = tid & 63, r32 = lane & 31, hi = lane >> 5;
;   const int wm = wid >> 1, wn = wid & 1;
;   constexpr int RS = 144, ABYTES = 256 * RS, STAGE = ABYTES + 128 * RS;
;   f32x16 acc[2][2];
; #pragma unroll
;   for (int i = 0; i < 2; ++i)
; #pragma unroll
;     for (int j = 0; j < 2; ++j)
; #pragma unroll
;       for (int r = 0; r < 16; ++r) acc[i][j][r] = 0.f;
;   const int KT = K >> 6;
;   u32x4 ra0[4], rb0[2], ra1[4], rb1[2];
;   const int srow = tid >> 3, sch = tid & 7;
;     ...
;   GLOAD(ra0, rb0, 0); GLOAD(ra1, rb1, 1); LWRITE(0, ra0, rb0); __syncthreads();
;   for (int kt = 0; kt < KT; kt += 2) {
;     if (kt + 2 < KT) GLOAD(ra0, rb0, kt + 2);
;     __builtin_amdgcn_sched_barrier(0);
;     COMPUTE(0);
; template <class AS, class EP>
; DEVI void gemm_phase(const AS& as, const u16* Bt, int K, int mtiles, int ntiles, const EP& ep, char* lds) {
;     ...
;     const int x = lbid() & 7, j = lbid() >> 3, nb = gridDim.x >> 3, ltot = (mtiles >> 3) * ntiles;
;     for (int lt = j; lt < ltot; lt += nb) {
;       int mt = (lt / ntiles) * 8 + x, nt = lt % ntiles;
;       gemm_tile(as, Bt, K, mt * 256, nt * 128, ep, lds);
.LBB0_960:
	s_mul_hi_i32 s6, s14, 0x92492493
	s_add_i32 s6, s6, s14
	s_lshr_b32 s7, s6, 31
	s_ashr_i32 s6, s6, 3
	s_add_i32 s12, s6, s7
	s_lshl_b32 s6, s12, 11
	v_mov_b32_e32 v36, v131
	s_or_b32 s18, s6, s15
	s_mulk_i32 s12, 0x700
	v_ashrrev_i32_e32 v37, 3, v36
	v_add_u32_e32 v0, s18, v37
	v_lshlrev_b32_e32 v1, 4, v36
	v_and_b32_e32 v128, 0x70, v1
	v_ashrrev_i32_e32 v1, 31, v0
	v_lshlrev_b64 v[24:25], 11, v[0:1]
	s_mov_b64 s[6:7], 0x20000
	v_subrev_u32_e32 v16, s12, v37
	v_lshl_add_u64 v[26:27], v[24:25], 0, s[6:7]
	s_mov_b64 s[6:7], 0x40000
	v_add_u32_e32 v20, s16, v16
	v_lshl_add_u64 v[8:9], s[0:1], 0, v[128:129]
	v_lshl_add_u64 v[28:29], v[24:25], 0, s[6:7]
	s_mov_b64 s[6:7], 0x60000
	v_ashrrev_i32_e32 v21, 31, v20
	v_lshl_add_u64 v[112:113], v[8:9], 0, v[24:25]
	v_lshl_add_u64 v[116:117], v[8:9], 0, v[28:29]
	v_lshl_add_u64 v[30:31], v[24:25], 0, s[6:7]
	v_lshl_add_u64 v[22:23], s[10:11], 0, v[128:129]
	v_lshlrev_b64 v[32:33], 11, v[20:21]
	v_lshl_add_u64 v[114:115], v[8:9], 0, v[26:27]
	global_load_dwordx4 v[0:3], v[112:113], off
	global_load_dwordx4 v[4:7], v[114:115], off
	v_lshl_add_u64 v[118:119], v[8:9], 0, v[30:31]
	global_load_dwordx4 v[8:11], v[116:117], off
	global_load_dwordx4 v[12:15], v[118:119], off
	v_lshl_add_u64 v[120:121], v[22:23], 0, v[32:33]
	global_load_dwordx4 v[16:19], v[120:121], off
	v_add_u32_e32 v20, 64, v20
	v_ashrrev_i32_e32 v21, 31, v20
	v_lshlrev_b64 v[34:35], 11, v[20:21]
	v_lshl_add_u64 v[122:123], v[22:23], 0, v[34:35]
	global_load_dwordx4 v[20:23], v[122:123], off
	v_mul_lo_u32 v37, v37, s96
	v_lshl_add_u64 v[24:25], s[0:1], 0, v[24:25]
	v_add3_u32 v134, 16, v128, v37
	v_lshl_add_u64 v[32:33], s[10:11], 0, v[32:33]
	v_lshl_add_u64 v[24:25], v[24:25], 0, v[128:129]
	v_lshl_add_u64 v[26:27], s[0:1], 0, v[26:27]
	v_lshl_add_u64 v[28:29], s[0:1], 0, v[28:29]
	v_lshl_add_u64 v[30:31], s[0:1], 0, v[30:31]
	v_lshl_add_u64 v[34:35], s[10:11], 0, v[34:35]
	v_lshl_add_u64 v[32:33], v[32:33], 0, v[128:129]
	v_lshl_add_u64 v[26:27], v[26:27], 0, v[128:129]
	v_lshl_add_u64 v[28:29], v[28:29], 0, v[128:129]
	v_lshl_add_u64 v[30:31], v[30:31], 0, v[128:129]
	v_lshl_add_u64 v[34:35], v[34:35], 0, v[128:129]
	global_load_dwordx4 v[88:91], v[24:25], off offset:128
	global_load_dwordx4 v[92:95], v[26:27], off offset:128
	global_load_dwordx4 v[96:99], v[28:29], off offset:128
	global_load_dwordx4 v[100:103], v[30:31], off offset:128
	global_load_dwordx4 v[104:107], v[32:33], off offset:128
	global_load_dwordx4 v[108:111], v[34:35], off offset:128
	v_and_b32_e32 v125, 31, v36
	v_bfe_u32 v124, v36, 5, 1
	v_bfe_u32 v126, v36, 6, 1
	v_add_u32_e32 v135, 0xd800, v134
	v_add3_u32 v128, s85, v128, v37
	s_waitcnt vmcnt(11)
	ds_write_b128 v134, v[0:3]
	s_waitcnt vmcnt(7)
	ds_write_b128 v134, v[16:19] offset:36864
	ds_write_b128 v134, v[4:7] offset:9216
	ds_write_b128 v134, v[8:11] offset:18432
	ds_write_b128 v134, v[12:15] offset:27648
	s_waitcnt vmcnt(6)
	ds_write_b128 v134, v[20:23] offset:46080
	s_waitcnt lgkmcnt(0)
	s_barrier
	global_load_dwordx4 v[64:67], v[112:113], off offset:256
	global_load_dwordx4 v[68:71], v[114:115], off offset:256
	global_load_dwordx4 v[72:75], v[116:117], off offset:256
	global_load_dwordx4 v[76:79], v[118:119], off offset:256
	global_load_dwordx4 v[80:83], v[120:121], off offset:256
	global_load_dwordx4 v[84:87], v[122:123], off offset:256
	v_ashrrev_i32_e32 v0, 1, v36
	v_and_b32_e32 v127, 0xffffffc0, v0
	v_or_b32_e32 v0, v127, v125
	v_mul_lo_u32 v0, v0, s96
	v_lshlrev_b32_e32 v1, 4, v124
	v_add3_u32 v132, 16, v0, v1
	v_lshl_or_b32 v0, v126, 6, v125
	v_mul_u32_u24_e32 v0, 0x90, v0
	v_add3_u32 v136, 16, v0, v1
	v_add3_u32 v133, s85, v0, v1
	ds_read_b128 v[170:173], v132
	ds_read_b128 v[174:177], v136 offset:36864
	ds_read_b128 v[178:181], v136 offset:41472
	ds_read_b128 v[182:185], v132 offset:4608
	ds_read_b128 v[186:189], v132 offset:32
	ds_read_b128 v[190:193], v136 offset:36896
	ds_read_b128 v[194:197], v136 offset:41504
	ds_read_b128 v[198:201], v132 offset:4640
	ds_read_b128 v[202:205], v132 offset:64
	ds_read_b128 v[206:209], v136 offset:36928
	ds_read_b128 v[210:213], v136 offset:41536
	ds_read_b128 v[214:217], v132 offset:4672
	s_waitcnt lgkmcnt(10)
	v_mfma_f32_32x32x16_bf16 v[48:63], v[170:173], v[174:177], 0
	s_waitcnt lgkmcnt(9)
	v_mfma_f32_32x32x16_bf16 v[32:47], v[170:173], v[178:181], 0
	s_waitcnt lgkmcnt(8)
	v_mfma_f32_32x32x16_bf16 v[16:31], v[182:185], v[174:177], 0
	v_mfma_f32_32x32x16_bf16 v[0:15], v[182:185], v[178:181], 0
	ds_read_b128 v[222:225], v132 offset:96
	ds_read_b128 v[226:229], v136 offset:36960
	ds_read_b128 v[230:233], v136 offset:41568
	ds_read_b128 v[234:237], v132 offset:4704
	s_waitcnt lgkmcnt(10)
	v_mfma_f32_32x32x16_bf16 v[48:63], v[186:189], v[190:193], v[48:63]
	s_waitcnt lgkmcnt(9)
	v_mfma_f32_32x32x16_bf16 v[32:47], v[186:189], v[194:197], v[32:47]
	s_waitcnt lgkmcnt(8)
	v_mfma_f32_32x32x16_bf16 v[16:31], v[198:201], v[190:193], v[16:31]
	v_mfma_f32_32x32x16_bf16 v[0:15], v[198:201], v[194:197], v[0:15]
	s_waitcnt vmcnt(11)
	ds_write_b128 v134, v[88:91] offset:55296
	s_waitcnt lgkmcnt(7)
	v_mfma_f32_32x32x16_bf16 v[48:63], v[202:205], v[206:209], v[48:63]
	s_waitcnt vmcnt(10)
	ds_write_b128 v134, v[92:95] offset:64512
	s_waitcnt lgkmcnt(7)
	v_mfma_f32_32x32x16_bf16 v[32:47], v[202:205], v[210:213], v[32:47]
	s_waitcnt vmcnt(9)
	ds_write_b128 v135, v[96:99] offset:18432
	s_waitcnt lgkmcnt(7)
	v_mfma_f32_32x32x16_bf16 v[16:31], v[214:217], v[206:209], v[16:31]
	v_mfma_f32_32x32x16_bf16 v[0:15], v[214:217], v[210:213], v[0:15]
	s_waitcnt vmcnt(8)
	ds_write_b128 v135, v[100:103] offset:27648
	s_waitcnt lgkmcnt(6)
	v_mfma_f32_32x32x16_bf16 v[48:63], v[222:225], v[226:229], v[48:63]
	s_waitcnt vmcnt(7)
	ds_write_b128 v128, v[104:107]
	s_waitcnt lgkmcnt(6)
	v_mfma_f32_32x32x16_bf16 v[32:47], v[222:225], v[230:233], v[32:47]
	s_waitcnt vmcnt(6)
	ds_write_b128 v128, v[108:111] offset:9216
	s_waitcnt lgkmcnt(6)
	v_mfma_f32_32x32x16_bf16 v[16:31], v[234:237], v[226:229], v[16:31]
	v_mfma_f32_32x32x16_bf16 v[0:15], v[234:237], v[230:233], v[0:15]
	s_waitcnt lgkmcnt(0)
	s_barrier
; template <class AS, class EP>
; DEVI void gemm_tile(const AS& as, const u16* __restrict__ Bt, int K, int m0, int n0, const EP& ep, char* lds) {
;     ...
;   GLOAD(ra0, rb0, 0); GLOAD(ra1, rb1, 1); LWRITE(0, ra0, rb0); __syncthreads();
;   for (int kt = 0; kt < KT; kt += 2) {
;     if (kt + 2 < KT) GLOAD(ra0, rb0, kt + 2);
;     __builtin_amdgcn_sched_barrier(0);
;     COMPUTE(0);
;     __builtin_amdgcn_sched_barrier(0);
;     LWRITE(1, ra1, rb1);
;     __syncthreads();
;     if (kt + 3 < KT) GLOAD(ra1, rb1, kt + 3);
;     __builtin_amdgcn_sched_barrier(0);
;     COMPUTE(1);
;     __builtin_amdgcn_sched_barrier(0);
;     if (kt + 2 < KT) LWRITE(0, ra0, rb0);
;     __syncthreads();
	global_load_dwordx4 v[88:91], v[112:113], off offset:384
	global_load_dwordx4 v[92:95], v[114:115], off offset:384
	global_load_dwordx4 v[96:99], v[116:117], off offset:384
	global_load_dwordx4 v[100:103], v[118:119], off offset:384
	global_load_dwordx4 v[104:107], v[120:121], off offset:384
	global_load_dwordx4 v[108:111], v[122:123], off offset:384
	ds_read_b128 v[170:173], v132 offset:55296
	ds_read_b128 v[174:177], v133
	ds_read_b128 v[178:181], v133 offset:4608
	ds_read_b128 v[182:185], v132 offset:59904
	ds_read_b128 v[186:189], v132 offset:55328
	ds_read_b128 v[190:193], v133 offset:32
	ds_read_b128 v[194:197], v133 offset:4640
	ds_read_b128 v[198:201], v132 offset:59936
	ds_read_b128 v[202:205], v132 offset:55360
	ds_read_b128 v[206:209], v133 offset:64
	ds_read_b128 v[210:213], v133 offset:4672
	ds_read_b128 v[214:217], v132 offset:59968
	s_waitcnt lgkmcnt(10)
	v_mfma_f32_32x32x16_bf16 v[48:63], v[170:173], v[174:177], v[48:63]
	s_waitcnt lgkmcnt(9)
	v_mfma_f32_32x32x16_bf16 v[32:47], v[170:173], v[178:181], v[32:47]
	s_waitcnt lgkmcnt(8)
	v_mfma_f32_32x32x16_bf16 v[16:31], v[182:185], v[174:177], v[16:31]
	v_mfma_f32_32x32x16_bf16 v[0:15], v[182:185], v[178:181], v[0:15]
	ds_read_b128 v[222:225], v132 offset:55392
	ds_read_b128 v[226:229], v133 offset:96
	ds_read_b128 v[230:233], v133 offset:4704
	ds_read_b128 v[234:237], v132 offset:60000
	s_waitcnt lgkmcnt(10)
	v_mfma_f32_32x32x16_bf16 v[48:63], v[186:189], v[190:193], v[48:63]
	s_waitcnt lgkmcnt(9)
	v_mfma_f32_32x32x16_bf16 v[32:47], v[186:189], v[194:197], v[32:47]
	s_waitcnt lgkmcnt(8)
	v_mfma_f32_32x32x16_bf16 v[16:31], v[198:201], v[190:193], v[16:31]
	v_mfma_f32_32x32x16_bf16 v[0:15], v[198:201], v[194:197], v[0:15]
	s_waitcnt vmcnt(11)
	ds_write_b128 v134, v[64:67]
	s_waitcnt lgkmcnt(7)
	v_mfma_f32_32x32x16_bf16 v[48:63], v[202:205], v[206:209], v[48:63]
	s_waitcnt vmcnt(10)
	ds_write_b128 v134, v[68:71] offset:9216
	s_waitcnt lgkmcnt(7)
	v_mfma_f32_32x32x16_bf16 v[32:47], v[202:205], v[210:213], v[32:47]
	s_waitcnt vmcnt(9)
	ds_write_b128 v134, v[72:75] offset:18432
	s_waitcnt lgkmcnt(7)
	v_mfma_f32_32x32x16_bf16 v[16:31], v[214:217], v[206:209], v[16:31]
	v_mfma_f32_32x32x16_bf16 v[0:15], v[214:217], v[210:213], v[0:15]
	s_waitcnt vmcnt(8)
	ds_write_b128 v134, v[76:79] offset:27648
	s_waitcnt lgkmcnt(6)
	v_mfma_f32_32x32x16_bf16 v[48:63], v[222:225], v[226:229], v[48:63]
	s_waitcnt vmcnt(7)
	ds_write_b128 v134, v[80:83] offset:36864
	s_waitcnt lgkmcnt(6)
	v_mfma_f32_32x32x16_bf16 v[32:47], v[222:225], v[230:233], v[32:47]
	s_waitcnt vmcnt(6)
	ds_write_b128 v134, v[84:87] offset:46080
	s_waitcnt lgkmcnt(6)
	v_mfma_f32_32x32x16_bf16 v[16:31], v[234:237], v[226:229], v[16:31]
	v_mfma_f32_32x32x16_bf16 v[0:15], v[234:237], v[230:233], v[0:15]
	s_waitcnt lgkmcnt(0)
	s_barrier
	global_load_dwordx4 v[64:67], v[112:113], off offset:512
	global_load_dwordx4 v[68:71], v[114:115], off offset:512
	global_load_dwordx4 v[72:75], v[116:117], off offset:512
	global_load_dwordx4 v[76:79], v[118:119], off offset:512
	global_load_dwordx4 v[80:83], v[120:121], off offset:512
	global_load_dwordx4 v[84:87], v[122:123], off offset:512
	ds_read_b128 v[170:173], v132
	ds_read_b128 v[174:177], v136 offset:36864
	ds_read_b128 v[178:181], v136 offset:41472
	ds_read_b128 v[182:185], v132 offset:4608
	ds_read_b128 v[186:189], v132 offset:32
	ds_read_b128 v[190:193], v136 offset:36896
	ds_read_b128 v[194:197], v136 offset:41504
	ds_read_b128 v[198:201], v132 offset:4640
	ds_read_b128 v[202:205], v132 offset:64
	ds_read_b128 v[206:209], v136 offset:36928
	ds_read_b128 v[210:213], v136 offset:41536
	ds_read_b128 v[214:217], v132 offset:4672
	s_waitcnt lgkmcnt(10)
	v_mfma_f32_32x32x16_bf16 v[48:63], v[170:173], v[174:177], v[48:63]
	s_waitcnt lgkmcnt(9)
	v_mfma_f32_32x32x16_bf16 v[32:47], v[170:173], v[178:181], v[32:47]
	s_waitcnt lgkmcnt(8)
	v_mfma_f32_32x32x16_bf16 v[16:31], v[182:185], v[174:177], v[16:31]
	v_mfma_f32_32x32x16_bf16 v[0:15], v[182:185], v[178:181], v[0:15]
	ds_read_b128 v[222:225], v132 offset:96
	ds_read_b128 v[226:229], v136 offset:36960
	ds_read_b128 v[230:233], v136 offset:41568
	ds_read_b128 v[234:237], v132 offset:4704
	s_waitcnt lgkmcnt(10)
	v_mfma_f32_32x32x16_bf16 v[48:63], v[186:189], v[190:193], v[48:63]
	s_waitcnt lgkmcnt(9)
	v_mfma_f32_32x32x16_bf16 v[32:47], v[186:189], v[194:197], v[32:47]
	s_waitcnt lgkmcnt(8)
	v_mfma_f32_32x32x16_bf16 v[16:31], v[198:201], v[190:193], v[16:31]
	v_mfma_f32_32x32x16_bf16 v[0:15], v[198:201], v[194:197], v[0:15]
	s_waitcnt vmcnt(11)
	ds_write_b128 v134, v[88:91] offset:55296
	s_waitcnt lgkmcnt(7)
	v_mfma_f32_32x32x16_bf16 v[48:63], v[202:205], v[206:209], v[48:63]
	s_waitcnt vmcnt(10)
	ds_write_b128 v134, v[92:95] offset:64512
	s_waitcnt lgkmcnt(7)
	v_mfma_f32_32x32x16_bf16 v[32:47], v[202:205], v[210:213], v[32:47]
	s_waitcnt vmcnt(9)
	ds_write_b128 v135, v[96:99] offset:18432
	s_waitcnt lgkmcnt(7)
	v_mfma_f32_32x32x16_bf16 v[16:31], v[214:217], v[206:209], v[16:31]
	v_mfma_f32_32x32x16_bf16 v[0:15], v[214:217], v[210:213], v[0:15]
	s_waitcnt vmcnt(8)
	ds_write_b128 v135, v[100:103] offset:27648
	s_waitcnt lgkmcnt(6)
	v_mfma_f32_32x32x16_bf16 v[48:63], v[222:225], v[226:229], v[48:63]
	s_waitcnt vmcnt(7)
	ds_write_b128 v128, v[104:107]
	s_waitcnt lgkmcnt(6)
	v_mfma_f32_32x32x16_bf16 v[32:47], v[222:225], v[230:233], v[32:47]
	s_waitcnt vmcnt(6)
	ds_write_b128 v128, v[108:111] offset:9216
	s_waitcnt lgkmcnt(6)
	v_mfma_f32_32x32x16_bf16 v[16:31], v[234:237], v[226:229], v[16:31]
	v_mfma_f32_32x32x16_bf16 v[0:15], v[234:237], v[230:233], v[0:15]
	s_waitcnt lgkmcnt(0)
	s_barrier
; template <class AS, class EP>
; DEVI void gemm_tile(const AS& as, const u16* __restrict__ Bt, int K, int m0, int n0, const EP& ep, char* lds) {
;     ...
;   GLOAD(ra0, rb0, 0); GLOAD(ra1, rb1, 1); LWRITE(0, ra0, rb0); __syncthreads();
;   for (int kt = 0; kt < KT; kt += 2) {
;     if (kt + 2 < KT) GLOAD(ra0, rb0, kt + 2);
;     __builtin_amdgcn_sched_barrier(0);
;     COMPUTE(0);
;     __builtin_amdgcn_sched_barrier(0);
;     LWRITE(1, ra1, rb1);
;     __syncthreads();
;     if (kt + 3 < KT) GLOAD(ra1, rb1, kt + 3);
;     __builtin_amdgcn_sched_barrier(0);
;     COMPUTE(1);
;     __builtin_amdgcn_sched_barrier(0);
;     if (kt + 2 < KT) LWRITE(0, ra0, rb0);
;     __syncthreads();
	global_load_dwordx4 v[88:91], v[112:113], off offset:640
	global_load_dwordx4 v[92:95], v[114:115], off offset:640
	global_load_dwordx4 v[96:99], v[116:117], off offset:640
	global_load_dwordx4 v[100:103], v[118:119], off offset:640
	global_load_dwordx4 v[104:107], v[120:121], off offset:640
	global_load_dwordx4 v[108:111], v[122:123], off offset:640
	ds_read_b128 v[170:173], v132 offset:55296
	ds_read_b128 v[174:177], v133
	ds_read_b128 v[178:181], v133 offset:4608
	ds_read_b128 v[182:185], v132 offset:59904
	ds_read_b128 v[186:189], v132 offset:55328
	ds_read_b128 v[190:193], v133 offset:32
	ds_read_b128 v[194:197], v133 offset:4640
	ds_read_b128 v[198:201], v132 offset:59936
	ds_read_b128 v[202:205], v132 offset:55360
	ds_read_b128 v[206:209], v133 offset:64
	ds_read_b128 v[210:213], v133 offset:4672
	ds_read_b128 v[214:217], v132 offset:59968
	s_waitcnt lgkmcnt(10)
	v_mfma_f32_32x32x16_bf16 v[48:63], v[170:173], v[174:177], v[48:63]
	s_waitcnt lgkmcnt(9)
	v_mfma_f32_32x32x16_bf16 v[32:47], v[170:173], v[178:181], v[32:47]
	s_waitcnt lgkmcnt(8)
	v_mfma_f32_32x32x16_bf16 v[16:31], v[182:185], v[174:177], v[16:31]
	v_mfma_f32_32x32x16_bf16 v[0:15], v[182:185], v[178:181], v[0:15]
	ds_read_b128 v[222:225], v132 offset:55392
	ds_read_b128 v[226:229], v133 offset:96
	ds_read_b128 v[230:233], v133 offset:4704
	ds_read_b128 v[234:237], v132 offset:60000
	s_waitcnt lgkmcnt(10)
	v_mfma_f32_32x32x16_bf16 v[48:63], v[186:189], v[190:193], v[48:63]
	s_waitcnt lgkmcnt(9)
	v_mfma_f32_32x32x16_bf16 v[32:47], v[186:189], v[194:197], v[32:47]
	s_waitcnt lgkmcnt(8)
	v_mfma_f32_32x32x16_bf16 v[16:31], v[198:201], v[190:193], v[16:31]
	v_mfma_f32_32x32x16_bf16 v[0:15], v[198:201], v[194:197], v[0:15]
	s_waitcnt vmcnt(11)
	ds_write_b128 v134, v[64:67]
	s_waitcnt lgkmcnt(7)
	v_mfma_f32_32x32x16_bf16 v[48:63], v[202:205], v[206:209], v[48:63]
	s_waitcnt vmcnt(10)
	ds_write_b128 v134, v[68:71] offset:9216
	s_waitcnt lgkmcnt(7)
	v_mfma_f32_32x32x16_bf16 v[32:47], v[202:205], v[210:213], v[32:47]
	s_waitcnt vmcnt(9)
	ds_write_b128 v134, v[72:75] offset:18432
	s_waitcnt lgkmcnt(7)
	v_mfma_f32_32x32x16_bf16 v[16:31], v[214:217], v[206:209], v[16:31]
	v_mfma_f32_32x32x16_bf16 v[0:15], v[214:217], v[210:213], v[0:15]
	s_waitcnt vmcnt(8)
	ds_write_b128 v134, v[76:79] offset:27648
	s_waitcnt lgkmcnt(6)
	v_mfma_f32_32x32x16_bf16 v[48:63], v[222:225], v[226:229], v[48:63]
	s_waitcnt vmcnt(7)
	ds_write_b128 v134, v[80:83] offset:36864
	s_waitcnt lgkmcnt(6)
	v_mfma_f32_32x32x16_bf16 v[32:47], v[222:225], v[230:233], v[32:47]
	s_waitcnt vmcnt(6)
	ds_write_b128 v134, v[84:87] offset:46080
	s_waitcnt lgkmcnt(6)
	v_mfma_f32_32x32x16_bf16 v[16:31], v[234:237], v[226:229], v[16:31]
	v_mfma_f32_32x32x16_bf16 v[0:15], v[234:237], v[230:233], v[0:15]
	s_waitcnt lgkmcnt(0)
	s_barrier
	global_load_dwordx4 v[64:67], v[112:113], off offset:768
	global_load_dwordx4 v[68:71], v[114:115], off offset:768
	global_load_dwordx4 v[72:75], v[116:117], off offset:768
	global_load_dwordx4 v[76:79], v[118:119], off offset:768
	global_load_dwordx4 v[80:83], v[120:121], off offset:768
	global_load_dwordx4 v[84:87], v[122:123], off offset:768
	ds_read_b128 v[170:173], v132
	ds_read_b128 v[174:177], v136 offset:36864
	ds_read_b128 v[178:181], v136 offset:41472
	ds_read_b128 v[182:185], v132 offset:4608
	ds_read_b128 v[186:189], v132 offset:32
	ds_read_b128 v[190:193], v136 offset:36896
	ds_read_b128 v[194:197], v136 offset:41504
	ds_read_b128 v[198:201], v132 offset:4640
	ds_read_b128 v[202:205], v132 offset:64
	ds_read_b128 v[206:209], v136 offset:36928
	ds_read_b128 v[210:213], v136 offset:41536
	ds_read_b128 v[214:217], v132 offset:4672
	s_waitcnt lgkmcnt(10)
	v_mfma_f32_32x32x16_bf16 v[48:63], v[170:173], v[174:177], v[48:63]
	s_waitcnt lgkmcnt(9)
	v_mfma_f32_32x32x16_bf16 v[32:47], v[170:173], v[178:181], v[32:47]
	s_waitcnt lgkmcnt(8)
	v_mfma_f32_32x32x16_bf16 v[16:31], v[182:185], v[174:177], v[16:31]
	v_mfma_f32_32x32x16_bf16 v[0:15], v[182:185], v[178:181], v[0:15]
	ds_read_b128 v[222:225], v132 offset:96
	ds_read_b128 v[226:229], v136 offset:36960
	ds_read_b128 v[230:233], v136 offset:41568
	ds_read_b128 v[234:237], v132 offset:4704
	s_waitcnt lgkmcnt(10)
	v_mfma_f32_32x32x16_bf16 v[48:63], v[186:189], v[190:193], v[48:63]
	s_waitcnt lgkmcnt(9)
	v_mfma_f32_32x32x16_bf16 v[32:47], v[186:189], v[194:197], v[32:47]
	s_waitcnt lgkmcnt(8)
	v_mfma_f32_32x32x16_bf16 v[16:31], v[198:201], v[190:193], v[16:31]
	v_mfma_f32_32x32x16_bf16 v[0:15], v[198:201], v[194:197], v[0:15]
	s_waitcnt vmcnt(11)
	ds_write_b128 v134, v[88:91] offset:55296
	s_waitcnt lgkmcnt(7)
	v_mfma_f32_32x32x16_bf16 v[48:63], v[202:205], v[206:209], v[48:63]
	s_waitcnt vmcnt(10)
	ds_write_b128 v134, v[92:95] offset:64512
	s_waitcnt lgkmcnt(7)
	v_mfma_f32_32x32x16_bf16 v[32:47], v[202:205], v[210:213], v[32:47]
	s_waitcnt vmcnt(9)
	ds_write_b128 v135, v[96:99] offset:18432
	s_waitcnt lgkmcnt(7)
	v_mfma_f32_32x32x16_bf16 v[16:31], v[214:217], v[206:209], v[16:31]
	v_mfma_f32_32x32x16_bf16 v[0:15], v[214:217], v[210:213], v[0:15]
	s_waitcnt vmcnt(8)
	ds_write_b128 v135, v[100:103] offset:27648
	s_waitcnt lgkmcnt(6)
	v_mfma_f32_32x32x16_bf16 v[48:63], v[222:225], v[226:229], v[48:63]
	s_waitcnt vmcnt(7)
	ds_write_b128 v128, v[104:107]
	s_waitcnt lgkmcnt(6)
	v_mfma_f32_32x32x16_bf16 v[32:47], v[222:225], v[230:233], v[32:47]
	s_waitcnt vmcnt(6)
	ds_write_b128 v128, v[108:111] offset:9216
	s_waitcnt lgkmcnt(6)
	v_mfma_f32_32x32x16_bf16 v[16:31], v[234:237], v[226:229], v[16:31]
	v_mfma_f32_32x32x16_bf16 v[0:15], v[234:237], v[230:233], v[0:15]
	s_waitcnt lgkmcnt(0)
	s_barrier
; template <class AS, class EP>
; DEVI void gemm_tile(const AS& as, const u16* __restrict__ Bt, int K, int m0, int n0, const EP& ep, char* lds) {
;     ...
;   GLOAD(ra0, rb0, 0); GLOAD(ra1, rb1, 1); LWRITE(0, ra0, rb0); __syncthreads();
;   for (int kt = 0; kt < KT; kt += 2) {
;     if (kt + 2 < KT) GLOAD(ra0, rb0, kt + 2);
;     __builtin_amdgcn_sched_barrier(0);
;     COMPUTE(0);
;     __builtin_amdgcn_sched_barrier(0);
;     LWRITE(1, ra1, rb1);
;     __syncthreads();
;     if (kt + 3 < KT) GLOAD(ra1, rb1, kt + 3);
;     __builtin_amdgcn_sched_barrier(0);
;     COMPUTE(1);
;     __builtin_amdgcn_sched_barrier(0);
;     if (kt + 2 < KT) LWRITE(0, ra0, rb0);
;     __syncthreads();
	global_load_dwordx4 v[88:91], v[112:113], off offset:896
	global_load_dwordx4 v[92:95], v[114:115], off offset:896
	global_load_dwordx4 v[96:99], v[116:117], off offset:896
	global_load_dwordx4 v[100:103], v[118:119], off offset:896
	global_load_dwordx4 v[104:107], v[120:121], off offset:896
	global_load_dwordx4 v[108:111], v[122:123], off offset:896
	ds_read_b128 v[170:173], v132 offset:55296
	ds_read_b128 v[174:177], v133
	ds_read_b128 v[178:181], v133 offset:4608
	ds_read_b128 v[182:185], v132 offset:59904
	ds_read_b128 v[186:189], v132 offset:55328
	ds_read_b128 v[190:193], v133 offset:32
	ds_read_b128 v[194:197], v133 offset:4640
	ds_read_b128 v[198:201], v132 offset:59936
	ds_read_b128 v[202:205], v132 offset:55360
	ds_read_b128 v[206:209], v133 offset:64
	ds_read_b128 v[210:213], v133 offset:4672
	ds_read_b128 v[214:217], v132 offset:59968
	s_waitcnt lgkmcnt(10)
	v_mfma_f32_32x32x16_bf16 v[48:63], v[170:173], v[174:177], v[48:63]
	s_waitcnt lgkmcnt(9)
	v_mfma_f32_32x32x16_bf16 v[32:47], v[170:173], v[178:181], v[32:47]
	s_waitcnt lgkmcnt(8)
	v_mfma_f32_32x32x16_bf16 v[16:31], v[182:185], v[174:177], v[16:31]
	v_mfma_f32_32x32x16_bf16 v[0:15], v[182:185], v[178:181], v[0:15]
	ds_read_b128 v[222:225], v132 offset:55392
	ds_read_b128 v[226:229], v133 offset:96
	ds_read_b128 v[230:233], v133 offset:4704
	ds_read_b128 v[234:237], v132 offset:60000
	s_waitcnt lgkmcnt(10)
	v_mfma_f32_32x32x16_bf16 v[48:63], v[186:189], v[190:193], v[48:63]
	s_waitcnt lgkmcnt(9)
	v_mfma_f32_32x32x16_bf16 v[32:47], v[186:189], v[194:197], v[32:47]
	s_waitcnt lgkmcnt(8)
	v_mfma_f32_32x32x16_bf16 v[16:31], v[198:201], v[190:193], v[16:31]
	v_mfma_f32_32x32x16_bf16 v[0:15], v[198:201], v[194:197], v[0:15]
	s_waitcnt vmcnt(11)
	ds_write_b128 v134, v[64:67]
	s_waitcnt lgkmcnt(7)
	v_mfma_f32_32x32x16_bf16 v[48:63], v[202:205], v[206:209], v[48:63]
	s_waitcnt vmcnt(10)
	ds_write_b128 v134, v[68:71] offset:9216
	s_waitcnt lgkmcnt(7)
	v_mfma_f32_32x32x16_bf16 v[32:47], v[202:205], v[210:213], v[32:47]
	s_waitcnt vmcnt(9)
	ds_write_b128 v134, v[72:75] offset:18432
	s_waitcnt lgkmcnt(7)
	v_mfma_f32_32x32x16_bf16 v[16:31], v[214:217], v[206:209], v[16:31]
	v_mfma_f32_32x32x16_bf16 v[0:15], v[214:217], v[210:213], v[0:15]
	s_waitcnt vmcnt(8)
	ds_write_b128 v134, v[76:79] offset:27648
	s_waitcnt lgkmcnt(6)
	v_mfma_f32_32x32x16_bf16 v[48:63], v[222:225], v[226:229], v[48:63]
	s_waitcnt vmcnt(7)
	ds_write_b128 v134, v[80:83] offset:36864
	s_waitcnt lgkmcnt(6)
	v_mfma_f32_32x32x16_bf16 v[32:47], v[222:225], v[230:233], v[32:47]
	s_waitcnt vmcnt(6)
	ds_write_b128 v134, v[84:87] offset:46080
	s_waitcnt lgkmcnt(6)
	v_mfma_f32_32x32x16_bf16 v[16:31], v[234:237], v[226:229], v[16:31]
	v_mfma_f32_32x32x16_bf16 v[0:15], v[234:237], v[230:233], v[0:15]
	s_waitcnt lgkmcnt(0)
	s_barrier
	global_load_dwordx4 v[64:67], v[112:113], off offset:1024
	global_load_dwordx4 v[68:71], v[114:115], off offset:1024
	global_load_dwordx4 v[72:75], v[116:117], off offset:1024
	global_load_dwordx4 v[76:79], v[118:119], off offset:1024
	global_load_dwordx4 v[80:83], v[120:121], off offset:1024
	global_load_dwordx4 v[84:87], v[122:123], off offset:1024
	ds_read_b128 v[170:173], v132
	ds_read_b128 v[174:177], v136 offset:36864
	ds_read_b128 v[178:181], v136 offset:41472
	ds_read_b128 v[182:185], v132 offset:4608
	ds_read_b128 v[186:189], v132 offset:32
	ds_read_b128 v[190:193], v136 offset:36896
	ds_read_b128 v[194:197], v136 offset:41504
	ds_read_b128 v[198:201], v132 offset:4640
	ds_read_b128 v[202:205], v132 offset:64
	ds_read_b128 v[206:209], v136 offset:36928
	ds_read_b128 v[210:213], v136 offset:41536
	ds_read_b128 v[214:217], v132 offset:4672
	s_waitcnt lgkmcnt(10)
	v_mfma_f32_32x32x16_bf16 v[48:63], v[170:173], v[174:177], v[48:63]
	s_waitcnt lgkmcnt(9)
	v_mfma_f32_32x32x16_bf16 v[32:47], v[170:173], v[178:181], v[32:47]
	s_waitcnt lgkmcnt(8)
	v_mfma_f32_32x32x16_bf16 v[16:31], v[182:185], v[174:177], v[16:31]
	v_mfma_f32_32x32x16_bf16 v[0:15], v[182:185], v[178:181], v[0:15]
	ds_read_b128 v[222:225], v132 offset:96
	ds_read_b128 v[226:229], v136 offset:36960
	ds_read_b128 v[230:233], v136 offset:41568
	ds_read_b128 v[234:237], v132 offset:4704
	s_waitcnt lgkmcnt(10)
	v_mfma_f32_32x32x16_bf16 v[48:63], v[186:189], v[190:193], v[48:63]
	s_waitcnt lgkmcnt(9)
	v_mfma_f32_32x32x16_bf16 v[32:47], v[186:189], v[194:197], v[32:47]
	s_waitcnt lgkmcnt(8)
	v_mfma_f32_32x32x16_bf16 v[16:31], v[198:201], v[190:193], v[16:31]
	v_mfma_f32_32x32x16_bf16 v[0:15], v[198:201], v[194:197], v[0:15]
	s_waitcnt vmcnt(11)
	ds_write_b128 v134, v[88:91] offset:55296
	s_waitcnt lgkmcnt(7)
	v_mfma_f32_32x32x16_bf16 v[48:63], v[202:205], v[206:209], v[48:63]
	s_waitcnt vmcnt(10)
	ds_write_b128 v134, v[92:95] offset:64512
	s_waitcnt lgkmcnt(7)
	v_mfma_f32_32x32x16_bf16 v[32:47], v[202:205], v[210:213], v[32:47]
	s_waitcnt vmcnt(9)
	ds_write_b128 v135, v[96:99] offset:18432
	s_waitcnt lgkmcnt(7)
	v_mfma_f32_32x32x16_bf16 v[16:31], v[214:217], v[206:209], v[16:31]
	v_mfma_f32_32x32x16_bf16 v[0:15], v[214:217], v[210:213], v[0:15]
	s_waitcnt vmcnt(8)
	ds_write_b128 v135, v[100:103] offset:27648
	s_waitcnt lgkmcnt(6)
	v_mfma_f32_32x32x16_bf16 v[48:63], v[222:225], v[226:229], v[48:63]
	s_waitcnt vmcnt(7)
	ds_write_b128 v128, v[104:107]
	s_waitcnt lgkmcnt(6)
	v_mfma_f32_32x32x16_bf16 v[32:47], v[222:225], v[230:233], v[32:47]
	s_waitcnt vmcnt(6)
	ds_write_b128 v128, v[108:111] offset:9216
	s_waitcnt lgkmcnt(6)
	v_mfma_f32_32x32x16_bf16 v[16:31], v[234:237], v[226:229], v[16:31]
	v_mfma_f32_32x32x16_bf16 v[0:15], v[234:237], v[230:233], v[0:15]
	s_waitcnt lgkmcnt(0)
	s_barrier
; template <class AS, class EP>
; DEVI void gemm_tile(const AS& as, const u16* __restrict__ Bt, int K, int m0, int n0, const EP& ep, char* lds) {
;     ...
;   GLOAD(ra0, rb0, 0); GLOAD(ra1, rb1, 1); LWRITE(0, ra0, rb0); __syncthreads();
;   for (int kt = 0; kt < KT; kt += 2) {
;     if (kt + 2 < KT) GLOAD(ra0, rb0, kt + 2);
;     __builtin_amdgcn_sched_barrier(0);
;     COMPUTE(0);
;     __builtin_amdgcn_sched_barrier(0);
;     LWRITE(1, ra1, rb1);
;     __syncthreads();
;     if (kt + 3 < KT) GLOAD(ra1, rb1, kt + 3);
;     __builtin_amdgcn_sched_barrier(0);
;     COMPUTE(1);
;     __builtin_amdgcn_sched_barrier(0);
;     if (kt + 2 < KT) LWRITE(0, ra0, rb0);
;     __syncthreads();
	global_load_dwordx4 v[88:91], v[112:113], off offset:1152
	global_load_dwordx4 v[92:95], v[114:115], off offset:1152
	global_load_dwordx4 v[96:99], v[116:117], off offset:1152
	global_load_dwordx4 v[100:103], v[118:119], off offset:1152
	global_load_dwordx4 v[104:107], v[120:121], off offset:1152
	global_load_dwordx4 v[108:111], v[122:123], off offset:1152
	ds_read_b128 v[170:173], v132 offset:55296
	ds_read_b128 v[174:177], v133
	ds_read_b128 v[178:181], v133 offset:4608
	ds_read_b128 v[182:185], v132 offset:59904
	ds_read_b128 v[186:189], v132 offset:55328
	ds_read_b128 v[190:193], v133 offset:32
	ds_read_b128 v[194:197], v133 offset:4640
	ds_read_b128 v[198:201], v132 offset:59936
	ds_read_b128 v[202:205], v132 offset:55360
	ds_read_b128 v[206:209], v133 offset:64
	ds_read_b128 v[210:213], v133 offset:4672
	ds_read_b128 v[214:217], v132 offset:59968
	s_waitcnt lgkmcnt(10)
	v_mfma_f32_32x32x16_bf16 v[48:63], v[170:173], v[174:177], v[48:63]
	s_waitcnt lgkmcnt(9)
	v_mfma_f32_32x32x16_bf16 v[32:47], v[170:173], v[178:181], v[32:47]
	s_waitcnt lgkmcnt(8)
	v_mfma_f32_32x32x16_bf16 v[16:31], v[182:185], v[174:177], v[16:31]
	v_mfma_f32_32x32x16_bf16 v[0:15], v[182:185], v[178:181], v[0:15]
	ds_read_b128 v[222:225], v132 offset:55392
	ds_read_b128 v[226:229], v133 offset:96
	ds_read_b128 v[230:233], v133 offset:4704
	ds_read_b128 v[234:237], v132 offset:60000
	s_waitcnt lgkmcnt(10)
	v_mfma_f32_32x32x16_bf16 v[48:63], v[186:189], v[190:193], v[48:63]
	s_waitcnt lgkmcnt(9)
	v_mfma_f32_32x32x16_bf16 v[32:47], v[186:189], v[194:197], v[32:47]
	s_waitcnt lgkmcnt(8)
	v_mfma_f32_32x32x16_bf16 v[16:31], v[198:201], v[190:193], v[16:31]
	v_mfma_f32_32x32x16_bf16 v[0:15], v[198:201], v[194:197], v[0:15]
	s_waitcnt vmcnt(11)
	ds_write_b128 v134, v[64:67]
	s_waitcnt lgkmcnt(7)
	v_mfma_f32_32x32x16_bf16 v[48:63], v[202:205], v[206:209], v[48:63]
	s_waitcnt vmcnt(10)
	ds_write_b128 v134, v[68:71] offset:9216
	s_waitcnt lgkmcnt(7)
	v_mfma_f32_32x32x16_bf16 v[32:47], v[202:205], v[210:213], v[32:47]
	s_waitcnt vmcnt(9)
	ds_write_b128 v134, v[72:75] offset:18432
	s_waitcnt lgkmcnt(7)
	v_mfma_f32_32x32x16_bf16 v[16:31], v[214:217], v[206:209], v[16:31]
	v_mfma_f32_32x32x16_bf16 v[0:15], v[214:217], v[210:213], v[0:15]
	s_waitcnt vmcnt(8)
	ds_write_b128 v134, v[76:79] offset:27648
	s_waitcnt lgkmcnt(6)
	v_mfma_f32_32x32x16_bf16 v[48:63], v[222:225], v[226:229], v[48:63]
	s_waitcnt vmcnt(7)
	ds_write_b128 v134, v[80:83] offset:36864
	s_waitcnt lgkmcnt(6)
	v_mfma_f32_32x32x16_bf16 v[32:47], v[222:225], v[230:233], v[32:47]
	s_waitcnt vmcnt(6)
	ds_write_b128 v134, v[84:87] offset:46080
	s_waitcnt lgkmcnt(6)
	v_mfma_f32_32x32x16_bf16 v[16:31], v[234:237], v[226:229], v[16:31]
	v_mfma_f32_32x32x16_bf16 v[0:15], v[234:237], v[230:233], v[0:15]
	s_waitcnt lgkmcnt(0)
	s_barrier
	global_load_dwordx4 v[64:67], v[112:113], off offset:1280
	global_load_dwordx4 v[68:71], v[114:115], off offset:1280
	global_load_dwordx4 v[72:75], v[116:117], off offset:1280
	global_load_dwordx4 v[76:79], v[118:119], off offset:1280
	global_load_dwordx4 v[80:83], v[120:121], off offset:1280
	global_load_dwordx4 v[84:87], v[122:123], off offset:1280
	ds_read_b128 v[170:173], v132
	ds_read_b128 v[174:177], v136 offset:36864
	ds_read_b128 v[178:181], v136 offset:41472
	ds_read_b128 v[182:185], v132 offset:4608
	ds_read_b128 v[186:189], v132 offset:32
	ds_read_b128 v[190:193], v136 offset:36896
	ds_read_b128 v[194:197], v136 offset:41504
	ds_read_b128 v[198:201], v132 offset:4640
	ds_read_b128 v[202:205], v132 offset:64
	ds_read_b128 v[206:209], v136 offset:36928
	ds_read_b128 v[210:213], v136 offset:41536
	ds_read_b128 v[214:217], v132 offset:4672
	s_waitcnt lgkmcnt(10)
	v_mfma_f32_32x32x16_bf16 v[48:63], v[170:173], v[174:177], v[48:63]
	s_waitcnt lgkmcnt(9)
	v_mfma_f32_32x32x16_bf16 v[32:47], v[170:173], v[178:181], v[32:47]
	s_waitcnt lgkmcnt(8)
	v_mfma_f32_32x32x16_bf16 v[16:31], v[182:185], v[174:177], v[16:31]
	v_mfma_f32_32x32x16_bf16 v[0:15], v[182:185], v[178:181], v[0:15]
	ds_read_b128 v[222:225], v132 offset:96
	ds_read_b128 v[226:229], v136 offset:36960
	ds_read_b128 v[230:233], v136 offset:41568
	ds_read_b128 v[234:237], v132 offset:4704
	s_waitcnt lgkmcnt(10)
	v_mfma_f32_32x32x16_bf16 v[48:63], v[186:189], v[190:193], v[48:63]
	s_waitcnt lgkmcnt(9)
	v_mfma_f32_32x32x16_bf16 v[32:47], v[186:189], v[194:197], v[32:47]
	s_waitcnt lgkmcnt(8)
	v_mfma_f32_32x32x16_bf16 v[16:31], v[198:201], v[190:193], v[16:31]
	v_mfma_f32_32x32x16_bf16 v[0:15], v[198:201], v[194:197], v[0:15]
	s_waitcnt vmcnt(11)
	ds_write_b128 v134, v[88:91] offset:55296
	s_waitcnt lgkmcnt(7)
	v_mfma_f32_32x32x16_bf16 v[48:63], v[202:205], v[206:209], v[48:63]
	s_waitcnt vmcnt(10)
	ds_write_b128 v134, v[92:95] offset:64512
	s_waitcnt lgkmcnt(7)
	v_mfma_f32_32x32x16_bf16 v[32:47], v[202:205], v[210:213], v[32:47]
	s_waitcnt vmcnt(9)
	ds_write_b128 v135, v[96:99] offset:18432
	s_waitcnt lgkmcnt(7)
	v_mfma_f32_32x32x16_bf16 v[16:31], v[214:217], v[206:209], v[16:31]
	v_mfma_f32_32x32x16_bf16 v[0:15], v[214:217], v[210:213], v[0:15]
	s_waitcnt vmcnt(8)
	ds_write_b128 v135, v[100:103] offset:27648
	s_waitcnt lgkmcnt(6)
	v_mfma_f32_32x32x16_bf16 v[48:63], v[222:225], v[226:229], v[48:63]
	s_waitcnt vmcnt(7)
	ds_write_b128 v128, v[104:107]
	s_waitcnt lgkmcnt(6)
	v_mfma_f32_32x32x16_bf16 v[32:47], v[222:225], v[230:233], v[32:47]
	s_waitcnt vmcnt(6)
	ds_write_b128 v128, v[108:111] offset:9216
	s_waitcnt lgkmcnt(6)
	v_mfma_f32_32x32x16_bf16 v[16:31], v[234:237], v[226:229], v[16:31]
	v_mfma_f32_32x32x16_bf16 v[0:15], v[234:237], v[230:233], v[0:15]
	s_waitcnt lgkmcnt(0)
	s_barrier
; template <class AS, class EP>
; DEVI void gemm_tile(const AS& as, const u16* __restrict__ Bt, int K, int m0, int n0, const EP& ep, char* lds) {
;     ...
;   GLOAD(ra0, rb0, 0); GLOAD(ra1, rb1, 1); LWRITE(0, ra0, rb0); __syncthreads();
;   for (int kt = 0; kt < KT; kt += 2) {
;     if (kt + 2 < KT) GLOAD(ra0, rb0, kt + 2);
;     __builtin_amdgcn_sched_barrier(0);
;     COMPUTE(0);
;     __builtin_amdgcn_sched_barrier(0);
;     LWRITE(1, ra1, rb1);
;     __syncthreads();
;     if (kt + 3 < KT) GLOAD(ra1, rb1, kt + 3);
;     __builtin_amdgcn_sched_barrier(0);
;     COMPUTE(1);
;     __builtin_amdgcn_sched_barrier(0);
;     if (kt + 2 < KT) LWRITE(0, ra0, rb0);
;     __syncthreads();
	global_load_dwordx4 v[88:91], v[112:113], off offset:1408
	global_load_dwordx4 v[92:95], v[114:115], off offset:1408
	global_load_dwordx4 v[96:99], v[116:117], off offset:1408
	global_load_dwordx4 v[100:103], v[118:119], off offset:1408
	global_load_dwordx4 v[104:107], v[120:121], off offset:1408
	global_load_dwordx4 v[108:111], v[122:123], off offset:1408
	ds_read_b128 v[170:173], v132 offset:55296
	ds_read_b128 v[174:177], v133
	ds_read_b128 v[178:181], v133 offset:4608
	ds_read_b128 v[182:185], v132 offset:59904
	ds_read_b128 v[186:189], v132 offset:55328
	ds_read_b128 v[190:193], v133 offset:32
	ds_read_b128 v[194:197], v133 offset:4640
	ds_read_b128 v[198:201], v132 offset:59936
	ds_read_b128 v[202:205], v132 offset:55360
	ds_read_b128 v[206:209], v133 offset:64
	ds_read_b128 v[210:213], v133 offset:4672
	ds_read_b128 v[214:217], v132 offset:59968
	s_waitcnt lgkmcnt(10)
	v_mfma_f32_32x32x16_bf16 v[48:63], v[170:173], v[174:177], v[48:63]
	s_waitcnt lgkmcnt(9)
	v_mfma_f32_32x32x16_bf16 v[32:47], v[170:173], v[178:181], v[32:47]
	s_waitcnt lgkmcnt(8)
	v_mfma_f32_32x32x16_bf16 v[16:31], v[182:185], v[174:177], v[16:31]
	v_mfma_f32_32x32x16_bf16 v[0:15], v[182:185], v[178:181], v[0:15]
	ds_read_b128 v[222:225], v132 offset:55392
	ds_read_b128 v[226:229], v133 offset:96
	ds_read_b128 v[230:233], v133 offset:4704
	ds_read_b128 v[234:237], v132 offset:60000
	s_waitcnt lgkmcnt(10)
	v_mfma_f32_32x32x16_bf16 v[48:63], v[186:189], v[190:193], v[48:63]
	s_waitcnt lgkmcnt(9)
	v_mfma_f32_32x32x16_bf16 v[32:47], v[186:189], v[194:197], v[32:47]
	s_waitcnt lgkmcnt(8)
	v_mfma_f32_32x32x16_bf16 v[16:31], v[198:201], v[190:193], v[16:31]
	v_mfma_f32_32x32x16_bf16 v[0:15], v[198:201], v[194:197], v[0:15]
	s_waitcnt vmcnt(11)
	ds_write_b128 v134, v[64:67]
	s_waitcnt lgkmcnt(7)
	v_mfma_f32_32x32x16_bf16 v[48:63], v[202:205], v[206:209], v[48:63]
	s_waitcnt vmcnt(10)
	ds_write_b128 v134, v[68:71] offset:9216
	s_waitcnt lgkmcnt(7)
	v_mfma_f32_32x32x16_bf16 v[32:47], v[202:205], v[210:213], v[32:47]
	s_waitcnt vmcnt(9)
	ds_write_b128 v134, v[72:75] offset:18432
	s_waitcnt lgkmcnt(7)
	v_mfma_f32_32x32x16_bf16 v[16:31], v[214:217], v[206:209], v[16:31]
	v_mfma_f32_32x32x16_bf16 v[0:15], v[214:217], v[210:213], v[0:15]
	s_waitcnt vmcnt(8)
	ds_write_b128 v134, v[76:79] offset:27648
	s_waitcnt lgkmcnt(6)
	v_mfma_f32_32x32x16_bf16 v[48:63], v[222:225], v[226:229], v[48:63]
	s_waitcnt vmcnt(7)
	ds_write_b128 v134, v[80:83] offset:36864
	s_waitcnt lgkmcnt(6)
	v_mfma_f32_32x32x16_bf16 v[32:47], v[222:225], v[230:233], v[32:47]
	s_waitcnt vmcnt(6)
	ds_write_b128 v134, v[84:87] offset:46080
	s_waitcnt lgkmcnt(6)
	v_mfma_f32_32x32x16_bf16 v[16:31], v[234:237], v[226:229], v[16:31]
	v_mfma_f32_32x32x16_bf16 v[0:15], v[234:237], v[230:233], v[0:15]
	s_waitcnt lgkmcnt(0)
	s_barrier
	global_load_dwordx4 v[64:67], v[112:113], off offset:1536
	global_load_dwordx4 v[68:71], v[114:115], off offset:1536
	global_load_dwordx4 v[72:75], v[116:117], off offset:1536
	global_load_dwordx4 v[76:79], v[118:119], off offset:1536
	global_load_dwordx4 v[80:83], v[120:121], off offset:1536
	global_load_dwordx4 v[84:87], v[122:123], off offset:1536
	ds_read_b128 v[170:173], v132
	ds_read_b128 v[174:177], v136 offset:36864
	ds_read_b128 v[178:181], v136 offset:41472
	ds_read_b128 v[182:185], v132 offset:4608
	ds_read_b128 v[186:189], v132 offset:32
	ds_read_b128 v[190:193], v136 offset:36896
	ds_read_b128 v[194:197], v136 offset:41504
	ds_read_b128 v[198:201], v132 offset:4640
	ds_read_b128 v[202:205], v132 offset:64
	ds_read_b128 v[206:209], v136 offset:36928
	ds_read_b128 v[210:213], v136 offset:41536
	ds_read_b128 v[214:217], v132 offset:4672
	s_waitcnt lgkmcnt(10)
	v_mfma_f32_32x32x16_bf16 v[48:63], v[170:173], v[174:177], v[48:63]
	s_waitcnt lgkmcnt(9)
	v_mfma_f32_32x32x16_bf16 v[32:47], v[170:173], v[178:181], v[32:47]
	s_waitcnt lgkmcnt(8)
	v_mfma_f32_32x32x16_bf16 v[16:31], v[182:185], v[174:177], v[16:31]
	v_mfma_f32_32x32x16_bf16 v[0:15], v[182:185], v[178:181], v[0:15]
	ds_read_b128 v[222:225], v132 offset:96
	ds_read_b128 v[226:229], v136 offset:36960
	ds_read_b128 v[230:233], v136 offset:41568
	ds_read_b128 v[234:237], v132 offset:4704
	s_waitcnt lgkmcnt(10)
	v_mfma_f32_32x32x16_bf16 v[48:63], v[186:189], v[190:193], v[48:63]
	s_waitcnt lgkmcnt(9)
	v_mfma_f32_32x32x16_bf16 v[32:47], v[186:189], v[194:197], v[32:47]
	s_waitcnt lgkmcnt(8)
	v_mfma_f32_32x32x16_bf16 v[16:31], v[198:201], v[190:193], v[16:31]
	v_mfma_f32_32x32x16_bf16 v[0:15], v[198:201], v[194:197], v[0:15]
	s_waitcnt vmcnt(11)
	ds_write_b128 v134, v[88:91] offset:55296
	s_waitcnt lgkmcnt(7)
	v_mfma_f32_32x32x16_bf16 v[48:63], v[202:205], v[206:209], v[48:63]
	s_waitcnt vmcnt(10)
	ds_write_b128 v134, v[92:95] offset:64512
	s_waitcnt lgkmcnt(7)
	v_mfma_f32_32x32x16_bf16 v[32:47], v[202:205], v[210:213], v[32:47]
	s_waitcnt vmcnt(9)
	ds_write_b128 v135, v[96:99] offset:18432
	s_waitcnt lgkmcnt(7)
	v_mfma_f32_32x32x16_bf16 v[16:31], v[214:217], v[206:209], v[16:31]
	v_mfma_f32_32x32x16_bf16 v[0:15], v[214:217], v[210:213], v[0:15]
	s_waitcnt vmcnt(8)
	ds_write_b128 v135, v[100:103] offset:27648
	s_waitcnt lgkmcnt(6)
	v_mfma_f32_32x32x16_bf16 v[48:63], v[222:225], v[226:229], v[48:63]
	s_waitcnt vmcnt(7)
	ds_write_b128 v128, v[104:107]
	s_waitcnt lgkmcnt(6)
	v_mfma_f32_32x32x16_bf16 v[32:47], v[222:225], v[230:233], v[32:47]
	s_waitcnt vmcnt(6)
	ds_write_b128 v128, v[108:111] offset:9216
	s_waitcnt lgkmcnt(6)
	v_mfma_f32_32x32x16_bf16 v[16:31], v[234:237], v[226:229], v[16:31]
	v_mfma_f32_32x32x16_bf16 v[0:15], v[234:237], v[230:233], v[0:15]
	s_waitcnt lgkmcnt(0)
	s_barrier
; template <class AS, class EP>
; DEVI void gemm_tile(const AS& as, const u16* __restrict__ Bt, int K, int m0, int n0, const EP& ep, char* lds) {
;     ...
;   GLOAD(ra0, rb0, 0); GLOAD(ra1, rb1, 1); LWRITE(0, ra0, rb0); __syncthreads();
;   for (int kt = 0; kt < KT; kt += 2) {
;     if (kt + 2 < KT) GLOAD(ra0, rb0, kt + 2);
;     __builtin_amdgcn_sched_barrier(0);
;     COMPUTE(0);
;     __builtin_amdgcn_sched_barrier(0);
;     LWRITE(1, ra1, rb1);
;     __syncthreads();
;     if (kt + 3 < KT) GLOAD(ra1, rb1, kt + 3);
;     __builtin_amdgcn_sched_barrier(0);
;     COMPUTE(1);
;     __builtin_amdgcn_sched_barrier(0);
;     if (kt + 2 < KT) LWRITE(0, ra0, rb0);
;     __syncthreads();
	global_load_dwordx4 v[88:91], v[112:113], off offset:1664
	global_load_dwordx4 v[92:95], v[114:115], off offset:1664
	global_load_dwordx4 v[96:99], v[116:117], off offset:1664
	global_load_dwordx4 v[100:103], v[118:119], off offset:1664
	global_load_dwordx4 v[104:107], v[120:121], off offset:1664
	global_load_dwordx4 v[108:111], v[122:123], off offset:1664
	ds_read_b128 v[170:173], v132 offset:55296
	ds_read_b128 v[174:177], v133
	ds_read_b128 v[178:181], v133 offset:4608
	ds_read_b128 v[182:185], v132 offset:59904
	ds_read_b128 v[186:189], v132 offset:55328
	ds_read_b128 v[190:193], v133 offset:32
	ds_read_b128 v[194:197], v133 offset:4640
	ds_read_b128 v[198:201], v132 offset:59936
	ds_read_b128 v[202:205], v132 offset:55360
	ds_read_b128 v[206:209], v133 offset:64
	ds_read_b128 v[210:213], v133 offset:4672
	ds_read_b128 v[214:217], v132 offset:59968
	s_waitcnt lgkmcnt(10)
	v_mfma_f32_32x32x16_bf16 v[48:63], v[170:173], v[174:177], v[48:63]
	s_waitcnt lgkmcnt(9)
	v_mfma_f32_32x32x16_bf16 v[32:47], v[170:173], v[178:181], v[32:47]
	s_waitcnt lgkmcnt(8)
	v_mfma_f32_32x32x16_bf16 v[16:31], v[182:185], v[174:177], v[16:31]
	v_mfma_f32_32x32x16_bf16 v[0:15], v[182:185], v[178:181], v[0:15]
	ds_read_b128 v[222:225], v132 offset:55392
	ds_read_b128 v[226:229], v133 offset:96
	ds_read_b128 v[230:233], v133 offset:4704
	ds_read_b128 v[234:237], v132 offset:60000
	s_waitcnt lgkmcnt(10)
	v_mfma_f32_32x32x16_bf16 v[48:63], v[186:189], v[190:193], v[48:63]
	s_waitcnt lgkmcnt(9)
	v_mfma_f32_32x32x16_bf16 v[32:47], v[186:189], v[194:197], v[32:47]
	s_waitcnt lgkmcnt(8)
	v_mfma_f32_32x32x16_bf16 v[16:31], v[198:201], v[190:193], v[16:31]
	v_mfma_f32_32x32x16_bf16 v[0:15], v[198:201], v[194:197], v[0:15]
	s_waitcnt vmcnt(11)
	ds_write_b128 v134, v[64:67]
	s_waitcnt lgkmcnt(7)
	v_mfma_f32_32x32x16_bf16 v[48:63], v[202:205], v[206:209], v[48:63]
	s_waitcnt vmcnt(10)
	ds_write_b128 v134, v[68:71] offset:9216
	s_waitcnt lgkmcnt(7)
	v_mfma_f32_32x32x16_bf16 v[32:47], v[202:205], v[210:213], v[32:47]
	s_waitcnt vmcnt(9)
	ds_write_b128 v134, v[72:75] offset:18432
	s_waitcnt lgkmcnt(7)
	v_mfma_f32_32x32x16_bf16 v[16:31], v[214:217], v[206:209], v[16:31]
	v_mfma_f32_32x32x16_bf16 v[0:15], v[214:217], v[210:213], v[0:15]
	s_waitcnt vmcnt(8)
	ds_write_b128 v134, v[76:79] offset:27648
	s_waitcnt lgkmcnt(6)
	v_mfma_f32_32x32x16_bf16 v[48:63], v[222:225], v[226:229], v[48:63]
	s_waitcnt vmcnt(7)
	ds_write_b128 v134, v[80:83] offset:36864
	s_waitcnt lgkmcnt(6)
	v_mfma_f32_32x32x16_bf16 v[32:47], v[222:225], v[230:233], v[32:47]
	s_waitcnt vmcnt(6)
	ds_write_b128 v134, v[84:87] offset:46080
	s_waitcnt lgkmcnt(6)
	v_mfma_f32_32x32x16_bf16 v[16:31], v[234:237], v[226:229], v[16:31]
	v_mfma_f32_32x32x16_bf16 v[0:15], v[234:237], v[230:233], v[0:15]
	s_waitcnt lgkmcnt(0)
	s_barrier
	global_load_dwordx4 v[64:67], v[112:113], off offset:1792
	global_load_dwordx4 v[68:71], v[114:115], off offset:1792
	global_load_dwordx4 v[72:75], v[116:117], off offset:1792
	global_load_dwordx4 v[76:79], v[118:119], off offset:1792
	global_load_dwordx4 v[80:83], v[120:121], off offset:1792
	global_load_dwordx4 v[84:87], v[122:123], off offset:1792
	ds_read_b128 v[170:173], v132
	ds_read_b128 v[174:177], v136 offset:36864
	ds_read_b128 v[178:181], v136 offset:41472
	ds_read_b128 v[182:185], v132 offset:4608
	ds_read_b128 v[186:189], v132 offset:32
	ds_read_b128 v[190:193], v136 offset:36896
	ds_read_b128 v[194:197], v136 offset:41504
	ds_read_b128 v[198:201], v132 offset:4640
	ds_read_b128 v[202:205], v132 offset:64
	ds_read_b128 v[206:209], v136 offset:36928
	ds_read_b128 v[210:213], v136 offset:41536
	ds_read_b128 v[214:217], v132 offset:4672
	s_waitcnt lgkmcnt(10)
	v_mfma_f32_32x32x16_bf16 v[48:63], v[170:173], v[174:177], v[48:63]
	s_waitcnt lgkmcnt(9)
	v_mfma_f32_32x32x16_bf16 v[32:47], v[170:173], v[178:181], v[32:47]
	s_waitcnt lgkmcnt(8)
	v_mfma_f32_32x32x16_bf16 v[16:31], v[182:185], v[174:177], v[16:31]
	v_mfma_f32_32x32x16_bf16 v[0:15], v[182:185], v[178:181], v[0:15]
	ds_read_b128 v[222:225], v132 offset:96
	ds_read_b128 v[226:229], v136 offset:36960
	ds_read_b128 v[230:233], v136 offset:41568
	ds_read_b128 v[234:237], v132 offset:4704
	s_waitcnt lgkmcnt(10)
	v_mfma_f32_32x32x16_bf16 v[48:63], v[186:189], v[190:193], v[48:63]
	s_waitcnt lgkmcnt(9)
	v_mfma_f32_32x32x16_bf16 v[32:47], v[186:189], v[194:197], v[32:47]
	s_waitcnt lgkmcnt(8)
	v_mfma_f32_32x32x16_bf16 v[16:31], v[198:201], v[190:193], v[16:31]
	v_mfma_f32_32x32x16_bf16 v[0:15], v[198:201], v[194:197], v[0:15]
	s_waitcnt vmcnt(11)
	ds_write_b128 v134, v[88:91] offset:55296
	s_waitcnt lgkmcnt(7)
	v_mfma_f32_32x32x16_bf16 v[48:63], v[202:205], v[206:209], v[48:63]
	s_waitcnt vmcnt(10)
	ds_write_b128 v134, v[92:95] offset:64512
	s_waitcnt lgkmcnt(7)
	v_mfma_f32_32x32x16_bf16 v[32:47], v[202:205], v[210:213], v[32:47]
	s_waitcnt vmcnt(9)
	ds_write_b128 v135, v[96:99] offset:18432
	s_waitcnt lgkmcnt(7)
	v_mfma_f32_32x32x16_bf16 v[16:31], v[214:217], v[206:209], v[16:31]
	v_mfma_f32_32x32x16_bf16 v[0:15], v[214:217], v[210:213], v[0:15]
	s_waitcnt vmcnt(8)
	ds_write_b128 v135, v[100:103] offset:27648
	s_waitcnt lgkmcnt(6)
	v_mfma_f32_32x32x16_bf16 v[48:63], v[222:225], v[226:229], v[48:63]
	s_waitcnt vmcnt(7)
	ds_write_b128 v128, v[104:107]
	s_waitcnt lgkmcnt(6)
	v_mfma_f32_32x32x16_bf16 v[32:47], v[222:225], v[230:233], v[32:47]
	s_waitcnt vmcnt(6)
	ds_write_b128 v128, v[108:111] offset:9216
	s_waitcnt lgkmcnt(6)
	v_mfma_f32_32x32x16_bf16 v[16:31], v[234:237], v[226:229], v[16:31]
	v_mfma_f32_32x32x16_bf16 v[0:15], v[234:237], v[230:233], v[0:15]
	s_waitcnt lgkmcnt(0)
	s_barrier
; template <class AS, class EP>
; DEVI void gemm_tile(const AS& as, const u16* __restrict__ Bt, int K, int m0, int n0, const EP& ep, char* lds) {
;     ...
;   GLOAD(ra0, rb0, 0); GLOAD(ra1, rb1, 1); LWRITE(0, ra0, rb0); __syncthreads();
;   for (int kt = 0; kt < KT; kt += 2) {
;     if (kt + 2 < KT) GLOAD(ra0, rb0, kt + 2);
;     __builtin_amdgcn_sched_barrier(0);
;     COMPUTE(0);
;     __builtin_amdgcn_sched_barrier(0);
;     LWRITE(1, ra1, rb1);
;     __syncthreads();
;     if (kt + 3 < KT) GLOAD(ra1, rb1, kt + 3);
;     __builtin_amdgcn_sched_barrier(0);
;     COMPUTE(1);
;     __builtin_amdgcn_sched_barrier(0);
;     if (kt + 2 < KT) LWRITE(0, ra0, rb0);
;     __syncthreads();
	global_load_dwordx4 v[88:91], v[112:113], off offset:1920
	global_load_dwordx4 v[92:95], v[114:115], off offset:1920
	global_load_dwordx4 v[96:99], v[116:117], off offset:1920
	global_load_dwordx4 v[100:103], v[118:119], off offset:1920
	global_load_dwordx4 v[104:107], v[120:121], off offset:1920
	global_load_dwordx4 v[108:111], v[122:123], off offset:1920
	ds_read_b128 v[170:173], v132 offset:55296
	ds_read_b128 v[174:177], v133
	ds_read_b128 v[178:181], v133 offset:4608
	ds_read_b128 v[182:185], v132 offset:59904
	ds_read_b128 v[186:189], v132 offset:55328
	ds_read_b128 v[190:193], v133 offset:32
	ds_read_b128 v[194:197], v133 offset:4640
	ds_read_b128 v[198:201], v132 offset:59936
	ds_read_b128 v[202:205], v132 offset:55360
	ds_read_b128 v[206:209], v133 offset:64
	ds_read_b128 v[210:213], v133 offset:4672
	ds_read_b128 v[214:217], v132 offset:59968
	s_waitcnt lgkmcnt(10)
	v_mfma_f32_32x32x16_bf16 v[48:63], v[170:173], v[174:177], v[48:63]
	s_waitcnt lgkmcnt(9)
	v_mfma_f32_32x32x16_bf16 v[32:47], v[170:173], v[178:181], v[32:47]
	s_waitcnt lgkmcnt(8)
	v_mfma_f32_32x32x16_bf16 v[16:31], v[182:185], v[174:177], v[16:31]
	v_mfma_f32_32x32x16_bf16 v[0:15], v[182:185], v[178:181], v[0:15]
	ds_read_b128 v[222:225], v132 offset:55392
	ds_read_b128 v[226:229], v133 offset:96
	ds_read_b128 v[230:233], v133 offset:4704
	ds_read_b128 v[234:237], v132 offset:60000
	s_waitcnt lgkmcnt(10)
	v_mfma_f32_32x32x16_bf16 v[48:63], v[186:189], v[190:193], v[48:63]
	s_waitcnt lgkmcnt(9)
	v_mfma_f32_32x32x16_bf16 v[32:47], v[186:189], v[194:197], v[32:47]
	s_waitcnt lgkmcnt(8)
	v_mfma_f32_32x32x16_bf16 v[16:31], v[198:201], v[190:193], v[16:31]
	v_mfma_f32_32x32x16_bf16 v[0:15], v[198:201], v[194:197], v[0:15]
	s_waitcnt vmcnt(11)
	ds_write_b128 v134, v[64:67]
	s_waitcnt lgkmcnt(7)
	v_mfma_f32_32x32x16_bf16 v[48:63], v[202:205], v[206:209], v[48:63]
	s_waitcnt vmcnt(10)
	ds_write_b128 v134, v[68:71] offset:9216
	s_waitcnt lgkmcnt(7)
	v_mfma_f32_32x32x16_bf16 v[32:47], v[202:205], v[210:213], v[32:47]
	s_waitcnt vmcnt(9)
	ds_write_b128 v134, v[72:75] offset:18432
	s_waitcnt lgkmcnt(7)
	v_mfma_f32_32x32x16_bf16 v[16:31], v[214:217], v[206:209], v[16:31]
	v_mfma_f32_32x32x16_bf16 v[0:15], v[214:217], v[210:213], v[0:15]
	s_waitcnt vmcnt(8)
	ds_write_b128 v134, v[76:79] offset:27648
	s_waitcnt lgkmcnt(6)
	v_mfma_f32_32x32x16_bf16 v[48:63], v[222:225], v[226:229], v[48:63]
	s_waitcnt vmcnt(7)
	ds_write_b128 v134, v[80:83] offset:36864
	s_waitcnt lgkmcnt(6)
	v_mfma_f32_32x32x16_bf16 v[32:47], v[222:225], v[230:233], v[32:47]
	s_waitcnt vmcnt(6)
	ds_write_b128 v134, v[84:87] offset:46080
	s_waitcnt lgkmcnt(6)
	v_mfma_f32_32x32x16_bf16 v[16:31], v[234:237], v[226:229], v[16:31]
	v_mfma_f32_32x32x16_bf16 v[0:15], v[234:237], v[230:233], v[0:15]
	s_waitcnt lgkmcnt(0)
	s_barrier
	ds_read_b128 v[170:173], v132
	ds_read_b128 v[174:177], v136 offset:36864
	ds_read_b128 v[178:181], v136 offset:41472
	ds_read_b128 v[182:185], v132 offset:4608
	ds_read_b128 v[186:189], v132 offset:32
	ds_read_b128 v[190:193], v136 offset:36896
	ds_read_b128 v[194:197], v136 offset:41504
	ds_read_b128 v[198:201], v132 offset:4640
	ds_read_b128 v[202:205], v132 offset:64
	ds_read_b128 v[206:209], v136 offset:36928
	ds_read_b128 v[210:213], v136 offset:41536
	ds_read_b128 v[214:217], v132 offset:4672
	s_waitcnt lgkmcnt(10)
	v_mfma_f32_32x32x16_bf16 v[48:63], v[170:173], v[174:177], v[48:63]
	s_waitcnt lgkmcnt(9)
	v_mfma_f32_32x32x16_bf16 v[32:47], v[170:173], v[178:181], v[32:47]
	s_waitcnt lgkmcnt(8)
	v_mfma_f32_32x32x16_bf16 v[16:31], v[182:185], v[174:177], v[16:31]
	v_mfma_f32_32x32x16_bf16 v[0:15], v[182:185], v[178:181], v[0:15]
	ds_read_b128 v[222:225], v132 offset:96
	ds_read_b128 v[226:229], v136 offset:36960
	ds_read_b128 v[230:233], v136 offset:41568
	ds_read_b128 v[234:237], v132 offset:4704
	s_waitcnt lgkmcnt(10)
	v_mfma_f32_32x32x16_bf16 v[48:63], v[186:189], v[190:193], v[48:63]
	s_waitcnt lgkmcnt(9)
	v_mfma_f32_32x32x16_bf16 v[32:47], v[186:189], v[194:197], v[32:47]
	s_waitcnt lgkmcnt(8)
	v_mfma_f32_32x32x16_bf16 v[16:31], v[198:201], v[190:193], v[16:31]
	v_mfma_f32_32x32x16_bf16 v[0:15], v[198:201], v[194:197], v[0:15]
	s_waitcnt vmcnt(5)
	ds_write_b128 v134, v[88:91] offset:55296
	s_waitcnt lgkmcnt(7)
	v_mfma_f32_32x32x16_bf16 v[48:63], v[202:205], v[206:209], v[48:63]
	s_waitcnt vmcnt(4)
	ds_write_b128 v134, v[92:95] offset:64512
	s_waitcnt lgkmcnt(7)
	v_mfma_f32_32x32x16_bf16 v[32:47], v[202:205], v[210:213], v[32:47]
	s_waitcnt vmcnt(3)
	ds_write_b128 v135, v[96:99] offset:18432
	s_waitcnt lgkmcnt(7)
	v_mfma_f32_32x32x16_bf16 v[16:31], v[214:217], v[206:209], v[16:31]
	v_mfma_f32_32x32x16_bf16 v[0:15], v[214:217], v[210:213], v[0:15]
	s_waitcnt vmcnt(2)
	ds_write_b128 v135, v[100:103] offset:27648
	s_waitcnt lgkmcnt(6)
	v_mfma_f32_32x32x16_bf16 v[48:63], v[222:225], v[226:229], v[48:63]
	s_waitcnt vmcnt(1)
	ds_write_b128 v128, v[104:107]
	s_waitcnt lgkmcnt(6)
	v_mfma_f32_32x32x16_bf16 v[32:47], v[222:225], v[230:233], v[32:47]
	s_waitcnt vmcnt(0)
	ds_write_b128 v128, v[108:111] offset:9216
	s_waitcnt lgkmcnt(6)
	v_mfma_f32_32x32x16_bf16 v[16:31], v[234:237], v[226:229], v[16:31]
	v_mfma_f32_32x32x16_bf16 v[0:15], v[234:237], v[230:233], v[0:15]
	s_waitcnt lgkmcnt(0)
	s_barrier
; DEVI int crow(int r, int hi) { return (r & 3) + 8 * (r >> 2) + 4 * hi; }
;   DEVI void operator()(const f32x16 (&acc)[2][2], int m0, int n0, int wm, int wn, int r32, int hi, char* lds) const {
;     constexpr int RS = 272;
; #pragma unroll
;     for (int i = 0; i < 2; ++i)
; #pragma unroll
;       for (int j = 0; j < 2; ++j)
; #pragma unroll
;         for (int r = 0; r < 16; ++r) {
;           int row = wm * 64 + i * 32 + crow(r, hi), col = wn * 64 + j * 32 + r32;
;           *(h16*)(lds + row * RS + col * 2) = (h16)acc[i][j][r];
;         }
;     __syncthreads();
	ds_read_b128 v[170:173], v132 offset:55296
	ds_read_b128 v[174:177], v133
	ds_read_b128 v[178:181], v133 offset:4608
	ds_read_b128 v[182:185], v132 offset:59904
	ds_read_b128 v[186:189], v132 offset:55328
	ds_read_b128 v[190:193], v133 offset:32
	ds_read_b128 v[194:197], v133 offset:4640
	ds_read_b128 v[198:201], v132 offset:59936
	ds_read_b128 v[202:205], v132 offset:55360
	ds_read_b128 v[206:209], v133 offset:64
	ds_read_b128 v[210:213], v133 offset:4672
	ds_read_b128 v[214:217], v132 offset:59968
	s_waitcnt lgkmcnt(10)
	v_mfma_f32_32x32x16_bf16 v[48:63], v[170:173], v[174:177], v[48:63]
	s_waitcnt lgkmcnt(9)
	v_mfma_f32_32x32x16_bf16 v[32:47], v[170:173], v[178:181], v[32:47]
	s_waitcnt lgkmcnt(8)
	v_mfma_f32_32x32x16_bf16 v[16:31], v[182:185], v[174:177], v[16:31]
	v_mfma_f32_32x32x16_bf16 v[0:15], v[182:185], v[178:181], v[0:15]
	ds_read_b128 v[222:225], v132 offset:55392
	ds_read_b128 v[226:229], v133 offset:96
	ds_read_b128 v[230:233], v133 offset:4704
	ds_read_b128 v[234:237], v132 offset:60000
	s_waitcnt lgkmcnt(10)
	v_mfma_f32_32x32x16_bf16 v[48:63], v[186:189], v[190:193], v[48:63]
	s_waitcnt lgkmcnt(9)
	v_mfma_f32_32x32x16_bf16 v[32:47], v[186:189], v[194:197], v[32:47]
	s_waitcnt lgkmcnt(8)
	v_mfma_f32_32x32x16_bf16 v[16:31], v[198:201], v[190:193], v[16:31]
	v_mfma_f32_32x32x16_bf16 v[0:15], v[198:201], v[194:197], v[0:15]
	s_waitcnt lgkmcnt(6)
	v_mfma_f32_32x32x16_bf16 v[48:63], v[202:205], v[206:209], v[48:63]
	s_waitcnt lgkmcnt(5)
	v_mfma_f32_32x32x16_bf16 v[32:47], v[202:205], v[210:213], v[32:47]
	s_waitcnt lgkmcnt(4)
	v_mfma_f32_32x32x16_bf16 v[16:31], v[214:217], v[206:209], v[16:31]
	v_mfma_f32_32x32x16_bf16 v[0:15], v[214:217], v[210:213], v[0:15]
	s_waitcnt lgkmcnt(2)
	v_mfma_f32_32x32x16_bf16 v[48:63], v[222:225], v[226:229], v[48:63]
	s_waitcnt lgkmcnt(1)
	v_mfma_f32_32x32x16_bf16 v[32:47], v[222:225], v[230:233], v[32:47]
	s_waitcnt lgkmcnt(0)
	v_mfma_f32_32x32x16_bf16 v[16:31], v[234:237], v[226:229], v[16:31]
	v_mfma_f32_32x32x16_bf16 v[0:15], v[234:237], v[230:233], v[0:15]
	s_nop 9
	v_cvt_f16_f32_e32 v48, v48
	v_lshl_or_b32 v64, v124, 2, v127
	v_cvt_f16_f32_e32 v49, v49
	v_lshlrev_b32_e32 v65, 1, v125
	v_lshl_add_u32 v66, v126, 7, 16
	v_mul_lo_u32 v64, v64, s27
	v_cvt_f16_f32_e32 v50, v50
	v_add3_u32 v64, v66, v65, v64
	v_cvt_f16_f32_e32 v51, v51
	s_barrier
	ds_write_b16 v64, v48
	ds_write_b16 v64, v49 offset:272
	ds_write_b16 v64, v50 offset:544
	ds_write_b16 v64, v51 offset:816
	v_cvt_f16_f32_e32 v48, v52
	v_cvt_f16_f32_e32 v49, v53
	v_cvt_f16_f32_e32 v50, v54
	v_cvt_f16_f32_e32 v51, v55
	ds_write_b16 v64, v48 offset:2176
	ds_write_b16 v64, v49 offset:2448
	ds_write_b16 v64, v50 offset:2720
	ds_write_b16 v64, v51 offset:2992
	v_cvt_f16_f32_e32 v48, v56
	v_cvt_f16_f32_e32 v49, v57
	v_cvt_f16_f32_e32 v50, v58
	v_cvt_f16_f32_e32 v51, v59
	ds_write_b16 v64, v48 offset:4352
	ds_write_b16 v64, v49 offset:4624
	ds_write_b16 v64, v50 offset:4896
	ds_write_b16 v64, v51 offset:5168
	v_cvt_f16_f32_e32 v48, v60
	v_cvt_f16_f32_e32 v32, v32
	v_cvt_f16_f32_e32 v49, v61
	v_cvt_f16_f32_e32 v33, v33
	v_cvt_f16_f32_e32 v50, v62
	v_cvt_f16_f32_e32 v34, v34
	v_cvt_f16_f32_e32 v51, v63
	v_cvt_f16_f32_e32 v35, v35
	ds_write_b16 v64, v48 offset:6528
	ds_write_b16 v64, v49 offset:6800
	ds_write_b16 v64, v50 offset:7072
	ds_write_b16 v64, v51 offset:7344
	ds_write_b16 v64, v32 offset:64
	ds_write_b16 v64, v33 offset:336
	ds_write_b16 v64, v34 offset:608
	ds_write_b16 v64, v35 offset:880
	v_cvt_f16_f32_e32 v32, v36
	v_cvt_f16_f32_e32 v33, v37
	v_cvt_f16_f32_e32 v34, v38
	v_cvt_f16_f32_e32 v35, v39
	ds_write_b16 v64, v32 offset:2240
	ds_write_b16 v64, v33 offset:2512
	ds_write_b16 v64, v34 offset:2784
	ds_write_b16 v64, v35 offset:3056
	v_cvt_f16_f32_e32 v32, v40
	v_cvt_f16_f32_e32 v33, v41
	v_cvt_f16_f32_e32 v34, v42
	v_cvt_f16_f32_e32 v35, v43
	ds_write_b16 v64, v32 offset:4416
	ds_write_b16 v64, v33 offset:4688
	ds_write_b16 v64, v34 offset:4960
	ds_write_b16 v64, v35 offset:5232
	v_cvt_f16_f32_e32 v32, v44
	v_cvt_f16_f32_e32 v16, v16
	v_cvt_f16_f32_e32 v33, v45
	v_cvt_f16_f32_e32 v17, v17
	v_cvt_f16_f32_e32 v34, v46
	v_cvt_f16_f32_e32 v18, v18
	v_cvt_f16_f32_e32 v35, v47
	v_cvt_f16_f32_e32 v19, v19
	ds_write_b16 v64, v32 offset:6592
	ds_write_b16 v64, v33 offset:6864
	ds_write_b16 v64, v34 offset:7136
	ds_write_b16 v64, v35 offset:7408
	ds_write_b16 v64, v16 offset:8704
	ds_write_b16 v64, v17 offset:8976
	ds_write_b16 v64, v18 offset:9248
	ds_write_b16 v64, v19 offset:9520
	v_cvt_f16_f32_e32 v16, v20
	v_cvt_f16_f32_e32 v17, v21
	v_cvt_f16_f32_e32 v18, v22
	v_cvt_f16_f32_e32 v19, v23
	ds_write_b16 v64, v16 offset:10880
	ds_write_b16 v64, v17 offset:11152
	ds_write_b16 v64, v18 offset:11424
	ds_write_b16 v64, v19 offset:11696
	v_cvt_f16_f32_e32 v16, v24
	v_cvt_f16_f32_e32 v17, v25
	v_cvt_f16_f32_e32 v18, v26
	v_cvt_f16_f32_e32 v19, v27
	ds_write_b16 v64, v16 offset:13056
	ds_write_b16 v64, v17 offset:13328
	ds_write_b16 v64, v18 offset:13600
	ds_write_b16 v64, v19 offset:13872
	v_cvt_f16_f32_e32 v16, v28
	v_cvt_f16_f32_e32 v0, v0
	v_cvt_f16_f32_e32 v17, v29
	v_cvt_f16_f32_e32 v1, v1
	v_cvt_f16_f32_e32 v18, v30
	v_cvt_f16_f32_e32 v2, v2
	v_cvt_f16_f32_e32 v19, v31
	v_cvt_f16_f32_e32 v3, v3
	ds_write_b16 v64, v16 offset:15232
	ds_write_b16 v64, v17 offset:15504
	ds_write_b16 v64, v18 offset:15776
	ds_write_b16 v64, v19 offset:16048
	ds_write_b16 v64, v0 offset:8768
	ds_write_b16 v64, v1 offset:9040
	ds_write_b16 v64, v2 offset:9312
	ds_write_b16 v64, v3 offset:9584
	v_cvt_f16_f32_e32 v0, v4
	v_cvt_f16_f32_e32 v1, v5
	v_cvt_f16_f32_e32 v2, v6
	v_cvt_f16_f32_e32 v3, v7
	ds_write_b16 v64, v0 offset:10944
	ds_write_b16 v64, v1 offset:11216
	ds_write_b16 v64, v2 offset:11488
	ds_write_b16 v64, v3 offset:11760
	v_cvt_f16_f32_e32 v0, v8
	v_cvt_f16_f32_e32 v1, v9
	v_cvt_f16_f32_e32 v2, v10
	v_cvt_f16_f32_e32 v3, v11
	ds_write_b16 v64, v0 offset:13120
	ds_write_b16 v64, v1 offset:13392
	ds_write_b16 v64, v2 offset:13664
	ds_write_b16 v64, v3 offset:13936
	v_cvt_f16_f32_e32 v0, v12
	v_cvt_f16_f32_e32 v1, v13
	v_cvt_f16_f32_e32 v2, v14
	v_cvt_f16_f32_e32 v3, v15
	ds_write_b16 v64, v0 offset:15296
	ds_write_b16 v64, v1 offset:15568
	ds_write_b16 v64, v2 offset:15840
	ds_write_b16 v64, v3 offset:16112
	v_mov_b32_e32 v2, v131
	s_waitcnt lgkmcnt(0)
	s_barrier
; DEVI int ltid() { int t = __builtin_amdgcn_workitem_id_x(); asm volatile("" : "+v"(t)); return t; }
;   DEVI void operator()(const f32x16 (&acc)[2][2], int m0, int n0, int wm, int wn, int r32, int hi, char* lds) const {
;     ...
;     const int tid = ltid();
; #pragma unroll
;     for (int i = 0; i < 8; ++i) {
;       int c = tid + i * 512; int row = c >> 4, ch = c & 15;
;       int col = n0 + ch * 8;
;       if (col < nvalid) *(u32x4*)(Z + (size_t)(m0 + row) * ldz + col) = *(const u32x4*)(lds + row * RS + ch * 16);
;     }
;     __syncthreads();
	s_movk_i32 s6, 0x700
	v_and_b32_e32 v3, 15, v2
	v_lshlrev_b32_e32 v0, 3, v3
	v_subrev_u32_e32 v0, s12, v0
	v_add_u32_e32 v0, s16, v0
	v_cmp_gt_i32_e32 vcc, s6, v0
	s_and_saveexec_b64 s[12:13], vcc
	s_cbranch_execz .LBB0_959
	v_lshl_add_u32 v12, v3, 4, 16
	v_ashrrev_i32_e32 v3, 4, v2
	v_mad_u64_u32 v[4:5], s[6:7], v3, s27, v[12:13]
	v_add_u32_e32 v3, s18, v3
	v_mov_b64_e32 v[14:15], s[8:9]
	v_ashrrev_i32_e32 v1, 31, v0
	ds_read_b128 v[4:7], v4
	v_mad_i64_i32 v[8:9], s[6:7], v3, s25, v[14:15]
	v_add_u32_e32 v3, 0x200, v2
	v_lshlrev_b64 v[16:17], 1, v[0:1]
	v_ashrrev_i32_e32 v3, 4, v3
	v_lshl_add_u64 v[0:1], v[8:9], 0, v[16:17]
	v_mad_u64_u32 v[8:9], s[6:7], v3, s27, v[12:13]
	ds_read_b128 v[8:11], v8
	s_waitcnt lgkmcnt(1)
	global_store_dwordx4 v[0:1], v[4:7], off
	v_add_u32_e32 v0, s18, v3
	v_mad_i64_i32 v[0:1], s[6:7], v0, s25, v[14:15]
	v_lshl_add_u64 v[0:1], v[0:1], 0, v[16:17]
	s_waitcnt lgkmcnt(0)
	global_store_dwordx4 v[0:1], v[8:11], off
	v_add_u32_e32 v0, 0x400, v2
	v_ashrrev_i32_e32 v3, 4, v0
	v_mad_u64_u32 v[0:1], s[6:7], v3, s27, v[12:13]
	ds_read_b128 v[4:7], v0
	v_add_u32_e32 v0, s18, v3
	v_add_u32_e32 v3, 0x600, v2
	v_ashrrev_i32_e32 v3, 4, v3
	v_mad_u64_u32 v[8:9], s[6:7], v3, s27, v[12:13]
	v_mad_i64_i32 v[0:1], s[6:7], v0, s25, v[14:15]
	ds_read_b128 v[8:11], v8
	v_lshl_add_u64 v[0:1], v[0:1], 0, v[16:17]
	s_waitcnt lgkmcnt(1)
	global_store_dwordx4 v[0:1], v[4:7], off
	v_add_u32_e32 v0, s18, v3
	v_mad_i64_i32 v[0:1], s[6:7], v0, s25, v[14:15]
	v_lshl_add_u64 v[0:1], v[0:1], 0, v[16:17]
	s_waitcnt lgkmcnt(0)
	global_store_dwordx4 v[0:1], v[8:11], off
	v_add_u32_e32 v0, 0x800, v2
	v_ashrrev_i32_e32 v3, 4, v0
	v_mad_u64_u32 v[0:1], s[6:7], v3, s27, v[12:13]
	ds_read_b128 v[4:7], v0
	v_add_u32_e32 v0, s18, v3
	v_add_u32_e32 v3, 0xa00, v2
	v_ashrrev_i32_e32 v3, 4, v3
	v_mad_u64_u32 v[8:9], s[6:7], v3, s27, v[12:13]
	v_mad_i64_i32 v[0:1], s[6:7], v0, s25, v[14:15]
	ds_read_b128 v[8:11], v8
	v_lshl_add_u64 v[0:1], v[0:1], 0, v[16:17]
	s_waitcnt lgkmcnt(1)
	global_store_dwordx4 v[0:1], v[4:7], off
	v_add_u32_e32 v0, s18, v3
	v_mad_i64_i32 v[0:1], s[6:7], v0, s25, v[14:15]
	v_lshl_add_u64 v[0:1], v[0:1], 0, v[16:17]
	s_waitcnt lgkmcnt(0)
	global_store_dwordx4 v[0:1], v[8:11], off
	v_add_u32_e32 v0, 0xc00, v2
	v_ashrrev_i32_e32 v3, 4, v0
	v_mad_u64_u32 v[0:1], s[6:7], v3, s27, v[12:13]
	ds_read_b128 v[4:7], v0
	v_add_u32_e32 v0, s18, v3
	v_mad_i64_i32 v[0:1], s[6:7], v0, s25, v[14:15]
	v_lshl_add_u64 v[8:9], v[0:1], 0, v[16:17]
	v_add_u32_e32 v0, 0xe00, v2
	v_ashrrev_i32_e32 v10, 4, v0
	v_mad_u64_u32 v[0:1], s[6:7], v10, s27, v[12:13]
	ds_read_b128 v[0:3], v0
	s_waitcnt lgkmcnt(1)
	global_store_dwordx4 v[8:9], v[4:7], off
	s_nop 1
	v_add_u32_e32 v4, s18, v10
	v_mad_i64_i32 v[4:5], s[6:7], v4, s25, v[14:15]
	v_lshl_add_u64 v[4:5], v[4:5], 0, v[16:17]
	s_waitcnt lgkmcnt(0)
	global_store_dwordx4 v[4:5], v[0:3], off
	s_branch .LBB0_959
